# adds K-loop issue-slot trims (m0 write before address add replaces s_nop; mid-block setprio pair dropped) to v019
# baseline (speedup 1.0000x reference)
.Lmy_nobar2_2:
	ds_read_b128 v[152:155], v157
	ds_read_b128 v[160:163], v157 offset:1024
	ds_read_b128 v[164:167], v157 offset:2048
	ds_read_b128 v[168:171], v157 offset:3072
	ds_read_b128 v[172:175], v158
	ds_read_b128 v[176:179], v158 offset:1024
	ds_read_b128 v[180:183], v158 offset:2048
	ds_read_b128 v[184:187], v158 offset:3072
	s_add_u32 s34, s50, 0xfffc0080
	s_addc_u32 s35, s51, -1
	s_cmp_eq_u32 s86, 12
	s_cselect_b32 s55, s7, s35
	s_cselect_b32 s54, s8, s34
	s_cselect_b32 s53, s12, s41
	s_cselect_b32 s52, s13, s29
	v_lshl_add_u64 v[220:221], s[50:51], 0, v[144:145]
	s_add_i32 m0, s63, 0xc000
	ds_read_b128 v[188:191], v159
	ds_read_b128 v[192:195], v159 offset:1024
	ds_read_b128 v[196:199], v159 offset:2048
	ds_read_b128 v[200:203], v159 offset:3072
	ds_read_b128 v[204:207], v159 offset:4096
	ds_read_b128 v[208:211], v159 offset:5120
	ds_read_b128 v[212:215], v159 offset:6144
	ds_read_b128 v[216:219], v159 offset:7168
	global_load_lds_dwordx4 v[220:221], off
	s_add_i32 m0, s63, 0xe000
	v_lshl_add_u64 v[220:221], s[50:51], 0, v[146:147]
	global_load_lds_dwordx4 v[220:221], off
	s_waitcnt vmcnt(8)
	s_waitcnt lgkmcnt(0)
	s_barrier
	s_setprio 1
	s_waitcnt lgkmcnt(0)
	v_mfma_f32_16x16x32_bf16 v[124:127], v[152:155], v[188:191], 0
	v_mfma_f32_16x16x32_bf16 v[120:123], v[164:167], v[188:191], 0
	v_mfma_f32_16x16x32_bf16 v[108:111], v[152:155], v[196:199], 0
	v_mfma_f32_16x16x32_bf16 v[104:107], v[164:167], v[196:199], 0
	v_mfma_f32_16x16x32_bf16 v[92:95], v[152:155], v[204:207], 0
	v_mfma_f32_16x16x32_bf16 v[88:91], v[164:167], v[204:207], 0
	v_mfma_f32_16x16x32_bf16 v[76:79], v[152:155], v[212:215], 0
	v_mfma_f32_16x16x32_bf16 v[72:75], v[164:167], v[212:215], 0
	v_mfma_f32_16x16x32_bf16 v[124:127], v[160:163], v[192:195], v[124:127]
	v_mfma_f32_16x16x32_bf16 v[120:123], v[168:171], v[192:195], v[120:123]
	v_mfma_f32_16x16x32_bf16 v[108:111], v[160:163], v[200:203], v[108:111]
	v_mfma_f32_16x16x32_bf16 v[104:107], v[168:171], v[200:203], v[104:107]
	v_mfma_f32_16x16x32_bf16 v[92:95], v[160:163], v[208:211], v[92:95]
	v_mfma_f32_16x16x32_bf16 v[88:91], v[168:171], v[208:211], v[88:91]
	v_mfma_f32_16x16x32_bf16 v[76:79], v[160:163], v[216:219], v[76:79]
	v_mfma_f32_16x16x32_bf16 v[72:75], v[168:171], v[216:219], v[72:75]
	v_mfma_f32_16x16x32_bf16 v[116:119], v[172:175], v[188:191], 0
	v_mfma_f32_16x16x32_bf16 v[112:115], v[180:183], v[188:191], 0
	v_mfma_f32_16x16x32_bf16 v[100:103], v[172:175], v[196:199], 0
	v_mfma_f32_16x16x32_bf16 v[96:99], v[180:183], v[196:199], 0
	v_mfma_f32_16x16x32_bf16 v[84:87], v[172:175], v[204:207], 0
	v_mfma_f32_16x16x32_bf16 v[80:83], v[180:183], v[204:207], 0
	v_mfma_f32_16x16x32_bf16 v[68:71], v[172:175], v[212:215], 0
	v_mfma_f32_16x16x32_bf16 v[64:67], v[180:183], v[212:215], 0
	v_mfma_f32_16x16x32_bf16 v[116:119], v[176:179], v[192:195], v[116:119]
	v_mfma_f32_16x16x32_bf16 v[112:115], v[184:187], v[192:195], v[112:115]
	v_mfma_f32_16x16x32_bf16 v[100:103], v[176:179], v[200:203], v[100:103]
	v_mfma_f32_16x16x32_bf16 v[96:99], v[184:187], v[200:203], v[96:99]
	v_mfma_f32_16x16x32_bf16 v[84:87], v[176:179], v[208:211], v[84:87]
	v_mfma_f32_16x16x32_bf16 v[80:83], v[184:187], v[208:211], v[80:83]
	v_mfma_f32_16x16x32_bf16 v[68:71], v[176:179], v[216:219], v[68:71]
	v_mfma_f32_16x16x32_bf16 v[64:67], v[184:187], v[216:219], v[64:67]
	s_setprio 0
	s_barrier
	s_add_i32 s34, s82, s58
	v_lshl_add_u64 v[220:221], s[52:53], 0, v[136:137]
	s_mov_b32 m0, s34
	ds_read_b128 v[188:191], v159 offset:16384
	ds_read_b128 v[192:195], v159 offset:17408
	ds_read_b128 v[196:199], v159 offset:18432
	ds_read_b128 v[200:203], v159 offset:19456
	ds_read_b128 v[204:207], v159 offset:20480
	ds_read_b128 v[208:211], v159 offset:21504
	ds_read_b128 v[212:215], v159 offset:22528
	ds_read_b128 v[216:219], v159 offset:23552
	global_load_lds_dwordx4 v[220:221], off
	s_add_i32 m0, s34, 0x2000
	s_add_u32 s34, s52, 0x40000
	v_lshl_add_u64 v[222:223], s[52:53], 0, v[140:141]
	s_addc_u32 s35, s53, 0
	s_add_i32 s87, s83, s58
	global_load_lds_dwordx4 v[222:223], off
	v_lshl_add_u64 v[224:225], s[34:35], 0, v[136:137]
	s_mov_b32 m0, s87
	v_lshl_add_u64 v[226:227], s[54:55], 0, v[138:139]
	global_load_lds_dwordx4 v[224:225], off
	s_add_i32 m0, s87, 0x2000
	v_lshl_add_u64 v[224:225], s[34:35], 0, v[140:141]
	global_load_lds_dwordx4 v[224:225], off
	s_mov_b32 m0, s63
	v_lshl_add_u64 v[224:225], s[54:55], 0, v[134:135]
	global_load_lds_dwordx4 v[224:225], off
	s_mov_b32 m0, s64
	s_nop 0
	global_load_lds_dwordx4 v[226:227], off
	s_waitcnt vmcnt(8)
	s_waitcnt lgkmcnt(0)
	s_barrier
	s_setprio 1
	s_waitcnt lgkmcnt(0)
	v_mfma_f32_16x16x32_bf16 v[60:63], v[152:155], v[188:191], 0
	v_mfma_f32_16x16x32_bf16 v[56:59], v[164:167], v[188:191], 0
	v_mfma_f32_16x16x32_bf16 v[44:47], v[152:155], v[196:199], 0
	v_mfma_f32_16x16x32_bf16 v[40:43], v[164:167], v[196:199], 0
	v_mfma_f32_16x16x32_bf16 v[28:31], v[152:155], v[204:207], 0
	v_mfma_f32_16x16x32_bf16 v[24:27], v[164:167], v[204:207], 0
	v_mfma_f32_16x16x32_bf16 v[12:15], v[152:155], v[212:215], 0
	v_mfma_f32_16x16x32_bf16 v[8:11], v[164:167], v[212:215], 0
	v_mfma_f32_16x16x32_bf16 v[60:63], v[160:163], v[192:195], v[60:63]
	v_mfma_f32_16x16x32_bf16 v[56:59], v[168:171], v[192:195], v[56:59]
	v_mfma_f32_16x16x32_bf16 v[44:47], v[160:163], v[200:203], v[44:47]
	v_mfma_f32_16x16x32_bf16 v[40:43], v[168:171], v[200:203], v[40:43]
	v_mfma_f32_16x16x32_bf16 v[28:31], v[160:163], v[208:211], v[28:31]
	v_mfma_f32_16x16x32_bf16 v[24:27], v[168:171], v[208:211], v[24:27]
	v_mfma_f32_16x16x32_bf16 v[12:15], v[160:163], v[216:219], v[12:15]
	v_mfma_f32_16x16x32_bf16 v[8:11], v[168:171], v[216:219], v[8:11]
	v_mfma_f32_16x16x32_bf16 v[52:55], v[172:175], v[188:191], 0
	v_mfma_f32_16x16x32_bf16 v[48:51], v[180:183], v[188:191], 0
	v_mfma_f32_16x16x32_bf16 v[36:39], v[172:175], v[196:199], 0
	v_mfma_f32_16x16x32_bf16 v[32:35], v[180:183], v[196:199], 0
	v_mfma_f32_16x16x32_bf16 v[20:23], v[172:175], v[204:207], 0
	v_mfma_f32_16x16x32_bf16 v[16:19], v[180:183], v[204:207], 0
	v_mfma_f32_16x16x32_bf16 v[4:7], v[172:175], v[212:215], 0
	v_mfma_f32_16x16x32_bf16 v[0:3], v[180:183], v[212:215], 0
	v_mfma_f32_16x16x32_bf16 v[52:55], v[176:179], v[192:195], v[52:55]
	v_mfma_f32_16x16x32_bf16 v[48:51], v[184:187], v[192:195], v[48:51]
	v_mfma_f32_16x16x32_bf16 v[36:39], v[176:179], v[200:203], v[36:39]
	v_mfma_f32_16x16x32_bf16 v[32:35], v[184:187], v[200:203], v[32:35]
	v_mfma_f32_16x16x32_bf16 v[20:23], v[176:179], v[208:211], v[20:23]
	v_mfma_f32_16x16x32_bf16 v[16:19], v[184:187], v[208:211], v[16:19]
	v_mfma_f32_16x16x32_bf16 v[4:7], v[176:179], v[216:219], v[4:7]
	v_mfma_f32_16x16x32_bf16 v[0:3], v[184:187], v[216:219], v[0:3]
	s_setprio 0
	s_barrier
	s_add_i32 s87, 0, 0x18000
	v_add_u32_e32 v142, s87, v133
	s_add_i32 s88, 0, 0x1c000
	ds_read_b128 v[152:155], v142
	ds_read_b128 v[160:163], v142 offset:1024
	ds_read_b128 v[164:167], v142 offset:2048
	ds_read_b128 v[168:171], v142 offset:3072
	v_add_u32_e32 v142, s88, v133
	ds_read_b128 v[172:175], v142
	ds_read_b128 v[176:179], v142 offset:1024
	ds_read_b128 v[180:183], v142 offset:2048
	ds_read_b128 v[184:187], v142 offset:3072
	s_add_u32 s34, s54, 0x40000
	s_addc_u32 s35, s55, 0
	s_mov_b32 m0, s65
	v_lshl_add_u64 v[228:229], s[34:35], 0, v[134:135]
	ds_read_b128 v[188:191], v159 offset:32768
	ds_read_b128 v[192:195], v159 offset:33792
	ds_read_b128 v[196:199], v159 offset:34816
	ds_read_b128 v[200:203], v159 offset:35840
	ds_read_b128 v[204:207], v159 offset:36864
	ds_read_b128 v[208:211], v159 offset:37888
	ds_read_b128 v[212:215], v159 offset:38912
	ds_read_b128 v[216:219], v159 offset:39936
	global_load_lds_dwordx4 v[228:229], off
	s_mov_b32 m0, s66
	v_lshl_add_u64 v[228:229], s[34:35], 0, v[138:139]
	global_load_lds_dwordx4 v[228:229], off
	s_waitcnt vmcnt(8)
	s_waitcnt lgkmcnt(0)
	s_barrier
	s_setprio 1
	s_waitcnt lgkmcnt(0)
	v_mfma_f32_16x16x32_bf16 v[124:127], v[152:155], v[188:191], v[124:127]
	v_mfma_f32_16x16x32_bf16 v[120:123], v[164:167], v[188:191], v[120:123]
	v_mfma_f32_16x16x32_bf16 v[108:111], v[152:155], v[196:199], v[108:111]
	v_mfma_f32_16x16x32_bf16 v[104:107], v[164:167], v[196:199], v[104:107]
	v_mfma_f32_16x16x32_bf16 v[92:95], v[152:155], v[204:207], v[92:95]
	v_mfma_f32_16x16x32_bf16 v[88:91], v[164:167], v[204:207], v[88:91]
	v_mfma_f32_16x16x32_bf16 v[76:79], v[152:155], v[212:215], v[76:79]
	v_mfma_f32_16x16x32_bf16 v[72:75], v[164:167], v[212:215], v[72:75]
	v_mfma_f32_16x16x32_bf16 v[124:127], v[160:163], v[192:195], v[124:127]
	v_mfma_f32_16x16x32_bf16 v[120:123], v[168:171], v[192:195], v[120:123]
	v_mfma_f32_16x16x32_bf16 v[108:111], v[160:163], v[200:203], v[108:111]
	v_mfma_f32_16x16x32_bf16 v[104:107], v[168:171], v[200:203], v[104:107]
	v_mfma_f32_16x16x32_bf16 v[92:95], v[160:163], v[208:211], v[92:95]
	v_mfma_f32_16x16x32_bf16 v[88:91], v[168:171], v[208:211], v[88:91]
	v_mfma_f32_16x16x32_bf16 v[76:79], v[160:163], v[216:219], v[76:79]
	v_mfma_f32_16x16x32_bf16 v[72:75], v[168:171], v[216:219], v[72:75]
	v_mfma_f32_16x16x32_bf16 v[116:119], v[172:175], v[188:191], v[116:119]
	v_mfma_f32_16x16x32_bf16 v[112:115], v[180:183], v[188:191], v[112:115]
	v_mfma_f32_16x16x32_bf16 v[100:103], v[172:175], v[196:199], v[100:103]
	v_mfma_f32_16x16x32_bf16 v[96:99], v[180:183], v[196:199], v[96:99]
	v_mfma_f32_16x16x32_bf16 v[84:87], v[172:175], v[204:207], v[84:87]
	v_mfma_f32_16x16x32_bf16 v[80:83], v[180:183], v[204:207], v[80:83]
	v_mfma_f32_16x16x32_bf16 v[68:71], v[172:175], v[212:215], v[68:71]
	v_mfma_f32_16x16x32_bf16 v[64:67], v[180:183], v[212:215], v[64:67]
	v_mfma_f32_16x16x32_bf16 v[116:119], v[176:179], v[192:195], v[116:119]
	v_mfma_f32_16x16x32_bf16 v[112:115], v[184:187], v[192:195], v[112:115]
	v_mfma_f32_16x16x32_bf16 v[100:103], v[176:179], v[200:203], v[100:103]
	v_mfma_f32_16x16x32_bf16 v[96:99], v[184:187], v[200:203], v[96:99]
	v_mfma_f32_16x16x32_bf16 v[84:87], v[176:179], v[208:211], v[84:87]
	v_mfma_f32_16x16x32_bf16 v[80:83], v[184:187], v[208:211], v[80:83]
	v_mfma_f32_16x16x32_bf16 v[68:71], v[176:179], v[216:219], v[68:71]
	v_mfma_f32_16x16x32_bf16 v[64:67], v[184:187], v[216:219], v[64:67]
	s_setprio 0
	s_barrier
	s_add_i32 s34, s87, s58
	v_lshl_add_u64 v[220:221], v[220:221], 0, s[22:23]
	s_mov_b32 m0, s34
	ds_read_b128 v[188:191], v159 offset:49152
	ds_read_b128 v[192:195], v159 offset:50176
	ds_read_b128 v[196:199], v159 offset:51200
	ds_read_b128 v[200:203], v159 offset:52224
	ds_read_b128 v[204:207], v159 offset:53248
	ds_read_b128 v[208:211], v159 offset:54272
	ds_read_b128 v[212:215], v159 offset:55296
	ds_read_b128 v[216:219], v159 offset:56320
	global_load_lds_dwordx4 v[220:221], off
	s_add_i32 m0, s34, 0x2000
	s_add_u32 s34, s52, 0x40080
	v_lshl_add_u64 v[220:221], v[222:223], 0, s[22:23]
	s_addc_u32 s35, s53, 0
	s_add_i32 s52, s88, s58
	global_load_lds_dwordx4 v[220:221], off
	s_mov_b32 m0, s52
	v_lshl_add_u64 v[220:221], s[34:35], 0, v[136:137]
	global_load_lds_dwordx4 v[220:221], off
	s_add_i32 m0, s52, 0x2000
	v_lshl_add_u64 v[220:221], s[34:35], 0, v[140:141]
	global_load_lds_dwordx4 v[220:221], off
	s_mov_b32 m0, s79
	v_lshl_add_u64 v[220:221], v[224:225], 0, s[22:23]
	global_load_lds_dwordx4 v[220:221], off
	s_mov_b32 m0, s81
	v_lshl_add_u64 v[220:221], v[226:227], 0, s[22:23]
	global_load_lds_dwordx4 v[220:221], off
	s_waitcnt vmcnt(8)
	s_waitcnt lgkmcnt(0)
	s_barrier
	s_setprio 1
	s_waitcnt lgkmcnt(0)
	v_mfma_f32_16x16x32_bf16 v[60:63], v[152:155], v[188:191], v[60:63]
	v_mfma_f32_16x16x32_bf16 v[56:59], v[164:167], v[188:191], v[56:59]
	v_mfma_f32_16x16x32_bf16 v[44:47], v[152:155], v[196:199], v[44:47]
	v_mfma_f32_16x16x32_bf16 v[40:43], v[164:167], v[196:199], v[40:43]
	v_mfma_f32_16x16x32_bf16 v[28:31], v[152:155], v[204:207], v[28:31]
	v_mfma_f32_16x16x32_bf16 v[24:27], v[164:167], v[204:207], v[24:27]
	v_mfma_f32_16x16x32_bf16 v[12:15], v[152:155], v[212:215], v[12:15]
	v_mfma_f32_16x16x32_bf16 v[8:11], v[164:167], v[212:215], v[8:11]
	v_mfma_f32_16x16x32_bf16 v[60:63], v[160:163], v[192:195], v[60:63]
	v_mfma_f32_16x16x32_bf16 v[56:59], v[168:171], v[192:195], v[56:59]
	v_mfma_f32_16x16x32_bf16 v[44:47], v[160:163], v[200:203], v[44:47]
	v_mfma_f32_16x16x32_bf16 v[40:43], v[168:171], v[200:203], v[40:43]
	v_mfma_f32_16x16x32_bf16 v[28:31], v[160:163], v[208:211], v[28:31]
	v_mfma_f32_16x16x32_bf16 v[24:27], v[168:171], v[208:211], v[24:27]
	v_mfma_f32_16x16x32_bf16 v[12:15], v[160:163], v[216:219], v[12:15]
	v_mfma_f32_16x16x32_bf16 v[8:11], v[168:171], v[216:219], v[8:11]
	v_mfma_f32_16x16x32_bf16 v[52:55], v[172:175], v[188:191], v[52:55]
	v_mfma_f32_16x16x32_bf16 v[48:51], v[180:183], v[188:191], v[48:51]
	v_mfma_f32_16x16x32_bf16 v[36:39], v[172:175], v[196:199], v[36:39]
	v_mfma_f32_16x16x32_bf16 v[32:35], v[180:183], v[196:199], v[32:35]
	v_mfma_f32_16x16x32_bf16 v[20:23], v[172:175], v[204:207], v[20:23]
	v_mfma_f32_16x16x32_bf16 v[16:19], v[180:183], v[204:207], v[16:19]
	v_mfma_f32_16x16x32_bf16 v[4:7], v[172:175], v[212:215], v[4:7]
	v_mfma_f32_16x16x32_bf16 v[0:3], v[180:183], v[212:215], v[0:3]
	v_mfma_f32_16x16x32_bf16 v[52:55], v[176:179], v[192:195], v[52:55]
	v_mfma_f32_16x16x32_bf16 v[48:51], v[184:187], v[192:195], v[48:51]
	v_mfma_f32_16x16x32_bf16 v[36:39], v[176:179], v[200:203], v[36:39]
	v_mfma_f32_16x16x32_bf16 v[32:35], v[184:187], v[200:203], v[32:35]
	v_mfma_f32_16x16x32_bf16 v[20:23], v[176:179], v[208:211], v[20:23]
	v_mfma_f32_16x16x32_bf16 v[16:19], v[184:187], v[208:211], v[16:19]
	v_mfma_f32_16x16x32_bf16 v[4:7], v[176:179], v[216:219], v[4:7]
	v_mfma_f32_16x16x32_bf16 v[0:3], v[184:187], v[216:219], v[0:3]
	s_setprio 0
	s_barrier
	s_add_i32 s86, s86, 2
	s_add_u32 s50, s50, 0x100
	s_addc_u32 s51, s51, 0
	s_add_u32 s29, s29, 0x100
	s_addc_u32 s41, s41, 0
.LBB0_211:
	ds_read_b128 v[152:155], v157
	ds_read_b128 v[160:163], v157 offset:1024
	ds_read_b128 v[164:167], v157 offset:2048
	ds_read_b128 v[168:171], v157 offset:3072
	ds_read_b128 v[172:175], v158
	ds_read_b128 v[176:179], v158 offset:1024
	ds_read_b128 v[180:183], v158 offset:2048
	ds_read_b128 v[184:187], v158 offset:3072
	s_add_u32 s34, s50, 0xfffc0080
	s_addc_u32 s35, s51, -1
	s_cmp_eq_u32 s86, 12
	s_cselect_b32 s55, s7, s35
	s_cselect_b32 s54, s8, s34
	s_cselect_b32 s53, s12, s41
	s_cselect_b32 s52, s13, s29
	v_lshl_add_u64 v[220:221], s[50:51], 0, v[144:145]
	s_add_i32 m0, s63, 0xc000
	ds_read_b128 v[188:191], v159
	ds_read_b128 v[192:195], v159 offset:1024
	ds_read_b128 v[196:199], v159 offset:2048
	ds_read_b128 v[200:203], v159 offset:3072
	ds_read_b128 v[204:207], v159 offset:4096
	ds_read_b128 v[208:211], v159 offset:5120
	ds_read_b128 v[212:215], v159 offset:6144
	ds_read_b128 v[216:219], v159 offset:7168
	global_load_lds_dwordx4 v[220:221], off
	s_add_i32 m0, s63, 0xe000
	v_lshl_add_u64 v[220:221], s[50:51], 0, v[146:147]
	global_load_lds_dwordx4 v[220:221], off
	s_waitcnt vmcnt(8)
	s_waitcnt lgkmcnt(0)
	s_barrier
	s_setprio 1
	s_waitcnt lgkmcnt(0)
	v_mfma_f32_16x16x32_bf16 v[124:127], v[152:155], v[188:191], v[124:127]
	v_mfma_f32_16x16x32_bf16 v[120:123], v[164:167], v[188:191], v[120:123]
	v_mfma_f32_16x16x32_bf16 v[108:111], v[152:155], v[196:199], v[108:111]
	v_mfma_f32_16x16x32_bf16 v[104:107], v[164:167], v[196:199], v[104:107]
	v_mfma_f32_16x16x32_bf16 v[92:95], v[152:155], v[204:207], v[92:95]
	v_mfma_f32_16x16x32_bf16 v[88:91], v[164:167], v[204:207], v[88:91]
	v_mfma_f32_16x16x32_bf16 v[76:79], v[152:155], v[212:215], v[76:79]
	v_mfma_f32_16x16x32_bf16 v[72:75], v[164:167], v[212:215], v[72:75]
	v_mfma_f32_16x16x32_bf16 v[124:127], v[160:163], v[192:195], v[124:127]
	v_mfma_f32_16x16x32_bf16 v[120:123], v[168:171], v[192:195], v[120:123]
	v_mfma_f32_16x16x32_bf16 v[108:111], v[160:163], v[200:203], v[108:111]
	v_mfma_f32_16x16x32_bf16 v[104:107], v[168:171], v[200:203], v[104:107]
	v_mfma_f32_16x16x32_bf16 v[92:95], v[160:163], v[208:211], v[92:95]
	v_mfma_f32_16x16x32_bf16 v[88:91], v[168:171], v[208:211], v[88:91]
	v_mfma_f32_16x16x32_bf16 v[76:79], v[160:163], v[216:219], v[76:79]
	v_mfma_f32_16x16x32_bf16 v[72:75], v[168:171], v[216:219], v[72:75]
	v_mfma_f32_16x16x32_bf16 v[116:119], v[172:175], v[188:191], v[116:119]
	v_mfma_f32_16x16x32_bf16 v[112:115], v[180:183], v[188:191], v[112:115]
	v_mfma_f32_16x16x32_bf16 v[100:103], v[172:175], v[196:199], v[100:103]
	v_mfma_f32_16x16x32_bf16 v[96:99], v[180:183], v[196:199], v[96:99]
	v_mfma_f32_16x16x32_bf16 v[84:87], v[172:175], v[204:207], v[84:87]
	v_mfma_f32_16x16x32_bf16 v[80:83], v[180:183], v[204:207], v[80:83]
	v_mfma_f32_16x16x32_bf16 v[68:71], v[172:175], v[212:215], v[68:71]
	v_mfma_f32_16x16x32_bf16 v[64:67], v[180:183], v[212:215], v[64:67]
	v_mfma_f32_16x16x32_bf16 v[116:119], v[176:179], v[192:195], v[116:119]
	v_mfma_f32_16x16x32_bf16 v[112:115], v[184:187], v[192:195], v[112:115]
	v_mfma_f32_16x16x32_bf16 v[100:103], v[176:179], v[200:203], v[100:103]
	v_mfma_f32_16x16x32_bf16 v[96:99], v[184:187], v[200:203], v[96:99]
	v_mfma_f32_16x16x32_bf16 v[84:87], v[176:179], v[208:211], v[84:87]
	v_mfma_f32_16x16x32_bf16 v[80:83], v[184:187], v[208:211], v[80:83]
	v_mfma_f32_16x16x32_bf16 v[68:71], v[176:179], v[216:219], v[68:71]
	v_mfma_f32_16x16x32_bf16 v[64:67], v[184:187], v[216:219], v[64:67]
	s_setprio 0
	s_barrier
	s_add_i32 s34, s82, s58
	v_lshl_add_u64 v[220:221], s[52:53], 0, v[136:137]
	s_mov_b32 m0, s34
	ds_read_b128 v[188:191], v159 offset:16384
	ds_read_b128 v[192:195], v159 offset:17408
	ds_read_b128 v[196:199], v159 offset:18432
	ds_read_b128 v[200:203], v159 offset:19456
	ds_read_b128 v[204:207], v159 offset:20480
	ds_read_b128 v[208:211], v159 offset:21504
	ds_read_b128 v[212:215], v159 offset:22528
	ds_read_b128 v[216:219], v159 offset:23552
	global_load_lds_dwordx4 v[220:221], off
	s_add_i32 m0, s34, 0x2000
	s_add_u32 s34, s52, 0x40000
	v_lshl_add_u64 v[222:223], s[52:53], 0, v[140:141]
	s_addc_u32 s35, s53, 0
	s_add_i32 s87, s83, s58
	global_load_lds_dwordx4 v[222:223], off
	v_lshl_add_u64 v[224:225], s[34:35], 0, v[136:137]
	s_mov_b32 m0, s87
	v_lshl_add_u64 v[226:227], s[54:55], 0, v[138:139]
	global_load_lds_dwordx4 v[224:225], off
	s_add_i32 m0, s87, 0x2000
	v_lshl_add_u64 v[224:225], s[34:35], 0, v[140:141]
	global_load_lds_dwordx4 v[224:225], off
	s_mov_b32 m0, s63
	v_lshl_add_u64 v[224:225], s[54:55], 0, v[134:135]
	global_load_lds_dwordx4 v[224:225], off
	s_mov_b32 m0, s64
	s_nop 0
	global_load_lds_dwordx4 v[226:227], off
	s_waitcnt vmcnt(8)
	s_waitcnt lgkmcnt(0)
	s_barrier
	s_setprio 1
	s_waitcnt lgkmcnt(0)
	v_mfma_f32_16x16x32_bf16 v[60:63], v[152:155], v[188:191], v[60:63]
	v_mfma_f32_16x16x32_bf16 v[56:59], v[164:167], v[188:191], v[56:59]
	v_mfma_f32_16x16x32_bf16 v[44:47], v[152:155], v[196:199], v[44:47]
	v_mfma_f32_16x16x32_bf16 v[40:43], v[164:167], v[196:199], v[40:43]
	v_mfma_f32_16x16x32_bf16 v[28:31], v[152:155], v[204:207], v[28:31]
	v_mfma_f32_16x16x32_bf16 v[24:27], v[164:167], v[204:207], v[24:27]
	v_mfma_f32_16x16x32_bf16 v[12:15], v[152:155], v[212:215], v[12:15]
	v_mfma_f32_16x16x32_bf16 v[8:11], v[164:167], v[212:215], v[8:11]
	v_mfma_f32_16x16x32_bf16 v[60:63], v[160:163], v[192:195], v[60:63]
	v_mfma_f32_16x16x32_bf16 v[56:59], v[168:171], v[192:195], v[56:59]
	v_mfma_f32_16x16x32_bf16 v[44:47], v[160:163], v[200:203], v[44:47]
	v_mfma_f32_16x16x32_bf16 v[40:43], v[168:171], v[200:203], v[40:43]
	v_mfma_f32_16x16x32_bf16 v[28:31], v[160:163], v[208:211], v[28:31]
	v_mfma_f32_16x16x32_bf16 v[24:27], v[168:171], v[208:211], v[24:27]
	v_mfma_f32_16x16x32_bf16 v[12:15], v[160:163], v[216:219], v[12:15]
	v_mfma_f32_16x16x32_bf16 v[8:11], v[168:171], v[216:219], v[8:11]
	v_mfma_f32_16x16x32_bf16 v[52:55], v[172:175], v[188:191], v[52:55]
	v_mfma_f32_16x16x32_bf16 v[48:51], v[180:183], v[188:191], v[48:51]
	v_mfma_f32_16x16x32_bf16 v[36:39], v[172:175], v[196:199], v[36:39]
	v_mfma_f32_16x16x32_bf16 v[32:35], v[180:183], v[196:199], v[32:35]
	v_mfma_f32_16x16x32_bf16 v[20:23], v[172:175], v[204:207], v[20:23]
	v_mfma_f32_16x16x32_bf16 v[16:19], v[180:183], v[204:207], v[16:19]
	v_mfma_f32_16x16x32_bf16 v[4:7], v[172:175], v[212:215], v[4:7]
	v_mfma_f32_16x16x32_bf16 v[0:3], v[180:183], v[212:215], v[0:3]
	v_mfma_f32_16x16x32_bf16 v[52:55], v[176:179], v[192:195], v[52:55]
	v_mfma_f32_16x16x32_bf16 v[48:51], v[184:187], v[192:195], v[48:51]
	v_mfma_f32_16x16x32_bf16 v[36:39], v[176:179], v[200:203], v[36:39]
	v_mfma_f32_16x16x32_bf16 v[32:35], v[184:187], v[200:203], v[32:35]
	v_mfma_f32_16x16x32_bf16 v[20:23], v[176:179], v[208:211], v[20:23]
	v_mfma_f32_16x16x32_bf16 v[16:19], v[184:187], v[208:211], v[16:19]
	v_mfma_f32_16x16x32_bf16 v[4:7], v[176:179], v[216:219], v[4:7]
	v_mfma_f32_16x16x32_bf16 v[0:3], v[184:187], v[216:219], v[0:3]
	s_setprio 0
	s_barrier
	s_add_i32 s87, 0, 0x18000
	v_add_u32_e32 v142, s87, v133
	s_add_i32 s88, 0, 0x1c000
	ds_read_b128 v[152:155], v142
	ds_read_b128 v[160:163], v142 offset:1024
	ds_read_b128 v[164:167], v142 offset:2048
	ds_read_b128 v[168:171], v142 offset:3072
	v_add_u32_e32 v142, s88, v133
	ds_read_b128 v[172:175], v142
	ds_read_b128 v[176:179], v142 offset:1024
	ds_read_b128 v[180:183], v142 offset:2048
	ds_read_b128 v[184:187], v142 offset:3072
	s_add_u32 s34, s54, 0x40000
	s_addc_u32 s35, s55, 0
	s_mov_b32 m0, s65
	v_lshl_add_u64 v[228:229], s[34:35], 0, v[134:135]
	ds_read_b128 v[188:191], v159 offset:32768
	ds_read_b128 v[192:195], v159 offset:33792
	ds_read_b128 v[196:199], v159 offset:34816
	ds_read_b128 v[200:203], v159 offset:35840
	ds_read_b128 v[204:207], v159 offset:36864
	ds_read_b128 v[208:211], v159 offset:37888
	ds_read_b128 v[212:215], v159 offset:38912
	ds_read_b128 v[216:219], v159 offset:39936
	global_load_lds_dwordx4 v[228:229], off
	s_mov_b32 m0, s66
	v_lshl_add_u64 v[228:229], s[34:35], 0, v[138:139]
	global_load_lds_dwordx4 v[228:229], off
	s_waitcnt vmcnt(8)
	s_waitcnt lgkmcnt(0)
	s_barrier
	s_setprio 1
	s_waitcnt lgkmcnt(0)
	v_mfma_f32_16x16x32_bf16 v[124:127], v[152:155], v[188:191], v[124:127]
	v_mfma_f32_16x16x32_bf16 v[120:123], v[164:167], v[188:191], v[120:123]
	v_mfma_f32_16x16x32_bf16 v[108:111], v[152:155], v[196:199], v[108:111]
	v_mfma_f32_16x16x32_bf16 v[104:107], v[164:167], v[196:199], v[104:107]
	v_mfma_f32_16x16x32_bf16 v[92:95], v[152:155], v[204:207], v[92:95]
	v_mfma_f32_16x16x32_bf16 v[88:91], v[164:167], v[204:207], v[88:91]
	v_mfma_f32_16x16x32_bf16 v[76:79], v[152:155], v[212:215], v[76:79]
	v_mfma_f32_16x16x32_bf16 v[72:75], v[164:167], v[212:215], v[72:75]
	v_mfma_f32_16x16x32_bf16 v[124:127], v[160:163], v[192:195], v[124:127]
	v_mfma_f32_16x16x32_bf16 v[120:123], v[168:171], v[192:195], v[120:123]
	v_mfma_f32_16x16x32_bf16 v[108:111], v[160:163], v[200:203], v[108:111]
	v_mfma_f32_16x16x32_bf16 v[104:107], v[168:171], v[200:203], v[104:107]
	v_mfma_f32_16x16x32_bf16 v[92:95], v[160:163], v[208:211], v[92:95]
	v_mfma_f32_16x16x32_bf16 v[88:91], v[168:171], v[208:211], v[88:91]
	v_mfma_f32_16x16x32_bf16 v[76:79], v[160:163], v[216:219], v[76:79]
	v_mfma_f32_16x16x32_bf16 v[72:75], v[168:171], v[216:219], v[72:75]
	v_mfma_f32_16x16x32_bf16 v[116:119], v[172:175], v[188:191], v[116:119]
	v_mfma_f32_16x16x32_bf16 v[112:115], v[180:183], v[188:191], v[112:115]
	v_mfma_f32_16x16x32_bf16 v[100:103], v[172:175], v[196:199], v[100:103]
	v_mfma_f32_16x16x32_bf16 v[96:99], v[180:183], v[196:199], v[96:99]
	v_mfma_f32_16x16x32_bf16 v[84:87], v[172:175], v[204:207], v[84:87]
	v_mfma_f32_16x16x32_bf16 v[80:83], v[180:183], v[204:207], v[80:83]
	v_mfma_f32_16x16x32_bf16 v[68:71], v[172:175], v[212:215], v[68:71]
	v_mfma_f32_16x16x32_bf16 v[64:67], v[180:183], v[212:215], v[64:67]
	v_mfma_f32_16x16x32_bf16 v[116:119], v[176:179], v[192:195], v[116:119]
	v_mfma_f32_16x16x32_bf16 v[112:115], v[184:187], v[192:195], v[112:115]
	v_mfma_f32_16x16x32_bf16 v[100:103], v[176:179], v[200:203], v[100:103]
	v_mfma_f32_16x16x32_bf16 v[96:99], v[184:187], v[200:203], v[96:99]
	v_mfma_f32_16x16x32_bf16 v[84:87], v[176:179], v[208:211], v[84:87]
	v_mfma_f32_16x16x32_bf16 v[80:83], v[184:187], v[208:211], v[80:83]
	v_mfma_f32_16x16x32_bf16 v[68:71], v[176:179], v[216:219], v[68:71]
	v_mfma_f32_16x16x32_bf16 v[64:67], v[184:187], v[216:219], v[64:67]
	s_setprio 0
	s_barrier
	s_add_i32 s34, s87, s58
	v_lshl_add_u64 v[220:221], v[220:221], 0, s[22:23]
	s_mov_b32 m0, s34
	ds_read_b128 v[188:191], v159 offset:49152
	ds_read_b128 v[192:195], v159 offset:50176
	ds_read_b128 v[196:199], v159 offset:51200
	ds_read_b128 v[200:203], v159 offset:52224
	ds_read_b128 v[204:207], v159 offset:53248
	ds_read_b128 v[208:211], v159 offset:54272
	ds_read_b128 v[212:215], v159 offset:55296
	ds_read_b128 v[216:219], v159 offset:56320
	global_load_lds_dwordx4 v[220:221], off
	s_add_i32 m0, s34, 0x2000
	s_add_u32 s34, s52, 0x40080
	v_lshl_add_u64 v[220:221], v[222:223], 0, s[22:23]
	s_addc_u32 s35, s53, 0
	s_add_i32 s52, s88, s58
	global_load_lds_dwordx4 v[220:221], off
	s_mov_b32 m0, s52
	v_lshl_add_u64 v[220:221], s[34:35], 0, v[136:137]
	global_load_lds_dwordx4 v[220:221], off
	s_add_i32 m0, s52, 0x2000
	v_lshl_add_u64 v[220:221], s[34:35], 0, v[140:141]
	global_load_lds_dwordx4 v[220:221], off
	s_mov_b32 m0, s79
	v_lshl_add_u64 v[220:221], v[224:225], 0, s[22:23]
	global_load_lds_dwordx4 v[220:221], off
	s_mov_b32 m0, s81
	v_lshl_add_u64 v[220:221], v[226:227], 0, s[22:23]
	global_load_lds_dwordx4 v[220:221], off
	s_waitcnt vmcnt(8)
	s_waitcnt lgkmcnt(0)
	s_barrier
	s_setprio 1
	s_waitcnt lgkmcnt(0)
	v_mfma_f32_16x16x32_bf16 v[60:63], v[152:155], v[188:191], v[60:63]
	v_mfma_f32_16x16x32_bf16 v[56:59], v[164:167], v[188:191], v[56:59]
	v_mfma_f32_16x16x32_bf16 v[44:47], v[152:155], v[196:199], v[44:47]
	v_mfma_f32_16x16x32_bf16 v[40:43], v[164:167], v[196:199], v[40:43]
	v_mfma_f32_16x16x32_bf16 v[28:31], v[152:155], v[204:207], v[28:31]
	v_mfma_f32_16x16x32_bf16 v[24:27], v[164:167], v[204:207], v[24:27]
	v_mfma_f32_16x16x32_bf16 v[12:15], v[152:155], v[212:215], v[12:15]
	v_mfma_f32_16x16x32_bf16 v[8:11], v[164:167], v[212:215], v[8:11]
	v_mfma_f32_16x16x32_bf16 v[60:63], v[160:163], v[192:195], v[60:63]
	v_mfma_f32_16x16x32_bf16 v[56:59], v[168:171], v[192:195], v[56:59]
	v_mfma_f32_16x16x32_bf16 v[44:47], v[160:163], v[200:203], v[44:47]
	v_mfma_f32_16x16x32_bf16 v[40:43], v[168:171], v[200:203], v[40:43]
	v_mfma_f32_16x16x32_bf16 v[28:31], v[160:163], v[208:211], v[28:31]
	v_mfma_f32_16x16x32_bf16 v[24:27], v[168:171], v[208:211], v[24:27]
	v_mfma_f32_16x16x32_bf16 v[12:15], v[160:163], v[216:219], v[12:15]
	v_mfma_f32_16x16x32_bf16 v[8:11], v[168:171], v[216:219], v[8:11]
	v_mfma_f32_16x16x32_bf16 v[52:55], v[172:175], v[188:191], v[52:55]
	v_mfma_f32_16x16x32_bf16 v[48:51], v[180:183], v[188:191], v[48:51]
	v_mfma_f32_16x16x32_bf16 v[36:39], v[172:175], v[196:199], v[36:39]
	v_mfma_f32_16x16x32_bf16 v[32:35], v[180:183], v[196:199], v[32:35]
	v_mfma_f32_16x16x32_bf16 v[20:23], v[172:175], v[204:207], v[20:23]
	v_mfma_f32_16x16x32_bf16 v[16:19], v[180:183], v[204:207], v[16:19]
	v_mfma_f32_16x16x32_bf16 v[4:7], v[172:175], v[212:215], v[4:7]
	v_mfma_f32_16x16x32_bf16 v[0:3], v[180:183], v[212:215], v[0:3]
	v_mfma_f32_16x16x32_bf16 v[52:55], v[176:179], v[192:195], v[52:55]
	v_mfma_f32_16x16x32_bf16 v[48:51], v[184:187], v[192:195], v[48:51]
	v_mfma_f32_16x16x32_bf16 v[36:39], v[176:179], v[200:203], v[36:39]
	v_mfma_f32_16x16x32_bf16 v[32:35], v[184:187], v[200:203], v[32:35]
	v_mfma_f32_16x16x32_bf16 v[20:23], v[176:179], v[208:211], v[20:23]
	v_mfma_f32_16x16x32_bf16 v[16:19], v[184:187], v[208:211], v[16:19]
	v_mfma_f32_16x16x32_bf16 v[4:7], v[176:179], v[216:219], v[4:7]
	v_mfma_f32_16x16x32_bf16 v[0:3], v[184:187], v[216:219], v[0:3]
	s_setprio 0
	s_cmp_eq_u32 s86, s98
	s_cbranch_scc1 .Lmy_nobar_2
	s_barrier

.Lmy_nobar2_4:
	ds_read_b128 v[148:151], v154
	ds_read_b128 v[160:163], v154 offset:1024
	ds_read_b128 v[164:167], v154 offset:2048
	ds_read_b128 v[168:171], v154 offset:3072
	ds_read_b128 v[172:175], v155
	ds_read_b128 v[176:179], v155 offset:1024
	ds_read_b128 v[180:183], v155 offset:2048
	ds_read_b128 v[184:187], v155 offset:3072
	s_add_u32 s34, s50, 0xfffc0080
	s_addc_u32 s35, s51, -1
	s_cmp_eq_u32 s85, 12
	s_cselect_b32 s55, s12, s35
	s_cselect_b32 s54, s13, s34
	s_cselect_b32 s53, s27, s77
	s_cselect_b32 s52, s29, s49
	v_lshl_add_u64 v[220:221], s[50:51], 0, v[140:141]
	s_add_i32 m0, s58, 0xc000
	ds_read_b128 v[188:191], v157
	ds_read_b128 v[192:195], v157 offset:1024
	ds_read_b128 v[196:199], v157 offset:2048
	ds_read_b128 v[200:203], v157 offset:3072
	ds_read_b128 v[204:207], v157 offset:4096
	ds_read_b128 v[208:211], v157 offset:5120
	ds_read_b128 v[212:215], v157 offset:6144
	ds_read_b128 v[216:219], v157 offset:7168
	global_load_lds_dwordx4 v[220:221], off
	s_add_i32 m0, s58, 0xe000
	v_lshl_add_u64 v[220:221], s[50:51], 0, v[142:143]
	global_load_lds_dwordx4 v[220:221], off
	s_waitcnt vmcnt(8)
	s_waitcnt lgkmcnt(0)
	s_barrier
	s_setprio 1
	s_waitcnt lgkmcnt(0)
	v_mfma_f32_16x16x32_bf16 v[124:127], v[148:151], v[188:191], 0
	v_mfma_f32_16x16x32_bf16 v[120:123], v[164:167], v[188:191], 0
	v_mfma_f32_16x16x32_bf16 v[108:111], v[148:151], v[196:199], 0
	v_mfma_f32_16x16x32_bf16 v[104:107], v[164:167], v[196:199], 0
	v_mfma_f32_16x16x32_bf16 v[92:95], v[148:151], v[204:207], 0
	v_mfma_f32_16x16x32_bf16 v[88:91], v[164:167], v[204:207], 0
	v_mfma_f32_16x16x32_bf16 v[76:79], v[148:151], v[212:215], 0
	v_mfma_f32_16x16x32_bf16 v[72:75], v[164:167], v[212:215], 0
	v_mfma_f32_16x16x32_bf16 v[124:127], v[160:163], v[192:195], v[124:127]
	v_mfma_f32_16x16x32_bf16 v[120:123], v[168:171], v[192:195], v[120:123]
	v_mfma_f32_16x16x32_bf16 v[108:111], v[160:163], v[200:203], v[108:111]
	v_mfma_f32_16x16x32_bf16 v[104:107], v[168:171], v[200:203], v[104:107]
	v_mfma_f32_16x16x32_bf16 v[92:95], v[160:163], v[208:211], v[92:95]
	v_mfma_f32_16x16x32_bf16 v[88:91], v[168:171], v[208:211], v[88:91]
	v_mfma_f32_16x16x32_bf16 v[76:79], v[160:163], v[216:219], v[76:79]
	v_mfma_f32_16x16x32_bf16 v[72:75], v[168:171], v[216:219], v[72:75]
	v_mfma_f32_16x16x32_bf16 v[116:119], v[172:175], v[188:191], 0
	v_mfma_f32_16x16x32_bf16 v[112:115], v[180:183], v[188:191], 0
	v_mfma_f32_16x16x32_bf16 v[100:103], v[172:175], v[196:199], 0
	v_mfma_f32_16x16x32_bf16 v[96:99], v[180:183], v[196:199], 0
	v_mfma_f32_16x16x32_bf16 v[84:87], v[172:175], v[204:207], 0
	v_mfma_f32_16x16x32_bf16 v[80:83], v[180:183], v[204:207], 0
	v_mfma_f32_16x16x32_bf16 v[68:71], v[172:175], v[212:215], 0
	v_mfma_f32_16x16x32_bf16 v[64:67], v[180:183], v[212:215], 0
	v_mfma_f32_16x16x32_bf16 v[116:119], v[176:179], v[192:195], v[116:119]
	v_mfma_f32_16x16x32_bf16 v[112:115], v[184:187], v[192:195], v[112:115]
	v_mfma_f32_16x16x32_bf16 v[100:103], v[176:179], v[200:203], v[100:103]
	v_mfma_f32_16x16x32_bf16 v[96:99], v[184:187], v[200:203], v[96:99]
	v_mfma_f32_16x16x32_bf16 v[84:87], v[176:179], v[208:211], v[84:87]
	v_mfma_f32_16x16x32_bf16 v[80:83], v[184:187], v[208:211], v[80:83]
	v_mfma_f32_16x16x32_bf16 v[68:71], v[176:179], v[216:219], v[68:71]
	v_mfma_f32_16x16x32_bf16 v[64:67], v[184:187], v[216:219], v[64:67]
	s_setprio 0
	s_barrier
	s_add_i32 s34, s82, s57
	v_lshl_add_u64 v[220:221], s[52:53], 0, v[134:135]
	s_mov_b32 m0, s34
	ds_read_b128 v[188:191], v157 offset:16384
	ds_read_b128 v[192:195], v157 offset:17408
	ds_read_b128 v[196:199], v157 offset:18432
	ds_read_b128 v[200:203], v157 offset:19456
	ds_read_b128 v[204:207], v157 offset:20480
	ds_read_b128 v[208:211], v157 offset:21504
	ds_read_b128 v[212:215], v157 offset:22528
	ds_read_b128 v[216:219], v157 offset:23552
	global_load_lds_dwordx4 v[220:221], off
	s_add_i32 m0, s34, 0x2000
	s_add_u32 s34, s52, 0x40000
	v_lshl_add_u64 v[222:223], s[52:53], 0, v[138:139]
	s_addc_u32 s35, s53, 0
	s_add_i32 s86, s83, s57
	global_load_lds_dwordx4 v[222:223], off
	v_lshl_add_u64 v[224:225], s[34:35], 0, v[134:135]
	s_mov_b32 m0, s86
	v_lshl_add_u64 v[226:227], s[54:55], 0, v[136:137]
	global_load_lds_dwordx4 v[224:225], off
	s_add_i32 m0, s86, 0x2000
	v_lshl_add_u64 v[224:225], s[34:35], 0, v[138:139]
	global_load_lds_dwordx4 v[224:225], off
	s_mov_b32 m0, s58
	v_lshl_add_u64 v[224:225], s[54:55], 0, v[132:133]
	global_load_lds_dwordx4 v[224:225], off
	s_mov_b32 m0, s59
	s_nop 0
	global_load_lds_dwordx4 v[226:227], off
	s_waitcnt vmcnt(8)
	s_waitcnt lgkmcnt(0)
	s_barrier
	s_setprio 1
	s_waitcnt lgkmcnt(0)
	v_mfma_f32_16x16x32_bf16 v[60:63], v[148:151], v[188:191], 0
	v_mfma_f32_16x16x32_bf16 v[56:59], v[164:167], v[188:191], 0
	v_mfma_f32_16x16x32_bf16 v[44:47], v[148:151], v[196:199], 0
	v_mfma_f32_16x16x32_bf16 v[40:43], v[164:167], v[196:199], 0
	v_mfma_f32_16x16x32_bf16 v[28:31], v[148:151], v[204:207], 0
	v_mfma_f32_16x16x32_bf16 v[24:27], v[164:167], v[204:207], 0
	v_mfma_f32_16x16x32_bf16 v[12:15], v[148:151], v[212:215], 0
	v_mfma_f32_16x16x32_bf16 v[8:11], v[164:167], v[212:215], 0
	v_mfma_f32_16x16x32_bf16 v[60:63], v[160:163], v[192:195], v[60:63]
	v_mfma_f32_16x16x32_bf16 v[56:59], v[168:171], v[192:195], v[56:59]
	v_mfma_f32_16x16x32_bf16 v[44:47], v[160:163], v[200:203], v[44:47]
	v_mfma_f32_16x16x32_bf16 v[40:43], v[168:171], v[200:203], v[40:43]
	v_mfma_f32_16x16x32_bf16 v[28:31], v[160:163], v[208:211], v[28:31]
	v_mfma_f32_16x16x32_bf16 v[24:27], v[168:171], v[208:211], v[24:27]
	v_mfma_f32_16x16x32_bf16 v[12:15], v[160:163], v[216:219], v[12:15]
	v_mfma_f32_16x16x32_bf16 v[8:11], v[168:171], v[216:219], v[8:11]
	v_mfma_f32_16x16x32_bf16 v[52:55], v[172:175], v[188:191], 0
	v_mfma_f32_16x16x32_bf16 v[48:51], v[180:183], v[188:191], 0
	v_mfma_f32_16x16x32_bf16 v[36:39], v[172:175], v[196:199], 0
	v_mfma_f32_16x16x32_bf16 v[32:35], v[180:183], v[196:199], 0
	v_mfma_f32_16x16x32_bf16 v[20:23], v[172:175], v[204:207], 0
	v_mfma_f32_16x16x32_bf16 v[16:19], v[180:183], v[204:207], 0
	v_mfma_f32_16x16x32_bf16 v[4:7], v[172:175], v[212:215], 0
	v_mfma_f32_16x16x32_bf16 v[0:3], v[180:183], v[212:215], 0
	v_mfma_f32_16x16x32_bf16 v[52:55], v[176:179], v[192:195], v[52:55]
	v_mfma_f32_16x16x32_bf16 v[48:51], v[184:187], v[192:195], v[48:51]
	v_mfma_f32_16x16x32_bf16 v[36:39], v[176:179], v[200:203], v[36:39]
	v_mfma_f32_16x16x32_bf16 v[32:35], v[184:187], v[200:203], v[32:35]
	v_mfma_f32_16x16x32_bf16 v[20:23], v[176:179], v[208:211], v[20:23]
	v_mfma_f32_16x16x32_bf16 v[16:19], v[184:187], v[208:211], v[16:19]
	v_mfma_f32_16x16x32_bf16 v[4:7], v[176:179], v[216:219], v[4:7]
	v_mfma_f32_16x16x32_bf16 v[0:3], v[184:187], v[216:219], v[0:3]
	s_setprio 0
	s_barrier
	s_add_i32 s86, 0, 0x18000
	v_add_u32_e32 v159, s86, v152
	s_add_i32 s87, 0, 0x1c000
	ds_read_b128 v[148:151], v159
	ds_read_b128 v[160:163], v159 offset:1024
	ds_read_b128 v[164:167], v159 offset:2048
	ds_read_b128 v[168:171], v159 offset:3072
	v_add_u32_e32 v159, s87, v152
	ds_read_b128 v[172:175], v159
	ds_read_b128 v[176:179], v159 offset:1024
	ds_read_b128 v[180:183], v159 offset:2048
	ds_read_b128 v[184:187], v159 offset:3072
	s_add_u32 s34, s54, 0x40000
	s_addc_u32 s35, s55, 0
	s_mov_b32 m0, s62
	v_lshl_add_u64 v[228:229], s[34:35], 0, v[132:133]
	ds_read_b128 v[188:191], v157 offset:32768
	ds_read_b128 v[192:195], v157 offset:33792
	ds_read_b128 v[196:199], v157 offset:34816
	ds_read_b128 v[200:203], v157 offset:35840
	ds_read_b128 v[204:207], v157 offset:36864
	ds_read_b128 v[208:211], v157 offset:37888
	ds_read_b128 v[212:215], v157 offset:38912
	ds_read_b128 v[216:219], v157 offset:39936
	global_load_lds_dwordx4 v[228:229], off
	s_mov_b32 m0, s63
	v_lshl_add_u64 v[228:229], s[34:35], 0, v[136:137]
	global_load_lds_dwordx4 v[228:229], off
	s_waitcnt vmcnt(8)
	s_waitcnt lgkmcnt(0)
	s_barrier
	s_setprio 1
	s_waitcnt lgkmcnt(0)
	v_mfma_f32_16x16x32_bf16 v[124:127], v[148:151], v[188:191], v[124:127]
	v_mfma_f32_16x16x32_bf16 v[120:123], v[164:167], v[188:191], v[120:123]
	v_mfma_f32_16x16x32_bf16 v[108:111], v[148:151], v[196:199], v[108:111]
	v_mfma_f32_16x16x32_bf16 v[104:107], v[164:167], v[196:199], v[104:107]
	v_mfma_f32_16x16x32_bf16 v[92:95], v[148:151], v[204:207], v[92:95]
	v_mfma_f32_16x16x32_bf16 v[88:91], v[164:167], v[204:207], v[88:91]
	v_mfma_f32_16x16x32_bf16 v[76:79], v[148:151], v[212:215], v[76:79]
	v_mfma_f32_16x16x32_bf16 v[72:75], v[164:167], v[212:215], v[72:75]
	v_mfma_f32_16x16x32_bf16 v[124:127], v[160:163], v[192:195], v[124:127]
	v_mfma_f32_16x16x32_bf16 v[120:123], v[168:171], v[192:195], v[120:123]
	v_mfma_f32_16x16x32_bf16 v[108:111], v[160:163], v[200:203], v[108:111]
	v_mfma_f32_16x16x32_bf16 v[104:107], v[168:171], v[200:203], v[104:107]
	v_mfma_f32_16x16x32_bf16 v[92:95], v[160:163], v[208:211], v[92:95]
	v_mfma_f32_16x16x32_bf16 v[88:91], v[168:171], v[208:211], v[88:91]
	v_mfma_f32_16x16x32_bf16 v[76:79], v[160:163], v[216:219], v[76:79]
	v_mfma_f32_16x16x32_bf16 v[72:75], v[168:171], v[216:219], v[72:75]
	v_mfma_f32_16x16x32_bf16 v[116:119], v[172:175], v[188:191], v[116:119]
	v_mfma_f32_16x16x32_bf16 v[112:115], v[180:183], v[188:191], v[112:115]
	v_mfma_f32_16x16x32_bf16 v[100:103], v[172:175], v[196:199], v[100:103]
	v_mfma_f32_16x16x32_bf16 v[96:99], v[180:183], v[196:199], v[96:99]
	v_mfma_f32_16x16x32_bf16 v[84:87], v[172:175], v[204:207], v[84:87]
	v_mfma_f32_16x16x32_bf16 v[80:83], v[180:183], v[204:207], v[80:83]
	v_mfma_f32_16x16x32_bf16 v[68:71], v[172:175], v[212:215], v[68:71]
	v_mfma_f32_16x16x32_bf16 v[64:67], v[180:183], v[212:215], v[64:67]
	v_mfma_f32_16x16x32_bf16 v[116:119], v[176:179], v[192:195], v[116:119]
	v_mfma_f32_16x16x32_bf16 v[112:115], v[184:187], v[192:195], v[112:115]
	v_mfma_f32_16x16x32_bf16 v[100:103], v[176:179], v[200:203], v[100:103]
	v_mfma_f32_16x16x32_bf16 v[96:99], v[184:187], v[200:203], v[96:99]
	v_mfma_f32_16x16x32_bf16 v[84:87], v[176:179], v[208:211], v[84:87]
	v_mfma_f32_16x16x32_bf16 v[80:83], v[184:187], v[208:211], v[80:83]
	v_mfma_f32_16x16x32_bf16 v[68:71], v[176:179], v[216:219], v[68:71]
	v_mfma_f32_16x16x32_bf16 v[64:67], v[184:187], v[216:219], v[64:67]
	s_setprio 0
	s_barrier
	s_add_i32 s34, s86, s57
	v_lshl_add_u64 v[220:221], v[220:221], 0, s[10:11]
	s_mov_b32 m0, s34
	ds_read_b128 v[188:191], v157 offset:49152
	ds_read_b128 v[192:195], v157 offset:50176
	ds_read_b128 v[196:199], v157 offset:51200
	ds_read_b128 v[200:203], v157 offset:52224
	ds_read_b128 v[204:207], v157 offset:53248
	ds_read_b128 v[208:211], v157 offset:54272
	ds_read_b128 v[212:215], v157 offset:55296
	ds_read_b128 v[216:219], v157 offset:56320
	global_load_lds_dwordx4 v[220:221], off
	s_add_i32 m0, s34, 0x2000
	s_add_u32 s34, s52, 0x40080
	v_lshl_add_u64 v[220:221], v[222:223], 0, s[10:11]
	s_addc_u32 s35, s53, 0
	s_add_i32 s52, s87, s57
	global_load_lds_dwordx4 v[220:221], off
	s_mov_b32 m0, s52
	v_lshl_add_u64 v[220:221], s[34:35], 0, v[134:135]
	global_load_lds_dwordx4 v[220:221], off
	s_add_i32 m0, s52, 0x2000
	v_lshl_add_u64 v[220:221], s[34:35], 0, v[138:139]
	global_load_lds_dwordx4 v[220:221], off
	s_mov_b32 m0, s65
	v_lshl_add_u64 v[220:221], v[224:225], 0, s[10:11]
	global_load_lds_dwordx4 v[220:221], off
	s_mov_b32 m0, s66
	v_lshl_add_u64 v[220:221], v[226:227], 0, s[10:11]
	global_load_lds_dwordx4 v[220:221], off
	s_waitcnt vmcnt(8)
	s_waitcnt lgkmcnt(0)
	s_barrier
	s_setprio 1
	s_waitcnt lgkmcnt(0)
	v_mfma_f32_16x16x32_bf16 v[60:63], v[148:151], v[188:191], v[60:63]
	v_mfma_f32_16x16x32_bf16 v[56:59], v[164:167], v[188:191], v[56:59]
	v_mfma_f32_16x16x32_bf16 v[44:47], v[148:151], v[196:199], v[44:47]
	v_mfma_f32_16x16x32_bf16 v[40:43], v[164:167], v[196:199], v[40:43]
	v_mfma_f32_16x16x32_bf16 v[28:31], v[148:151], v[204:207], v[28:31]
	v_mfma_f32_16x16x32_bf16 v[24:27], v[164:167], v[204:207], v[24:27]
	v_mfma_f32_16x16x32_bf16 v[12:15], v[148:151], v[212:215], v[12:15]
	v_mfma_f32_16x16x32_bf16 v[8:11], v[164:167], v[212:215], v[8:11]
	v_mfma_f32_16x16x32_bf16 v[60:63], v[160:163], v[192:195], v[60:63]
	v_mfma_f32_16x16x32_bf16 v[56:59], v[168:171], v[192:195], v[56:59]
	v_mfma_f32_16x16x32_bf16 v[44:47], v[160:163], v[200:203], v[44:47]
	v_mfma_f32_16x16x32_bf16 v[40:43], v[168:171], v[200:203], v[40:43]
	v_mfma_f32_16x16x32_bf16 v[28:31], v[160:163], v[208:211], v[28:31]
	v_mfma_f32_16x16x32_bf16 v[24:27], v[168:171], v[208:211], v[24:27]
	v_mfma_f32_16x16x32_bf16 v[12:15], v[160:163], v[216:219], v[12:15]
	v_mfma_f32_16x16x32_bf16 v[8:11], v[168:171], v[216:219], v[8:11]
	v_mfma_f32_16x16x32_bf16 v[52:55], v[172:175], v[188:191], v[52:55]
	v_mfma_f32_16x16x32_bf16 v[48:51], v[180:183], v[188:191], v[48:51]
	v_mfma_f32_16x16x32_bf16 v[36:39], v[172:175], v[196:199], v[36:39]
	v_mfma_f32_16x16x32_bf16 v[32:35], v[180:183], v[196:199], v[32:35]
	v_mfma_f32_16x16x32_bf16 v[20:23], v[172:175], v[204:207], v[20:23]
	v_mfma_f32_16x16x32_bf16 v[16:19], v[180:183], v[204:207], v[16:19]
	v_mfma_f32_16x16x32_bf16 v[4:7], v[172:175], v[212:215], v[4:7]
	v_mfma_f32_16x16x32_bf16 v[0:3], v[180:183], v[212:215], v[0:3]
	v_mfma_f32_16x16x32_bf16 v[52:55], v[176:179], v[192:195], v[52:55]
	v_mfma_f32_16x16x32_bf16 v[48:51], v[184:187], v[192:195], v[48:51]
	v_mfma_f32_16x16x32_bf16 v[36:39], v[176:179], v[200:203], v[36:39]
	v_mfma_f32_16x16x32_bf16 v[32:35], v[184:187], v[200:203], v[32:35]
	v_mfma_f32_16x16x32_bf16 v[20:23], v[176:179], v[208:211], v[20:23]
	v_mfma_f32_16x16x32_bf16 v[16:19], v[184:187], v[208:211], v[16:19]
	v_mfma_f32_16x16x32_bf16 v[4:7], v[176:179], v[216:219], v[4:7]
	v_mfma_f32_16x16x32_bf16 v[0:3], v[184:187], v[216:219], v[0:3]
	s_setprio 0
	s_barrier
	s_add_i32 s85, s85, 2
	s_add_u32 s50, s50, 0x100
	s_addc_u32 s51, s51, 0
	s_add_u32 s49, s49, 0x100
	s_addc_u32 s77, s77, 0
.LBB0_386:
	ds_read_b128 v[148:151], v154
	ds_read_b128 v[160:163], v154 offset:1024
	ds_read_b128 v[164:167], v154 offset:2048
	ds_read_b128 v[168:171], v154 offset:3072
	ds_read_b128 v[172:175], v155
	ds_read_b128 v[176:179], v155 offset:1024
	ds_read_b128 v[180:183], v155 offset:2048
	ds_read_b128 v[184:187], v155 offset:3072
	s_add_u32 s34, s50, 0xfffc0080
	s_addc_u32 s35, s51, -1
	s_cmp_eq_u32 s85, 12
	s_cselect_b32 s55, s12, s35
	s_cselect_b32 s54, s13, s34
	s_cselect_b32 s53, s27, s77
	s_cselect_b32 s52, s29, s49
	v_lshl_add_u64 v[220:221], s[50:51], 0, v[140:141]
	s_add_i32 m0, s58, 0xc000
	ds_read_b128 v[188:191], v157
	ds_read_b128 v[192:195], v157 offset:1024
	ds_read_b128 v[196:199], v157 offset:2048
	ds_read_b128 v[200:203], v157 offset:3072
	ds_read_b128 v[204:207], v157 offset:4096
	ds_read_b128 v[208:211], v157 offset:5120
	ds_read_b128 v[212:215], v157 offset:6144
	ds_read_b128 v[216:219], v157 offset:7168
	global_load_lds_dwordx4 v[220:221], off
	s_add_i32 m0, s58, 0xe000
	v_lshl_add_u64 v[220:221], s[50:51], 0, v[142:143]
	global_load_lds_dwordx4 v[220:221], off
	s_waitcnt vmcnt(8)
	s_waitcnt lgkmcnt(0)
	s_barrier
	s_setprio 1
	s_waitcnt lgkmcnt(0)
	v_mfma_f32_16x16x32_bf16 v[124:127], v[148:151], v[188:191], v[124:127]
	v_mfma_f32_16x16x32_bf16 v[120:123], v[164:167], v[188:191], v[120:123]
	v_mfma_f32_16x16x32_bf16 v[108:111], v[148:151], v[196:199], v[108:111]
	v_mfma_f32_16x16x32_bf16 v[104:107], v[164:167], v[196:199], v[104:107]
	v_mfma_f32_16x16x32_bf16 v[92:95], v[148:151], v[204:207], v[92:95]
	v_mfma_f32_16x16x32_bf16 v[88:91], v[164:167], v[204:207], v[88:91]
	v_mfma_f32_16x16x32_bf16 v[76:79], v[148:151], v[212:215], v[76:79]
	v_mfma_f32_16x16x32_bf16 v[72:75], v[164:167], v[212:215], v[72:75]
	v_mfma_f32_16x16x32_bf16 v[124:127], v[160:163], v[192:195], v[124:127]
	v_mfma_f32_16x16x32_bf16 v[120:123], v[168:171], v[192:195], v[120:123]
	v_mfma_f32_16x16x32_bf16 v[108:111], v[160:163], v[200:203], v[108:111]
	v_mfma_f32_16x16x32_bf16 v[104:107], v[168:171], v[200:203], v[104:107]
	v_mfma_f32_16x16x32_bf16 v[92:95], v[160:163], v[208:211], v[92:95]
	v_mfma_f32_16x16x32_bf16 v[88:91], v[168:171], v[208:211], v[88:91]
	v_mfma_f32_16x16x32_bf16 v[76:79], v[160:163], v[216:219], v[76:79]
	v_mfma_f32_16x16x32_bf16 v[72:75], v[168:171], v[216:219], v[72:75]
	v_mfma_f32_16x16x32_bf16 v[116:119], v[172:175], v[188:191], v[116:119]
	v_mfma_f32_16x16x32_bf16 v[112:115], v[180:183], v[188:191], v[112:115]
	v_mfma_f32_16x16x32_bf16 v[100:103], v[172:175], v[196:199], v[100:103]
	v_mfma_f32_16x16x32_bf16 v[96:99], v[180:183], v[196:199], v[96:99]
	v_mfma_f32_16x16x32_bf16 v[84:87], v[172:175], v[204:207], v[84:87]
	v_mfma_f32_16x16x32_bf16 v[80:83], v[180:183], v[204:207], v[80:83]
	v_mfma_f32_16x16x32_bf16 v[68:71], v[172:175], v[212:215], v[68:71]
	v_mfma_f32_16x16x32_bf16 v[64:67], v[180:183], v[212:215], v[64:67]
	v_mfma_f32_16x16x32_bf16 v[116:119], v[176:179], v[192:195], v[116:119]
	v_mfma_f32_16x16x32_bf16 v[112:115], v[184:187], v[192:195], v[112:115]
	v_mfma_f32_16x16x32_bf16 v[100:103], v[176:179], v[200:203], v[100:103]
	v_mfma_f32_16x16x32_bf16 v[96:99], v[184:187], v[200:203], v[96:99]
	v_mfma_f32_16x16x32_bf16 v[84:87], v[176:179], v[208:211], v[84:87]
	v_mfma_f32_16x16x32_bf16 v[80:83], v[184:187], v[208:211], v[80:83]
	v_mfma_f32_16x16x32_bf16 v[68:71], v[176:179], v[216:219], v[68:71]
	v_mfma_f32_16x16x32_bf16 v[64:67], v[184:187], v[216:219], v[64:67]
	s_setprio 0
	s_barrier
	s_add_i32 s34, s82, s57
	v_lshl_add_u64 v[220:221], s[52:53], 0, v[134:135]
	s_mov_b32 m0, s34
	ds_read_b128 v[188:191], v157 offset:16384
	ds_read_b128 v[192:195], v157 offset:17408
	ds_read_b128 v[196:199], v157 offset:18432
	ds_read_b128 v[200:203], v157 offset:19456
	ds_read_b128 v[204:207], v157 offset:20480
	ds_read_b128 v[208:211], v157 offset:21504
	ds_read_b128 v[212:215], v157 offset:22528
	ds_read_b128 v[216:219], v157 offset:23552
	global_load_lds_dwordx4 v[220:221], off
	s_add_i32 m0, s34, 0x2000
	s_add_u32 s34, s52, 0x40000
	v_lshl_add_u64 v[222:223], s[52:53], 0, v[138:139]
	s_addc_u32 s35, s53, 0
	s_add_i32 s86, s83, s57
	global_load_lds_dwordx4 v[222:223], off
	v_lshl_add_u64 v[224:225], s[34:35], 0, v[134:135]
	s_mov_b32 m0, s86
	v_lshl_add_u64 v[226:227], s[54:55], 0, v[136:137]
	global_load_lds_dwordx4 v[224:225], off
	s_add_i32 m0, s86, 0x2000
	v_lshl_add_u64 v[224:225], s[34:35], 0, v[138:139]
	global_load_lds_dwordx4 v[224:225], off
	s_mov_b32 m0, s58
	v_lshl_add_u64 v[224:225], s[54:55], 0, v[132:133]
	global_load_lds_dwordx4 v[224:225], off
	s_mov_b32 m0, s59
	s_nop 0
	global_load_lds_dwordx4 v[226:227], off
	s_waitcnt vmcnt(8)
	s_waitcnt lgkmcnt(0)
	s_barrier
	s_setprio 1
	s_waitcnt lgkmcnt(0)
	v_mfma_f32_16x16x32_bf16 v[60:63], v[148:151], v[188:191], v[60:63]
	v_mfma_f32_16x16x32_bf16 v[56:59], v[164:167], v[188:191], v[56:59]
	v_mfma_f32_16x16x32_bf16 v[44:47], v[148:151], v[196:199], v[44:47]
	v_mfma_f32_16x16x32_bf16 v[40:43], v[164:167], v[196:199], v[40:43]
	v_mfma_f32_16x16x32_bf16 v[28:31], v[148:151], v[204:207], v[28:31]
	v_mfma_f32_16x16x32_bf16 v[24:27], v[164:167], v[204:207], v[24:27]
	v_mfma_f32_16x16x32_bf16 v[12:15], v[148:151], v[212:215], v[12:15]
	v_mfma_f32_16x16x32_bf16 v[8:11], v[164:167], v[212:215], v[8:11]
	v_mfma_f32_16x16x32_bf16 v[60:63], v[160:163], v[192:195], v[60:63]
	v_mfma_f32_16x16x32_bf16 v[56:59], v[168:171], v[192:195], v[56:59]
	v_mfma_f32_16x16x32_bf16 v[44:47], v[160:163], v[200:203], v[44:47]
	v_mfma_f32_16x16x32_bf16 v[40:43], v[168:171], v[200:203], v[40:43]
	v_mfma_f32_16x16x32_bf16 v[28:31], v[160:163], v[208:211], v[28:31]
	v_mfma_f32_16x16x32_bf16 v[24:27], v[168:171], v[208:211], v[24:27]
	v_mfma_f32_16x16x32_bf16 v[12:15], v[160:163], v[216:219], v[12:15]
	v_mfma_f32_16x16x32_bf16 v[8:11], v[168:171], v[216:219], v[8:11]
	v_mfma_f32_16x16x32_bf16 v[52:55], v[172:175], v[188:191], v[52:55]
	v_mfma_f32_16x16x32_bf16 v[48:51], v[180:183], v[188:191], v[48:51]
	v_mfma_f32_16x16x32_bf16 v[36:39], v[172:175], v[196:199], v[36:39]
	v_mfma_f32_16x16x32_bf16 v[32:35], v[180:183], v[196:199], v[32:35]
	v_mfma_f32_16x16x32_bf16 v[20:23], v[172:175], v[204:207], v[20:23]
	v_mfma_f32_16x16x32_bf16 v[16:19], v[180:183], v[204:207], v[16:19]
	v_mfma_f32_16x16x32_bf16 v[4:7], v[172:175], v[212:215], v[4:7]
	v_mfma_f32_16x16x32_bf16 v[0:3], v[180:183], v[212:215], v[0:3]
	v_mfma_f32_16x16x32_bf16 v[52:55], v[176:179], v[192:195], v[52:55]
	v_mfma_f32_16x16x32_bf16 v[48:51], v[184:187], v[192:195], v[48:51]
	v_mfma_f32_16x16x32_bf16 v[36:39], v[176:179], v[200:203], v[36:39]
	v_mfma_f32_16x16x32_bf16 v[32:35], v[184:187], v[200:203], v[32:35]
	v_mfma_f32_16x16x32_bf16 v[20:23], v[176:179], v[208:211], v[20:23]
	v_mfma_f32_16x16x32_bf16 v[16:19], v[184:187], v[208:211], v[16:19]
	v_mfma_f32_16x16x32_bf16 v[4:7], v[176:179], v[216:219], v[4:7]
	v_mfma_f32_16x16x32_bf16 v[0:3], v[184:187], v[216:219], v[0:3]
	s_setprio 0
	s_barrier
	s_add_i32 s86, 0, 0x18000
	v_add_u32_e32 v159, s86, v152
	s_add_i32 s87, 0, 0x1c000
	ds_read_b128 v[148:151], v159
	ds_read_b128 v[160:163], v159 offset:1024
	ds_read_b128 v[164:167], v159 offset:2048
	ds_read_b128 v[168:171], v159 offset:3072
	v_add_u32_e32 v159, s87, v152
	ds_read_b128 v[172:175], v159
	ds_read_b128 v[176:179], v159 offset:1024
	ds_read_b128 v[180:183], v159 offset:2048
	ds_read_b128 v[184:187], v159 offset:3072
	s_add_u32 s34, s54, 0x40000
	s_addc_u32 s35, s55, 0
	s_mov_b32 m0, s62
	v_lshl_add_u64 v[228:229], s[34:35], 0, v[132:133]
	ds_read_b128 v[188:191], v157 offset:32768
	ds_read_b128 v[192:195], v157 offset:33792
	ds_read_b128 v[196:199], v157 offset:34816
	ds_read_b128 v[200:203], v157 offset:35840
	ds_read_b128 v[204:207], v157 offset:36864
	ds_read_b128 v[208:211], v157 offset:37888
	ds_read_b128 v[212:215], v157 offset:38912
	ds_read_b128 v[216:219], v157 offset:39936
	global_load_lds_dwordx4 v[228:229], off
	s_mov_b32 m0, s63
	v_lshl_add_u64 v[228:229], s[34:35], 0, v[136:137]
	global_load_lds_dwordx4 v[228:229], off
	s_waitcnt vmcnt(8)
	s_waitcnt lgkmcnt(0)
	s_barrier
	s_setprio 1
	s_waitcnt lgkmcnt(0)
	v_mfma_f32_16x16x32_bf16 v[124:127], v[148:151], v[188:191], v[124:127]
	v_mfma_f32_16x16x32_bf16 v[120:123], v[164:167], v[188:191], v[120:123]
	v_mfma_f32_16x16x32_bf16 v[108:111], v[148:151], v[196:199], v[108:111]
	v_mfma_f32_16x16x32_bf16 v[104:107], v[164:167], v[196:199], v[104:107]
	v_mfma_f32_16x16x32_bf16 v[92:95], v[148:151], v[204:207], v[92:95]
	v_mfma_f32_16x16x32_bf16 v[88:91], v[164:167], v[204:207], v[88:91]
	v_mfma_f32_16x16x32_bf16 v[76:79], v[148:151], v[212:215], v[76:79]
	v_mfma_f32_16x16x32_bf16 v[72:75], v[164:167], v[212:215], v[72:75]
	v_mfma_f32_16x16x32_bf16 v[124:127], v[160:163], v[192:195], v[124:127]
	v_mfma_f32_16x16x32_bf16 v[120:123], v[168:171], v[192:195], v[120:123]
	v_mfma_f32_16x16x32_bf16 v[108:111], v[160:163], v[200:203], v[108:111]
	v_mfma_f32_16x16x32_bf16 v[104:107], v[168:171], v[200:203], v[104:107]
	v_mfma_f32_16x16x32_bf16 v[92:95], v[160:163], v[208:211], v[92:95]
	v_mfma_f32_16x16x32_bf16 v[88:91], v[168:171], v[208:211], v[88:91]
	v_mfma_f32_16x16x32_bf16 v[76:79], v[160:163], v[216:219], v[76:79]
	v_mfma_f32_16x16x32_bf16 v[72:75], v[168:171], v[216:219], v[72:75]
	v_mfma_f32_16x16x32_bf16 v[116:119], v[172:175], v[188:191], v[116:119]
	v_mfma_f32_16x16x32_bf16 v[112:115], v[180:183], v[188:191], v[112:115]
	v_mfma_f32_16x16x32_bf16 v[100:103], v[172:175], v[196:199], v[100:103]
	v_mfma_f32_16x16x32_bf16 v[96:99], v[180:183], v[196:199], v[96:99]
	v_mfma_f32_16x16x32_bf16 v[84:87], v[172:175], v[204:207], v[84:87]
	v_mfma_f32_16x16x32_bf16 v[80:83], v[180:183], v[204:207], v[80:83]
	v_mfma_f32_16x16x32_bf16 v[68:71], v[172:175], v[212:215], v[68:71]
	v_mfma_f32_16x16x32_bf16 v[64:67], v[180:183], v[212:215], v[64:67]
	v_mfma_f32_16x16x32_bf16 v[116:119], v[176:179], v[192:195], v[116:119]
	v_mfma_f32_16x16x32_bf16 v[112:115], v[184:187], v[192:195], v[112:115]
	v_mfma_f32_16x16x32_bf16 v[100:103], v[176:179], v[200:203], v[100:103]
	v_mfma_f32_16x16x32_bf16 v[96:99], v[184:187], v[200:203], v[96:99]
	v_mfma_f32_16x16x32_bf16 v[84:87], v[176:179], v[208:211], v[84:87]
	v_mfma_f32_16x16x32_bf16 v[80:83], v[184:187], v[208:211], v[80:83]
	v_mfma_f32_16x16x32_bf16 v[68:71], v[176:179], v[216:219], v[68:71]
	v_mfma_f32_16x16x32_bf16 v[64:67], v[184:187], v[216:219], v[64:67]
	s_setprio 0
	s_barrier
	s_add_i32 s34, s86, s57
	v_lshl_add_u64 v[220:221], v[220:221], 0, s[10:11]
	s_mov_b32 m0, s34
	ds_read_b128 v[188:191], v157 offset:49152
	ds_read_b128 v[192:195], v157 offset:50176
	ds_read_b128 v[196:199], v157 offset:51200
	ds_read_b128 v[200:203], v157 offset:52224
	ds_read_b128 v[204:207], v157 offset:53248
	ds_read_b128 v[208:211], v157 offset:54272
	ds_read_b128 v[212:215], v157 offset:55296
	ds_read_b128 v[216:219], v157 offset:56320
	global_load_lds_dwordx4 v[220:221], off
	s_add_i32 m0, s34, 0x2000
	s_add_u32 s34, s52, 0x40080
	v_lshl_add_u64 v[220:221], v[222:223], 0, s[10:11]
	s_addc_u32 s35, s53, 0
	s_add_i32 s52, s87, s57
	global_load_lds_dwordx4 v[220:221], off
	s_mov_b32 m0, s52
	v_lshl_add_u64 v[220:221], s[34:35], 0, v[134:135]
	global_load_lds_dwordx4 v[220:221], off
	s_add_i32 m0, s52, 0x2000
	v_lshl_add_u64 v[220:221], s[34:35], 0, v[138:139]
	global_load_lds_dwordx4 v[220:221], off
	s_mov_b32 m0, s65
	v_lshl_add_u64 v[220:221], v[224:225], 0, s[10:11]
	global_load_lds_dwordx4 v[220:221], off
	s_mov_b32 m0, s66
	v_lshl_add_u64 v[220:221], v[226:227], 0, s[10:11]
	global_load_lds_dwordx4 v[220:221], off
	s_waitcnt vmcnt(8)
	s_waitcnt lgkmcnt(0)
	s_barrier
	s_setprio 1
	s_waitcnt lgkmcnt(0)
	v_mfma_f32_16x16x32_bf16 v[60:63], v[148:151], v[188:191], v[60:63]
	v_mfma_f32_16x16x32_bf16 v[56:59], v[164:167], v[188:191], v[56:59]
	v_mfma_f32_16x16x32_bf16 v[44:47], v[148:151], v[196:199], v[44:47]
	v_mfma_f32_16x16x32_bf16 v[40:43], v[164:167], v[196:199], v[40:43]
	v_mfma_f32_16x16x32_bf16 v[28:31], v[148:151], v[204:207], v[28:31]
	v_mfma_f32_16x16x32_bf16 v[24:27], v[164:167], v[204:207], v[24:27]
	v_mfma_f32_16x16x32_bf16 v[12:15], v[148:151], v[212:215], v[12:15]
	v_mfma_f32_16x16x32_bf16 v[8:11], v[164:167], v[212:215], v[8:11]
	v_mfma_f32_16x16x32_bf16 v[60:63], v[160:163], v[192:195], v[60:63]
	v_mfma_f32_16x16x32_bf16 v[56:59], v[168:171], v[192:195], v[56:59]
	v_mfma_f32_16x16x32_bf16 v[44:47], v[160:163], v[200:203], v[44:47]
	v_mfma_f32_16x16x32_bf16 v[40:43], v[168:171], v[200:203], v[40:43]
	v_mfma_f32_16x16x32_bf16 v[28:31], v[160:163], v[208:211], v[28:31]
	v_mfma_f32_16x16x32_bf16 v[24:27], v[168:171], v[208:211], v[24:27]
	v_mfma_f32_16x16x32_bf16 v[12:15], v[160:163], v[216:219], v[12:15]
	v_mfma_f32_16x16x32_bf16 v[8:11], v[168:171], v[216:219], v[8:11]
	v_mfma_f32_16x16x32_bf16 v[52:55], v[172:175], v[188:191], v[52:55]
	v_mfma_f32_16x16x32_bf16 v[48:51], v[180:183], v[188:191], v[48:51]
	v_mfma_f32_16x16x32_bf16 v[36:39], v[172:175], v[196:199], v[36:39]
	v_mfma_f32_16x16x32_bf16 v[32:35], v[180:183], v[196:199], v[32:35]
	v_mfma_f32_16x16x32_bf16 v[20:23], v[172:175], v[204:207], v[20:23]
	v_mfma_f32_16x16x32_bf16 v[16:19], v[180:183], v[204:207], v[16:19]
	v_mfma_f32_16x16x32_bf16 v[4:7], v[172:175], v[212:215], v[4:7]
	v_mfma_f32_16x16x32_bf16 v[0:3], v[180:183], v[212:215], v[0:3]
	v_mfma_f32_16x16x32_bf16 v[52:55], v[176:179], v[192:195], v[52:55]
	v_mfma_f32_16x16x32_bf16 v[48:51], v[184:187], v[192:195], v[48:51]
	v_mfma_f32_16x16x32_bf16 v[36:39], v[176:179], v[200:203], v[36:39]
	v_mfma_f32_16x16x32_bf16 v[32:35], v[184:187], v[200:203], v[32:35]
	v_mfma_f32_16x16x32_bf16 v[20:23], v[176:179], v[208:211], v[20:23]
	v_mfma_f32_16x16x32_bf16 v[16:19], v[184:187], v[208:211], v[16:19]
	v_mfma_f32_16x16x32_bf16 v[4:7], v[176:179], v[216:219], v[4:7]
	v_mfma_f32_16x16x32_bf16 v[0:3], v[184:187], v[216:219], v[0:3]
	s_setprio 0
	s_cmp_eq_u32 s85, s98
	s_cbranch_scc1 .Lmy_nobar_4
	s_barrier

.Lmy_nobar2_5:
	ds_read_b128 v[148:151], v155
	ds_read_b128 v[160:163], v155 offset:1024
	ds_read_b128 v[164:167], v155 offset:2048
	ds_read_b128 v[168:171], v155 offset:3072
	ds_read_b128 v[172:175], v157
	ds_read_b128 v[176:179], v157 offset:1024
	ds_read_b128 v[180:183], v157 offset:2048
	ds_read_b128 v[184:187], v157 offset:3072
	s_add_u32 s34, s42, 0xfffc0080
	s_addc_u32 s35, s43, -1
	s_cmp_eq_u32 s85, 12
	s_cselect_b32 s51, s23, s35
	s_cselect_b32 s50, s81, s34
	s_cselect_b32 s49, s11, s84
	s_cselect_b32 s48, s82, s83
	v_lshl_add_u64 v[220:221], s[42:43], 0, v[140:141]
	s_add_i32 m0, s41, 0xc000
	ds_read_b128 v[188:191], v158
	ds_read_b128 v[192:195], v158 offset:1024
	ds_read_b128 v[196:199], v158 offset:2048
	ds_read_b128 v[200:203], v158 offset:3072
	ds_read_b128 v[204:207], v158 offset:4096
	ds_read_b128 v[208:211], v158 offset:5120
	ds_read_b128 v[212:215], v158 offset:6144
	ds_read_b128 v[216:219], v158 offset:7168
	global_load_lds_dwordx4 v[220:221], off
	s_add_i32 m0, s41, 0xe000
	v_lshl_add_u64 v[220:221], s[42:43], 0, v[142:143]
	global_load_lds_dwordx4 v[220:221], off
	s_waitcnt vmcnt(8)
	s_waitcnt lgkmcnt(0)
	s_barrier
	s_setprio 1
	s_waitcnt lgkmcnt(0)
	v_mfma_f32_16x16x32_bf16 v[124:127], v[148:151], v[188:191], 0
	v_mfma_f32_16x16x32_bf16 v[120:123], v[164:167], v[188:191], 0
	v_mfma_f32_16x16x32_bf16 v[108:111], v[148:151], v[196:199], 0
	v_mfma_f32_16x16x32_bf16 v[104:107], v[164:167], v[196:199], 0
	v_mfma_f32_16x16x32_bf16 v[92:95], v[148:151], v[204:207], 0
	v_mfma_f32_16x16x32_bf16 v[88:91], v[164:167], v[204:207], 0
	v_mfma_f32_16x16x32_bf16 v[76:79], v[148:151], v[212:215], 0
	v_mfma_f32_16x16x32_bf16 v[72:75], v[164:167], v[212:215], 0
	v_mfma_f32_16x16x32_bf16 v[124:127], v[160:163], v[192:195], v[124:127]
	v_mfma_f32_16x16x32_bf16 v[120:123], v[168:171], v[192:195], v[120:123]
	v_mfma_f32_16x16x32_bf16 v[108:111], v[160:163], v[200:203], v[108:111]
	v_mfma_f32_16x16x32_bf16 v[104:107], v[168:171], v[200:203], v[104:107]
	v_mfma_f32_16x16x32_bf16 v[92:95], v[160:163], v[208:211], v[92:95]
	v_mfma_f32_16x16x32_bf16 v[88:91], v[168:171], v[208:211], v[88:91]
	v_mfma_f32_16x16x32_bf16 v[76:79], v[160:163], v[216:219], v[76:79]
	v_mfma_f32_16x16x32_bf16 v[72:75], v[168:171], v[216:219], v[72:75]
	v_mfma_f32_16x16x32_bf16 v[116:119], v[172:175], v[188:191], 0
	v_mfma_f32_16x16x32_bf16 v[112:115], v[180:183], v[188:191], 0
	v_mfma_f32_16x16x32_bf16 v[100:103], v[172:175], v[196:199], 0
	v_mfma_f32_16x16x32_bf16 v[96:99], v[180:183], v[196:199], 0
	v_mfma_f32_16x16x32_bf16 v[84:87], v[172:175], v[204:207], 0
	v_mfma_f32_16x16x32_bf16 v[80:83], v[180:183], v[204:207], 0
	v_mfma_f32_16x16x32_bf16 v[68:71], v[172:175], v[212:215], 0
	v_mfma_f32_16x16x32_bf16 v[64:67], v[180:183], v[212:215], 0
	v_mfma_f32_16x16x32_bf16 v[116:119], v[176:179], v[192:195], v[116:119]
	v_mfma_f32_16x16x32_bf16 v[112:115], v[184:187], v[192:195], v[112:115]
	v_mfma_f32_16x16x32_bf16 v[100:103], v[176:179], v[200:203], v[100:103]
	v_mfma_f32_16x16x32_bf16 v[96:99], v[184:187], v[200:203], v[96:99]
	v_mfma_f32_16x16x32_bf16 v[84:87], v[176:179], v[208:211], v[84:87]
	v_mfma_f32_16x16x32_bf16 v[80:83], v[184:187], v[208:211], v[80:83]
	v_mfma_f32_16x16x32_bf16 v[68:71], v[176:179], v[216:219], v[68:71]
	v_mfma_f32_16x16x32_bf16 v[64:67], v[184:187], v[216:219], v[64:67]
	s_setprio 0
	s_barrier
	s_add_i32 s34, s65, s54
	v_lshl_add_u64 v[220:221], s[48:49], 0, v[136:137]
	s_mov_b32 m0, s34
	ds_read_b128 v[188:191], v158 offset:16384
	ds_read_b128 v[192:195], v158 offset:17408
	ds_read_b128 v[196:199], v158 offset:18432
	ds_read_b128 v[200:203], v158 offset:19456
	ds_read_b128 v[204:207], v158 offset:20480
	ds_read_b128 v[208:211], v158 offset:21504
	ds_read_b128 v[212:215], v158 offset:22528
	ds_read_b128 v[216:219], v158 offset:23552
	global_load_lds_dwordx4 v[220:221], off
	s_add_i32 m0, s34, 0x2000
	s_add_u32 s34, s48, 0x40000
	v_lshl_add_u64 v[222:223], s[48:49], 0, v[132:133]
	s_addc_u32 s35, s49, 0
	s_add_i32 s86, s66, s54
	global_load_lds_dwordx4 v[222:223], off
	v_lshl_add_u64 v[224:225], s[34:35], 0, v[136:137]
	s_mov_b32 m0, s86
	v_lshl_add_u64 v[226:227], s[50:51], 0, v[134:135]
	global_load_lds_dwordx4 v[224:225], off
	s_add_i32 m0, s86, 0x2000
	v_lshl_add_u64 v[224:225], s[34:35], 0, v[132:133]
	global_load_lds_dwordx4 v[224:225], off
	s_mov_b32 m0, s41
	v_lshl_add_u64 v[224:225], s[50:51], 0, v[138:139]
	global_load_lds_dwordx4 v[224:225], off
	s_mov_b32 m0, s58
	s_nop 0
	global_load_lds_dwordx4 v[226:227], off
	s_waitcnt vmcnt(8)
	s_waitcnt lgkmcnt(0)
	s_barrier
	s_setprio 1
	s_waitcnt lgkmcnt(0)
	v_mfma_f32_16x16x32_bf16 v[60:63], v[148:151], v[188:191], 0
	v_mfma_f32_16x16x32_bf16 v[56:59], v[164:167], v[188:191], 0
	v_mfma_f32_16x16x32_bf16 v[44:47], v[148:151], v[196:199], 0
	v_mfma_f32_16x16x32_bf16 v[40:43], v[164:167], v[196:199], 0
	v_mfma_f32_16x16x32_bf16 v[28:31], v[148:151], v[204:207], 0
	v_mfma_f32_16x16x32_bf16 v[24:27], v[164:167], v[204:207], 0
	v_mfma_f32_16x16x32_bf16 v[12:15], v[148:151], v[212:215], 0
	v_mfma_f32_16x16x32_bf16 v[8:11], v[164:167], v[212:215], 0
	v_mfma_f32_16x16x32_bf16 v[60:63], v[160:163], v[192:195], v[60:63]
	v_mfma_f32_16x16x32_bf16 v[56:59], v[168:171], v[192:195], v[56:59]
	v_mfma_f32_16x16x32_bf16 v[44:47], v[160:163], v[200:203], v[44:47]
	v_mfma_f32_16x16x32_bf16 v[40:43], v[168:171], v[200:203], v[40:43]
	v_mfma_f32_16x16x32_bf16 v[28:31], v[160:163], v[208:211], v[28:31]
	v_mfma_f32_16x16x32_bf16 v[24:27], v[168:171], v[208:211], v[24:27]
	v_mfma_f32_16x16x32_bf16 v[12:15], v[160:163], v[216:219], v[12:15]
	v_mfma_f32_16x16x32_bf16 v[8:11], v[168:171], v[216:219], v[8:11]
	v_mfma_f32_16x16x32_bf16 v[52:55], v[172:175], v[188:191], 0
	v_mfma_f32_16x16x32_bf16 v[48:51], v[180:183], v[188:191], 0
	v_mfma_f32_16x16x32_bf16 v[36:39], v[172:175], v[196:199], 0
	v_mfma_f32_16x16x32_bf16 v[32:35], v[180:183], v[196:199], 0
	v_mfma_f32_16x16x32_bf16 v[20:23], v[172:175], v[204:207], 0
	v_mfma_f32_16x16x32_bf16 v[16:19], v[180:183], v[204:207], 0
	v_mfma_f32_16x16x32_bf16 v[4:7], v[172:175], v[212:215], 0
	v_mfma_f32_16x16x32_bf16 v[0:3], v[180:183], v[212:215], 0
	v_mfma_f32_16x16x32_bf16 v[52:55], v[176:179], v[192:195], v[52:55]
	v_mfma_f32_16x16x32_bf16 v[48:51], v[184:187], v[192:195], v[48:51]
	v_mfma_f32_16x16x32_bf16 v[36:39], v[176:179], v[200:203], v[36:39]
	v_mfma_f32_16x16x32_bf16 v[32:35], v[184:187], v[200:203], v[32:35]
	v_mfma_f32_16x16x32_bf16 v[20:23], v[176:179], v[208:211], v[20:23]
	v_mfma_f32_16x16x32_bf16 v[16:19], v[184:187], v[208:211], v[16:19]
	v_mfma_f32_16x16x32_bf16 v[4:7], v[176:179], v[216:219], v[4:7]
	v_mfma_f32_16x16x32_bf16 v[0:3], v[184:187], v[216:219], v[0:3]
	s_setprio 0
	s_barrier
	s_add_i32 s86, 0, 0x18000
	v_add_u32_e32 v159, s86, v152
	s_add_i32 s87, 0, 0x1c000
	ds_read_b128 v[148:151], v159
	ds_read_b128 v[160:163], v159 offset:1024
	ds_read_b128 v[164:167], v159 offset:2048
	ds_read_b128 v[168:171], v159 offset:3072
	v_add_u32_e32 v159, s87, v152
	ds_read_b128 v[172:175], v159
	ds_read_b128 v[176:179], v159 offset:1024
	ds_read_b128 v[180:183], v159 offset:2048
	ds_read_b128 v[184:187], v159 offset:3072
	s_add_u32 s34, s50, 0x40000
	s_addc_u32 s35, s51, 0
	s_mov_b32 m0, s59
	v_lshl_add_u64 v[228:229], s[34:35], 0, v[138:139]
	ds_read_b128 v[188:191], v158 offset:32768
	ds_read_b128 v[192:195], v158 offset:33792
	ds_read_b128 v[196:199], v158 offset:34816
	ds_read_b128 v[200:203], v158 offset:35840
	ds_read_b128 v[204:207], v158 offset:36864
	ds_read_b128 v[208:211], v158 offset:37888
	ds_read_b128 v[212:215], v158 offset:38912
	ds_read_b128 v[216:219], v158 offset:39936
	global_load_lds_dwordx4 v[228:229], off
	s_mov_b32 m0, s62
	v_lshl_add_u64 v[228:229], s[34:35], 0, v[134:135]
	global_load_lds_dwordx4 v[228:229], off
	s_waitcnt vmcnt(8)
	s_waitcnt lgkmcnt(0)
	s_barrier
	s_setprio 1
	s_waitcnt lgkmcnt(0)
	v_mfma_f32_16x16x32_bf16 v[124:127], v[148:151], v[188:191], v[124:127]
	v_mfma_f32_16x16x32_bf16 v[120:123], v[164:167], v[188:191], v[120:123]
	v_mfma_f32_16x16x32_bf16 v[108:111], v[148:151], v[196:199], v[108:111]
	v_mfma_f32_16x16x32_bf16 v[104:107], v[164:167], v[196:199], v[104:107]
	v_mfma_f32_16x16x32_bf16 v[92:95], v[148:151], v[204:207], v[92:95]
	v_mfma_f32_16x16x32_bf16 v[88:91], v[164:167], v[204:207], v[88:91]
	v_mfma_f32_16x16x32_bf16 v[76:79], v[148:151], v[212:215], v[76:79]
	v_mfma_f32_16x16x32_bf16 v[72:75], v[164:167], v[212:215], v[72:75]
	v_mfma_f32_16x16x32_bf16 v[124:127], v[160:163], v[192:195], v[124:127]
	v_mfma_f32_16x16x32_bf16 v[120:123], v[168:171], v[192:195], v[120:123]
	v_mfma_f32_16x16x32_bf16 v[108:111], v[160:163], v[200:203], v[108:111]
	v_mfma_f32_16x16x32_bf16 v[104:107], v[168:171], v[200:203], v[104:107]
	v_mfma_f32_16x16x32_bf16 v[92:95], v[160:163], v[208:211], v[92:95]
	v_mfma_f32_16x16x32_bf16 v[88:91], v[168:171], v[208:211], v[88:91]
	v_mfma_f32_16x16x32_bf16 v[76:79], v[160:163], v[216:219], v[76:79]
	v_mfma_f32_16x16x32_bf16 v[72:75], v[168:171], v[216:219], v[72:75]
	v_mfma_f32_16x16x32_bf16 v[116:119], v[172:175], v[188:191], v[116:119]
	v_mfma_f32_16x16x32_bf16 v[112:115], v[180:183], v[188:191], v[112:115]
	v_mfma_f32_16x16x32_bf16 v[100:103], v[172:175], v[196:199], v[100:103]
	v_mfma_f32_16x16x32_bf16 v[96:99], v[180:183], v[196:199], v[96:99]
	v_mfma_f32_16x16x32_bf16 v[84:87], v[172:175], v[204:207], v[84:87]
	v_mfma_f32_16x16x32_bf16 v[80:83], v[180:183], v[204:207], v[80:83]
	v_mfma_f32_16x16x32_bf16 v[68:71], v[172:175], v[212:215], v[68:71]
	v_mfma_f32_16x16x32_bf16 v[64:67], v[180:183], v[212:215], v[64:67]
	v_mfma_f32_16x16x32_bf16 v[116:119], v[176:179], v[192:195], v[116:119]
	v_mfma_f32_16x16x32_bf16 v[112:115], v[184:187], v[192:195], v[112:115]
	v_mfma_f32_16x16x32_bf16 v[100:103], v[176:179], v[200:203], v[100:103]
	v_mfma_f32_16x16x32_bf16 v[96:99], v[184:187], v[200:203], v[96:99]
	v_mfma_f32_16x16x32_bf16 v[84:87], v[176:179], v[208:211], v[84:87]
	v_mfma_f32_16x16x32_bf16 v[80:83], v[184:187], v[208:211], v[80:83]
	v_mfma_f32_16x16x32_bf16 v[68:71], v[176:179], v[216:219], v[68:71]
	v_mfma_f32_16x16x32_bf16 v[64:67], v[184:187], v[216:219], v[64:67]
	s_setprio 0
	s_barrier
	s_add_i32 s34, s86, s54
	v_lshl_add_u64 v[220:221], v[220:221], 0, s[6:7]
	s_mov_b32 m0, s34
	ds_read_b128 v[188:191], v158 offset:49152
	ds_read_b128 v[192:195], v158 offset:50176
	ds_read_b128 v[196:199], v158 offset:51200
	ds_read_b128 v[200:203], v158 offset:52224
	ds_read_b128 v[204:207], v158 offset:53248
	ds_read_b128 v[208:211], v158 offset:54272
	ds_read_b128 v[212:215], v158 offset:55296
	ds_read_b128 v[216:219], v158 offset:56320
	global_load_lds_dwordx4 v[220:221], off
	s_add_i32 m0, s34, 0x2000
	s_add_u32 s34, s48, 0x40080
	v_lshl_add_u64 v[220:221], v[222:223], 0, s[6:7]
	s_addc_u32 s35, s49, 0
	s_add_i32 s48, s87, s54
	global_load_lds_dwordx4 v[220:221], off
	s_mov_b32 m0, s48
	v_lshl_add_u64 v[220:221], s[34:35], 0, v[136:137]
	global_load_lds_dwordx4 v[220:221], off
	s_add_i32 m0, s48, 0x2000
	v_lshl_add_u64 v[220:221], s[34:35], 0, v[132:133]
	global_load_lds_dwordx4 v[220:221], off
	s_mov_b32 m0, s63
	v_lshl_add_u64 v[220:221], v[224:225], 0, s[6:7]
	global_load_lds_dwordx4 v[220:221], off
	s_mov_b32 m0, s64
	v_lshl_add_u64 v[220:221], v[226:227], 0, s[6:7]
	global_load_lds_dwordx4 v[220:221], off
	s_waitcnt vmcnt(8)
	s_waitcnt lgkmcnt(0)
	s_barrier
	s_setprio 1
	s_waitcnt lgkmcnt(0)
	v_mfma_f32_16x16x32_bf16 v[60:63], v[148:151], v[188:191], v[60:63]
	v_mfma_f32_16x16x32_bf16 v[56:59], v[164:167], v[188:191], v[56:59]
	v_mfma_f32_16x16x32_bf16 v[44:47], v[148:151], v[196:199], v[44:47]
	v_mfma_f32_16x16x32_bf16 v[40:43], v[164:167], v[196:199], v[40:43]
	v_mfma_f32_16x16x32_bf16 v[28:31], v[148:151], v[204:207], v[28:31]
	v_mfma_f32_16x16x32_bf16 v[24:27], v[164:167], v[204:207], v[24:27]
	v_mfma_f32_16x16x32_bf16 v[12:15], v[148:151], v[212:215], v[12:15]
	v_mfma_f32_16x16x32_bf16 v[8:11], v[164:167], v[212:215], v[8:11]
	v_mfma_f32_16x16x32_bf16 v[60:63], v[160:163], v[192:195], v[60:63]
	v_mfma_f32_16x16x32_bf16 v[56:59], v[168:171], v[192:195], v[56:59]
	v_mfma_f32_16x16x32_bf16 v[44:47], v[160:163], v[200:203], v[44:47]
	v_mfma_f32_16x16x32_bf16 v[40:43], v[168:171], v[200:203], v[40:43]
	v_mfma_f32_16x16x32_bf16 v[28:31], v[160:163], v[208:211], v[28:31]
	v_mfma_f32_16x16x32_bf16 v[24:27], v[168:171], v[208:211], v[24:27]
	v_mfma_f32_16x16x32_bf16 v[12:15], v[160:163], v[216:219], v[12:15]
	v_mfma_f32_16x16x32_bf16 v[8:11], v[168:171], v[216:219], v[8:11]
	v_mfma_f32_16x16x32_bf16 v[52:55], v[172:175], v[188:191], v[52:55]
	v_mfma_f32_16x16x32_bf16 v[48:51], v[180:183], v[188:191], v[48:51]
	v_mfma_f32_16x16x32_bf16 v[36:39], v[172:175], v[196:199], v[36:39]
	v_mfma_f32_16x16x32_bf16 v[32:35], v[180:183], v[196:199], v[32:35]
	v_mfma_f32_16x16x32_bf16 v[20:23], v[172:175], v[204:207], v[20:23]
	v_mfma_f32_16x16x32_bf16 v[16:19], v[180:183], v[204:207], v[16:19]
	v_mfma_f32_16x16x32_bf16 v[4:7], v[172:175], v[212:215], v[4:7]
	v_mfma_f32_16x16x32_bf16 v[0:3], v[180:183], v[212:215], v[0:3]
	v_mfma_f32_16x16x32_bf16 v[52:55], v[176:179], v[192:195], v[52:55]
	v_mfma_f32_16x16x32_bf16 v[48:51], v[184:187], v[192:195], v[48:51]
	v_mfma_f32_16x16x32_bf16 v[36:39], v[176:179], v[200:203], v[36:39]
	v_mfma_f32_16x16x32_bf16 v[32:35], v[184:187], v[200:203], v[32:35]
	v_mfma_f32_16x16x32_bf16 v[20:23], v[176:179], v[208:211], v[20:23]
	v_mfma_f32_16x16x32_bf16 v[16:19], v[184:187], v[208:211], v[16:19]
	v_mfma_f32_16x16x32_bf16 v[4:7], v[176:179], v[216:219], v[4:7]
	v_mfma_f32_16x16x32_bf16 v[0:3], v[184:187], v[216:219], v[0:3]
	s_setprio 0
	s_barrier
	s_add_i32 s85, s85, 2
	s_add_u32 s42, s42, 0x100
	s_addc_u32 s43, s43, 0
	s_add_u32 s83, s83, 0x100
	s_addc_u32 s84, s84, 0
.LBB0_476:
	ds_read_b128 v[148:151], v155
	ds_read_b128 v[160:163], v155 offset:1024
	ds_read_b128 v[164:167], v155 offset:2048
	ds_read_b128 v[168:171], v155 offset:3072
	ds_read_b128 v[172:175], v157
	ds_read_b128 v[176:179], v157 offset:1024
	ds_read_b128 v[180:183], v157 offset:2048
	ds_read_b128 v[184:187], v157 offset:3072
	s_add_u32 s34, s42, 0xfffc0080
	s_addc_u32 s35, s43, -1
	s_cmp_eq_u32 s85, 12
	s_cselect_b32 s51, s23, s35
	s_cselect_b32 s50, s81, s34
	s_cselect_b32 s49, s11, s84
	s_cselect_b32 s48, s82, s83
	v_lshl_add_u64 v[220:221], s[42:43], 0, v[140:141]
	s_add_i32 m0, s41, 0xc000
	ds_read_b128 v[188:191], v158
	ds_read_b128 v[192:195], v158 offset:1024
	ds_read_b128 v[196:199], v158 offset:2048
	ds_read_b128 v[200:203], v158 offset:3072
	ds_read_b128 v[204:207], v158 offset:4096
	ds_read_b128 v[208:211], v158 offset:5120
	ds_read_b128 v[212:215], v158 offset:6144
	ds_read_b128 v[216:219], v158 offset:7168
	global_load_lds_dwordx4 v[220:221], off
	s_add_i32 m0, s41, 0xe000
	v_lshl_add_u64 v[220:221], s[42:43], 0, v[142:143]
	global_load_lds_dwordx4 v[220:221], off
	s_waitcnt vmcnt(8)
	s_waitcnt lgkmcnt(0)
	s_barrier
	s_setprio 1
	s_waitcnt lgkmcnt(0)
	v_mfma_f32_16x16x32_bf16 v[124:127], v[148:151], v[188:191], v[124:127]
	v_mfma_f32_16x16x32_bf16 v[120:123], v[164:167], v[188:191], v[120:123]
	v_mfma_f32_16x16x32_bf16 v[108:111], v[148:151], v[196:199], v[108:111]
	v_mfma_f32_16x16x32_bf16 v[104:107], v[164:167], v[196:199], v[104:107]
	v_mfma_f32_16x16x32_bf16 v[92:95], v[148:151], v[204:207], v[92:95]
	v_mfma_f32_16x16x32_bf16 v[88:91], v[164:167], v[204:207], v[88:91]
	v_mfma_f32_16x16x32_bf16 v[76:79], v[148:151], v[212:215], v[76:79]
	v_mfma_f32_16x16x32_bf16 v[72:75], v[164:167], v[212:215], v[72:75]
	v_mfma_f32_16x16x32_bf16 v[124:127], v[160:163], v[192:195], v[124:127]
	v_mfma_f32_16x16x32_bf16 v[120:123], v[168:171], v[192:195], v[120:123]
	v_mfma_f32_16x16x32_bf16 v[108:111], v[160:163], v[200:203], v[108:111]
	v_mfma_f32_16x16x32_bf16 v[104:107], v[168:171], v[200:203], v[104:107]
	v_mfma_f32_16x16x32_bf16 v[92:95], v[160:163], v[208:211], v[92:95]
	v_mfma_f32_16x16x32_bf16 v[88:91], v[168:171], v[208:211], v[88:91]
	v_mfma_f32_16x16x32_bf16 v[76:79], v[160:163], v[216:219], v[76:79]
	v_mfma_f32_16x16x32_bf16 v[72:75], v[168:171], v[216:219], v[72:75]
	v_mfma_f32_16x16x32_bf16 v[116:119], v[172:175], v[188:191], v[116:119]
	v_mfma_f32_16x16x32_bf16 v[112:115], v[180:183], v[188:191], v[112:115]
	v_mfma_f32_16x16x32_bf16 v[100:103], v[172:175], v[196:199], v[100:103]
	v_mfma_f32_16x16x32_bf16 v[96:99], v[180:183], v[196:199], v[96:99]
	v_mfma_f32_16x16x32_bf16 v[84:87], v[172:175], v[204:207], v[84:87]
	v_mfma_f32_16x16x32_bf16 v[80:83], v[180:183], v[204:207], v[80:83]
	v_mfma_f32_16x16x32_bf16 v[68:71], v[172:175], v[212:215], v[68:71]
	v_mfma_f32_16x16x32_bf16 v[64:67], v[180:183], v[212:215], v[64:67]
	v_mfma_f32_16x16x32_bf16 v[116:119], v[176:179], v[192:195], v[116:119]
	v_mfma_f32_16x16x32_bf16 v[112:115], v[184:187], v[192:195], v[112:115]
	v_mfma_f32_16x16x32_bf16 v[100:103], v[176:179], v[200:203], v[100:103]
	v_mfma_f32_16x16x32_bf16 v[96:99], v[184:187], v[200:203], v[96:99]
	v_mfma_f32_16x16x32_bf16 v[84:87], v[176:179], v[208:211], v[84:87]
	v_mfma_f32_16x16x32_bf16 v[80:83], v[184:187], v[208:211], v[80:83]
	v_mfma_f32_16x16x32_bf16 v[68:71], v[176:179], v[216:219], v[68:71]
	v_mfma_f32_16x16x32_bf16 v[64:67], v[184:187], v[216:219], v[64:67]
	s_setprio 0
	s_barrier
	s_add_i32 s34, s65, s54
	v_lshl_add_u64 v[220:221], s[48:49], 0, v[136:137]
	s_mov_b32 m0, s34
	ds_read_b128 v[188:191], v158 offset:16384
	ds_read_b128 v[192:195], v158 offset:17408
	ds_read_b128 v[196:199], v158 offset:18432
	ds_read_b128 v[200:203], v158 offset:19456
	ds_read_b128 v[204:207], v158 offset:20480
	ds_read_b128 v[208:211], v158 offset:21504
	ds_read_b128 v[212:215], v158 offset:22528
	ds_read_b128 v[216:219], v158 offset:23552
	global_load_lds_dwordx4 v[220:221], off
	s_add_i32 m0, s34, 0x2000
	s_add_u32 s34, s48, 0x40000
	v_lshl_add_u64 v[222:223], s[48:49], 0, v[132:133]
	s_addc_u32 s35, s49, 0
	s_add_i32 s86, s66, s54
	global_load_lds_dwordx4 v[222:223], off
	v_lshl_add_u64 v[224:225], s[34:35], 0, v[136:137]
	s_mov_b32 m0, s86
	v_lshl_add_u64 v[226:227], s[50:51], 0, v[134:135]
	global_load_lds_dwordx4 v[224:225], off
	s_add_i32 m0, s86, 0x2000
	v_lshl_add_u64 v[224:225], s[34:35], 0, v[132:133]
	global_load_lds_dwordx4 v[224:225], off
	s_mov_b32 m0, s41
	v_lshl_add_u64 v[224:225], s[50:51], 0, v[138:139]
	global_load_lds_dwordx4 v[224:225], off
	s_mov_b32 m0, s58
	s_nop 0
	global_load_lds_dwordx4 v[226:227], off
	s_waitcnt vmcnt(8)
	s_waitcnt lgkmcnt(0)
	s_barrier
	s_setprio 1
	s_waitcnt lgkmcnt(0)
	v_mfma_f32_16x16x32_bf16 v[60:63], v[148:151], v[188:191], v[60:63]
	v_mfma_f32_16x16x32_bf16 v[56:59], v[164:167], v[188:191], v[56:59]
	v_mfma_f32_16x16x32_bf16 v[44:47], v[148:151], v[196:199], v[44:47]
	v_mfma_f32_16x16x32_bf16 v[40:43], v[164:167], v[196:199], v[40:43]
	v_mfma_f32_16x16x32_bf16 v[28:31], v[148:151], v[204:207], v[28:31]
	v_mfma_f32_16x16x32_bf16 v[24:27], v[164:167], v[204:207], v[24:27]
	v_mfma_f32_16x16x32_bf16 v[12:15], v[148:151], v[212:215], v[12:15]
	v_mfma_f32_16x16x32_bf16 v[8:11], v[164:167], v[212:215], v[8:11]
	v_mfma_f32_16x16x32_bf16 v[60:63], v[160:163], v[192:195], v[60:63]
	v_mfma_f32_16x16x32_bf16 v[56:59], v[168:171], v[192:195], v[56:59]
	v_mfma_f32_16x16x32_bf16 v[44:47], v[160:163], v[200:203], v[44:47]
	v_mfma_f32_16x16x32_bf16 v[40:43], v[168:171], v[200:203], v[40:43]
	v_mfma_f32_16x16x32_bf16 v[28:31], v[160:163], v[208:211], v[28:31]
	v_mfma_f32_16x16x32_bf16 v[24:27], v[168:171], v[208:211], v[24:27]
	v_mfma_f32_16x16x32_bf16 v[12:15], v[160:163], v[216:219], v[12:15]
	v_mfma_f32_16x16x32_bf16 v[8:11], v[168:171], v[216:219], v[8:11]
	v_mfma_f32_16x16x32_bf16 v[52:55], v[172:175], v[188:191], v[52:55]
	v_mfma_f32_16x16x32_bf16 v[48:51], v[180:183], v[188:191], v[48:51]
	v_mfma_f32_16x16x32_bf16 v[36:39], v[172:175], v[196:199], v[36:39]
	v_mfma_f32_16x16x32_bf16 v[32:35], v[180:183], v[196:199], v[32:35]
	v_mfma_f32_16x16x32_bf16 v[20:23], v[172:175], v[204:207], v[20:23]
	v_mfma_f32_16x16x32_bf16 v[16:19], v[180:183], v[204:207], v[16:19]
	v_mfma_f32_16x16x32_bf16 v[4:7], v[172:175], v[212:215], v[4:7]
	v_mfma_f32_16x16x32_bf16 v[0:3], v[180:183], v[212:215], v[0:3]
	v_mfma_f32_16x16x32_bf16 v[52:55], v[176:179], v[192:195], v[52:55]
	v_mfma_f32_16x16x32_bf16 v[48:51], v[184:187], v[192:195], v[48:51]
	v_mfma_f32_16x16x32_bf16 v[36:39], v[176:179], v[200:203], v[36:39]
	v_mfma_f32_16x16x32_bf16 v[32:35], v[184:187], v[200:203], v[32:35]
	v_mfma_f32_16x16x32_bf16 v[20:23], v[176:179], v[208:211], v[20:23]
	v_mfma_f32_16x16x32_bf16 v[16:19], v[184:187], v[208:211], v[16:19]
	v_mfma_f32_16x16x32_bf16 v[4:7], v[176:179], v[216:219], v[4:7]
	v_mfma_f32_16x16x32_bf16 v[0:3], v[184:187], v[216:219], v[0:3]
	s_setprio 0
	s_barrier
	s_add_i32 s86, 0, 0x18000
	v_add_u32_e32 v159, s86, v152
	s_add_i32 s87, 0, 0x1c000
	ds_read_b128 v[148:151], v159
	ds_read_b128 v[160:163], v159 offset:1024
	ds_read_b128 v[164:167], v159 offset:2048
	ds_read_b128 v[168:171], v159 offset:3072
	v_add_u32_e32 v159, s87, v152
	ds_read_b128 v[172:175], v159
	ds_read_b128 v[176:179], v159 offset:1024
	ds_read_b128 v[180:183], v159 offset:2048
	ds_read_b128 v[184:187], v159 offset:3072
	s_add_u32 s34, s50, 0x40000
	s_addc_u32 s35, s51, 0
	s_mov_b32 m0, s59
	v_lshl_add_u64 v[228:229], s[34:35], 0, v[138:139]
	ds_read_b128 v[188:191], v158 offset:32768
	ds_read_b128 v[192:195], v158 offset:33792
	ds_read_b128 v[196:199], v158 offset:34816
	ds_read_b128 v[200:203], v158 offset:35840
	ds_read_b128 v[204:207], v158 offset:36864
	ds_read_b128 v[208:211], v158 offset:37888
	ds_read_b128 v[212:215], v158 offset:38912
	ds_read_b128 v[216:219], v158 offset:39936
	global_load_lds_dwordx4 v[228:229], off
	s_mov_b32 m0, s62
	v_lshl_add_u64 v[228:229], s[34:35], 0, v[134:135]
	global_load_lds_dwordx4 v[228:229], off
	s_waitcnt vmcnt(8)
	s_waitcnt lgkmcnt(0)
	s_barrier
	s_setprio 1
	s_waitcnt lgkmcnt(0)
	v_mfma_f32_16x16x32_bf16 v[124:127], v[148:151], v[188:191], v[124:127]
	v_mfma_f32_16x16x32_bf16 v[120:123], v[164:167], v[188:191], v[120:123]
	v_mfma_f32_16x16x32_bf16 v[108:111], v[148:151], v[196:199], v[108:111]
	v_mfma_f32_16x16x32_bf16 v[104:107], v[164:167], v[196:199], v[104:107]
	v_mfma_f32_16x16x32_bf16 v[92:95], v[148:151], v[204:207], v[92:95]
	v_mfma_f32_16x16x32_bf16 v[88:91], v[164:167], v[204:207], v[88:91]
	v_mfma_f32_16x16x32_bf16 v[76:79], v[148:151], v[212:215], v[76:79]
	v_mfma_f32_16x16x32_bf16 v[72:75], v[164:167], v[212:215], v[72:75]
	v_mfma_f32_16x16x32_bf16 v[124:127], v[160:163], v[192:195], v[124:127]
	v_mfma_f32_16x16x32_bf16 v[120:123], v[168:171], v[192:195], v[120:123]
	v_mfma_f32_16x16x32_bf16 v[108:111], v[160:163], v[200:203], v[108:111]
	v_mfma_f32_16x16x32_bf16 v[104:107], v[168:171], v[200:203], v[104:107]
	v_mfma_f32_16x16x32_bf16 v[92:95], v[160:163], v[208:211], v[92:95]
	v_mfma_f32_16x16x32_bf16 v[88:91], v[168:171], v[208:211], v[88:91]
	v_mfma_f32_16x16x32_bf16 v[76:79], v[160:163], v[216:219], v[76:79]
	v_mfma_f32_16x16x32_bf16 v[72:75], v[168:171], v[216:219], v[72:75]
	v_mfma_f32_16x16x32_bf16 v[116:119], v[172:175], v[188:191], v[116:119]
	v_mfma_f32_16x16x32_bf16 v[112:115], v[180:183], v[188:191], v[112:115]
	v_mfma_f32_16x16x32_bf16 v[100:103], v[172:175], v[196:199], v[100:103]
	v_mfma_f32_16x16x32_bf16 v[96:99], v[180:183], v[196:199], v[96:99]
	v_mfma_f32_16x16x32_bf16 v[84:87], v[172:175], v[204:207], v[84:87]
	v_mfma_f32_16x16x32_bf16 v[80:83], v[180:183], v[204:207], v[80:83]
	v_mfma_f32_16x16x32_bf16 v[68:71], v[172:175], v[212:215], v[68:71]
	v_mfma_f32_16x16x32_bf16 v[64:67], v[180:183], v[212:215], v[64:67]
	v_mfma_f32_16x16x32_bf16 v[116:119], v[176:179], v[192:195], v[116:119]
	v_mfma_f32_16x16x32_bf16 v[112:115], v[184:187], v[192:195], v[112:115]
	v_mfma_f32_16x16x32_bf16 v[100:103], v[176:179], v[200:203], v[100:103]
	v_mfma_f32_16x16x32_bf16 v[96:99], v[184:187], v[200:203], v[96:99]
	v_mfma_f32_16x16x32_bf16 v[84:87], v[176:179], v[208:211], v[84:87]
	v_mfma_f32_16x16x32_bf16 v[80:83], v[184:187], v[208:211], v[80:83]
	v_mfma_f32_16x16x32_bf16 v[68:71], v[176:179], v[216:219], v[68:71]
	v_mfma_f32_16x16x32_bf16 v[64:67], v[184:187], v[216:219], v[64:67]
	s_setprio 0
	s_barrier
	s_add_i32 s34, s86, s54
	v_lshl_add_u64 v[220:221], v[220:221], 0, s[6:7]
	s_mov_b32 m0, s34
	ds_read_b128 v[188:191], v158 offset:49152
	ds_read_b128 v[192:195], v158 offset:50176
	ds_read_b128 v[196:199], v158 offset:51200
	ds_read_b128 v[200:203], v158 offset:52224
	ds_read_b128 v[204:207], v158 offset:53248
	ds_read_b128 v[208:211], v158 offset:54272
	ds_read_b128 v[212:215], v158 offset:55296
	ds_read_b128 v[216:219], v158 offset:56320
	global_load_lds_dwordx4 v[220:221], off
	s_add_i32 m0, s34, 0x2000
	s_add_u32 s34, s48, 0x40080
	v_lshl_add_u64 v[220:221], v[222:223], 0, s[6:7]
	s_addc_u32 s35, s49, 0
	s_add_i32 s48, s87, s54
	global_load_lds_dwordx4 v[220:221], off
	s_mov_b32 m0, s48
	v_lshl_add_u64 v[220:221], s[34:35], 0, v[136:137]
	global_load_lds_dwordx4 v[220:221], off
	s_add_i32 m0, s48, 0x2000
	v_lshl_add_u64 v[220:221], s[34:35], 0, v[132:133]
	global_load_lds_dwordx4 v[220:221], off
	s_mov_b32 m0, s63
	v_lshl_add_u64 v[220:221], v[224:225], 0, s[6:7]
	global_load_lds_dwordx4 v[220:221], off
	s_mov_b32 m0, s64
	v_lshl_add_u64 v[220:221], v[226:227], 0, s[6:7]
	global_load_lds_dwordx4 v[220:221], off
	s_waitcnt vmcnt(8)
	s_waitcnt lgkmcnt(0)
	s_barrier
	s_setprio 1
	s_waitcnt lgkmcnt(0)
	v_mfma_f32_16x16x32_bf16 v[60:63], v[148:151], v[188:191], v[60:63]
	v_mfma_f32_16x16x32_bf16 v[56:59], v[164:167], v[188:191], v[56:59]
	v_mfma_f32_16x16x32_bf16 v[44:47], v[148:151], v[196:199], v[44:47]
	v_mfma_f32_16x16x32_bf16 v[40:43], v[164:167], v[196:199], v[40:43]
	v_mfma_f32_16x16x32_bf16 v[28:31], v[148:151], v[204:207], v[28:31]
	v_mfma_f32_16x16x32_bf16 v[24:27], v[164:167], v[204:207], v[24:27]
	v_mfma_f32_16x16x32_bf16 v[12:15], v[148:151], v[212:215], v[12:15]
	v_mfma_f32_16x16x32_bf16 v[8:11], v[164:167], v[212:215], v[8:11]
	v_mfma_f32_16x16x32_bf16 v[60:63], v[160:163], v[192:195], v[60:63]
	v_mfma_f32_16x16x32_bf16 v[56:59], v[168:171], v[192:195], v[56:59]
	v_mfma_f32_16x16x32_bf16 v[44:47], v[160:163], v[200:203], v[44:47]
	v_mfma_f32_16x16x32_bf16 v[40:43], v[168:171], v[200:203], v[40:43]
	v_mfma_f32_16x16x32_bf16 v[28:31], v[160:163], v[208:211], v[28:31]
	v_mfma_f32_16x16x32_bf16 v[24:27], v[168:171], v[208:211], v[24:27]
	v_mfma_f32_16x16x32_bf16 v[12:15], v[160:163], v[216:219], v[12:15]
	v_mfma_f32_16x16x32_bf16 v[8:11], v[168:171], v[216:219], v[8:11]
	v_mfma_f32_16x16x32_bf16 v[52:55], v[172:175], v[188:191], v[52:55]
	v_mfma_f32_16x16x32_bf16 v[48:51], v[180:183], v[188:191], v[48:51]
	v_mfma_f32_16x16x32_bf16 v[36:39], v[172:175], v[196:199], v[36:39]
	v_mfma_f32_16x16x32_bf16 v[32:35], v[180:183], v[196:199], v[32:35]
	v_mfma_f32_16x16x32_bf16 v[20:23], v[172:175], v[204:207], v[20:23]
	v_mfma_f32_16x16x32_bf16 v[16:19], v[180:183], v[204:207], v[16:19]
	v_mfma_f32_16x16x32_bf16 v[4:7], v[172:175], v[212:215], v[4:7]
	v_mfma_f32_16x16x32_bf16 v[0:3], v[180:183], v[212:215], v[0:3]
	v_mfma_f32_16x16x32_bf16 v[52:55], v[176:179], v[192:195], v[52:55]
	v_mfma_f32_16x16x32_bf16 v[48:51], v[184:187], v[192:195], v[48:51]
	v_mfma_f32_16x16x32_bf16 v[36:39], v[176:179], v[200:203], v[36:39]
	v_mfma_f32_16x16x32_bf16 v[32:35], v[184:187], v[200:203], v[32:35]
	v_mfma_f32_16x16x32_bf16 v[20:23], v[176:179], v[208:211], v[20:23]
	v_mfma_f32_16x16x32_bf16 v[16:19], v[184:187], v[208:211], v[16:19]
	v_mfma_f32_16x16x32_bf16 v[4:7], v[176:179], v[216:219], v[4:7]
	v_mfma_f32_16x16x32_bf16 v[0:3], v[184:187], v[216:219], v[0:3]
	s_setprio 0
	s_cmp_eq_u32 s85, s98
	s_cbranch_scc1 .Lmy_nobar_5
	s_barrier

.Lmy_nobar2_6:
	ds_read_b128 v[148:151], v154
	ds_read_b128 v[160:163], v154 offset:1024
	ds_read_b128 v[164:167], v154 offset:2048
	ds_read_b128 v[168:171], v154 offset:3072
	ds_read_b128 v[172:175], v155
	ds_read_b128 v[176:179], v155 offset:1024
	ds_read_b128 v[180:183], v155 offset:2048
	ds_read_b128 v[184:187], v155 offset:3072
	s_add_u32 s34, s40, 0xfff50080
	s_addc_u32 s35, s41, -1
	s_cmp_eq_u32 s81, 40
	s_cselect_b32 s49, s1, s35
	s_cselect_b32 s48, s0, s34
	s_cselect_b32 s43, s29, s77
	s_cselect_b32 s42, s28, s13
	v_lshl_add_u64 v[220:221], s[40:41], 0, v[140:141]
	s_add_i32 m0, s52, 0xc000
	ds_read_b128 v[188:191], v157
	ds_read_b128 v[192:195], v157 offset:1024
	ds_read_b128 v[196:199], v157 offset:2048
	ds_read_b128 v[200:203], v157 offset:3072
	ds_read_b128 v[204:207], v157 offset:4096
	ds_read_b128 v[208:211], v157 offset:5120
	ds_read_b128 v[212:215], v157 offset:6144
	ds_read_b128 v[216:219], v157 offset:7168
	global_load_lds_dwordx4 v[220:221], off
	s_add_i32 m0, s52, 0xe000
	v_lshl_add_u64 v[220:221], s[40:41], 0, v[142:143]
	global_load_lds_dwordx4 v[220:221], off
	s_waitcnt vmcnt(8)
	s_waitcnt lgkmcnt(0)
	s_barrier
	s_setprio 1
	s_waitcnt lgkmcnt(0)
	v_mfma_f32_16x16x32_bf16 v[124:127], v[148:151], v[188:191], 0
	v_mfma_f32_16x16x32_bf16 v[120:123], v[164:167], v[188:191], 0
	v_mfma_f32_16x16x32_bf16 v[108:111], v[148:151], v[196:199], 0
	v_mfma_f32_16x16x32_bf16 v[104:107], v[164:167], v[196:199], 0
	v_mfma_f32_16x16x32_bf16 v[92:95], v[148:151], v[204:207], 0
	v_mfma_f32_16x16x32_bf16 v[88:91], v[164:167], v[204:207], 0
	v_mfma_f32_16x16x32_bf16 v[76:79], v[148:151], v[212:215], 0
	v_mfma_f32_16x16x32_bf16 v[72:75], v[164:167], v[212:215], 0
	v_mfma_f32_16x16x32_bf16 v[124:127], v[160:163], v[192:195], v[124:127]
	v_mfma_f32_16x16x32_bf16 v[120:123], v[168:171], v[192:195], v[120:123]
	v_mfma_f32_16x16x32_bf16 v[108:111], v[160:163], v[200:203], v[108:111]
	v_mfma_f32_16x16x32_bf16 v[104:107], v[168:171], v[200:203], v[104:107]
	v_mfma_f32_16x16x32_bf16 v[92:95], v[160:163], v[208:211], v[92:95]
	v_mfma_f32_16x16x32_bf16 v[88:91], v[168:171], v[208:211], v[88:91]
	v_mfma_f32_16x16x32_bf16 v[76:79], v[160:163], v[216:219], v[76:79]
	v_mfma_f32_16x16x32_bf16 v[72:75], v[168:171], v[216:219], v[72:75]
	v_mfma_f32_16x16x32_bf16 v[116:119], v[172:175], v[188:191], 0
	v_mfma_f32_16x16x32_bf16 v[112:115], v[180:183], v[188:191], 0
	v_mfma_f32_16x16x32_bf16 v[100:103], v[172:175], v[196:199], 0
	v_mfma_f32_16x16x32_bf16 v[96:99], v[180:183], v[196:199], 0
	v_mfma_f32_16x16x32_bf16 v[84:87], v[172:175], v[204:207], 0
	v_mfma_f32_16x16x32_bf16 v[80:83], v[180:183], v[204:207], 0
	v_mfma_f32_16x16x32_bf16 v[68:71], v[172:175], v[212:215], 0
	v_mfma_f32_16x16x32_bf16 v[64:67], v[180:183], v[212:215], 0
	v_mfma_f32_16x16x32_bf16 v[116:119], v[176:179], v[192:195], v[116:119]
	v_mfma_f32_16x16x32_bf16 v[112:115], v[184:187], v[192:195], v[112:115]
	v_mfma_f32_16x16x32_bf16 v[100:103], v[176:179], v[200:203], v[100:103]
	v_mfma_f32_16x16x32_bf16 v[96:99], v[184:187], v[200:203], v[96:99]
	v_mfma_f32_16x16x32_bf16 v[84:87], v[176:179], v[208:211], v[84:87]
	v_mfma_f32_16x16x32_bf16 v[80:83], v[184:187], v[208:211], v[80:83]
	v_mfma_f32_16x16x32_bf16 v[68:71], v[176:179], v[216:219], v[68:71]
	v_mfma_f32_16x16x32_bf16 v[64:67], v[184:187], v[216:219], v[64:67]
	s_setprio 0
	s_barrier
	s_add_i32 s34, s64, s51
	v_lshl_add_u64 v[220:221], s[42:43], 0, v[134:135]
	s_mov_b32 m0, s34
	ds_read_b128 v[188:191], v157 offset:16384
	ds_read_b128 v[192:195], v157 offset:17408
	ds_read_b128 v[196:199], v157 offset:18432
	ds_read_b128 v[200:203], v157 offset:19456
	ds_read_b128 v[204:207], v157 offset:20480
	ds_read_b128 v[208:211], v157 offset:21504
	ds_read_b128 v[212:215], v157 offset:22528
	ds_read_b128 v[216:219], v157 offset:23552
	global_load_lds_dwordx4 v[220:221], off
	s_add_i32 m0, s34, 0x2000
	s_add_u32 s34, s42, 0xb0000
	v_lshl_add_u64 v[222:223], s[42:43], 0, v[138:139]
	s_addc_u32 s35, s43, 0
	s_add_i32 s82, s65, s51
	global_load_lds_dwordx4 v[222:223], off
	v_lshl_add_u64 v[224:225], s[34:35], 0, v[134:135]
	s_mov_b32 m0, s82
	v_lshl_add_u64 v[226:227], s[48:49], 0, v[136:137]
	global_load_lds_dwordx4 v[224:225], off
	s_add_i32 m0, s82, 0x2000
	v_lshl_add_u64 v[224:225], s[34:35], 0, v[138:139]
	global_load_lds_dwordx4 v[224:225], off
	s_mov_b32 m0, s52
	v_lshl_add_u64 v[224:225], s[48:49], 0, v[132:133]
	global_load_lds_dwordx4 v[224:225], off
	s_mov_b32 m0, s53
	s_nop 0
	global_load_lds_dwordx4 v[226:227], off
	s_waitcnt vmcnt(8)
	s_waitcnt lgkmcnt(0)
	s_barrier
	s_setprio 1
	s_waitcnt lgkmcnt(0)
	v_mfma_f32_16x16x32_bf16 v[60:63], v[148:151], v[188:191], 0
	v_mfma_f32_16x16x32_bf16 v[56:59], v[164:167], v[188:191], 0
	v_mfma_f32_16x16x32_bf16 v[44:47], v[148:151], v[196:199], 0
	v_mfma_f32_16x16x32_bf16 v[40:43], v[164:167], v[196:199], 0
	v_mfma_f32_16x16x32_bf16 v[28:31], v[148:151], v[204:207], 0
	v_mfma_f32_16x16x32_bf16 v[24:27], v[164:167], v[204:207], 0
	v_mfma_f32_16x16x32_bf16 v[12:15], v[148:151], v[212:215], 0
	v_mfma_f32_16x16x32_bf16 v[8:11], v[164:167], v[212:215], 0
	v_mfma_f32_16x16x32_bf16 v[60:63], v[160:163], v[192:195], v[60:63]
	v_mfma_f32_16x16x32_bf16 v[56:59], v[168:171], v[192:195], v[56:59]
	v_mfma_f32_16x16x32_bf16 v[44:47], v[160:163], v[200:203], v[44:47]
	v_mfma_f32_16x16x32_bf16 v[40:43], v[168:171], v[200:203], v[40:43]
	v_mfma_f32_16x16x32_bf16 v[28:31], v[160:163], v[208:211], v[28:31]
	v_mfma_f32_16x16x32_bf16 v[24:27], v[168:171], v[208:211], v[24:27]
	v_mfma_f32_16x16x32_bf16 v[12:15], v[160:163], v[216:219], v[12:15]
	v_mfma_f32_16x16x32_bf16 v[8:11], v[168:171], v[216:219], v[8:11]
	v_mfma_f32_16x16x32_bf16 v[52:55], v[172:175], v[188:191], 0
	v_mfma_f32_16x16x32_bf16 v[48:51], v[180:183], v[188:191], 0
	v_mfma_f32_16x16x32_bf16 v[36:39], v[172:175], v[196:199], 0
	v_mfma_f32_16x16x32_bf16 v[32:35], v[180:183], v[196:199], 0
	v_mfma_f32_16x16x32_bf16 v[20:23], v[172:175], v[204:207], 0
	v_mfma_f32_16x16x32_bf16 v[16:19], v[180:183], v[204:207], 0
	v_mfma_f32_16x16x32_bf16 v[4:7], v[172:175], v[212:215], 0
	v_mfma_f32_16x16x32_bf16 v[0:3], v[180:183], v[212:215], 0
	v_mfma_f32_16x16x32_bf16 v[52:55], v[176:179], v[192:195], v[52:55]
	v_mfma_f32_16x16x32_bf16 v[48:51], v[184:187], v[192:195], v[48:51]
	v_mfma_f32_16x16x32_bf16 v[36:39], v[176:179], v[200:203], v[36:39]
	v_mfma_f32_16x16x32_bf16 v[32:35], v[184:187], v[200:203], v[32:35]
	v_mfma_f32_16x16x32_bf16 v[20:23], v[176:179], v[208:211], v[20:23]
	v_mfma_f32_16x16x32_bf16 v[16:19], v[184:187], v[208:211], v[16:19]
	v_mfma_f32_16x16x32_bf16 v[4:7], v[176:179], v[216:219], v[4:7]
	v_mfma_f32_16x16x32_bf16 v[0:3], v[184:187], v[216:219], v[0:3]
	s_setprio 0
	s_barrier
	s_add_i32 s82, 0, 0x18000
	v_add_u32_e32 v159, s82, v152
	s_add_i32 s83, 0, 0x1c000
	ds_read_b128 v[148:151], v159
	ds_read_b128 v[160:163], v159 offset:1024
	ds_read_b128 v[164:167], v159 offset:2048
	ds_read_b128 v[168:171], v159 offset:3072
	v_add_u32_e32 v159, s83, v152
	ds_read_b128 v[172:175], v159
	ds_read_b128 v[176:179], v159 offset:1024
	ds_read_b128 v[180:183], v159 offset:2048
	ds_read_b128 v[184:187], v159 offset:3072
	s_add_u32 s34, s48, 0xb0000
	s_addc_u32 s35, s49, 0
	s_mov_b32 m0, s54
	v_lshl_add_u64 v[228:229], s[34:35], 0, v[132:133]
	ds_read_b128 v[188:191], v157 offset:32768
	ds_read_b128 v[192:195], v157 offset:33792
	ds_read_b128 v[196:199], v157 offset:34816
	ds_read_b128 v[200:203], v157 offset:35840
	ds_read_b128 v[204:207], v157 offset:36864
	ds_read_b128 v[208:211], v157 offset:37888
	ds_read_b128 v[212:215], v157 offset:38912
	ds_read_b128 v[216:219], v157 offset:39936
	global_load_lds_dwordx4 v[228:229], off
	s_mov_b32 m0, s55
	v_lshl_add_u64 v[228:229], s[34:35], 0, v[136:137]
	global_load_lds_dwordx4 v[228:229], off
	s_waitcnt vmcnt(8)
	s_waitcnt lgkmcnt(0)
	s_barrier
	s_setprio 1
	s_waitcnt lgkmcnt(0)
	v_mfma_f32_16x16x32_bf16 v[124:127], v[148:151], v[188:191], v[124:127]
	v_mfma_f32_16x16x32_bf16 v[120:123], v[164:167], v[188:191], v[120:123]
	v_mfma_f32_16x16x32_bf16 v[108:111], v[148:151], v[196:199], v[108:111]
	v_mfma_f32_16x16x32_bf16 v[104:107], v[164:167], v[196:199], v[104:107]
	v_mfma_f32_16x16x32_bf16 v[92:95], v[148:151], v[204:207], v[92:95]
	v_mfma_f32_16x16x32_bf16 v[88:91], v[164:167], v[204:207], v[88:91]
	v_mfma_f32_16x16x32_bf16 v[76:79], v[148:151], v[212:215], v[76:79]
	v_mfma_f32_16x16x32_bf16 v[72:75], v[164:167], v[212:215], v[72:75]
	v_mfma_f32_16x16x32_bf16 v[124:127], v[160:163], v[192:195], v[124:127]
	v_mfma_f32_16x16x32_bf16 v[120:123], v[168:171], v[192:195], v[120:123]
	v_mfma_f32_16x16x32_bf16 v[108:111], v[160:163], v[200:203], v[108:111]
	v_mfma_f32_16x16x32_bf16 v[104:107], v[168:171], v[200:203], v[104:107]
	v_mfma_f32_16x16x32_bf16 v[92:95], v[160:163], v[208:211], v[92:95]
	v_mfma_f32_16x16x32_bf16 v[88:91], v[168:171], v[208:211], v[88:91]
	v_mfma_f32_16x16x32_bf16 v[76:79], v[160:163], v[216:219], v[76:79]
	v_mfma_f32_16x16x32_bf16 v[72:75], v[168:171], v[216:219], v[72:75]
	v_mfma_f32_16x16x32_bf16 v[116:119], v[172:175], v[188:191], v[116:119]
	v_mfma_f32_16x16x32_bf16 v[112:115], v[180:183], v[188:191], v[112:115]
	v_mfma_f32_16x16x32_bf16 v[100:103], v[172:175], v[196:199], v[100:103]
	v_mfma_f32_16x16x32_bf16 v[96:99], v[180:183], v[196:199], v[96:99]
	v_mfma_f32_16x16x32_bf16 v[84:87], v[172:175], v[204:207], v[84:87]
	v_mfma_f32_16x16x32_bf16 v[80:83], v[180:183], v[204:207], v[80:83]
	v_mfma_f32_16x16x32_bf16 v[68:71], v[172:175], v[212:215], v[68:71]
	v_mfma_f32_16x16x32_bf16 v[64:67], v[180:183], v[212:215], v[64:67]
	v_mfma_f32_16x16x32_bf16 v[116:119], v[176:179], v[192:195], v[116:119]
	v_mfma_f32_16x16x32_bf16 v[112:115], v[184:187], v[192:195], v[112:115]
	v_mfma_f32_16x16x32_bf16 v[100:103], v[176:179], v[200:203], v[100:103]
	v_mfma_f32_16x16x32_bf16 v[96:99], v[184:187], v[200:203], v[96:99]
	v_mfma_f32_16x16x32_bf16 v[84:87], v[176:179], v[208:211], v[84:87]
	v_mfma_f32_16x16x32_bf16 v[80:83], v[184:187], v[208:211], v[80:83]
	v_mfma_f32_16x16x32_bf16 v[68:71], v[176:179], v[216:219], v[68:71]
	v_mfma_f32_16x16x32_bf16 v[64:67], v[184:187], v[216:219], v[64:67]
	s_setprio 0
	s_barrier
	s_add_i32 s34, s82, s51
	v_lshl_add_u64 v[220:221], v[220:221], 0, s[22:23]
	s_mov_b32 m0, s34
	ds_read_b128 v[188:191], v157 offset:49152
	ds_read_b128 v[192:195], v157 offset:50176
	ds_read_b128 v[196:199], v157 offset:51200
	ds_read_b128 v[200:203], v157 offset:52224
	ds_read_b128 v[204:207], v157 offset:53248
	ds_read_b128 v[208:211], v157 offset:54272
	ds_read_b128 v[212:215], v157 offset:55296
	ds_read_b128 v[216:219], v157 offset:56320
	global_load_lds_dwordx4 v[220:221], off
	s_add_i32 m0, s34, 0x2000
	s_add_u32 s34, s42, 0xb0080
	v_lshl_add_u64 v[220:221], v[222:223], 0, s[22:23]
	s_addc_u32 s35, s43, 0
	s_add_i32 s42, s83, s51
	global_load_lds_dwordx4 v[220:221], off
	s_mov_b32 m0, s42
	v_lshl_add_u64 v[220:221], s[34:35], 0, v[134:135]
	global_load_lds_dwordx4 v[220:221], off
	s_add_i32 m0, s42, 0x2000
	v_lshl_add_u64 v[220:221], s[34:35], 0, v[138:139]
	global_load_lds_dwordx4 v[220:221], off
	s_mov_b32 m0, s57
	v_lshl_add_u64 v[220:221], v[224:225], 0, s[22:23]
	global_load_lds_dwordx4 v[220:221], off
	s_mov_b32 m0, s58
	v_lshl_add_u64 v[220:221], v[226:227], 0, s[22:23]
	global_load_lds_dwordx4 v[220:221], off
	s_waitcnt vmcnt(8)
	s_waitcnt lgkmcnt(0)
	s_barrier
	s_setprio 1
	s_waitcnt lgkmcnt(0)
	v_mfma_f32_16x16x32_bf16 v[60:63], v[148:151], v[188:191], v[60:63]
	v_mfma_f32_16x16x32_bf16 v[56:59], v[164:167], v[188:191], v[56:59]
	v_mfma_f32_16x16x32_bf16 v[44:47], v[148:151], v[196:199], v[44:47]
	v_mfma_f32_16x16x32_bf16 v[40:43], v[164:167], v[196:199], v[40:43]
	v_mfma_f32_16x16x32_bf16 v[28:31], v[148:151], v[204:207], v[28:31]
	v_mfma_f32_16x16x32_bf16 v[24:27], v[164:167], v[204:207], v[24:27]
	v_mfma_f32_16x16x32_bf16 v[12:15], v[148:151], v[212:215], v[12:15]
	v_mfma_f32_16x16x32_bf16 v[8:11], v[164:167], v[212:215], v[8:11]
	v_mfma_f32_16x16x32_bf16 v[60:63], v[160:163], v[192:195], v[60:63]
	v_mfma_f32_16x16x32_bf16 v[56:59], v[168:171], v[192:195], v[56:59]
	v_mfma_f32_16x16x32_bf16 v[44:47], v[160:163], v[200:203], v[44:47]
	v_mfma_f32_16x16x32_bf16 v[40:43], v[168:171], v[200:203], v[40:43]
	v_mfma_f32_16x16x32_bf16 v[28:31], v[160:163], v[208:211], v[28:31]
	v_mfma_f32_16x16x32_bf16 v[24:27], v[168:171], v[208:211], v[24:27]
	v_mfma_f32_16x16x32_bf16 v[12:15], v[160:163], v[216:219], v[12:15]
	v_mfma_f32_16x16x32_bf16 v[8:11], v[168:171], v[216:219], v[8:11]
	v_mfma_f32_16x16x32_bf16 v[52:55], v[172:175], v[188:191], v[52:55]
	v_mfma_f32_16x16x32_bf16 v[48:51], v[180:183], v[188:191], v[48:51]
	v_mfma_f32_16x16x32_bf16 v[36:39], v[172:175], v[196:199], v[36:39]
	v_mfma_f32_16x16x32_bf16 v[32:35], v[180:183], v[196:199], v[32:35]
	v_mfma_f32_16x16x32_bf16 v[20:23], v[172:175], v[204:207], v[20:23]
	v_mfma_f32_16x16x32_bf16 v[16:19], v[180:183], v[204:207], v[16:19]
	v_mfma_f32_16x16x32_bf16 v[4:7], v[172:175], v[212:215], v[4:7]
	v_mfma_f32_16x16x32_bf16 v[0:3], v[180:183], v[212:215], v[0:3]
	v_mfma_f32_16x16x32_bf16 v[52:55], v[176:179], v[192:195], v[52:55]
	v_mfma_f32_16x16x32_bf16 v[48:51], v[184:187], v[192:195], v[48:51]
	v_mfma_f32_16x16x32_bf16 v[36:39], v[176:179], v[200:203], v[36:39]
	v_mfma_f32_16x16x32_bf16 v[32:35], v[184:187], v[200:203], v[32:35]
	v_mfma_f32_16x16x32_bf16 v[20:23], v[176:179], v[208:211], v[20:23]
	v_mfma_f32_16x16x32_bf16 v[16:19], v[184:187], v[208:211], v[16:19]
	v_mfma_f32_16x16x32_bf16 v[4:7], v[176:179], v[216:219], v[4:7]
	v_mfma_f32_16x16x32_bf16 v[0:3], v[184:187], v[216:219], v[0:3]
	s_setprio 0
	s_barrier
	s_add_i32 s81, s81, 2
	s_add_u32 s40, s40, 0x100
	s_addc_u32 s41, s41, 0
	s_add_u32 s13, s13, 0x100
	s_addc_u32 s77, s77, 0
.LBB0_562:
	ds_read_b128 v[148:151], v154
	ds_read_b128 v[160:163], v154 offset:1024
	ds_read_b128 v[164:167], v154 offset:2048
	ds_read_b128 v[168:171], v154 offset:3072
	ds_read_b128 v[172:175], v155
	ds_read_b128 v[176:179], v155 offset:1024
	ds_read_b128 v[180:183], v155 offset:2048
	ds_read_b128 v[184:187], v155 offset:3072
	s_add_u32 s34, s40, 0xfff50080
	s_addc_u32 s35, s41, -1
	s_cmp_eq_u32 s81, 40
	s_cselect_b32 s49, s1, s35
	s_cselect_b32 s48, s0, s34
	s_cselect_b32 s43, s29, s77
	s_cselect_b32 s42, s28, s13
	v_lshl_add_u64 v[220:221], s[40:41], 0, v[140:141]
	s_add_i32 m0, s52, 0xc000
	ds_read_b128 v[188:191], v157
	ds_read_b128 v[192:195], v157 offset:1024
	ds_read_b128 v[196:199], v157 offset:2048
	ds_read_b128 v[200:203], v157 offset:3072
	ds_read_b128 v[204:207], v157 offset:4096
	ds_read_b128 v[208:211], v157 offset:5120
	ds_read_b128 v[212:215], v157 offset:6144
	ds_read_b128 v[216:219], v157 offset:7168
	global_load_lds_dwordx4 v[220:221], off
	s_add_i32 m0, s52, 0xe000
	v_lshl_add_u64 v[220:221], s[40:41], 0, v[142:143]
	global_load_lds_dwordx4 v[220:221], off
	s_waitcnt vmcnt(8)
	s_waitcnt lgkmcnt(0)
	s_barrier
	s_setprio 1
	s_waitcnt lgkmcnt(0)
	v_mfma_f32_16x16x32_bf16 v[124:127], v[148:151], v[188:191], v[124:127]
	v_mfma_f32_16x16x32_bf16 v[120:123], v[164:167], v[188:191], v[120:123]
	v_mfma_f32_16x16x32_bf16 v[108:111], v[148:151], v[196:199], v[108:111]
	v_mfma_f32_16x16x32_bf16 v[104:107], v[164:167], v[196:199], v[104:107]
	v_mfma_f32_16x16x32_bf16 v[92:95], v[148:151], v[204:207], v[92:95]
	v_mfma_f32_16x16x32_bf16 v[88:91], v[164:167], v[204:207], v[88:91]
	v_mfma_f32_16x16x32_bf16 v[76:79], v[148:151], v[212:215], v[76:79]
	v_mfma_f32_16x16x32_bf16 v[72:75], v[164:167], v[212:215], v[72:75]
	v_mfma_f32_16x16x32_bf16 v[124:127], v[160:163], v[192:195], v[124:127]
	v_mfma_f32_16x16x32_bf16 v[120:123], v[168:171], v[192:195], v[120:123]
	v_mfma_f32_16x16x32_bf16 v[108:111], v[160:163], v[200:203], v[108:111]
	v_mfma_f32_16x16x32_bf16 v[104:107], v[168:171], v[200:203], v[104:107]
	v_mfma_f32_16x16x32_bf16 v[92:95], v[160:163], v[208:211], v[92:95]
	v_mfma_f32_16x16x32_bf16 v[88:91], v[168:171], v[208:211], v[88:91]
	v_mfma_f32_16x16x32_bf16 v[76:79], v[160:163], v[216:219], v[76:79]
	v_mfma_f32_16x16x32_bf16 v[72:75], v[168:171], v[216:219], v[72:75]
	v_mfma_f32_16x16x32_bf16 v[116:119], v[172:175], v[188:191], v[116:119]
	v_mfma_f32_16x16x32_bf16 v[112:115], v[180:183], v[188:191], v[112:115]
	v_mfma_f32_16x16x32_bf16 v[100:103], v[172:175], v[196:199], v[100:103]
	v_mfma_f32_16x16x32_bf16 v[96:99], v[180:183], v[196:199], v[96:99]
	v_mfma_f32_16x16x32_bf16 v[84:87], v[172:175], v[204:207], v[84:87]
	v_mfma_f32_16x16x32_bf16 v[80:83], v[180:183], v[204:207], v[80:83]
	v_mfma_f32_16x16x32_bf16 v[68:71], v[172:175], v[212:215], v[68:71]
	v_mfma_f32_16x16x32_bf16 v[64:67], v[180:183], v[212:215], v[64:67]
	v_mfma_f32_16x16x32_bf16 v[116:119], v[176:179], v[192:195], v[116:119]
	v_mfma_f32_16x16x32_bf16 v[112:115], v[184:187], v[192:195], v[112:115]
	v_mfma_f32_16x16x32_bf16 v[100:103], v[176:179], v[200:203], v[100:103]
	v_mfma_f32_16x16x32_bf16 v[96:99], v[184:187], v[200:203], v[96:99]
	v_mfma_f32_16x16x32_bf16 v[84:87], v[176:179], v[208:211], v[84:87]
	v_mfma_f32_16x16x32_bf16 v[80:83], v[184:187], v[208:211], v[80:83]
	v_mfma_f32_16x16x32_bf16 v[68:71], v[176:179], v[216:219], v[68:71]
	v_mfma_f32_16x16x32_bf16 v[64:67], v[184:187], v[216:219], v[64:67]
	s_setprio 0
	s_barrier
	s_add_i32 s34, s64, s51
	v_lshl_add_u64 v[220:221], s[42:43], 0, v[134:135]
	s_mov_b32 m0, s34
	ds_read_b128 v[188:191], v157 offset:16384
	ds_read_b128 v[192:195], v157 offset:17408
	ds_read_b128 v[196:199], v157 offset:18432
	ds_read_b128 v[200:203], v157 offset:19456
	ds_read_b128 v[204:207], v157 offset:20480
	ds_read_b128 v[208:211], v157 offset:21504
	ds_read_b128 v[212:215], v157 offset:22528
	ds_read_b128 v[216:219], v157 offset:23552
	global_load_lds_dwordx4 v[220:221], off
	s_add_i32 m0, s34, 0x2000
	s_add_u32 s34, s42, 0xb0000
	v_lshl_add_u64 v[222:223], s[42:43], 0, v[138:139]
	s_addc_u32 s35, s43, 0
	s_add_i32 s82, s65, s51
	global_load_lds_dwordx4 v[222:223], off
	v_lshl_add_u64 v[224:225], s[34:35], 0, v[134:135]
	s_mov_b32 m0, s82
	v_lshl_add_u64 v[226:227], s[48:49], 0, v[136:137]
	global_load_lds_dwordx4 v[224:225], off
	s_add_i32 m0, s82, 0x2000
	v_lshl_add_u64 v[224:225], s[34:35], 0, v[138:139]
	global_load_lds_dwordx4 v[224:225], off
	s_mov_b32 m0, s52
	v_lshl_add_u64 v[224:225], s[48:49], 0, v[132:133]
	global_load_lds_dwordx4 v[224:225], off
	s_mov_b32 m0, s53
	s_nop 0
	global_load_lds_dwordx4 v[226:227], off
	s_waitcnt vmcnt(8)
	s_waitcnt lgkmcnt(0)
	s_barrier
	s_setprio 1
	s_waitcnt lgkmcnt(0)
	v_mfma_f32_16x16x32_bf16 v[60:63], v[148:151], v[188:191], v[60:63]
	v_mfma_f32_16x16x32_bf16 v[56:59], v[164:167], v[188:191], v[56:59]
	v_mfma_f32_16x16x32_bf16 v[44:47], v[148:151], v[196:199], v[44:47]
	v_mfma_f32_16x16x32_bf16 v[40:43], v[164:167], v[196:199], v[40:43]
	v_mfma_f32_16x16x32_bf16 v[28:31], v[148:151], v[204:207], v[28:31]
	v_mfma_f32_16x16x32_bf16 v[24:27], v[164:167], v[204:207], v[24:27]
	v_mfma_f32_16x16x32_bf16 v[12:15], v[148:151], v[212:215], v[12:15]
	v_mfma_f32_16x16x32_bf16 v[8:11], v[164:167], v[212:215], v[8:11]
	v_mfma_f32_16x16x32_bf16 v[60:63], v[160:163], v[192:195], v[60:63]
	v_mfma_f32_16x16x32_bf16 v[56:59], v[168:171], v[192:195], v[56:59]
	v_mfma_f32_16x16x32_bf16 v[44:47], v[160:163], v[200:203], v[44:47]
	v_mfma_f32_16x16x32_bf16 v[40:43], v[168:171], v[200:203], v[40:43]
	v_mfma_f32_16x16x32_bf16 v[28:31], v[160:163], v[208:211], v[28:31]
	v_mfma_f32_16x16x32_bf16 v[24:27], v[168:171], v[208:211], v[24:27]
	v_mfma_f32_16x16x32_bf16 v[12:15], v[160:163], v[216:219], v[12:15]
	v_mfma_f32_16x16x32_bf16 v[8:11], v[168:171], v[216:219], v[8:11]
	v_mfma_f32_16x16x32_bf16 v[52:55], v[172:175], v[188:191], v[52:55]
	v_mfma_f32_16x16x32_bf16 v[48:51], v[180:183], v[188:191], v[48:51]
	v_mfma_f32_16x16x32_bf16 v[36:39], v[172:175], v[196:199], v[36:39]
	v_mfma_f32_16x16x32_bf16 v[32:35], v[180:183], v[196:199], v[32:35]
	v_mfma_f32_16x16x32_bf16 v[20:23], v[172:175], v[204:207], v[20:23]
	v_mfma_f32_16x16x32_bf16 v[16:19], v[180:183], v[204:207], v[16:19]
	v_mfma_f32_16x16x32_bf16 v[4:7], v[172:175], v[212:215], v[4:7]
	v_mfma_f32_16x16x32_bf16 v[0:3], v[180:183], v[212:215], v[0:3]
	v_mfma_f32_16x16x32_bf16 v[52:55], v[176:179], v[192:195], v[52:55]
	v_mfma_f32_16x16x32_bf16 v[48:51], v[184:187], v[192:195], v[48:51]
	v_mfma_f32_16x16x32_bf16 v[36:39], v[176:179], v[200:203], v[36:39]
	v_mfma_f32_16x16x32_bf16 v[32:35], v[184:187], v[200:203], v[32:35]
	v_mfma_f32_16x16x32_bf16 v[20:23], v[176:179], v[208:211], v[20:23]
	v_mfma_f32_16x16x32_bf16 v[16:19], v[184:187], v[208:211], v[16:19]
	v_mfma_f32_16x16x32_bf16 v[4:7], v[176:179], v[216:219], v[4:7]
	v_mfma_f32_16x16x32_bf16 v[0:3], v[184:187], v[216:219], v[0:3]
	s_setprio 0
	s_barrier
	s_add_i32 s82, 0, 0x18000
	v_add_u32_e32 v159, s82, v152
	s_add_i32 s83, 0, 0x1c000
	ds_read_b128 v[148:151], v159
	ds_read_b128 v[160:163], v159 offset:1024
	ds_read_b128 v[164:167], v159 offset:2048
	ds_read_b128 v[168:171], v159 offset:3072
	v_add_u32_e32 v159, s83, v152
	ds_read_b128 v[172:175], v159
	ds_read_b128 v[176:179], v159 offset:1024
	ds_read_b128 v[180:183], v159 offset:2048
	ds_read_b128 v[184:187], v159 offset:3072
	s_add_u32 s34, s48, 0xb0000
	s_addc_u32 s35, s49, 0
	s_mov_b32 m0, s54
	v_lshl_add_u64 v[228:229], s[34:35], 0, v[132:133]
	ds_read_b128 v[188:191], v157 offset:32768
	ds_read_b128 v[192:195], v157 offset:33792
	ds_read_b128 v[196:199], v157 offset:34816
	ds_read_b128 v[200:203], v157 offset:35840
	ds_read_b128 v[204:207], v157 offset:36864
	ds_read_b128 v[208:211], v157 offset:37888
	ds_read_b128 v[212:215], v157 offset:38912
	ds_read_b128 v[216:219], v157 offset:39936
	global_load_lds_dwordx4 v[228:229], off
	s_mov_b32 m0, s55
	v_lshl_add_u64 v[228:229], s[34:35], 0, v[136:137]
	global_load_lds_dwordx4 v[228:229], off
	s_waitcnt vmcnt(8)
	s_waitcnt lgkmcnt(0)
	s_barrier
	s_setprio 1
	s_waitcnt lgkmcnt(0)
	v_mfma_f32_16x16x32_bf16 v[124:127], v[148:151], v[188:191], v[124:127]
	v_mfma_f32_16x16x32_bf16 v[120:123], v[164:167], v[188:191], v[120:123]
	v_mfma_f32_16x16x32_bf16 v[108:111], v[148:151], v[196:199], v[108:111]
	v_mfma_f32_16x16x32_bf16 v[104:107], v[164:167], v[196:199], v[104:107]
	v_mfma_f32_16x16x32_bf16 v[92:95], v[148:151], v[204:207], v[92:95]
	v_mfma_f32_16x16x32_bf16 v[88:91], v[164:167], v[204:207], v[88:91]
	v_mfma_f32_16x16x32_bf16 v[76:79], v[148:151], v[212:215], v[76:79]
	v_mfma_f32_16x16x32_bf16 v[72:75], v[164:167], v[212:215], v[72:75]
	v_mfma_f32_16x16x32_bf16 v[124:127], v[160:163], v[192:195], v[124:127]
	v_mfma_f32_16x16x32_bf16 v[120:123], v[168:171], v[192:195], v[120:123]
	v_mfma_f32_16x16x32_bf16 v[108:111], v[160:163], v[200:203], v[108:111]
	v_mfma_f32_16x16x32_bf16 v[104:107], v[168:171], v[200:203], v[104:107]
	v_mfma_f32_16x16x32_bf16 v[92:95], v[160:163], v[208:211], v[92:95]
	v_mfma_f32_16x16x32_bf16 v[88:91], v[168:171], v[208:211], v[88:91]
	v_mfma_f32_16x16x32_bf16 v[76:79], v[160:163], v[216:219], v[76:79]
	v_mfma_f32_16x16x32_bf16 v[72:75], v[168:171], v[216:219], v[72:75]
	v_mfma_f32_16x16x32_bf16 v[116:119], v[172:175], v[188:191], v[116:119]
	v_mfma_f32_16x16x32_bf16 v[112:115], v[180:183], v[188:191], v[112:115]
	v_mfma_f32_16x16x32_bf16 v[100:103], v[172:175], v[196:199], v[100:103]
	v_mfma_f32_16x16x32_bf16 v[96:99], v[180:183], v[196:199], v[96:99]
	v_mfma_f32_16x16x32_bf16 v[84:87], v[172:175], v[204:207], v[84:87]
	v_mfma_f32_16x16x32_bf16 v[80:83], v[180:183], v[204:207], v[80:83]
	v_mfma_f32_16x16x32_bf16 v[68:71], v[172:175], v[212:215], v[68:71]
	v_mfma_f32_16x16x32_bf16 v[64:67], v[180:183], v[212:215], v[64:67]
	v_mfma_f32_16x16x32_bf16 v[116:119], v[176:179], v[192:195], v[116:119]
	v_mfma_f32_16x16x32_bf16 v[112:115], v[184:187], v[192:195], v[112:115]
	v_mfma_f32_16x16x32_bf16 v[100:103], v[176:179], v[200:203], v[100:103]
	v_mfma_f32_16x16x32_bf16 v[96:99], v[184:187], v[200:203], v[96:99]
	v_mfma_f32_16x16x32_bf16 v[84:87], v[176:179], v[208:211], v[84:87]
	v_mfma_f32_16x16x32_bf16 v[80:83], v[184:187], v[208:211], v[80:83]
	v_mfma_f32_16x16x32_bf16 v[68:71], v[176:179], v[216:219], v[68:71]
	v_mfma_f32_16x16x32_bf16 v[64:67], v[184:187], v[216:219], v[64:67]
	s_setprio 0
	s_barrier
	s_add_i32 s34, s82, s51
	v_lshl_add_u64 v[220:221], v[220:221], 0, s[22:23]
	s_mov_b32 m0, s34
	ds_read_b128 v[188:191], v157 offset:49152
	ds_read_b128 v[192:195], v157 offset:50176
	ds_read_b128 v[196:199], v157 offset:51200
	ds_read_b128 v[200:203], v157 offset:52224
	ds_read_b128 v[204:207], v157 offset:53248
	ds_read_b128 v[208:211], v157 offset:54272
	ds_read_b128 v[212:215], v157 offset:55296
	ds_read_b128 v[216:219], v157 offset:56320
	global_load_lds_dwordx4 v[220:221], off
	s_add_i32 m0, s34, 0x2000
	s_add_u32 s34, s42, 0xb0080
	v_lshl_add_u64 v[220:221], v[222:223], 0, s[22:23]
	s_addc_u32 s35, s43, 0
	s_add_i32 s42, s83, s51
	global_load_lds_dwordx4 v[220:221], off
	s_mov_b32 m0, s42
	v_lshl_add_u64 v[220:221], s[34:35], 0, v[134:135]
	global_load_lds_dwordx4 v[220:221], off
	s_add_i32 m0, s42, 0x2000
	v_lshl_add_u64 v[220:221], s[34:35], 0, v[138:139]
	global_load_lds_dwordx4 v[220:221], off
	s_mov_b32 m0, s57
	v_lshl_add_u64 v[220:221], v[224:225], 0, s[22:23]
	global_load_lds_dwordx4 v[220:221], off
	s_mov_b32 m0, s58
	v_lshl_add_u64 v[220:221], v[226:227], 0, s[22:23]
	global_load_lds_dwordx4 v[220:221], off
	s_waitcnt vmcnt(8)
	s_waitcnt lgkmcnt(0)
	s_barrier
	s_setprio 1
	s_waitcnt lgkmcnt(0)
	v_mfma_f32_16x16x32_bf16 v[60:63], v[148:151], v[188:191], v[60:63]
	v_mfma_f32_16x16x32_bf16 v[56:59], v[164:167], v[188:191], v[56:59]
	v_mfma_f32_16x16x32_bf16 v[44:47], v[148:151], v[196:199], v[44:47]
	v_mfma_f32_16x16x32_bf16 v[40:43], v[164:167], v[196:199], v[40:43]
	v_mfma_f32_16x16x32_bf16 v[28:31], v[148:151], v[204:207], v[28:31]
	v_mfma_f32_16x16x32_bf16 v[24:27], v[164:167], v[204:207], v[24:27]
	v_mfma_f32_16x16x32_bf16 v[12:15], v[148:151], v[212:215], v[12:15]
	v_mfma_f32_16x16x32_bf16 v[8:11], v[164:167], v[212:215], v[8:11]
	v_mfma_f32_16x16x32_bf16 v[60:63], v[160:163], v[192:195], v[60:63]
	v_mfma_f32_16x16x32_bf16 v[56:59], v[168:171], v[192:195], v[56:59]
	v_mfma_f32_16x16x32_bf16 v[44:47], v[160:163], v[200:203], v[44:47]
	v_mfma_f32_16x16x32_bf16 v[40:43], v[168:171], v[200:203], v[40:43]
	v_mfma_f32_16x16x32_bf16 v[28:31], v[160:163], v[208:211], v[28:31]
	v_mfma_f32_16x16x32_bf16 v[24:27], v[168:171], v[208:211], v[24:27]
	v_mfma_f32_16x16x32_bf16 v[12:15], v[160:163], v[216:219], v[12:15]
	v_mfma_f32_16x16x32_bf16 v[8:11], v[168:171], v[216:219], v[8:11]
	v_mfma_f32_16x16x32_bf16 v[52:55], v[172:175], v[188:191], v[52:55]
	v_mfma_f32_16x16x32_bf16 v[48:51], v[180:183], v[188:191], v[48:51]
	v_mfma_f32_16x16x32_bf16 v[36:39], v[172:175], v[196:199], v[36:39]
	v_mfma_f32_16x16x32_bf16 v[32:35], v[180:183], v[196:199], v[32:35]
	v_mfma_f32_16x16x32_bf16 v[20:23], v[172:175], v[204:207], v[20:23]
	v_mfma_f32_16x16x32_bf16 v[16:19], v[180:183], v[204:207], v[16:19]
	v_mfma_f32_16x16x32_bf16 v[4:7], v[172:175], v[212:215], v[4:7]
	v_mfma_f32_16x16x32_bf16 v[0:3], v[180:183], v[212:215], v[0:3]
	v_mfma_f32_16x16x32_bf16 v[52:55], v[176:179], v[192:195], v[52:55]
	v_mfma_f32_16x16x32_bf16 v[48:51], v[184:187], v[192:195], v[48:51]
	v_mfma_f32_16x16x32_bf16 v[36:39], v[176:179], v[200:203], v[36:39]
	v_mfma_f32_16x16x32_bf16 v[32:35], v[184:187], v[200:203], v[32:35]
	v_mfma_f32_16x16x32_bf16 v[20:23], v[176:179], v[208:211], v[20:23]
	v_mfma_f32_16x16x32_bf16 v[16:19], v[184:187], v[208:211], v[16:19]
	v_mfma_f32_16x16x32_bf16 v[4:7], v[176:179], v[216:219], v[4:7]
	v_mfma_f32_16x16x32_bf16 v[0:3], v[184:187], v[216:219], v[0:3]
	s_setprio 0
	s_cmp_eq_u32 s81, s98
	s_cbranch_scc1 .Lmy_nobar_6
	s_barrier

.Lmy_nobar2_7:
	ds_read_b128 v[148:151], v160
	ds_read_b128 v[152:155], v160 offset:1024
	ds_read_b128 v[164:167], v160 offset:2048
	ds_read_b128 v[168:171], v160 offset:3072
	ds_read_b128 v[172:175], v161
	ds_read_b128 v[176:179], v161 offset:1024
	ds_read_b128 v[180:183], v161 offset:2048
	ds_read_b128 v[184:187], v161 offset:3072
	s_add_u32 s34, s52, 0xfffc0080
	s_addc_u32 s35, s53, -1
	s_cmp_eq_u32 s77, 12
	s_cselect_b32 s57, s9, s35
	s_cselect_b32 s56, s10, s34
	s_cselect_b32 s55, s12, s43
	s_cselect_b32 s54, s13, s41
	v_lshl_add_u64 v[220:221], s[52:53], 0, v[140:141]
	s_add_i32 m0, s65, 0xc000
	ds_read_b128 v[188:191], v162
	ds_read_b128 v[192:195], v162 offset:1024
	ds_read_b128 v[196:199], v162 offset:2048
	ds_read_b128 v[200:203], v162 offset:3072
	ds_read_b128 v[204:207], v162 offset:4096
	ds_read_b128 v[208:211], v162 offset:5120
	ds_read_b128 v[212:215], v162 offset:6144
	ds_read_b128 v[216:219], v162 offset:7168
	global_load_lds_dwordx4 v[220:221], off
	s_add_i32 m0, s65, 0xe000
	v_lshl_add_u64 v[220:221], s[52:53], 0, v[142:143]
	global_load_lds_dwordx4 v[220:221], off
	s_waitcnt vmcnt(8)
	s_waitcnt lgkmcnt(0)
	s_barrier
	s_setprio 1
	s_waitcnt lgkmcnt(0)
	v_mfma_f32_16x16x32_bf16 v[124:127], v[148:151], v[188:191], 0
	v_mfma_f32_16x16x32_bf16 v[120:123], v[164:167], v[188:191], 0
	v_mfma_f32_16x16x32_bf16 v[108:111], v[148:151], v[196:199], 0
	v_mfma_f32_16x16x32_bf16 v[104:107], v[164:167], v[196:199], 0
	v_mfma_f32_16x16x32_bf16 v[92:95], v[148:151], v[204:207], 0
	v_mfma_f32_16x16x32_bf16 v[88:91], v[164:167], v[204:207], 0
	v_mfma_f32_16x16x32_bf16 v[76:79], v[148:151], v[212:215], 0
	v_mfma_f32_16x16x32_bf16 v[72:75], v[164:167], v[212:215], 0
	v_mfma_f32_16x16x32_bf16 v[124:127], v[152:155], v[192:195], v[124:127]
	v_mfma_f32_16x16x32_bf16 v[120:123], v[168:171], v[192:195], v[120:123]
	v_mfma_f32_16x16x32_bf16 v[108:111], v[152:155], v[200:203], v[108:111]
	v_mfma_f32_16x16x32_bf16 v[104:107], v[168:171], v[200:203], v[104:107]
	v_mfma_f32_16x16x32_bf16 v[92:95], v[152:155], v[208:211], v[92:95]
	v_mfma_f32_16x16x32_bf16 v[88:91], v[168:171], v[208:211], v[88:91]
	v_mfma_f32_16x16x32_bf16 v[76:79], v[152:155], v[216:219], v[76:79]
	v_mfma_f32_16x16x32_bf16 v[72:75], v[168:171], v[216:219], v[72:75]
	v_mfma_f32_16x16x32_bf16 v[116:119], v[172:175], v[188:191], 0
	v_mfma_f32_16x16x32_bf16 v[112:115], v[180:183], v[188:191], 0
	v_mfma_f32_16x16x32_bf16 v[100:103], v[172:175], v[196:199], 0
	v_mfma_f32_16x16x32_bf16 v[96:99], v[180:183], v[196:199], 0
	v_mfma_f32_16x16x32_bf16 v[84:87], v[172:175], v[204:207], 0
	v_mfma_f32_16x16x32_bf16 v[80:83], v[180:183], v[204:207], 0
	v_mfma_f32_16x16x32_bf16 v[68:71], v[172:175], v[212:215], 0
	v_mfma_f32_16x16x32_bf16 v[64:67], v[180:183], v[212:215], 0
	v_mfma_f32_16x16x32_bf16 v[116:119], v[176:179], v[192:195], v[116:119]
	v_mfma_f32_16x16x32_bf16 v[112:115], v[184:187], v[192:195], v[112:115]
	v_mfma_f32_16x16x32_bf16 v[100:103], v[176:179], v[200:203], v[100:103]
	v_mfma_f32_16x16x32_bf16 v[96:99], v[184:187], v[200:203], v[96:99]
	v_mfma_f32_16x16x32_bf16 v[84:87], v[176:179], v[208:211], v[84:87]
	v_mfma_f32_16x16x32_bf16 v[80:83], v[184:187], v[208:211], v[80:83]
	v_mfma_f32_16x16x32_bf16 v[68:71], v[176:179], v[216:219], v[68:71]
	v_mfma_f32_16x16x32_bf16 v[64:67], v[184:187], v[216:219], v[64:67]
	s_setprio 0
	s_barrier
	s_add_i32 s34, s88, s62
	v_lshl_add_u64 v[220:221], s[54:55], 0, v[134:135]
	s_mov_b32 m0, s34
	ds_read_b128 v[188:191], v162 offset:16384
	ds_read_b128 v[192:195], v162 offset:17408
	ds_read_b128 v[196:199], v162 offset:18432
	ds_read_b128 v[200:203], v162 offset:19456
	ds_read_b128 v[204:207], v162 offset:20480
	ds_read_b128 v[208:211], v162 offset:21504
	ds_read_b128 v[212:215], v162 offset:22528
	ds_read_b128 v[216:219], v162 offset:23552
	global_load_lds_dwordx4 v[220:221], off
	s_add_i32 m0, s34, 0x2000
	s_add_u32 s34, s54, 0x40000
	v_lshl_add_u64 v[222:223], s[54:55], 0, v[138:139]
	s_addc_u32 s35, s55, 0
	s_add_i32 s90, s89, s62
	global_load_lds_dwordx4 v[222:223], off
	v_lshl_add_u64 v[224:225], s[34:35], 0, v[134:135]
	s_mov_b32 m0, s90
	v_lshl_add_u64 v[226:227], s[56:57], 0, v[136:137]
	global_load_lds_dwordx4 v[224:225], off
	s_add_i32 m0, s90, 0x2000
	v_lshl_add_u64 v[224:225], s[34:35], 0, v[138:139]
	global_load_lds_dwordx4 v[224:225], off
	s_mov_b32 m0, s65
	v_lshl_add_u64 v[224:225], s[56:57], 0, v[132:133]
	global_load_lds_dwordx4 v[224:225], off
	s_mov_b32 m0, s66
	s_nop 0
	global_load_lds_dwordx4 v[226:227], off
	s_waitcnt vmcnt(8)
	s_waitcnt lgkmcnt(0)
	s_barrier
	s_setprio 1
	s_waitcnt lgkmcnt(0)
	v_mfma_f32_16x16x32_bf16 v[60:63], v[148:151], v[188:191], 0
	v_mfma_f32_16x16x32_bf16 v[56:59], v[164:167], v[188:191], 0
	v_mfma_f32_16x16x32_bf16 v[44:47], v[148:151], v[196:199], 0
	v_mfma_f32_16x16x32_bf16 v[40:43], v[164:167], v[196:199], 0
	v_mfma_f32_16x16x32_bf16 v[28:31], v[148:151], v[204:207], 0
	v_mfma_f32_16x16x32_bf16 v[24:27], v[164:167], v[204:207], 0
	v_mfma_f32_16x16x32_bf16 v[12:15], v[148:151], v[212:215], 0
	v_mfma_f32_16x16x32_bf16 v[8:11], v[164:167], v[212:215], 0
	v_mfma_f32_16x16x32_bf16 v[60:63], v[152:155], v[192:195], v[60:63]
	v_mfma_f32_16x16x32_bf16 v[56:59], v[168:171], v[192:195], v[56:59]
	v_mfma_f32_16x16x32_bf16 v[44:47], v[152:155], v[200:203], v[44:47]
	v_mfma_f32_16x16x32_bf16 v[40:43], v[168:171], v[200:203], v[40:43]
	v_mfma_f32_16x16x32_bf16 v[28:31], v[152:155], v[208:211], v[28:31]
	v_mfma_f32_16x16x32_bf16 v[24:27], v[168:171], v[208:211], v[24:27]
	v_mfma_f32_16x16x32_bf16 v[12:15], v[152:155], v[216:219], v[12:15]
	v_mfma_f32_16x16x32_bf16 v[8:11], v[168:171], v[216:219], v[8:11]
	v_mfma_f32_16x16x32_bf16 v[52:55], v[172:175], v[188:191], 0
	v_mfma_f32_16x16x32_bf16 v[48:51], v[180:183], v[188:191], 0
	v_mfma_f32_16x16x32_bf16 v[36:39], v[172:175], v[196:199], 0
	v_mfma_f32_16x16x32_bf16 v[32:35], v[180:183], v[196:199], 0
	v_mfma_f32_16x16x32_bf16 v[20:23], v[172:175], v[204:207], 0
	v_mfma_f32_16x16x32_bf16 v[16:19], v[180:183], v[204:207], 0
	v_mfma_f32_16x16x32_bf16 v[4:7], v[172:175], v[212:215], 0
	v_mfma_f32_16x16x32_bf16 v[0:3], v[180:183], v[212:215], 0
	v_mfma_f32_16x16x32_bf16 v[52:55], v[176:179], v[192:195], v[52:55]
	v_mfma_f32_16x16x32_bf16 v[48:51], v[184:187], v[192:195], v[48:51]
	v_mfma_f32_16x16x32_bf16 v[36:39], v[176:179], v[200:203], v[36:39]
	v_mfma_f32_16x16x32_bf16 v[32:35], v[184:187], v[200:203], v[32:35]
	v_mfma_f32_16x16x32_bf16 v[20:23], v[176:179], v[208:211], v[20:23]
	v_mfma_f32_16x16x32_bf16 v[16:19], v[184:187], v[208:211], v[16:19]
	v_mfma_f32_16x16x32_bf16 v[4:7], v[176:179], v[216:219], v[4:7]
	v_mfma_f32_16x16x32_bf16 v[0:3], v[184:187], v[216:219], v[0:3]
	s_setprio 0
	s_barrier
	s_add_i32 s90, 0, 0x18000
	s_add_i32 s95, 0, 0x1c000
	v_add_u32_e32 v168, s90, v157
	v_add_u32_e32 v184, s95, v157
	ds_read_b128 v[148:151], v168
	ds_read_b128 v[152:155], v168 offset:1024
	ds_read_b128 v[164:167], v168 offset:2048
	ds_read_b128 v[168:171], v168 offset:3072
	ds_read_b128 v[172:175], v184
	ds_read_b128 v[176:179], v184 offset:1024
	ds_read_b128 v[180:183], v184 offset:2048
	ds_read_b128 v[184:187], v184 offset:3072
	s_add_u32 s34, s56, 0x40000
	s_addc_u32 s35, s57, 0
	s_mov_b32 m0, s67
	v_lshl_add_u64 v[228:229], s[34:35], 0, v[132:133]
	ds_read_b128 v[188:191], v162 offset:32768
	ds_read_b128 v[192:195], v162 offset:33792
	ds_read_b128 v[196:199], v162 offset:34816
	ds_read_b128 v[200:203], v162 offset:35840
	ds_read_b128 v[204:207], v162 offset:36864
	ds_read_b128 v[208:211], v162 offset:37888
	ds_read_b128 v[212:215], v162 offset:38912
	ds_read_b128 v[216:219], v162 offset:39936
	global_load_lds_dwordx4 v[228:229], off
	s_mov_b32 m0, s79
	v_lshl_add_u64 v[228:229], s[34:35], 0, v[136:137]
	global_load_lds_dwordx4 v[228:229], off
	s_waitcnt vmcnt(8)
	s_waitcnt lgkmcnt(0)
	s_barrier
	s_setprio 1
	s_waitcnt lgkmcnt(0)
	v_mfma_f32_16x16x32_bf16 v[124:127], v[148:151], v[188:191], v[124:127]
	v_mfma_f32_16x16x32_bf16 v[120:123], v[164:167], v[188:191], v[120:123]
	v_mfma_f32_16x16x32_bf16 v[108:111], v[148:151], v[196:199], v[108:111]
	v_mfma_f32_16x16x32_bf16 v[104:107], v[164:167], v[196:199], v[104:107]
	v_mfma_f32_16x16x32_bf16 v[92:95], v[148:151], v[204:207], v[92:95]
	v_mfma_f32_16x16x32_bf16 v[88:91], v[164:167], v[204:207], v[88:91]
	v_mfma_f32_16x16x32_bf16 v[76:79], v[148:151], v[212:215], v[76:79]
	v_mfma_f32_16x16x32_bf16 v[72:75], v[164:167], v[212:215], v[72:75]
	v_mfma_f32_16x16x32_bf16 v[124:127], v[152:155], v[192:195], v[124:127]
	v_mfma_f32_16x16x32_bf16 v[120:123], v[168:171], v[192:195], v[120:123]
	v_mfma_f32_16x16x32_bf16 v[108:111], v[152:155], v[200:203], v[108:111]
	v_mfma_f32_16x16x32_bf16 v[104:107], v[168:171], v[200:203], v[104:107]
	v_mfma_f32_16x16x32_bf16 v[92:95], v[152:155], v[208:211], v[92:95]
	v_mfma_f32_16x16x32_bf16 v[88:91], v[168:171], v[208:211], v[88:91]
	v_mfma_f32_16x16x32_bf16 v[76:79], v[152:155], v[216:219], v[76:79]
	v_mfma_f32_16x16x32_bf16 v[72:75], v[168:171], v[216:219], v[72:75]
	v_mfma_f32_16x16x32_bf16 v[116:119], v[172:175], v[188:191], v[116:119]
	v_mfma_f32_16x16x32_bf16 v[112:115], v[180:183], v[188:191], v[112:115]
	v_mfma_f32_16x16x32_bf16 v[100:103], v[172:175], v[196:199], v[100:103]
	v_mfma_f32_16x16x32_bf16 v[96:99], v[180:183], v[196:199], v[96:99]
	v_mfma_f32_16x16x32_bf16 v[84:87], v[172:175], v[204:207], v[84:87]
	v_mfma_f32_16x16x32_bf16 v[80:83], v[180:183], v[204:207], v[80:83]
	v_mfma_f32_16x16x32_bf16 v[68:71], v[172:175], v[212:215], v[68:71]
	v_mfma_f32_16x16x32_bf16 v[64:67], v[180:183], v[212:215], v[64:67]
	v_mfma_f32_16x16x32_bf16 v[116:119], v[176:179], v[192:195], v[116:119]
	v_mfma_f32_16x16x32_bf16 v[112:115], v[184:187], v[192:195], v[112:115]
	v_mfma_f32_16x16x32_bf16 v[100:103], v[176:179], v[200:203], v[100:103]
	v_mfma_f32_16x16x32_bf16 v[96:99], v[184:187], v[200:203], v[96:99]
	v_mfma_f32_16x16x32_bf16 v[84:87], v[176:179], v[208:211], v[84:87]
	v_mfma_f32_16x16x32_bf16 v[80:83], v[184:187], v[208:211], v[80:83]
	v_mfma_f32_16x16x32_bf16 v[68:71], v[176:179], v[216:219], v[68:71]
	v_mfma_f32_16x16x32_bf16 v[64:67], v[184:187], v[216:219], v[64:67]
	s_setprio 0
	s_barrier
	s_add_i32 s34, s90, s62
	v_lshl_add_u64 v[220:221], v[220:221], 0, s[26:27]
	s_mov_b32 m0, s34
	ds_read_b128 v[188:191], v162 offset:49152
	ds_read_b128 v[192:195], v162 offset:50176
	ds_read_b128 v[196:199], v162 offset:51200
	ds_read_b128 v[200:203], v162 offset:52224
	ds_read_b128 v[204:207], v162 offset:53248
	ds_read_b128 v[208:211], v162 offset:54272
	ds_read_b128 v[212:215], v162 offset:55296
	ds_read_b128 v[216:219], v162 offset:56320
	global_load_lds_dwordx4 v[220:221], off
	s_add_i32 m0, s34, 0x2000
	s_add_u32 s34, s54, 0x40080
	v_lshl_add_u64 v[220:221], v[222:223], 0, s[26:27]
	s_addc_u32 s35, s55, 0
	s_add_i32 s54, s95, s62
	global_load_lds_dwordx4 v[220:221], off
	s_mov_b32 m0, s54
	v_lshl_add_u64 v[220:221], s[34:35], 0, v[134:135]
	global_load_lds_dwordx4 v[220:221], off
	s_add_i32 m0, s54, 0x2000
	v_lshl_add_u64 v[220:221], s[34:35], 0, v[138:139]
	global_load_lds_dwordx4 v[220:221], off
	s_mov_b32 m0, s83
	v_lshl_add_u64 v[220:221], v[224:225], 0, s[26:27]
	global_load_lds_dwordx4 v[220:221], off
	s_mov_b32 m0, s84
	v_lshl_add_u64 v[220:221], v[226:227], 0, s[26:27]
	global_load_lds_dwordx4 v[220:221], off
	s_waitcnt vmcnt(8)
	s_waitcnt lgkmcnt(0)
	s_barrier
	s_setprio 1
	s_waitcnt lgkmcnt(0)
	v_mfma_f32_16x16x32_bf16 v[60:63], v[148:151], v[188:191], v[60:63]
	v_mfma_f32_16x16x32_bf16 v[56:59], v[164:167], v[188:191], v[56:59]
	v_mfma_f32_16x16x32_bf16 v[44:47], v[148:151], v[196:199], v[44:47]
	v_mfma_f32_16x16x32_bf16 v[40:43], v[164:167], v[196:199], v[40:43]
	v_mfma_f32_16x16x32_bf16 v[28:31], v[148:151], v[204:207], v[28:31]
	v_mfma_f32_16x16x32_bf16 v[24:27], v[164:167], v[204:207], v[24:27]
	v_mfma_f32_16x16x32_bf16 v[12:15], v[148:151], v[212:215], v[12:15]
	v_mfma_f32_16x16x32_bf16 v[8:11], v[164:167], v[212:215], v[8:11]
	v_mfma_f32_16x16x32_bf16 v[60:63], v[152:155], v[192:195], v[60:63]
	v_mfma_f32_16x16x32_bf16 v[56:59], v[168:171], v[192:195], v[56:59]
	v_mfma_f32_16x16x32_bf16 v[44:47], v[152:155], v[200:203], v[44:47]
	v_mfma_f32_16x16x32_bf16 v[40:43], v[168:171], v[200:203], v[40:43]
	v_mfma_f32_16x16x32_bf16 v[28:31], v[152:155], v[208:211], v[28:31]
	v_mfma_f32_16x16x32_bf16 v[24:27], v[168:171], v[208:211], v[24:27]
	v_mfma_f32_16x16x32_bf16 v[12:15], v[152:155], v[216:219], v[12:15]
	v_mfma_f32_16x16x32_bf16 v[8:11], v[168:171], v[216:219], v[8:11]
	v_mfma_f32_16x16x32_bf16 v[52:55], v[172:175], v[188:191], v[52:55]
	v_mfma_f32_16x16x32_bf16 v[48:51], v[180:183], v[188:191], v[48:51]
	v_mfma_f32_16x16x32_bf16 v[36:39], v[172:175], v[196:199], v[36:39]
	v_mfma_f32_16x16x32_bf16 v[32:35], v[180:183], v[196:199], v[32:35]
	v_mfma_f32_16x16x32_bf16 v[20:23], v[172:175], v[204:207], v[20:23]
	v_mfma_f32_16x16x32_bf16 v[16:19], v[180:183], v[204:207], v[16:19]
	v_mfma_f32_16x16x32_bf16 v[4:7], v[172:175], v[212:215], v[4:7]
	v_mfma_f32_16x16x32_bf16 v[0:3], v[180:183], v[212:215], v[0:3]
	v_mfma_f32_16x16x32_bf16 v[52:55], v[176:179], v[192:195], v[52:55]
	v_mfma_f32_16x16x32_bf16 v[48:51], v[184:187], v[192:195], v[48:51]
	v_mfma_f32_16x16x32_bf16 v[36:39], v[176:179], v[200:203], v[36:39]
	v_mfma_f32_16x16x32_bf16 v[32:35], v[184:187], v[200:203], v[32:35]
	v_mfma_f32_16x16x32_bf16 v[20:23], v[176:179], v[208:211], v[20:23]
	v_mfma_f32_16x16x32_bf16 v[16:19], v[184:187], v[208:211], v[16:19]
	v_mfma_f32_16x16x32_bf16 v[4:7], v[176:179], v[216:219], v[4:7]
	v_mfma_f32_16x16x32_bf16 v[0:3], v[184:187], v[216:219], v[0:3]
	s_setprio 0
	s_barrier
	s_add_i32 s77, s77, 2
	s_add_u32 s52, s52, 0x100
	s_addc_u32 s53, s53, 0
	s_add_u32 s41, s41, 0x100
	s_addc_u32 s43, s43, 0
.LBB0_655:
	ds_read_b128 v[148:151], v160
	ds_read_b128 v[152:155], v160 offset:1024
	ds_read_b128 v[164:167], v160 offset:2048
	ds_read_b128 v[168:171], v160 offset:3072
	ds_read_b128 v[172:175], v161
	ds_read_b128 v[176:179], v161 offset:1024
	ds_read_b128 v[180:183], v161 offset:2048
	ds_read_b128 v[184:187], v161 offset:3072
	s_add_u32 s34, s52, 0xfffc0080
	s_addc_u32 s35, s53, -1
	s_cmp_eq_u32 s77, 12
	s_cselect_b32 s57, s9, s35
	s_cselect_b32 s56, s10, s34
	s_cselect_b32 s55, s12, s43
	s_cselect_b32 s54, s13, s41
	v_lshl_add_u64 v[220:221], s[52:53], 0, v[140:141]
	s_add_i32 m0, s65, 0xc000
	ds_read_b128 v[188:191], v162
	ds_read_b128 v[192:195], v162 offset:1024
	ds_read_b128 v[196:199], v162 offset:2048
	ds_read_b128 v[200:203], v162 offset:3072
	ds_read_b128 v[204:207], v162 offset:4096
	ds_read_b128 v[208:211], v162 offset:5120
	ds_read_b128 v[212:215], v162 offset:6144
	ds_read_b128 v[216:219], v162 offset:7168
	global_load_lds_dwordx4 v[220:221], off
	s_add_i32 m0, s65, 0xe000
	v_lshl_add_u64 v[220:221], s[52:53], 0, v[142:143]
	global_load_lds_dwordx4 v[220:221], off
	s_waitcnt vmcnt(8)
	s_waitcnt lgkmcnt(0)
	s_barrier
	s_setprio 1
	s_waitcnt lgkmcnt(0)
	v_mfma_f32_16x16x32_bf16 v[124:127], v[148:151], v[188:191], v[124:127]
	v_mfma_f32_16x16x32_bf16 v[120:123], v[164:167], v[188:191], v[120:123]
	v_mfma_f32_16x16x32_bf16 v[108:111], v[148:151], v[196:199], v[108:111]
	v_mfma_f32_16x16x32_bf16 v[104:107], v[164:167], v[196:199], v[104:107]
	v_mfma_f32_16x16x32_bf16 v[92:95], v[148:151], v[204:207], v[92:95]
	v_mfma_f32_16x16x32_bf16 v[88:91], v[164:167], v[204:207], v[88:91]
	v_mfma_f32_16x16x32_bf16 v[76:79], v[148:151], v[212:215], v[76:79]
	v_mfma_f32_16x16x32_bf16 v[72:75], v[164:167], v[212:215], v[72:75]
	v_mfma_f32_16x16x32_bf16 v[124:127], v[152:155], v[192:195], v[124:127]
	v_mfma_f32_16x16x32_bf16 v[120:123], v[168:171], v[192:195], v[120:123]
	v_mfma_f32_16x16x32_bf16 v[108:111], v[152:155], v[200:203], v[108:111]
	v_mfma_f32_16x16x32_bf16 v[104:107], v[168:171], v[200:203], v[104:107]
	v_mfma_f32_16x16x32_bf16 v[92:95], v[152:155], v[208:211], v[92:95]
	v_mfma_f32_16x16x32_bf16 v[88:91], v[168:171], v[208:211], v[88:91]
	v_mfma_f32_16x16x32_bf16 v[76:79], v[152:155], v[216:219], v[76:79]
	v_mfma_f32_16x16x32_bf16 v[72:75], v[168:171], v[216:219], v[72:75]
	v_mfma_f32_16x16x32_bf16 v[116:119], v[172:175], v[188:191], v[116:119]
	v_mfma_f32_16x16x32_bf16 v[112:115], v[180:183], v[188:191], v[112:115]
	v_mfma_f32_16x16x32_bf16 v[100:103], v[172:175], v[196:199], v[100:103]
	v_mfma_f32_16x16x32_bf16 v[96:99], v[180:183], v[196:199], v[96:99]
	v_mfma_f32_16x16x32_bf16 v[84:87], v[172:175], v[204:207], v[84:87]
	v_mfma_f32_16x16x32_bf16 v[80:83], v[180:183], v[204:207], v[80:83]
	v_mfma_f32_16x16x32_bf16 v[68:71], v[172:175], v[212:215], v[68:71]
	v_mfma_f32_16x16x32_bf16 v[64:67], v[180:183], v[212:215], v[64:67]
	v_mfma_f32_16x16x32_bf16 v[116:119], v[176:179], v[192:195], v[116:119]
	v_mfma_f32_16x16x32_bf16 v[112:115], v[184:187], v[192:195], v[112:115]
	v_mfma_f32_16x16x32_bf16 v[100:103], v[176:179], v[200:203], v[100:103]
	v_mfma_f32_16x16x32_bf16 v[96:99], v[184:187], v[200:203], v[96:99]
	v_mfma_f32_16x16x32_bf16 v[84:87], v[176:179], v[208:211], v[84:87]
	v_mfma_f32_16x16x32_bf16 v[80:83], v[184:187], v[208:211], v[80:83]
	v_mfma_f32_16x16x32_bf16 v[68:71], v[176:179], v[216:219], v[68:71]
	v_mfma_f32_16x16x32_bf16 v[64:67], v[184:187], v[216:219], v[64:67]
	s_setprio 0
	s_barrier
	s_add_i32 s34, s88, s62
	v_lshl_add_u64 v[220:221], s[54:55], 0, v[134:135]
	s_mov_b32 m0, s34
	ds_read_b128 v[188:191], v162 offset:16384
	ds_read_b128 v[192:195], v162 offset:17408
	ds_read_b128 v[196:199], v162 offset:18432
	ds_read_b128 v[200:203], v162 offset:19456
	ds_read_b128 v[204:207], v162 offset:20480
	ds_read_b128 v[208:211], v162 offset:21504
	ds_read_b128 v[212:215], v162 offset:22528
	ds_read_b128 v[216:219], v162 offset:23552
	global_load_lds_dwordx4 v[220:221], off
	s_add_i32 m0, s34, 0x2000
	s_add_u32 s34, s54, 0x40000
	v_lshl_add_u64 v[222:223], s[54:55], 0, v[138:139]
	s_addc_u32 s35, s55, 0
	s_add_i32 s90, s89, s62
	global_load_lds_dwordx4 v[222:223], off
	v_lshl_add_u64 v[224:225], s[34:35], 0, v[134:135]
	s_mov_b32 m0, s90
	v_lshl_add_u64 v[226:227], s[56:57], 0, v[136:137]
	global_load_lds_dwordx4 v[224:225], off
	s_add_i32 m0, s90, 0x2000
	v_lshl_add_u64 v[224:225], s[34:35], 0, v[138:139]
	global_load_lds_dwordx4 v[224:225], off
	s_mov_b32 m0, s65
	v_lshl_add_u64 v[224:225], s[56:57], 0, v[132:133]
	global_load_lds_dwordx4 v[224:225], off
	s_mov_b32 m0, s66
	s_nop 0
	global_load_lds_dwordx4 v[226:227], off
	s_waitcnt vmcnt(8)
	s_waitcnt lgkmcnt(0)
	s_barrier
	s_setprio 1
	s_waitcnt lgkmcnt(0)
	v_mfma_f32_16x16x32_bf16 v[60:63], v[148:151], v[188:191], v[60:63]
	v_mfma_f32_16x16x32_bf16 v[56:59], v[164:167], v[188:191], v[56:59]
	v_mfma_f32_16x16x32_bf16 v[44:47], v[148:151], v[196:199], v[44:47]
	v_mfma_f32_16x16x32_bf16 v[40:43], v[164:167], v[196:199], v[40:43]
	v_mfma_f32_16x16x32_bf16 v[28:31], v[148:151], v[204:207], v[28:31]
	v_mfma_f32_16x16x32_bf16 v[24:27], v[164:167], v[204:207], v[24:27]
	v_mfma_f32_16x16x32_bf16 v[12:15], v[148:151], v[212:215], v[12:15]
	v_mfma_f32_16x16x32_bf16 v[8:11], v[164:167], v[212:215], v[8:11]
	v_mfma_f32_16x16x32_bf16 v[60:63], v[152:155], v[192:195], v[60:63]
	v_mfma_f32_16x16x32_bf16 v[56:59], v[168:171], v[192:195], v[56:59]
	v_mfma_f32_16x16x32_bf16 v[44:47], v[152:155], v[200:203], v[44:47]
	v_mfma_f32_16x16x32_bf16 v[40:43], v[168:171], v[200:203], v[40:43]
	v_mfma_f32_16x16x32_bf16 v[28:31], v[152:155], v[208:211], v[28:31]
	v_mfma_f32_16x16x32_bf16 v[24:27], v[168:171], v[208:211], v[24:27]
	v_mfma_f32_16x16x32_bf16 v[12:15], v[152:155], v[216:219], v[12:15]
	v_mfma_f32_16x16x32_bf16 v[8:11], v[168:171], v[216:219], v[8:11]
	v_mfma_f32_16x16x32_bf16 v[52:55], v[172:175], v[188:191], v[52:55]
	v_mfma_f32_16x16x32_bf16 v[48:51], v[180:183], v[188:191], v[48:51]
	v_mfma_f32_16x16x32_bf16 v[36:39], v[172:175], v[196:199], v[36:39]
	v_mfma_f32_16x16x32_bf16 v[32:35], v[180:183], v[196:199], v[32:35]
	v_mfma_f32_16x16x32_bf16 v[20:23], v[172:175], v[204:207], v[20:23]
	v_mfma_f32_16x16x32_bf16 v[16:19], v[180:183], v[204:207], v[16:19]
	v_mfma_f32_16x16x32_bf16 v[4:7], v[172:175], v[212:215], v[4:7]
	v_mfma_f32_16x16x32_bf16 v[0:3], v[180:183], v[212:215], v[0:3]
	v_mfma_f32_16x16x32_bf16 v[52:55], v[176:179], v[192:195], v[52:55]
	v_mfma_f32_16x16x32_bf16 v[48:51], v[184:187], v[192:195], v[48:51]
	v_mfma_f32_16x16x32_bf16 v[36:39], v[176:179], v[200:203], v[36:39]
	v_mfma_f32_16x16x32_bf16 v[32:35], v[184:187], v[200:203], v[32:35]
	v_mfma_f32_16x16x32_bf16 v[20:23], v[176:179], v[208:211], v[20:23]
	v_mfma_f32_16x16x32_bf16 v[16:19], v[184:187], v[208:211], v[16:19]
	v_mfma_f32_16x16x32_bf16 v[4:7], v[176:179], v[216:219], v[4:7]
	v_mfma_f32_16x16x32_bf16 v[0:3], v[184:187], v[216:219], v[0:3]
	s_setprio 0
	s_barrier
	s_add_i32 s90, 0, 0x18000
	s_add_i32 s95, 0, 0x1c000
	v_add_u32_e32 v168, s90, v157
	v_add_u32_e32 v184, s95, v157
	ds_read_b128 v[148:151], v168
	ds_read_b128 v[152:155], v168 offset:1024
	ds_read_b128 v[164:167], v168 offset:2048
	ds_read_b128 v[168:171], v168 offset:3072
	ds_read_b128 v[172:175], v184
	ds_read_b128 v[176:179], v184 offset:1024
	ds_read_b128 v[180:183], v184 offset:2048
	ds_read_b128 v[184:187], v184 offset:3072
	s_add_u32 s34, s56, 0x40000
	s_addc_u32 s35, s57, 0
	s_mov_b32 m0, s67
	v_lshl_add_u64 v[228:229], s[34:35], 0, v[132:133]
	ds_read_b128 v[188:191], v162 offset:32768
	ds_read_b128 v[192:195], v162 offset:33792
	ds_read_b128 v[196:199], v162 offset:34816
	ds_read_b128 v[200:203], v162 offset:35840
	ds_read_b128 v[204:207], v162 offset:36864
	ds_read_b128 v[208:211], v162 offset:37888
	ds_read_b128 v[212:215], v162 offset:38912
	ds_read_b128 v[216:219], v162 offset:39936
	global_load_lds_dwordx4 v[228:229], off
	s_mov_b32 m0, s79
	v_lshl_add_u64 v[228:229], s[34:35], 0, v[136:137]
	global_load_lds_dwordx4 v[228:229], off
	s_waitcnt vmcnt(8)
	s_waitcnt lgkmcnt(0)
	s_barrier
	s_setprio 1
	s_waitcnt lgkmcnt(0)
	v_mfma_f32_16x16x32_bf16 v[124:127], v[148:151], v[188:191], v[124:127]
	v_mfma_f32_16x16x32_bf16 v[120:123], v[164:167], v[188:191], v[120:123]
	v_mfma_f32_16x16x32_bf16 v[108:111], v[148:151], v[196:199], v[108:111]
	v_mfma_f32_16x16x32_bf16 v[104:107], v[164:167], v[196:199], v[104:107]
	v_mfma_f32_16x16x32_bf16 v[92:95], v[148:151], v[204:207], v[92:95]
	v_mfma_f32_16x16x32_bf16 v[88:91], v[164:167], v[204:207], v[88:91]
	v_mfma_f32_16x16x32_bf16 v[76:79], v[148:151], v[212:215], v[76:79]
	v_mfma_f32_16x16x32_bf16 v[72:75], v[164:167], v[212:215], v[72:75]
	v_mfma_f32_16x16x32_bf16 v[124:127], v[152:155], v[192:195], v[124:127]
	v_mfma_f32_16x16x32_bf16 v[120:123], v[168:171], v[192:195], v[120:123]
	v_mfma_f32_16x16x32_bf16 v[108:111], v[152:155], v[200:203], v[108:111]
	v_mfma_f32_16x16x32_bf16 v[104:107], v[168:171], v[200:203], v[104:107]
	v_mfma_f32_16x16x32_bf16 v[92:95], v[152:155], v[208:211], v[92:95]
	v_mfma_f32_16x16x32_bf16 v[88:91], v[168:171], v[208:211], v[88:91]
	v_mfma_f32_16x16x32_bf16 v[76:79], v[152:155], v[216:219], v[76:79]
	v_mfma_f32_16x16x32_bf16 v[72:75], v[168:171], v[216:219], v[72:75]
	v_mfma_f32_16x16x32_bf16 v[116:119], v[172:175], v[188:191], v[116:119]
	v_mfma_f32_16x16x32_bf16 v[112:115], v[180:183], v[188:191], v[112:115]
	v_mfma_f32_16x16x32_bf16 v[100:103], v[172:175], v[196:199], v[100:103]
	v_mfma_f32_16x16x32_bf16 v[96:99], v[180:183], v[196:199], v[96:99]
	v_mfma_f32_16x16x32_bf16 v[84:87], v[172:175], v[204:207], v[84:87]
	v_mfma_f32_16x16x32_bf16 v[80:83], v[180:183], v[204:207], v[80:83]
	v_mfma_f32_16x16x32_bf16 v[68:71], v[172:175], v[212:215], v[68:71]
	v_mfma_f32_16x16x32_bf16 v[64:67], v[180:183], v[212:215], v[64:67]
	v_mfma_f32_16x16x32_bf16 v[116:119], v[176:179], v[192:195], v[116:119]
	v_mfma_f32_16x16x32_bf16 v[112:115], v[184:187], v[192:195], v[112:115]
	v_mfma_f32_16x16x32_bf16 v[100:103], v[176:179], v[200:203], v[100:103]
	v_mfma_f32_16x16x32_bf16 v[96:99], v[184:187], v[200:203], v[96:99]
	v_mfma_f32_16x16x32_bf16 v[84:87], v[176:179], v[208:211], v[84:87]
	v_mfma_f32_16x16x32_bf16 v[80:83], v[184:187], v[208:211], v[80:83]
	v_mfma_f32_16x16x32_bf16 v[68:71], v[176:179], v[216:219], v[68:71]
	v_mfma_f32_16x16x32_bf16 v[64:67], v[184:187], v[216:219], v[64:67]
	s_setprio 0
	s_barrier
	s_add_i32 s34, s90, s62
	v_lshl_add_u64 v[220:221], v[220:221], 0, s[26:27]
	s_mov_b32 m0, s34
	ds_read_b128 v[188:191], v162 offset:49152
	ds_read_b128 v[192:195], v162 offset:50176
	ds_read_b128 v[196:199], v162 offset:51200
	ds_read_b128 v[200:203], v162 offset:52224
	ds_read_b128 v[204:207], v162 offset:53248
	ds_read_b128 v[208:211], v162 offset:54272
	ds_read_b128 v[212:215], v162 offset:55296
	ds_read_b128 v[216:219], v162 offset:56320
	global_load_lds_dwordx4 v[220:221], off
	s_add_i32 m0, s34, 0x2000
	s_add_u32 s34, s54, 0x40080
	v_lshl_add_u64 v[220:221], v[222:223], 0, s[26:27]
	s_addc_u32 s35, s55, 0
	s_add_i32 s54, s95, s62
	global_load_lds_dwordx4 v[220:221], off
	s_mov_b32 m0, s54
	v_lshl_add_u64 v[220:221], s[34:35], 0, v[134:135]
	global_load_lds_dwordx4 v[220:221], off
	s_add_i32 m0, s54, 0x2000
	v_lshl_add_u64 v[220:221], s[34:35], 0, v[138:139]
	global_load_lds_dwordx4 v[220:221], off
	s_mov_b32 m0, s83
	v_lshl_add_u64 v[220:221], v[224:225], 0, s[26:27]
	global_load_lds_dwordx4 v[220:221], off
	s_mov_b32 m0, s84
	v_lshl_add_u64 v[220:221], v[226:227], 0, s[26:27]
	global_load_lds_dwordx4 v[220:221], off
	s_waitcnt vmcnt(8)
	s_waitcnt lgkmcnt(0)
	s_barrier
	s_setprio 1
	s_waitcnt lgkmcnt(0)
	v_mfma_f32_16x16x32_bf16 v[60:63], v[148:151], v[188:191], v[60:63]
	v_mfma_f32_16x16x32_bf16 v[56:59], v[164:167], v[188:191], v[56:59]
	v_mfma_f32_16x16x32_bf16 v[44:47], v[148:151], v[196:199], v[44:47]
	v_mfma_f32_16x16x32_bf16 v[40:43], v[164:167], v[196:199], v[40:43]
	v_mfma_f32_16x16x32_bf16 v[28:31], v[148:151], v[204:207], v[28:31]
	v_mfma_f32_16x16x32_bf16 v[24:27], v[164:167], v[204:207], v[24:27]
	v_mfma_f32_16x16x32_bf16 v[12:15], v[148:151], v[212:215], v[12:15]
	v_mfma_f32_16x16x32_bf16 v[8:11], v[164:167], v[212:215], v[8:11]
	v_mfma_f32_16x16x32_bf16 v[60:63], v[152:155], v[192:195], v[60:63]
	v_mfma_f32_16x16x32_bf16 v[56:59], v[168:171], v[192:195], v[56:59]
	v_mfma_f32_16x16x32_bf16 v[44:47], v[152:155], v[200:203], v[44:47]
	v_mfma_f32_16x16x32_bf16 v[40:43], v[168:171], v[200:203], v[40:43]
	v_mfma_f32_16x16x32_bf16 v[28:31], v[152:155], v[208:211], v[28:31]
	v_mfma_f32_16x16x32_bf16 v[24:27], v[168:171], v[208:211], v[24:27]
	v_mfma_f32_16x16x32_bf16 v[12:15], v[152:155], v[216:219], v[12:15]
	v_mfma_f32_16x16x32_bf16 v[8:11], v[168:171], v[216:219], v[8:11]
	v_mfma_f32_16x16x32_bf16 v[52:55], v[172:175], v[188:191], v[52:55]
	v_mfma_f32_16x16x32_bf16 v[48:51], v[180:183], v[188:191], v[48:51]
	v_mfma_f32_16x16x32_bf16 v[36:39], v[172:175], v[196:199], v[36:39]
	v_mfma_f32_16x16x32_bf16 v[32:35], v[180:183], v[196:199], v[32:35]
	v_mfma_f32_16x16x32_bf16 v[20:23], v[172:175], v[204:207], v[20:23]
	v_mfma_f32_16x16x32_bf16 v[16:19], v[180:183], v[204:207], v[16:19]
	v_mfma_f32_16x16x32_bf16 v[4:7], v[172:175], v[212:215], v[4:7]
	v_mfma_f32_16x16x32_bf16 v[0:3], v[180:183], v[212:215], v[0:3]
	v_mfma_f32_16x16x32_bf16 v[52:55], v[176:179], v[192:195], v[52:55]
	v_mfma_f32_16x16x32_bf16 v[48:51], v[184:187], v[192:195], v[48:51]
	v_mfma_f32_16x16x32_bf16 v[36:39], v[176:179], v[200:203], v[36:39]
	v_mfma_f32_16x16x32_bf16 v[32:35], v[184:187], v[200:203], v[32:35]
	v_mfma_f32_16x16x32_bf16 v[20:23], v[176:179], v[208:211], v[20:23]
	v_mfma_f32_16x16x32_bf16 v[16:19], v[184:187], v[208:211], v[16:19]
	v_mfma_f32_16x16x32_bf16 v[4:7], v[176:179], v[216:219], v[4:7]
	v_mfma_f32_16x16x32_bf16 v[0:3], v[184:187], v[216:219], v[0:3]
	s_setprio 0
	s_cmp_eq_u32 s77, s98
	s_cbranch_scc1 .Lmy_nobar_7
	s_barrier

.Lmy_nobar2_9:
	ds_read_b128 v[148:151], v154
	ds_read_b128 v[160:163], v154 offset:1024
	ds_read_b128 v[164:167], v154 offset:2048
	ds_read_b128 v[168:171], v154 offset:3072
	ds_read_b128 v[172:175], v155
	ds_read_b128 v[176:179], v155 offset:1024
	ds_read_b128 v[180:183], v155 offset:2048
	ds_read_b128 v[184:187], v155 offset:3072
	s_add_u32 s34, s40, 0xfffc0080
	s_addc_u32 s35, s41, -1
	s_cmp_eq_u32 s77, 12
	s_cselect_b32 s49, s12, s35
	s_cselect_b32 s48, s13, s34
	s_cselect_b32 s43, s27, s67
	s_cselect_b32 s42, s29, s39
	v_lshl_add_u64 v[220:221], s[40:41], 0, v[140:141]
	s_add_i32 m0, s52, 0xc000
	ds_read_b128 v[188:191], v157
	ds_read_b128 v[192:195], v157 offset:1024
	ds_read_b128 v[196:199], v157 offset:2048
	ds_read_b128 v[200:203], v157 offset:3072
	ds_read_b128 v[204:207], v157 offset:4096
	ds_read_b128 v[208:211], v157 offset:5120
	ds_read_b128 v[212:215], v157 offset:6144
	ds_read_b128 v[216:219], v157 offset:7168
	global_load_lds_dwordx4 v[220:221], off
	s_add_i32 m0, s52, 0xe000
	v_lshl_add_u64 v[220:221], s[40:41], 0, v[142:143]
	global_load_lds_dwordx4 v[220:221], off
	s_waitcnt vmcnt(8)
	s_waitcnt lgkmcnt(0)
	s_barrier
	s_setprio 1
	s_waitcnt lgkmcnt(0)
	v_mfma_f32_16x16x32_bf16 v[124:127], v[148:151], v[188:191], 0
	v_mfma_f32_16x16x32_bf16 v[120:123], v[164:167], v[188:191], 0
	v_mfma_f32_16x16x32_bf16 v[108:111], v[148:151], v[196:199], 0
	v_mfma_f32_16x16x32_bf16 v[104:107], v[164:167], v[196:199], 0
	v_mfma_f32_16x16x32_bf16 v[92:95], v[148:151], v[204:207], 0
	v_mfma_f32_16x16x32_bf16 v[88:91], v[164:167], v[204:207], 0
	v_mfma_f32_16x16x32_bf16 v[76:79], v[148:151], v[212:215], 0
	v_mfma_f32_16x16x32_bf16 v[72:75], v[164:167], v[212:215], 0
	v_mfma_f32_16x16x32_bf16 v[124:127], v[160:163], v[192:195], v[124:127]
	v_mfma_f32_16x16x32_bf16 v[120:123], v[168:171], v[192:195], v[120:123]
	v_mfma_f32_16x16x32_bf16 v[108:111], v[160:163], v[200:203], v[108:111]
	v_mfma_f32_16x16x32_bf16 v[104:107], v[168:171], v[200:203], v[104:107]
	v_mfma_f32_16x16x32_bf16 v[92:95], v[160:163], v[208:211], v[92:95]
	v_mfma_f32_16x16x32_bf16 v[88:91], v[168:171], v[208:211], v[88:91]
	v_mfma_f32_16x16x32_bf16 v[76:79], v[160:163], v[216:219], v[76:79]
	v_mfma_f32_16x16x32_bf16 v[72:75], v[168:171], v[216:219], v[72:75]
	v_mfma_f32_16x16x32_bf16 v[116:119], v[172:175], v[188:191], 0
	v_mfma_f32_16x16x32_bf16 v[112:115], v[180:183], v[188:191], 0
	v_mfma_f32_16x16x32_bf16 v[100:103], v[172:175], v[196:199], 0
	v_mfma_f32_16x16x32_bf16 v[96:99], v[180:183], v[196:199], 0
	v_mfma_f32_16x16x32_bf16 v[84:87], v[172:175], v[204:207], 0
	v_mfma_f32_16x16x32_bf16 v[80:83], v[180:183], v[204:207], 0
	v_mfma_f32_16x16x32_bf16 v[68:71], v[172:175], v[212:215], 0
	v_mfma_f32_16x16x32_bf16 v[64:67], v[180:183], v[212:215], 0
	v_mfma_f32_16x16x32_bf16 v[116:119], v[176:179], v[192:195], v[116:119]
	v_mfma_f32_16x16x32_bf16 v[112:115], v[184:187], v[192:195], v[112:115]
	v_mfma_f32_16x16x32_bf16 v[100:103], v[176:179], v[200:203], v[100:103]
	v_mfma_f32_16x16x32_bf16 v[96:99], v[184:187], v[200:203], v[96:99]
	v_mfma_f32_16x16x32_bf16 v[84:87], v[176:179], v[208:211], v[84:87]
	v_mfma_f32_16x16x32_bf16 v[80:83], v[184:187], v[208:211], v[80:83]
	v_mfma_f32_16x16x32_bf16 v[68:71], v[176:179], v[216:219], v[68:71]
	v_mfma_f32_16x16x32_bf16 v[64:67], v[184:187], v[216:219], v[64:67]
	s_setprio 0
	s_barrier
	s_add_i32 s34, s64, s51
	v_lshl_add_u64 v[220:221], s[42:43], 0, v[134:135]
	s_mov_b32 m0, s34
	ds_read_b128 v[188:191], v157 offset:16384
	ds_read_b128 v[192:195], v157 offset:17408
	ds_read_b128 v[196:199], v157 offset:18432
	ds_read_b128 v[200:203], v157 offset:19456
	ds_read_b128 v[204:207], v157 offset:20480
	ds_read_b128 v[208:211], v157 offset:21504
	ds_read_b128 v[212:215], v157 offset:22528
	ds_read_b128 v[216:219], v157 offset:23552
	global_load_lds_dwordx4 v[220:221], off
	s_add_i32 m0, s34, 0x2000
	s_add_u32 s34, s42, 0x40000
	v_lshl_add_u64 v[222:223], s[42:43], 0, v[138:139]
	s_addc_u32 s35, s43, 0
	s_add_i32 s79, s65, s51
	global_load_lds_dwordx4 v[222:223], off
	v_lshl_add_u64 v[224:225], s[34:35], 0, v[134:135]
	s_mov_b32 m0, s79
	v_lshl_add_u64 v[226:227], s[48:49], 0, v[136:137]
	global_load_lds_dwordx4 v[224:225], off
	s_add_i32 m0, s79, 0x2000
	v_lshl_add_u64 v[224:225], s[34:35], 0, v[138:139]
	global_load_lds_dwordx4 v[224:225], off
	s_mov_b32 m0, s52
	v_lshl_add_u64 v[224:225], s[48:49], 0, v[132:133]
	global_load_lds_dwordx4 v[224:225], off
	s_mov_b32 m0, s53
	s_nop 0
	global_load_lds_dwordx4 v[226:227], off
	s_waitcnt vmcnt(8)
	s_waitcnt lgkmcnt(0)
	s_barrier
	s_setprio 1
	s_waitcnt lgkmcnt(0)
	v_mfma_f32_16x16x32_bf16 v[60:63], v[148:151], v[188:191], 0
	v_mfma_f32_16x16x32_bf16 v[56:59], v[164:167], v[188:191], 0
	v_mfma_f32_16x16x32_bf16 v[44:47], v[148:151], v[196:199], 0
	v_mfma_f32_16x16x32_bf16 v[40:43], v[164:167], v[196:199], 0
	v_mfma_f32_16x16x32_bf16 v[28:31], v[148:151], v[204:207], 0
	v_mfma_f32_16x16x32_bf16 v[24:27], v[164:167], v[204:207], 0
	v_mfma_f32_16x16x32_bf16 v[12:15], v[148:151], v[212:215], 0
	v_mfma_f32_16x16x32_bf16 v[8:11], v[164:167], v[212:215], 0
	v_mfma_f32_16x16x32_bf16 v[60:63], v[160:163], v[192:195], v[60:63]
	v_mfma_f32_16x16x32_bf16 v[56:59], v[168:171], v[192:195], v[56:59]
	v_mfma_f32_16x16x32_bf16 v[44:47], v[160:163], v[200:203], v[44:47]
	v_mfma_f32_16x16x32_bf16 v[40:43], v[168:171], v[200:203], v[40:43]
	v_mfma_f32_16x16x32_bf16 v[28:31], v[160:163], v[208:211], v[28:31]
	v_mfma_f32_16x16x32_bf16 v[24:27], v[168:171], v[208:211], v[24:27]
	v_mfma_f32_16x16x32_bf16 v[12:15], v[160:163], v[216:219], v[12:15]
	v_mfma_f32_16x16x32_bf16 v[8:11], v[168:171], v[216:219], v[8:11]
	v_mfma_f32_16x16x32_bf16 v[52:55], v[172:175], v[188:191], 0
	v_mfma_f32_16x16x32_bf16 v[48:51], v[180:183], v[188:191], 0
	v_mfma_f32_16x16x32_bf16 v[36:39], v[172:175], v[196:199], 0
	v_mfma_f32_16x16x32_bf16 v[32:35], v[180:183], v[196:199], 0
	v_mfma_f32_16x16x32_bf16 v[20:23], v[172:175], v[204:207], 0
	v_mfma_f32_16x16x32_bf16 v[16:19], v[180:183], v[204:207], 0
	v_mfma_f32_16x16x32_bf16 v[4:7], v[172:175], v[212:215], 0
	v_mfma_f32_16x16x32_bf16 v[0:3], v[180:183], v[212:215], 0
	v_mfma_f32_16x16x32_bf16 v[52:55], v[176:179], v[192:195], v[52:55]
	v_mfma_f32_16x16x32_bf16 v[48:51], v[184:187], v[192:195], v[48:51]
	v_mfma_f32_16x16x32_bf16 v[36:39], v[176:179], v[200:203], v[36:39]
	v_mfma_f32_16x16x32_bf16 v[32:35], v[184:187], v[200:203], v[32:35]
	v_mfma_f32_16x16x32_bf16 v[20:23], v[176:179], v[208:211], v[20:23]
	v_mfma_f32_16x16x32_bf16 v[16:19], v[184:187], v[208:211], v[16:19]
	v_mfma_f32_16x16x32_bf16 v[4:7], v[176:179], v[216:219], v[4:7]
	v_mfma_f32_16x16x32_bf16 v[0:3], v[184:187], v[216:219], v[0:3]
	s_setprio 0
	s_barrier
	s_add_i32 s79, 0, 0x18000
	v_add_u32_e32 v159, s79, v152
	s_add_i32 s81, 0, 0x1c000
	ds_read_b128 v[148:151], v159
	ds_read_b128 v[160:163], v159 offset:1024
	ds_read_b128 v[164:167], v159 offset:2048
	ds_read_b128 v[168:171], v159 offset:3072
	v_add_u32_e32 v159, s81, v152
	ds_read_b128 v[172:175], v159
	ds_read_b128 v[176:179], v159 offset:1024
	ds_read_b128 v[180:183], v159 offset:2048
	ds_read_b128 v[184:187], v159 offset:3072
	s_add_u32 s34, s48, 0x40000
	s_addc_u32 s35, s49, 0
	s_mov_b32 m0, s54
	v_lshl_add_u64 v[228:229], s[34:35], 0, v[132:133]
	ds_read_b128 v[188:191], v157 offset:32768
	ds_read_b128 v[192:195], v157 offset:33792
	ds_read_b128 v[196:199], v157 offset:34816
	ds_read_b128 v[200:203], v157 offset:35840
	ds_read_b128 v[204:207], v157 offset:36864
	ds_read_b128 v[208:211], v157 offset:37888
	ds_read_b128 v[212:215], v157 offset:38912
	ds_read_b128 v[216:219], v157 offset:39936
	global_load_lds_dwordx4 v[228:229], off
	s_mov_b32 m0, s55
	v_lshl_add_u64 v[228:229], s[34:35], 0, v[136:137]
	global_load_lds_dwordx4 v[228:229], off
	s_waitcnt vmcnt(8)
	s_waitcnt lgkmcnt(0)
	s_barrier
	s_setprio 1
	s_waitcnt lgkmcnt(0)
	v_mfma_f32_16x16x32_bf16 v[124:127], v[148:151], v[188:191], v[124:127]
	v_mfma_f32_16x16x32_bf16 v[120:123], v[164:167], v[188:191], v[120:123]
	v_mfma_f32_16x16x32_bf16 v[108:111], v[148:151], v[196:199], v[108:111]
	v_mfma_f32_16x16x32_bf16 v[104:107], v[164:167], v[196:199], v[104:107]
	v_mfma_f32_16x16x32_bf16 v[92:95], v[148:151], v[204:207], v[92:95]
	v_mfma_f32_16x16x32_bf16 v[88:91], v[164:167], v[204:207], v[88:91]
	v_mfma_f32_16x16x32_bf16 v[76:79], v[148:151], v[212:215], v[76:79]
	v_mfma_f32_16x16x32_bf16 v[72:75], v[164:167], v[212:215], v[72:75]
	v_mfma_f32_16x16x32_bf16 v[124:127], v[160:163], v[192:195], v[124:127]
	v_mfma_f32_16x16x32_bf16 v[120:123], v[168:171], v[192:195], v[120:123]
	v_mfma_f32_16x16x32_bf16 v[108:111], v[160:163], v[200:203], v[108:111]
	v_mfma_f32_16x16x32_bf16 v[104:107], v[168:171], v[200:203], v[104:107]
	v_mfma_f32_16x16x32_bf16 v[92:95], v[160:163], v[208:211], v[92:95]
	v_mfma_f32_16x16x32_bf16 v[88:91], v[168:171], v[208:211], v[88:91]
	v_mfma_f32_16x16x32_bf16 v[76:79], v[160:163], v[216:219], v[76:79]
	v_mfma_f32_16x16x32_bf16 v[72:75], v[168:171], v[216:219], v[72:75]
	v_mfma_f32_16x16x32_bf16 v[116:119], v[172:175], v[188:191], v[116:119]
	v_mfma_f32_16x16x32_bf16 v[112:115], v[180:183], v[188:191], v[112:115]
	v_mfma_f32_16x16x32_bf16 v[100:103], v[172:175], v[196:199], v[100:103]
	v_mfma_f32_16x16x32_bf16 v[96:99], v[180:183], v[196:199], v[96:99]
	v_mfma_f32_16x16x32_bf16 v[84:87], v[172:175], v[204:207], v[84:87]
	v_mfma_f32_16x16x32_bf16 v[80:83], v[180:183], v[204:207], v[80:83]
	v_mfma_f32_16x16x32_bf16 v[68:71], v[172:175], v[212:215], v[68:71]
	v_mfma_f32_16x16x32_bf16 v[64:67], v[180:183], v[212:215], v[64:67]
	v_mfma_f32_16x16x32_bf16 v[116:119], v[176:179], v[192:195], v[116:119]
	v_mfma_f32_16x16x32_bf16 v[112:115], v[184:187], v[192:195], v[112:115]
	v_mfma_f32_16x16x32_bf16 v[100:103], v[176:179], v[200:203], v[100:103]
	v_mfma_f32_16x16x32_bf16 v[96:99], v[184:187], v[200:203], v[96:99]
	v_mfma_f32_16x16x32_bf16 v[84:87], v[176:179], v[208:211], v[84:87]
	v_mfma_f32_16x16x32_bf16 v[80:83], v[184:187], v[208:211], v[80:83]
	v_mfma_f32_16x16x32_bf16 v[68:71], v[176:179], v[216:219], v[68:71]
	v_mfma_f32_16x16x32_bf16 v[64:67], v[184:187], v[216:219], v[64:67]
	s_setprio 0
	s_barrier
	s_add_i32 s34, s79, s51
	v_lshl_add_u64 v[220:221], v[220:221], 0, s[10:11]
	s_mov_b32 m0, s34
	ds_read_b128 v[188:191], v157 offset:49152
	ds_read_b128 v[192:195], v157 offset:50176
	ds_read_b128 v[196:199], v157 offset:51200
	ds_read_b128 v[200:203], v157 offset:52224
	ds_read_b128 v[204:207], v157 offset:53248
	ds_read_b128 v[208:211], v157 offset:54272
	ds_read_b128 v[212:215], v157 offset:55296
	ds_read_b128 v[216:219], v157 offset:56320
	global_load_lds_dwordx4 v[220:221], off
	s_add_i32 m0, s34, 0x2000
	s_add_u32 s34, s42, 0x40080
	v_lshl_add_u64 v[220:221], v[222:223], 0, s[10:11]
	s_addc_u32 s35, s43, 0
	s_add_i32 s42, s81, s51
	global_load_lds_dwordx4 v[220:221], off
	s_mov_b32 m0, s42
	v_lshl_add_u64 v[220:221], s[34:35], 0, v[134:135]
	global_load_lds_dwordx4 v[220:221], off
	s_add_i32 m0, s42, 0x2000
	v_lshl_add_u64 v[220:221], s[34:35], 0, v[138:139]
	global_load_lds_dwordx4 v[220:221], off
	s_mov_b32 m0, s57
	v_lshl_add_u64 v[220:221], v[224:225], 0, s[10:11]
	global_load_lds_dwordx4 v[220:221], off
	s_mov_b32 m0, s58
	v_lshl_add_u64 v[220:221], v[226:227], 0, s[10:11]
	global_load_lds_dwordx4 v[220:221], off
	s_waitcnt vmcnt(8)
	s_waitcnt lgkmcnt(0)
	s_barrier
	s_setprio 1
	s_waitcnt lgkmcnt(0)
	v_mfma_f32_16x16x32_bf16 v[60:63], v[148:151], v[188:191], v[60:63]
	v_mfma_f32_16x16x32_bf16 v[56:59], v[164:167], v[188:191], v[56:59]
	v_mfma_f32_16x16x32_bf16 v[44:47], v[148:151], v[196:199], v[44:47]
	v_mfma_f32_16x16x32_bf16 v[40:43], v[164:167], v[196:199], v[40:43]
	v_mfma_f32_16x16x32_bf16 v[28:31], v[148:151], v[204:207], v[28:31]
	v_mfma_f32_16x16x32_bf16 v[24:27], v[164:167], v[204:207], v[24:27]
	v_mfma_f32_16x16x32_bf16 v[12:15], v[148:151], v[212:215], v[12:15]
	v_mfma_f32_16x16x32_bf16 v[8:11], v[164:167], v[212:215], v[8:11]
	v_mfma_f32_16x16x32_bf16 v[60:63], v[160:163], v[192:195], v[60:63]
	v_mfma_f32_16x16x32_bf16 v[56:59], v[168:171], v[192:195], v[56:59]
	v_mfma_f32_16x16x32_bf16 v[44:47], v[160:163], v[200:203], v[44:47]
	v_mfma_f32_16x16x32_bf16 v[40:43], v[168:171], v[200:203], v[40:43]
	v_mfma_f32_16x16x32_bf16 v[28:31], v[160:163], v[208:211], v[28:31]
	v_mfma_f32_16x16x32_bf16 v[24:27], v[168:171], v[208:211], v[24:27]
	v_mfma_f32_16x16x32_bf16 v[12:15], v[160:163], v[216:219], v[12:15]
	v_mfma_f32_16x16x32_bf16 v[8:11], v[168:171], v[216:219], v[8:11]
	v_mfma_f32_16x16x32_bf16 v[52:55], v[172:175], v[188:191], v[52:55]
	v_mfma_f32_16x16x32_bf16 v[48:51], v[180:183], v[188:191], v[48:51]
	v_mfma_f32_16x16x32_bf16 v[36:39], v[172:175], v[196:199], v[36:39]
	v_mfma_f32_16x16x32_bf16 v[32:35], v[180:183], v[196:199], v[32:35]
	v_mfma_f32_16x16x32_bf16 v[20:23], v[172:175], v[204:207], v[20:23]
	v_mfma_f32_16x16x32_bf16 v[16:19], v[180:183], v[204:207], v[16:19]
	v_mfma_f32_16x16x32_bf16 v[4:7], v[172:175], v[212:215], v[4:7]
	v_mfma_f32_16x16x32_bf16 v[0:3], v[180:183], v[212:215], v[0:3]
	v_mfma_f32_16x16x32_bf16 v[52:55], v[176:179], v[192:195], v[52:55]
	v_mfma_f32_16x16x32_bf16 v[48:51], v[184:187], v[192:195], v[48:51]
	v_mfma_f32_16x16x32_bf16 v[36:39], v[176:179], v[200:203], v[36:39]
	v_mfma_f32_16x16x32_bf16 v[32:35], v[184:187], v[200:203], v[32:35]
	v_mfma_f32_16x16x32_bf16 v[20:23], v[176:179], v[208:211], v[20:23]
	v_mfma_f32_16x16x32_bf16 v[16:19], v[184:187], v[208:211], v[16:19]
	v_mfma_f32_16x16x32_bf16 v[4:7], v[176:179], v[216:219], v[4:7]
	v_mfma_f32_16x16x32_bf16 v[0:3], v[184:187], v[216:219], v[0:3]
	s_setprio 0
	s_barrier
	s_add_i32 s77, s77, 2
	s_add_u32 s40, s40, 0x100
	s_addc_u32 s41, s41, 0
	s_add_u32 s39, s39, 0x100
	s_addc_u32 s67, s67, 0
.LBB0_969:
	ds_read_b128 v[148:151], v154
	ds_read_b128 v[160:163], v154 offset:1024
	ds_read_b128 v[164:167], v154 offset:2048
	ds_read_b128 v[168:171], v154 offset:3072
	ds_read_b128 v[172:175], v155
	ds_read_b128 v[176:179], v155 offset:1024
	ds_read_b128 v[180:183], v155 offset:2048
	ds_read_b128 v[184:187], v155 offset:3072
	s_add_u32 s34, s40, 0xfffc0080
	s_addc_u32 s35, s41, -1
	s_cmp_eq_u32 s77, 12
	s_cselect_b32 s49, s12, s35
	s_cselect_b32 s48, s13, s34
	s_cselect_b32 s43, s27, s67
	s_cselect_b32 s42, s29, s39
	v_lshl_add_u64 v[220:221], s[40:41], 0, v[140:141]
	s_add_i32 m0, s52, 0xc000
	ds_read_b128 v[188:191], v157
	ds_read_b128 v[192:195], v157 offset:1024
	ds_read_b128 v[196:199], v157 offset:2048
	ds_read_b128 v[200:203], v157 offset:3072
	ds_read_b128 v[204:207], v157 offset:4096
	ds_read_b128 v[208:211], v157 offset:5120
	ds_read_b128 v[212:215], v157 offset:6144
	ds_read_b128 v[216:219], v157 offset:7168
	global_load_lds_dwordx4 v[220:221], off
	s_add_i32 m0, s52, 0xe000
	v_lshl_add_u64 v[220:221], s[40:41], 0, v[142:143]
	global_load_lds_dwordx4 v[220:221], off
	s_waitcnt vmcnt(8)
	s_waitcnt lgkmcnt(0)
	s_barrier
	s_setprio 1
	s_waitcnt lgkmcnt(0)
	v_mfma_f32_16x16x32_bf16 v[124:127], v[148:151], v[188:191], v[124:127]
	v_mfma_f32_16x16x32_bf16 v[120:123], v[164:167], v[188:191], v[120:123]
	v_mfma_f32_16x16x32_bf16 v[108:111], v[148:151], v[196:199], v[108:111]
	v_mfma_f32_16x16x32_bf16 v[104:107], v[164:167], v[196:199], v[104:107]
	v_mfma_f32_16x16x32_bf16 v[92:95], v[148:151], v[204:207], v[92:95]
	v_mfma_f32_16x16x32_bf16 v[88:91], v[164:167], v[204:207], v[88:91]
	v_mfma_f32_16x16x32_bf16 v[76:79], v[148:151], v[212:215], v[76:79]
	v_mfma_f32_16x16x32_bf16 v[72:75], v[164:167], v[212:215], v[72:75]
	v_mfma_f32_16x16x32_bf16 v[124:127], v[160:163], v[192:195], v[124:127]
	v_mfma_f32_16x16x32_bf16 v[120:123], v[168:171], v[192:195], v[120:123]
	v_mfma_f32_16x16x32_bf16 v[108:111], v[160:163], v[200:203], v[108:111]
	v_mfma_f32_16x16x32_bf16 v[104:107], v[168:171], v[200:203], v[104:107]
	v_mfma_f32_16x16x32_bf16 v[92:95], v[160:163], v[208:211], v[92:95]
	v_mfma_f32_16x16x32_bf16 v[88:91], v[168:171], v[208:211], v[88:91]
	v_mfma_f32_16x16x32_bf16 v[76:79], v[160:163], v[216:219], v[76:79]
	v_mfma_f32_16x16x32_bf16 v[72:75], v[168:171], v[216:219], v[72:75]
	v_mfma_f32_16x16x32_bf16 v[116:119], v[172:175], v[188:191], v[116:119]
	v_mfma_f32_16x16x32_bf16 v[112:115], v[180:183], v[188:191], v[112:115]
	v_mfma_f32_16x16x32_bf16 v[100:103], v[172:175], v[196:199], v[100:103]
	v_mfma_f32_16x16x32_bf16 v[96:99], v[180:183], v[196:199], v[96:99]
	v_mfma_f32_16x16x32_bf16 v[84:87], v[172:175], v[204:207], v[84:87]
	v_mfma_f32_16x16x32_bf16 v[80:83], v[180:183], v[204:207], v[80:83]
	v_mfma_f32_16x16x32_bf16 v[68:71], v[172:175], v[212:215], v[68:71]
	v_mfma_f32_16x16x32_bf16 v[64:67], v[180:183], v[212:215], v[64:67]
	v_mfma_f32_16x16x32_bf16 v[116:119], v[176:179], v[192:195], v[116:119]
	v_mfma_f32_16x16x32_bf16 v[112:115], v[184:187], v[192:195], v[112:115]
	v_mfma_f32_16x16x32_bf16 v[100:103], v[176:179], v[200:203], v[100:103]
	v_mfma_f32_16x16x32_bf16 v[96:99], v[184:187], v[200:203], v[96:99]
	v_mfma_f32_16x16x32_bf16 v[84:87], v[176:179], v[208:211], v[84:87]
	v_mfma_f32_16x16x32_bf16 v[80:83], v[184:187], v[208:211], v[80:83]
	v_mfma_f32_16x16x32_bf16 v[68:71], v[176:179], v[216:219], v[68:71]
	v_mfma_f32_16x16x32_bf16 v[64:67], v[184:187], v[216:219], v[64:67]
	s_setprio 0
	s_barrier
	s_add_i32 s34, s64, s51
	v_lshl_add_u64 v[220:221], s[42:43], 0, v[134:135]
	s_mov_b32 m0, s34
	ds_read_b128 v[188:191], v157 offset:16384
	ds_read_b128 v[192:195], v157 offset:17408
	ds_read_b128 v[196:199], v157 offset:18432
	ds_read_b128 v[200:203], v157 offset:19456
	ds_read_b128 v[204:207], v157 offset:20480
	ds_read_b128 v[208:211], v157 offset:21504
	ds_read_b128 v[212:215], v157 offset:22528
	ds_read_b128 v[216:219], v157 offset:23552
	global_load_lds_dwordx4 v[220:221], off
	s_add_i32 m0, s34, 0x2000
	s_add_u32 s34, s42, 0x40000
	v_lshl_add_u64 v[222:223], s[42:43], 0, v[138:139]
	s_addc_u32 s35, s43, 0
	s_add_i32 s79, s65, s51
	global_load_lds_dwordx4 v[222:223], off
	v_lshl_add_u64 v[224:225], s[34:35], 0, v[134:135]
	s_mov_b32 m0, s79
	v_lshl_add_u64 v[226:227], s[48:49], 0, v[136:137]
	global_load_lds_dwordx4 v[224:225], off
	s_add_i32 m0, s79, 0x2000
	v_lshl_add_u64 v[224:225], s[34:35], 0, v[138:139]
	global_load_lds_dwordx4 v[224:225], off
	s_mov_b32 m0, s52
	v_lshl_add_u64 v[224:225], s[48:49], 0, v[132:133]
	global_load_lds_dwordx4 v[224:225], off
	s_mov_b32 m0, s53
	s_nop 0
	global_load_lds_dwordx4 v[226:227], off
	s_waitcnt vmcnt(8)
	s_waitcnt lgkmcnt(0)
	s_barrier
	s_setprio 1
	s_waitcnt lgkmcnt(0)
	v_mfma_f32_16x16x32_bf16 v[60:63], v[148:151], v[188:191], v[60:63]
	v_mfma_f32_16x16x32_bf16 v[56:59], v[164:167], v[188:191], v[56:59]
	v_mfma_f32_16x16x32_bf16 v[44:47], v[148:151], v[196:199], v[44:47]
	v_mfma_f32_16x16x32_bf16 v[40:43], v[164:167], v[196:199], v[40:43]
	v_mfma_f32_16x16x32_bf16 v[28:31], v[148:151], v[204:207], v[28:31]
	v_mfma_f32_16x16x32_bf16 v[24:27], v[164:167], v[204:207], v[24:27]
	v_mfma_f32_16x16x32_bf16 v[12:15], v[148:151], v[212:215], v[12:15]
	v_mfma_f32_16x16x32_bf16 v[8:11], v[164:167], v[212:215], v[8:11]
	v_mfma_f32_16x16x32_bf16 v[60:63], v[160:163], v[192:195], v[60:63]
	v_mfma_f32_16x16x32_bf16 v[56:59], v[168:171], v[192:195], v[56:59]
	v_mfma_f32_16x16x32_bf16 v[44:47], v[160:163], v[200:203], v[44:47]
	v_mfma_f32_16x16x32_bf16 v[40:43], v[168:171], v[200:203], v[40:43]
	v_mfma_f32_16x16x32_bf16 v[28:31], v[160:163], v[208:211], v[28:31]
	v_mfma_f32_16x16x32_bf16 v[24:27], v[168:171], v[208:211], v[24:27]
	v_mfma_f32_16x16x32_bf16 v[12:15], v[160:163], v[216:219], v[12:15]
	v_mfma_f32_16x16x32_bf16 v[8:11], v[168:171], v[216:219], v[8:11]
	v_mfma_f32_16x16x32_bf16 v[52:55], v[172:175], v[188:191], v[52:55]
	v_mfma_f32_16x16x32_bf16 v[48:51], v[180:183], v[188:191], v[48:51]
	v_mfma_f32_16x16x32_bf16 v[36:39], v[172:175], v[196:199], v[36:39]
	v_mfma_f32_16x16x32_bf16 v[32:35], v[180:183], v[196:199], v[32:35]
	v_mfma_f32_16x16x32_bf16 v[20:23], v[172:175], v[204:207], v[20:23]
	v_mfma_f32_16x16x32_bf16 v[16:19], v[180:183], v[204:207], v[16:19]
	v_mfma_f32_16x16x32_bf16 v[4:7], v[172:175], v[212:215], v[4:7]
	v_mfma_f32_16x16x32_bf16 v[0:3], v[180:183], v[212:215], v[0:3]
	v_mfma_f32_16x16x32_bf16 v[52:55], v[176:179], v[192:195], v[52:55]
	v_mfma_f32_16x16x32_bf16 v[48:51], v[184:187], v[192:195], v[48:51]
	v_mfma_f32_16x16x32_bf16 v[36:39], v[176:179], v[200:203], v[36:39]
	v_mfma_f32_16x16x32_bf16 v[32:35], v[184:187], v[200:203], v[32:35]
	v_mfma_f32_16x16x32_bf16 v[20:23], v[176:179], v[208:211], v[20:23]
	v_mfma_f32_16x16x32_bf16 v[16:19], v[184:187], v[208:211], v[16:19]
	v_mfma_f32_16x16x32_bf16 v[4:7], v[176:179], v[216:219], v[4:7]
	v_mfma_f32_16x16x32_bf16 v[0:3], v[184:187], v[216:219], v[0:3]
	s_setprio 0
	s_barrier
	s_add_i32 s79, 0, 0x18000
	v_add_u32_e32 v159, s79, v152
	s_add_i32 s81, 0, 0x1c000
	ds_read_b128 v[148:151], v159
	ds_read_b128 v[160:163], v159 offset:1024
	ds_read_b128 v[164:167], v159 offset:2048
	ds_read_b128 v[168:171], v159 offset:3072
	v_add_u32_e32 v159, s81, v152
	ds_read_b128 v[172:175], v159
	ds_read_b128 v[176:179], v159 offset:1024
	ds_read_b128 v[180:183], v159 offset:2048
	ds_read_b128 v[184:187], v159 offset:3072
	s_add_u32 s34, s48, 0x40000
	s_addc_u32 s35, s49, 0
	s_mov_b32 m0, s54
	v_lshl_add_u64 v[228:229], s[34:35], 0, v[132:133]
	ds_read_b128 v[188:191], v157 offset:32768
	ds_read_b128 v[192:195], v157 offset:33792
	ds_read_b128 v[196:199], v157 offset:34816
	ds_read_b128 v[200:203], v157 offset:35840
	ds_read_b128 v[204:207], v157 offset:36864
	ds_read_b128 v[208:211], v157 offset:37888
	ds_read_b128 v[212:215], v157 offset:38912
	ds_read_b128 v[216:219], v157 offset:39936
	global_load_lds_dwordx4 v[228:229], off
	s_mov_b32 m0, s55
	v_lshl_add_u64 v[228:229], s[34:35], 0, v[136:137]
	global_load_lds_dwordx4 v[228:229], off
	s_waitcnt vmcnt(8)
	s_waitcnt lgkmcnt(0)
	s_barrier
	s_setprio 1
	s_waitcnt lgkmcnt(0)
	v_mfma_f32_16x16x32_bf16 v[124:127], v[148:151], v[188:191], v[124:127]
	v_mfma_f32_16x16x32_bf16 v[120:123], v[164:167], v[188:191], v[120:123]
	v_mfma_f32_16x16x32_bf16 v[108:111], v[148:151], v[196:199], v[108:111]
	v_mfma_f32_16x16x32_bf16 v[104:107], v[164:167], v[196:199], v[104:107]
	v_mfma_f32_16x16x32_bf16 v[92:95], v[148:151], v[204:207], v[92:95]
	v_mfma_f32_16x16x32_bf16 v[88:91], v[164:167], v[204:207], v[88:91]
	v_mfma_f32_16x16x32_bf16 v[76:79], v[148:151], v[212:215], v[76:79]
	v_mfma_f32_16x16x32_bf16 v[72:75], v[164:167], v[212:215], v[72:75]
	v_mfma_f32_16x16x32_bf16 v[124:127], v[160:163], v[192:195], v[124:127]
	v_mfma_f32_16x16x32_bf16 v[120:123], v[168:171], v[192:195], v[120:123]
	v_mfma_f32_16x16x32_bf16 v[108:111], v[160:163], v[200:203], v[108:111]
	v_mfma_f32_16x16x32_bf16 v[104:107], v[168:171], v[200:203], v[104:107]
	v_mfma_f32_16x16x32_bf16 v[92:95], v[160:163], v[208:211], v[92:95]
	v_mfma_f32_16x16x32_bf16 v[88:91], v[168:171], v[208:211], v[88:91]
	v_mfma_f32_16x16x32_bf16 v[76:79], v[160:163], v[216:219], v[76:79]
	v_mfma_f32_16x16x32_bf16 v[72:75], v[168:171], v[216:219], v[72:75]
	v_mfma_f32_16x16x32_bf16 v[116:119], v[172:175], v[188:191], v[116:119]
	v_mfma_f32_16x16x32_bf16 v[112:115], v[180:183], v[188:191], v[112:115]
	v_mfma_f32_16x16x32_bf16 v[100:103], v[172:175], v[196:199], v[100:103]
	v_mfma_f32_16x16x32_bf16 v[96:99], v[180:183], v[196:199], v[96:99]
	v_mfma_f32_16x16x32_bf16 v[84:87], v[172:175], v[204:207], v[84:87]
	v_mfma_f32_16x16x32_bf16 v[80:83], v[180:183], v[204:207], v[80:83]
	v_mfma_f32_16x16x32_bf16 v[68:71], v[172:175], v[212:215], v[68:71]
	v_mfma_f32_16x16x32_bf16 v[64:67], v[180:183], v[212:215], v[64:67]
	v_mfma_f32_16x16x32_bf16 v[116:119], v[176:179], v[192:195], v[116:119]
	v_mfma_f32_16x16x32_bf16 v[112:115], v[184:187], v[192:195], v[112:115]
	v_mfma_f32_16x16x32_bf16 v[100:103], v[176:179], v[200:203], v[100:103]
	v_mfma_f32_16x16x32_bf16 v[96:99], v[184:187], v[200:203], v[96:99]
	v_mfma_f32_16x16x32_bf16 v[84:87], v[176:179], v[208:211], v[84:87]
	v_mfma_f32_16x16x32_bf16 v[80:83], v[184:187], v[208:211], v[80:83]
	v_mfma_f32_16x16x32_bf16 v[68:71], v[176:179], v[216:219], v[68:71]
	v_mfma_f32_16x16x32_bf16 v[64:67], v[184:187], v[216:219], v[64:67]
	s_setprio 0
	s_barrier
	s_add_i32 s34, s79, s51
	v_lshl_add_u64 v[220:221], v[220:221], 0, s[10:11]
	s_mov_b32 m0, s34
	ds_read_b128 v[188:191], v157 offset:49152
	ds_read_b128 v[192:195], v157 offset:50176
	ds_read_b128 v[196:199], v157 offset:51200
	ds_read_b128 v[200:203], v157 offset:52224
	ds_read_b128 v[204:207], v157 offset:53248
	ds_read_b128 v[208:211], v157 offset:54272
	ds_read_b128 v[212:215], v157 offset:55296
	ds_read_b128 v[216:219], v157 offset:56320
	global_load_lds_dwordx4 v[220:221], off
	s_add_i32 m0, s34, 0x2000
	s_add_u32 s34, s42, 0x40080
	v_lshl_add_u64 v[220:221], v[222:223], 0, s[10:11]
	s_addc_u32 s35, s43, 0
	s_add_i32 s42, s81, s51
	global_load_lds_dwordx4 v[220:221], off
	s_mov_b32 m0, s42
	v_lshl_add_u64 v[220:221], s[34:35], 0, v[134:135]
	global_load_lds_dwordx4 v[220:221], off
	s_add_i32 m0, s42, 0x2000
	v_lshl_add_u64 v[220:221], s[34:35], 0, v[138:139]
	global_load_lds_dwordx4 v[220:221], off
	s_mov_b32 m0, s57
	v_lshl_add_u64 v[220:221], v[224:225], 0, s[10:11]
	global_load_lds_dwordx4 v[220:221], off
	s_mov_b32 m0, s58
	v_lshl_add_u64 v[220:221], v[226:227], 0, s[10:11]
	global_load_lds_dwordx4 v[220:221], off
	s_waitcnt vmcnt(8)
	s_waitcnt lgkmcnt(0)
	s_barrier
	s_setprio 1
	s_waitcnt lgkmcnt(0)
	v_mfma_f32_16x16x32_bf16 v[60:63], v[148:151], v[188:191], v[60:63]
	v_mfma_f32_16x16x32_bf16 v[56:59], v[164:167], v[188:191], v[56:59]
	v_mfma_f32_16x16x32_bf16 v[44:47], v[148:151], v[196:199], v[44:47]
	v_mfma_f32_16x16x32_bf16 v[40:43], v[164:167], v[196:199], v[40:43]
	v_mfma_f32_16x16x32_bf16 v[28:31], v[148:151], v[204:207], v[28:31]
	v_mfma_f32_16x16x32_bf16 v[24:27], v[164:167], v[204:207], v[24:27]
	v_mfma_f32_16x16x32_bf16 v[12:15], v[148:151], v[212:215], v[12:15]
	v_mfma_f32_16x16x32_bf16 v[8:11], v[164:167], v[212:215], v[8:11]
	v_mfma_f32_16x16x32_bf16 v[60:63], v[160:163], v[192:195], v[60:63]
	v_mfma_f32_16x16x32_bf16 v[56:59], v[168:171], v[192:195], v[56:59]
	v_mfma_f32_16x16x32_bf16 v[44:47], v[160:163], v[200:203], v[44:47]
	v_mfma_f32_16x16x32_bf16 v[40:43], v[168:171], v[200:203], v[40:43]
	v_mfma_f32_16x16x32_bf16 v[28:31], v[160:163], v[208:211], v[28:31]
	v_mfma_f32_16x16x32_bf16 v[24:27], v[168:171], v[208:211], v[24:27]
	v_mfma_f32_16x16x32_bf16 v[12:15], v[160:163], v[216:219], v[12:15]
	v_mfma_f32_16x16x32_bf16 v[8:11], v[168:171], v[216:219], v[8:11]
	v_mfma_f32_16x16x32_bf16 v[52:55], v[172:175], v[188:191], v[52:55]
	v_mfma_f32_16x16x32_bf16 v[48:51], v[180:183], v[188:191], v[48:51]
	v_mfma_f32_16x16x32_bf16 v[36:39], v[172:175], v[196:199], v[36:39]
	v_mfma_f32_16x16x32_bf16 v[32:35], v[180:183], v[196:199], v[32:35]
	v_mfma_f32_16x16x32_bf16 v[20:23], v[172:175], v[204:207], v[20:23]
	v_mfma_f32_16x16x32_bf16 v[16:19], v[180:183], v[204:207], v[16:19]
	v_mfma_f32_16x16x32_bf16 v[4:7], v[172:175], v[212:215], v[4:7]
	v_mfma_f32_16x16x32_bf16 v[0:3], v[180:183], v[212:215], v[0:3]
	v_mfma_f32_16x16x32_bf16 v[52:55], v[176:179], v[192:195], v[52:55]
	v_mfma_f32_16x16x32_bf16 v[48:51], v[184:187], v[192:195], v[48:51]
	v_mfma_f32_16x16x32_bf16 v[36:39], v[176:179], v[200:203], v[36:39]
	v_mfma_f32_16x16x32_bf16 v[32:35], v[184:187], v[200:203], v[32:35]
	v_mfma_f32_16x16x32_bf16 v[20:23], v[176:179], v[208:211], v[20:23]
	v_mfma_f32_16x16x32_bf16 v[16:19], v[184:187], v[208:211], v[16:19]
	v_mfma_f32_16x16x32_bf16 v[4:7], v[176:179], v[216:219], v[4:7]
	v_mfma_f32_16x16x32_bf16 v[0:3], v[184:187], v[216:219], v[0:3]
	s_setprio 0
	s_cmp_eq_u32 s77, s98
	s_cbranch_scc1 .Lmy_nobar_9
	s_barrier

.Lmy_nobar2_10:
	ds_read_b128 v[148:151], v155
	ds_read_b128 v[160:163], v155 offset:1024
	ds_read_b128 v[164:167], v155 offset:2048
	ds_read_b128 v[168:171], v155 offset:3072
	ds_read_b128 v[172:175], v157
	ds_read_b128 v[176:179], v157 offset:1024
	ds_read_b128 v[180:183], v157 offset:2048
	ds_read_b128 v[184:187], v157 offset:3072
	s_add_u32 s34, s36, 0xfffc0080
	s_addc_u32 s35, s37, -1
	s_cmp_eq_u32 s77, 12
	s_cselect_b32 s41, s23, s35
	s_cselect_b32 s40, s64, s34
	s_cselect_b32 s39, s11, s67
	s_cselect_b32 s38, s65, s66
	v_lshl_add_u64 v[220:221], s[36:37], 0, v[140:141]
	s_add_i32 m0, s31, 0xc000
	ds_read_b128 v[188:191], v158
	ds_read_b128 v[192:195], v158 offset:1024
	ds_read_b128 v[196:199], v158 offset:2048
	ds_read_b128 v[200:203], v158 offset:3072
	ds_read_b128 v[204:207], v158 offset:4096
	ds_read_b128 v[208:211], v158 offset:5120
	ds_read_b128 v[212:215], v158 offset:6144
	ds_read_b128 v[216:219], v158 offset:7168
	global_load_lds_dwordx4 v[220:221], off
	s_add_i32 m0, s31, 0xe000
	v_lshl_add_u64 v[220:221], s[36:37], 0, v[142:143]
	global_load_lds_dwordx4 v[220:221], off
	s_waitcnt vmcnt(8)
	s_waitcnt lgkmcnt(0)
	s_barrier
	s_setprio 1
	s_waitcnt lgkmcnt(0)
	v_mfma_f32_16x16x32_bf16 v[124:127], v[148:151], v[188:191], 0
	v_mfma_f32_16x16x32_bf16 v[120:123], v[164:167], v[188:191], 0
	v_mfma_f32_16x16x32_bf16 v[108:111], v[148:151], v[196:199], 0
	v_mfma_f32_16x16x32_bf16 v[104:107], v[164:167], v[196:199], 0
	v_mfma_f32_16x16x32_bf16 v[92:95], v[148:151], v[204:207], 0
	v_mfma_f32_16x16x32_bf16 v[88:91], v[164:167], v[204:207], 0
	v_mfma_f32_16x16x32_bf16 v[76:79], v[148:151], v[212:215], 0
	v_mfma_f32_16x16x32_bf16 v[72:75], v[164:167], v[212:215], 0
	v_mfma_f32_16x16x32_bf16 v[124:127], v[160:163], v[192:195], v[124:127]
	v_mfma_f32_16x16x32_bf16 v[120:123], v[168:171], v[192:195], v[120:123]
	v_mfma_f32_16x16x32_bf16 v[108:111], v[160:163], v[200:203], v[108:111]
	v_mfma_f32_16x16x32_bf16 v[104:107], v[168:171], v[200:203], v[104:107]
	v_mfma_f32_16x16x32_bf16 v[92:95], v[160:163], v[208:211], v[92:95]
	v_mfma_f32_16x16x32_bf16 v[88:91], v[168:171], v[208:211], v[88:91]
	v_mfma_f32_16x16x32_bf16 v[76:79], v[160:163], v[216:219], v[76:79]
	v_mfma_f32_16x16x32_bf16 v[72:75], v[168:171], v[216:219], v[72:75]
	v_mfma_f32_16x16x32_bf16 v[116:119], v[172:175], v[188:191], 0
	v_mfma_f32_16x16x32_bf16 v[112:115], v[180:183], v[188:191], 0
	v_mfma_f32_16x16x32_bf16 v[100:103], v[172:175], v[196:199], 0
	v_mfma_f32_16x16x32_bf16 v[96:99], v[180:183], v[196:199], 0
	v_mfma_f32_16x16x32_bf16 v[84:87], v[172:175], v[204:207], 0
	v_mfma_f32_16x16x32_bf16 v[80:83], v[180:183], v[204:207], 0
	v_mfma_f32_16x16x32_bf16 v[68:71], v[172:175], v[212:215], 0
	v_mfma_f32_16x16x32_bf16 v[64:67], v[180:183], v[212:215], 0
	v_mfma_f32_16x16x32_bf16 v[116:119], v[176:179], v[192:195], v[116:119]
	v_mfma_f32_16x16x32_bf16 v[112:115], v[184:187], v[192:195], v[112:115]
	v_mfma_f32_16x16x32_bf16 v[100:103], v[176:179], v[200:203], v[100:103]
	v_mfma_f32_16x16x32_bf16 v[96:99], v[184:187], v[200:203], v[96:99]
	v_mfma_f32_16x16x32_bf16 v[84:87], v[176:179], v[208:211], v[84:87]
	v_mfma_f32_16x16x32_bf16 v[80:83], v[184:187], v[208:211], v[80:83]
	v_mfma_f32_16x16x32_bf16 v[68:71], v[176:179], v[216:219], v[68:71]
	v_mfma_f32_16x16x32_bf16 v[64:67], v[184:187], v[216:219], v[64:67]
	s_setprio 0
	s_barrier
	s_add_i32 s34, s57, s48
	v_lshl_add_u64 v[220:221], s[38:39], 0, v[136:137]
	s_mov_b32 m0, s34
	ds_read_b128 v[188:191], v158 offset:16384
	ds_read_b128 v[192:195], v158 offset:17408
	ds_read_b128 v[196:199], v158 offset:18432
	ds_read_b128 v[200:203], v158 offset:19456
	ds_read_b128 v[204:207], v158 offset:20480
	ds_read_b128 v[208:211], v158 offset:21504
	ds_read_b128 v[212:215], v158 offset:22528
	ds_read_b128 v[216:219], v158 offset:23552
	global_load_lds_dwordx4 v[220:221], off
	s_add_i32 m0, s34, 0x2000
	s_add_u32 s34, s38, 0x40000
	v_lshl_add_u64 v[222:223], s[38:39], 0, v[132:133]
	s_addc_u32 s35, s39, 0
	s_add_i32 s79, s58, s48
	global_load_lds_dwordx4 v[222:223], off
	v_lshl_add_u64 v[224:225], s[34:35], 0, v[136:137]
	s_mov_b32 m0, s79
	v_lshl_add_u64 v[226:227], s[40:41], 0, v[134:135]
	global_load_lds_dwordx4 v[224:225], off
	s_add_i32 m0, s79, 0x2000
	v_lshl_add_u64 v[224:225], s[34:35], 0, v[132:133]
	global_load_lds_dwordx4 v[224:225], off
	s_mov_b32 m0, s31
	v_lshl_add_u64 v[224:225], s[40:41], 0, v[138:139]
	global_load_lds_dwordx4 v[224:225], off
	s_mov_b32 m0, s52
	s_nop 0
	global_load_lds_dwordx4 v[226:227], off
	s_waitcnt vmcnt(8)
	s_waitcnt lgkmcnt(0)
	s_barrier
	s_setprio 1
	s_waitcnt lgkmcnt(0)
	v_mfma_f32_16x16x32_bf16 v[60:63], v[148:151], v[188:191], 0
	v_mfma_f32_16x16x32_bf16 v[56:59], v[164:167], v[188:191], 0
	v_mfma_f32_16x16x32_bf16 v[44:47], v[148:151], v[196:199], 0
	v_mfma_f32_16x16x32_bf16 v[40:43], v[164:167], v[196:199], 0
	v_mfma_f32_16x16x32_bf16 v[28:31], v[148:151], v[204:207], 0
	v_mfma_f32_16x16x32_bf16 v[24:27], v[164:167], v[204:207], 0
	v_mfma_f32_16x16x32_bf16 v[12:15], v[148:151], v[212:215], 0
	v_mfma_f32_16x16x32_bf16 v[8:11], v[164:167], v[212:215], 0
	v_mfma_f32_16x16x32_bf16 v[60:63], v[160:163], v[192:195], v[60:63]
	v_mfma_f32_16x16x32_bf16 v[56:59], v[168:171], v[192:195], v[56:59]
	v_mfma_f32_16x16x32_bf16 v[44:47], v[160:163], v[200:203], v[44:47]
	v_mfma_f32_16x16x32_bf16 v[40:43], v[168:171], v[200:203], v[40:43]
	v_mfma_f32_16x16x32_bf16 v[28:31], v[160:163], v[208:211], v[28:31]
	v_mfma_f32_16x16x32_bf16 v[24:27], v[168:171], v[208:211], v[24:27]
	v_mfma_f32_16x16x32_bf16 v[12:15], v[160:163], v[216:219], v[12:15]
	v_mfma_f32_16x16x32_bf16 v[8:11], v[168:171], v[216:219], v[8:11]
	v_mfma_f32_16x16x32_bf16 v[52:55], v[172:175], v[188:191], 0
	v_mfma_f32_16x16x32_bf16 v[48:51], v[180:183], v[188:191], 0
	v_mfma_f32_16x16x32_bf16 v[36:39], v[172:175], v[196:199], 0
	v_mfma_f32_16x16x32_bf16 v[32:35], v[180:183], v[196:199], 0
	v_mfma_f32_16x16x32_bf16 v[20:23], v[172:175], v[204:207], 0
	v_mfma_f32_16x16x32_bf16 v[16:19], v[180:183], v[204:207], 0
	v_mfma_f32_16x16x32_bf16 v[4:7], v[172:175], v[212:215], 0
	v_mfma_f32_16x16x32_bf16 v[0:3], v[180:183], v[212:215], 0
	v_mfma_f32_16x16x32_bf16 v[52:55], v[176:179], v[192:195], v[52:55]
	v_mfma_f32_16x16x32_bf16 v[48:51], v[184:187], v[192:195], v[48:51]
	v_mfma_f32_16x16x32_bf16 v[36:39], v[176:179], v[200:203], v[36:39]
	v_mfma_f32_16x16x32_bf16 v[32:35], v[184:187], v[200:203], v[32:35]
	v_mfma_f32_16x16x32_bf16 v[20:23], v[176:179], v[208:211], v[20:23]
	v_mfma_f32_16x16x32_bf16 v[16:19], v[184:187], v[208:211], v[16:19]
	v_mfma_f32_16x16x32_bf16 v[4:7], v[176:179], v[216:219], v[4:7]
	v_mfma_f32_16x16x32_bf16 v[0:3], v[184:187], v[216:219], v[0:3]
	s_setprio 0
	s_barrier
	s_add_i32 s79, 0, 0x18000
	v_add_u32_e32 v159, s79, v152
	s_add_i32 s81, 0, 0x1c000
	ds_read_b128 v[148:151], v159
	ds_read_b128 v[160:163], v159 offset:1024
	ds_read_b128 v[164:167], v159 offset:2048
	ds_read_b128 v[168:171], v159 offset:3072
	v_add_u32_e32 v159, s81, v152
	ds_read_b128 v[172:175], v159
	ds_read_b128 v[176:179], v159 offset:1024
	ds_read_b128 v[180:183], v159 offset:2048
	ds_read_b128 v[184:187], v159 offset:3072
	s_add_u32 s34, s40, 0x40000
	s_addc_u32 s35, s41, 0
	s_mov_b32 m0, s53
	v_lshl_add_u64 v[228:229], s[34:35], 0, v[138:139]
	ds_read_b128 v[188:191], v158 offset:32768
	ds_read_b128 v[192:195], v158 offset:33792
	ds_read_b128 v[196:199], v158 offset:34816
	ds_read_b128 v[200:203], v158 offset:35840
	ds_read_b128 v[204:207], v158 offset:36864
	ds_read_b128 v[208:211], v158 offset:37888
	ds_read_b128 v[212:215], v158 offset:38912
	ds_read_b128 v[216:219], v158 offset:39936
	global_load_lds_dwordx4 v[228:229], off
	s_mov_b32 m0, s54
	v_lshl_add_u64 v[228:229], s[34:35], 0, v[134:135]
	global_load_lds_dwordx4 v[228:229], off
	s_waitcnt vmcnt(8)
	s_waitcnt lgkmcnt(0)
	s_barrier
	s_setprio 1
	s_waitcnt lgkmcnt(0)
	v_mfma_f32_16x16x32_bf16 v[124:127], v[148:151], v[188:191], v[124:127]
	v_mfma_f32_16x16x32_bf16 v[120:123], v[164:167], v[188:191], v[120:123]
	v_mfma_f32_16x16x32_bf16 v[108:111], v[148:151], v[196:199], v[108:111]
	v_mfma_f32_16x16x32_bf16 v[104:107], v[164:167], v[196:199], v[104:107]
	v_mfma_f32_16x16x32_bf16 v[92:95], v[148:151], v[204:207], v[92:95]
	v_mfma_f32_16x16x32_bf16 v[88:91], v[164:167], v[204:207], v[88:91]
	v_mfma_f32_16x16x32_bf16 v[76:79], v[148:151], v[212:215], v[76:79]
	v_mfma_f32_16x16x32_bf16 v[72:75], v[164:167], v[212:215], v[72:75]
	v_mfma_f32_16x16x32_bf16 v[124:127], v[160:163], v[192:195], v[124:127]
	v_mfma_f32_16x16x32_bf16 v[120:123], v[168:171], v[192:195], v[120:123]
	v_mfma_f32_16x16x32_bf16 v[108:111], v[160:163], v[200:203], v[108:111]
	v_mfma_f32_16x16x32_bf16 v[104:107], v[168:171], v[200:203], v[104:107]
	v_mfma_f32_16x16x32_bf16 v[92:95], v[160:163], v[208:211], v[92:95]
	v_mfma_f32_16x16x32_bf16 v[88:91], v[168:171], v[208:211], v[88:91]
	v_mfma_f32_16x16x32_bf16 v[76:79], v[160:163], v[216:219], v[76:79]
	v_mfma_f32_16x16x32_bf16 v[72:75], v[168:171], v[216:219], v[72:75]
	v_mfma_f32_16x16x32_bf16 v[116:119], v[172:175], v[188:191], v[116:119]
	v_mfma_f32_16x16x32_bf16 v[112:115], v[180:183], v[188:191], v[112:115]
	v_mfma_f32_16x16x32_bf16 v[100:103], v[172:175], v[196:199], v[100:103]
	v_mfma_f32_16x16x32_bf16 v[96:99], v[180:183], v[196:199], v[96:99]
	v_mfma_f32_16x16x32_bf16 v[84:87], v[172:175], v[204:207], v[84:87]
	v_mfma_f32_16x16x32_bf16 v[80:83], v[180:183], v[204:207], v[80:83]
	v_mfma_f32_16x16x32_bf16 v[68:71], v[172:175], v[212:215], v[68:71]
	v_mfma_f32_16x16x32_bf16 v[64:67], v[180:183], v[212:215], v[64:67]
	v_mfma_f32_16x16x32_bf16 v[116:119], v[176:179], v[192:195], v[116:119]
	v_mfma_f32_16x16x32_bf16 v[112:115], v[184:187], v[192:195], v[112:115]
	v_mfma_f32_16x16x32_bf16 v[100:103], v[176:179], v[200:203], v[100:103]
	v_mfma_f32_16x16x32_bf16 v[96:99], v[184:187], v[200:203], v[96:99]
	v_mfma_f32_16x16x32_bf16 v[84:87], v[176:179], v[208:211], v[84:87]
	v_mfma_f32_16x16x32_bf16 v[80:83], v[184:187], v[208:211], v[80:83]
	v_mfma_f32_16x16x32_bf16 v[68:71], v[176:179], v[216:219], v[68:71]
	v_mfma_f32_16x16x32_bf16 v[64:67], v[184:187], v[216:219], v[64:67]
	s_setprio 0
	s_barrier
	s_add_i32 s34, s79, s48
	v_lshl_add_u64 v[220:221], v[220:221], 0, s[6:7]
	s_mov_b32 m0, s34
	ds_read_b128 v[188:191], v158 offset:49152
	ds_read_b128 v[192:195], v158 offset:50176
	ds_read_b128 v[196:199], v158 offset:51200
	ds_read_b128 v[200:203], v158 offset:52224
	ds_read_b128 v[204:207], v158 offset:53248
	ds_read_b128 v[208:211], v158 offset:54272
	ds_read_b128 v[212:215], v158 offset:55296
	ds_read_b128 v[216:219], v158 offset:56320
	global_load_lds_dwordx4 v[220:221], off
	s_add_i32 m0, s34, 0x2000
	s_add_u32 s34, s38, 0x40080
	v_lshl_add_u64 v[220:221], v[222:223], 0, s[6:7]
	s_addc_u32 s35, s39, 0
	s_add_i32 s38, s81, s48
	global_load_lds_dwordx4 v[220:221], off
	s_mov_b32 m0, s38
	v_lshl_add_u64 v[220:221], s[34:35], 0, v[136:137]
	global_load_lds_dwordx4 v[220:221], off
	s_add_i32 m0, s38, 0x2000
	v_lshl_add_u64 v[220:221], s[34:35], 0, v[132:133]
	global_load_lds_dwordx4 v[220:221], off
	s_mov_b32 m0, s55
	v_lshl_add_u64 v[220:221], v[224:225], 0, s[6:7]
	global_load_lds_dwordx4 v[220:221], off
	s_mov_b32 m0, s56
	v_lshl_add_u64 v[220:221], v[226:227], 0, s[6:7]
	global_load_lds_dwordx4 v[220:221], off
	s_waitcnt vmcnt(8)
	s_waitcnt lgkmcnt(0)
	s_barrier
	s_setprio 1
	s_waitcnt lgkmcnt(0)
	v_mfma_f32_16x16x32_bf16 v[60:63], v[148:151], v[188:191], v[60:63]
	v_mfma_f32_16x16x32_bf16 v[56:59], v[164:167], v[188:191], v[56:59]
	v_mfma_f32_16x16x32_bf16 v[44:47], v[148:151], v[196:199], v[44:47]
	v_mfma_f32_16x16x32_bf16 v[40:43], v[164:167], v[196:199], v[40:43]
	v_mfma_f32_16x16x32_bf16 v[28:31], v[148:151], v[204:207], v[28:31]
	v_mfma_f32_16x16x32_bf16 v[24:27], v[164:167], v[204:207], v[24:27]
	v_mfma_f32_16x16x32_bf16 v[12:15], v[148:151], v[212:215], v[12:15]
	v_mfma_f32_16x16x32_bf16 v[8:11], v[164:167], v[212:215], v[8:11]
	v_mfma_f32_16x16x32_bf16 v[60:63], v[160:163], v[192:195], v[60:63]
	v_mfma_f32_16x16x32_bf16 v[56:59], v[168:171], v[192:195], v[56:59]
	v_mfma_f32_16x16x32_bf16 v[44:47], v[160:163], v[200:203], v[44:47]
	v_mfma_f32_16x16x32_bf16 v[40:43], v[168:171], v[200:203], v[40:43]
	v_mfma_f32_16x16x32_bf16 v[28:31], v[160:163], v[208:211], v[28:31]
	v_mfma_f32_16x16x32_bf16 v[24:27], v[168:171], v[208:211], v[24:27]
	v_mfma_f32_16x16x32_bf16 v[12:15], v[160:163], v[216:219], v[12:15]
	v_mfma_f32_16x16x32_bf16 v[8:11], v[168:171], v[216:219], v[8:11]
	v_mfma_f32_16x16x32_bf16 v[52:55], v[172:175], v[188:191], v[52:55]
	v_mfma_f32_16x16x32_bf16 v[48:51], v[180:183], v[188:191], v[48:51]
	v_mfma_f32_16x16x32_bf16 v[36:39], v[172:175], v[196:199], v[36:39]
	v_mfma_f32_16x16x32_bf16 v[32:35], v[180:183], v[196:199], v[32:35]
	v_mfma_f32_16x16x32_bf16 v[20:23], v[172:175], v[204:207], v[20:23]
	v_mfma_f32_16x16x32_bf16 v[16:19], v[180:183], v[204:207], v[16:19]
	v_mfma_f32_16x16x32_bf16 v[4:7], v[172:175], v[212:215], v[4:7]
	v_mfma_f32_16x16x32_bf16 v[0:3], v[180:183], v[212:215], v[0:3]
	v_mfma_f32_16x16x32_bf16 v[52:55], v[176:179], v[192:195], v[52:55]
	v_mfma_f32_16x16x32_bf16 v[48:51], v[184:187], v[192:195], v[48:51]
	v_mfma_f32_16x16x32_bf16 v[36:39], v[176:179], v[200:203], v[36:39]
	v_mfma_f32_16x16x32_bf16 v[32:35], v[184:187], v[200:203], v[32:35]
	v_mfma_f32_16x16x32_bf16 v[20:23], v[176:179], v[208:211], v[20:23]
	v_mfma_f32_16x16x32_bf16 v[16:19], v[184:187], v[208:211], v[16:19]
	v_mfma_f32_16x16x32_bf16 v[4:7], v[176:179], v[216:219], v[4:7]
	v_mfma_f32_16x16x32_bf16 v[0:3], v[184:187], v[216:219], v[0:3]
	s_setprio 0
	s_barrier
	s_add_i32 s77, s77, 2
	s_add_u32 s36, s36, 0x100
	s_addc_u32 s37, s37, 0
	s_add_u32 s66, s66, 0x100
	s_addc_u32 s67, s67, 0
.LBB0_1059:
	ds_read_b128 v[148:151], v155
	ds_read_b128 v[160:163], v155 offset:1024
	ds_read_b128 v[164:167], v155 offset:2048
	ds_read_b128 v[168:171], v155 offset:3072
	ds_read_b128 v[172:175], v157
	ds_read_b128 v[176:179], v157 offset:1024
	ds_read_b128 v[180:183], v157 offset:2048
	ds_read_b128 v[184:187], v157 offset:3072
	s_add_u32 s34, s36, 0xfffc0080
	s_addc_u32 s35, s37, -1
	s_cmp_eq_u32 s77, 12
	s_cselect_b32 s41, s23, s35
	s_cselect_b32 s40, s64, s34
	s_cselect_b32 s39, s11, s67
	s_cselect_b32 s38, s65, s66
	v_lshl_add_u64 v[220:221], s[36:37], 0, v[140:141]
	s_add_i32 m0, s31, 0xc000
	ds_read_b128 v[188:191], v158
	ds_read_b128 v[192:195], v158 offset:1024
	ds_read_b128 v[196:199], v158 offset:2048
	ds_read_b128 v[200:203], v158 offset:3072
	ds_read_b128 v[204:207], v158 offset:4096
	ds_read_b128 v[208:211], v158 offset:5120
	ds_read_b128 v[212:215], v158 offset:6144
	ds_read_b128 v[216:219], v158 offset:7168
	global_load_lds_dwordx4 v[220:221], off
	s_add_i32 m0, s31, 0xe000
	v_lshl_add_u64 v[220:221], s[36:37], 0, v[142:143]
	global_load_lds_dwordx4 v[220:221], off
	s_waitcnt vmcnt(8)
	s_waitcnt lgkmcnt(0)
	s_barrier
	s_setprio 1
	s_waitcnt lgkmcnt(0)
	v_mfma_f32_16x16x32_bf16 v[124:127], v[148:151], v[188:191], v[124:127]
	v_mfma_f32_16x16x32_bf16 v[120:123], v[164:167], v[188:191], v[120:123]
	v_mfma_f32_16x16x32_bf16 v[108:111], v[148:151], v[196:199], v[108:111]
	v_mfma_f32_16x16x32_bf16 v[104:107], v[164:167], v[196:199], v[104:107]
	v_mfma_f32_16x16x32_bf16 v[92:95], v[148:151], v[204:207], v[92:95]
	v_mfma_f32_16x16x32_bf16 v[88:91], v[164:167], v[204:207], v[88:91]
	v_mfma_f32_16x16x32_bf16 v[76:79], v[148:151], v[212:215], v[76:79]
	v_mfma_f32_16x16x32_bf16 v[72:75], v[164:167], v[212:215], v[72:75]
	v_mfma_f32_16x16x32_bf16 v[124:127], v[160:163], v[192:195], v[124:127]
	v_mfma_f32_16x16x32_bf16 v[120:123], v[168:171], v[192:195], v[120:123]
	v_mfma_f32_16x16x32_bf16 v[108:111], v[160:163], v[200:203], v[108:111]
	v_mfma_f32_16x16x32_bf16 v[104:107], v[168:171], v[200:203], v[104:107]
	v_mfma_f32_16x16x32_bf16 v[92:95], v[160:163], v[208:211], v[92:95]
	v_mfma_f32_16x16x32_bf16 v[88:91], v[168:171], v[208:211], v[88:91]
	v_mfma_f32_16x16x32_bf16 v[76:79], v[160:163], v[216:219], v[76:79]
	v_mfma_f32_16x16x32_bf16 v[72:75], v[168:171], v[216:219], v[72:75]
	v_mfma_f32_16x16x32_bf16 v[116:119], v[172:175], v[188:191], v[116:119]
	v_mfma_f32_16x16x32_bf16 v[112:115], v[180:183], v[188:191], v[112:115]
	v_mfma_f32_16x16x32_bf16 v[100:103], v[172:175], v[196:199], v[100:103]
	v_mfma_f32_16x16x32_bf16 v[96:99], v[180:183], v[196:199], v[96:99]
	v_mfma_f32_16x16x32_bf16 v[84:87], v[172:175], v[204:207], v[84:87]
	v_mfma_f32_16x16x32_bf16 v[80:83], v[180:183], v[204:207], v[80:83]
	v_mfma_f32_16x16x32_bf16 v[68:71], v[172:175], v[212:215], v[68:71]
	v_mfma_f32_16x16x32_bf16 v[64:67], v[180:183], v[212:215], v[64:67]
	v_mfma_f32_16x16x32_bf16 v[116:119], v[176:179], v[192:195], v[116:119]
	v_mfma_f32_16x16x32_bf16 v[112:115], v[184:187], v[192:195], v[112:115]
	v_mfma_f32_16x16x32_bf16 v[100:103], v[176:179], v[200:203], v[100:103]
	v_mfma_f32_16x16x32_bf16 v[96:99], v[184:187], v[200:203], v[96:99]
	v_mfma_f32_16x16x32_bf16 v[84:87], v[176:179], v[208:211], v[84:87]
	v_mfma_f32_16x16x32_bf16 v[80:83], v[184:187], v[208:211], v[80:83]
	v_mfma_f32_16x16x32_bf16 v[68:71], v[176:179], v[216:219], v[68:71]
	v_mfma_f32_16x16x32_bf16 v[64:67], v[184:187], v[216:219], v[64:67]
	s_setprio 0
	s_barrier
	s_add_i32 s34, s57, s48
	v_lshl_add_u64 v[220:221], s[38:39], 0, v[136:137]
	s_mov_b32 m0, s34
	ds_read_b128 v[188:191], v158 offset:16384
	ds_read_b128 v[192:195], v158 offset:17408
	ds_read_b128 v[196:199], v158 offset:18432
	ds_read_b128 v[200:203], v158 offset:19456
	ds_read_b128 v[204:207], v158 offset:20480
	ds_read_b128 v[208:211], v158 offset:21504
	ds_read_b128 v[212:215], v158 offset:22528
	ds_read_b128 v[216:219], v158 offset:23552
	global_load_lds_dwordx4 v[220:221], off
	s_add_i32 m0, s34, 0x2000
	s_add_u32 s34, s38, 0x40000
	v_lshl_add_u64 v[222:223], s[38:39], 0, v[132:133]
	s_addc_u32 s35, s39, 0
	s_add_i32 s79, s58, s48
	global_load_lds_dwordx4 v[222:223], off
	v_lshl_add_u64 v[224:225], s[34:35], 0, v[136:137]
	s_mov_b32 m0, s79
	v_lshl_add_u64 v[226:227], s[40:41], 0, v[134:135]
	global_load_lds_dwordx4 v[224:225], off
	s_add_i32 m0, s79, 0x2000
	v_lshl_add_u64 v[224:225], s[34:35], 0, v[132:133]
	global_load_lds_dwordx4 v[224:225], off
	s_mov_b32 m0, s31
	v_lshl_add_u64 v[224:225], s[40:41], 0, v[138:139]
	global_load_lds_dwordx4 v[224:225], off
	s_mov_b32 m0, s52
	s_nop 0
	global_load_lds_dwordx4 v[226:227], off
	s_waitcnt vmcnt(8)
	s_waitcnt lgkmcnt(0)
	s_barrier
	s_setprio 1
	s_waitcnt lgkmcnt(0)
	v_mfma_f32_16x16x32_bf16 v[60:63], v[148:151], v[188:191], v[60:63]
	v_mfma_f32_16x16x32_bf16 v[56:59], v[164:167], v[188:191], v[56:59]
	v_mfma_f32_16x16x32_bf16 v[44:47], v[148:151], v[196:199], v[44:47]
	v_mfma_f32_16x16x32_bf16 v[40:43], v[164:167], v[196:199], v[40:43]
	v_mfma_f32_16x16x32_bf16 v[28:31], v[148:151], v[204:207], v[28:31]
	v_mfma_f32_16x16x32_bf16 v[24:27], v[164:167], v[204:207], v[24:27]
	v_mfma_f32_16x16x32_bf16 v[12:15], v[148:151], v[212:215], v[12:15]
	v_mfma_f32_16x16x32_bf16 v[8:11], v[164:167], v[212:215], v[8:11]
	v_mfma_f32_16x16x32_bf16 v[60:63], v[160:163], v[192:195], v[60:63]
	v_mfma_f32_16x16x32_bf16 v[56:59], v[168:171], v[192:195], v[56:59]
	v_mfma_f32_16x16x32_bf16 v[44:47], v[160:163], v[200:203], v[44:47]
	v_mfma_f32_16x16x32_bf16 v[40:43], v[168:171], v[200:203], v[40:43]
	v_mfma_f32_16x16x32_bf16 v[28:31], v[160:163], v[208:211], v[28:31]
	v_mfma_f32_16x16x32_bf16 v[24:27], v[168:171], v[208:211], v[24:27]
	v_mfma_f32_16x16x32_bf16 v[12:15], v[160:163], v[216:219], v[12:15]
	v_mfma_f32_16x16x32_bf16 v[8:11], v[168:171], v[216:219], v[8:11]
	v_mfma_f32_16x16x32_bf16 v[52:55], v[172:175], v[188:191], v[52:55]
	v_mfma_f32_16x16x32_bf16 v[48:51], v[180:183], v[188:191], v[48:51]
	v_mfma_f32_16x16x32_bf16 v[36:39], v[172:175], v[196:199], v[36:39]
	v_mfma_f32_16x16x32_bf16 v[32:35], v[180:183], v[196:199], v[32:35]
	v_mfma_f32_16x16x32_bf16 v[20:23], v[172:175], v[204:207], v[20:23]
	v_mfma_f32_16x16x32_bf16 v[16:19], v[180:183], v[204:207], v[16:19]
	v_mfma_f32_16x16x32_bf16 v[4:7], v[172:175], v[212:215], v[4:7]
	v_mfma_f32_16x16x32_bf16 v[0:3], v[180:183], v[212:215], v[0:3]
	v_mfma_f32_16x16x32_bf16 v[52:55], v[176:179], v[192:195], v[52:55]
	v_mfma_f32_16x16x32_bf16 v[48:51], v[184:187], v[192:195], v[48:51]
	v_mfma_f32_16x16x32_bf16 v[36:39], v[176:179], v[200:203], v[36:39]
	v_mfma_f32_16x16x32_bf16 v[32:35], v[184:187], v[200:203], v[32:35]
	v_mfma_f32_16x16x32_bf16 v[20:23], v[176:179], v[208:211], v[20:23]
	v_mfma_f32_16x16x32_bf16 v[16:19], v[184:187], v[208:211], v[16:19]
	v_mfma_f32_16x16x32_bf16 v[4:7], v[176:179], v[216:219], v[4:7]
	v_mfma_f32_16x16x32_bf16 v[0:3], v[184:187], v[216:219], v[0:3]
	s_setprio 0
	s_barrier
	s_add_i32 s79, 0, 0x18000
	v_add_u32_e32 v159, s79, v152
	s_add_i32 s81, 0, 0x1c000
	ds_read_b128 v[148:151], v159
	ds_read_b128 v[160:163], v159 offset:1024
	ds_read_b128 v[164:167], v159 offset:2048
	ds_read_b128 v[168:171], v159 offset:3072
	v_add_u32_e32 v159, s81, v152
	ds_read_b128 v[172:175], v159
	ds_read_b128 v[176:179], v159 offset:1024
	ds_read_b128 v[180:183], v159 offset:2048
	ds_read_b128 v[184:187], v159 offset:3072
	s_add_u32 s34, s40, 0x40000
	s_addc_u32 s35, s41, 0
	s_mov_b32 m0, s53
	v_lshl_add_u64 v[228:229], s[34:35], 0, v[138:139]
	ds_read_b128 v[188:191], v158 offset:32768
	ds_read_b128 v[192:195], v158 offset:33792
	ds_read_b128 v[196:199], v158 offset:34816
	ds_read_b128 v[200:203], v158 offset:35840
	ds_read_b128 v[204:207], v158 offset:36864
	ds_read_b128 v[208:211], v158 offset:37888
	ds_read_b128 v[212:215], v158 offset:38912
	ds_read_b128 v[216:219], v158 offset:39936
	global_load_lds_dwordx4 v[228:229], off
	s_mov_b32 m0, s54
	v_lshl_add_u64 v[228:229], s[34:35], 0, v[134:135]
	global_load_lds_dwordx4 v[228:229], off
	s_waitcnt vmcnt(8)
	s_waitcnt lgkmcnt(0)
	s_barrier
	s_setprio 1
	s_waitcnt lgkmcnt(0)
	v_mfma_f32_16x16x32_bf16 v[124:127], v[148:151], v[188:191], v[124:127]
	v_mfma_f32_16x16x32_bf16 v[120:123], v[164:167], v[188:191], v[120:123]
	v_mfma_f32_16x16x32_bf16 v[108:111], v[148:151], v[196:199], v[108:111]
	v_mfma_f32_16x16x32_bf16 v[104:107], v[164:167], v[196:199], v[104:107]
	v_mfma_f32_16x16x32_bf16 v[92:95], v[148:151], v[204:207], v[92:95]
	v_mfma_f32_16x16x32_bf16 v[88:91], v[164:167], v[204:207], v[88:91]
	v_mfma_f32_16x16x32_bf16 v[76:79], v[148:151], v[212:215], v[76:79]
	v_mfma_f32_16x16x32_bf16 v[72:75], v[164:167], v[212:215], v[72:75]
	v_mfma_f32_16x16x32_bf16 v[124:127], v[160:163], v[192:195], v[124:127]
	v_mfma_f32_16x16x32_bf16 v[120:123], v[168:171], v[192:195], v[120:123]
	v_mfma_f32_16x16x32_bf16 v[108:111], v[160:163], v[200:203], v[108:111]
	v_mfma_f32_16x16x32_bf16 v[104:107], v[168:171], v[200:203], v[104:107]
	v_mfma_f32_16x16x32_bf16 v[92:95], v[160:163], v[208:211], v[92:95]
	v_mfma_f32_16x16x32_bf16 v[88:91], v[168:171], v[208:211], v[88:91]
	v_mfma_f32_16x16x32_bf16 v[76:79], v[160:163], v[216:219], v[76:79]
	v_mfma_f32_16x16x32_bf16 v[72:75], v[168:171], v[216:219], v[72:75]
	v_mfma_f32_16x16x32_bf16 v[116:119], v[172:175], v[188:191], v[116:119]
	v_mfma_f32_16x16x32_bf16 v[112:115], v[180:183], v[188:191], v[112:115]
	v_mfma_f32_16x16x32_bf16 v[100:103], v[172:175], v[196:199], v[100:103]
	v_mfma_f32_16x16x32_bf16 v[96:99], v[180:183], v[196:199], v[96:99]
	v_mfma_f32_16x16x32_bf16 v[84:87], v[172:175], v[204:207], v[84:87]
	v_mfma_f32_16x16x32_bf16 v[80:83], v[180:183], v[204:207], v[80:83]
	v_mfma_f32_16x16x32_bf16 v[68:71], v[172:175], v[212:215], v[68:71]
	v_mfma_f32_16x16x32_bf16 v[64:67], v[180:183], v[212:215], v[64:67]
	v_mfma_f32_16x16x32_bf16 v[116:119], v[176:179], v[192:195], v[116:119]
	v_mfma_f32_16x16x32_bf16 v[112:115], v[184:187], v[192:195], v[112:115]
	v_mfma_f32_16x16x32_bf16 v[100:103], v[176:179], v[200:203], v[100:103]
	v_mfma_f32_16x16x32_bf16 v[96:99], v[184:187], v[200:203], v[96:99]
	v_mfma_f32_16x16x32_bf16 v[84:87], v[176:179], v[208:211], v[84:87]
	v_mfma_f32_16x16x32_bf16 v[80:83], v[184:187], v[208:211], v[80:83]
	v_mfma_f32_16x16x32_bf16 v[68:71], v[176:179], v[216:219], v[68:71]
	v_mfma_f32_16x16x32_bf16 v[64:67], v[184:187], v[216:219], v[64:67]
	s_setprio 0
	s_barrier
	s_add_i32 s34, s79, s48
	v_lshl_add_u64 v[220:221], v[220:221], 0, s[6:7]
	s_mov_b32 m0, s34
	ds_read_b128 v[188:191], v158 offset:49152
	ds_read_b128 v[192:195], v158 offset:50176
	ds_read_b128 v[196:199], v158 offset:51200
	ds_read_b128 v[200:203], v158 offset:52224
	ds_read_b128 v[204:207], v158 offset:53248
	ds_read_b128 v[208:211], v158 offset:54272
	ds_read_b128 v[212:215], v158 offset:55296
	ds_read_b128 v[216:219], v158 offset:56320
	global_load_lds_dwordx4 v[220:221], off
	s_add_i32 m0, s34, 0x2000
	s_add_u32 s34, s38, 0x40080
	v_lshl_add_u64 v[220:221], v[222:223], 0, s[6:7]
	s_addc_u32 s35, s39, 0
	s_add_i32 s38, s81, s48
	global_load_lds_dwordx4 v[220:221], off
	s_mov_b32 m0, s38
	v_lshl_add_u64 v[220:221], s[34:35], 0, v[136:137]
	global_load_lds_dwordx4 v[220:221], off
	s_add_i32 m0, s38, 0x2000
	v_lshl_add_u64 v[220:221], s[34:35], 0, v[132:133]
	global_load_lds_dwordx4 v[220:221], off
	s_mov_b32 m0, s55
	v_lshl_add_u64 v[220:221], v[224:225], 0, s[6:7]
	global_load_lds_dwordx4 v[220:221], off
	s_mov_b32 m0, s56
	v_lshl_add_u64 v[220:221], v[226:227], 0, s[6:7]
	global_load_lds_dwordx4 v[220:221], off
	s_waitcnt vmcnt(8)
	s_waitcnt lgkmcnt(0)
	s_barrier
	s_setprio 1
	s_waitcnt lgkmcnt(0)
	v_mfma_f32_16x16x32_bf16 v[60:63], v[148:151], v[188:191], v[60:63]
	v_mfma_f32_16x16x32_bf16 v[56:59], v[164:167], v[188:191], v[56:59]
	v_mfma_f32_16x16x32_bf16 v[44:47], v[148:151], v[196:199], v[44:47]
	v_mfma_f32_16x16x32_bf16 v[40:43], v[164:167], v[196:199], v[40:43]
	v_mfma_f32_16x16x32_bf16 v[28:31], v[148:151], v[204:207], v[28:31]
	v_mfma_f32_16x16x32_bf16 v[24:27], v[164:167], v[204:207], v[24:27]
	v_mfma_f32_16x16x32_bf16 v[12:15], v[148:151], v[212:215], v[12:15]
	v_mfma_f32_16x16x32_bf16 v[8:11], v[164:167], v[212:215], v[8:11]
	v_mfma_f32_16x16x32_bf16 v[60:63], v[160:163], v[192:195], v[60:63]
	v_mfma_f32_16x16x32_bf16 v[56:59], v[168:171], v[192:195], v[56:59]
	v_mfma_f32_16x16x32_bf16 v[44:47], v[160:163], v[200:203], v[44:47]
	v_mfma_f32_16x16x32_bf16 v[40:43], v[168:171], v[200:203], v[40:43]
	v_mfma_f32_16x16x32_bf16 v[28:31], v[160:163], v[208:211], v[28:31]
	v_mfma_f32_16x16x32_bf16 v[24:27], v[168:171], v[208:211], v[24:27]
	v_mfma_f32_16x16x32_bf16 v[12:15], v[160:163], v[216:219], v[12:15]
	v_mfma_f32_16x16x32_bf16 v[8:11], v[168:171], v[216:219], v[8:11]
	v_mfma_f32_16x16x32_bf16 v[52:55], v[172:175], v[188:191], v[52:55]
	v_mfma_f32_16x16x32_bf16 v[48:51], v[180:183], v[188:191], v[48:51]
	v_mfma_f32_16x16x32_bf16 v[36:39], v[172:175], v[196:199], v[36:39]
	v_mfma_f32_16x16x32_bf16 v[32:35], v[180:183], v[196:199], v[32:35]
	v_mfma_f32_16x16x32_bf16 v[20:23], v[172:175], v[204:207], v[20:23]
	v_mfma_f32_16x16x32_bf16 v[16:19], v[180:183], v[204:207], v[16:19]
	v_mfma_f32_16x16x32_bf16 v[4:7], v[172:175], v[212:215], v[4:7]
	v_mfma_f32_16x16x32_bf16 v[0:3], v[180:183], v[212:215], v[0:3]
	v_mfma_f32_16x16x32_bf16 v[52:55], v[176:179], v[192:195], v[52:55]
	v_mfma_f32_16x16x32_bf16 v[48:51], v[184:187], v[192:195], v[48:51]
	v_mfma_f32_16x16x32_bf16 v[36:39], v[176:179], v[200:203], v[36:39]
	v_mfma_f32_16x16x32_bf16 v[32:35], v[184:187], v[200:203], v[32:35]
	v_mfma_f32_16x16x32_bf16 v[20:23], v[176:179], v[208:211], v[20:23]
	v_mfma_f32_16x16x32_bf16 v[16:19], v[184:187], v[208:211], v[16:19]
	v_mfma_f32_16x16x32_bf16 v[4:7], v[176:179], v[216:219], v[4:7]
	v_mfma_f32_16x16x32_bf16 v[0:3], v[184:187], v[216:219], v[0:3]
	s_setprio 0
	s_cmp_eq_u32 s77, s98
	s_cbranch_scc1 .Lmy_nobar_10
	s_barrier

.Lmy_nobar2_11:
	ds_read_b128 v[148:151], v154
	ds_read_b128 v[160:163], v154 offset:1024
	ds_read_b128 v[164:167], v154 offset:2048
	ds_read_b128 v[168:171], v154 offset:3072
	ds_read_b128 v[172:175], v155
	ds_read_b128 v[176:179], v155 offset:1024
	ds_read_b128 v[180:183], v155 offset:2048
	ds_read_b128 v[184:187], v155 offset:3072
	s_add_u32 s34, s30, 0xfff50080
	s_addc_u32 s35, s31, -1
	s_cmp_eq_u32 s64, 40
	s_cselect_b32 s39, s1, s35
	s_cselect_b32 s38, s0, s34
	s_cselect_b32 s37, s29, s63
	s_cselect_b32 s36, s28, s13
	v_lshl_add_u64 v[220:221], s[30:31], 0, v[140:141]
	s_add_i32 m0, s42, 0xc000
	ds_read_b128 v[188:191], v157
	ds_read_b128 v[192:195], v157 offset:1024
	ds_read_b128 v[196:199], v157 offset:2048
	ds_read_b128 v[200:203], v157 offset:3072
	ds_read_b128 v[204:207], v157 offset:4096
	ds_read_b128 v[208:211], v157 offset:5120
	ds_read_b128 v[212:215], v157 offset:6144
	ds_read_b128 v[216:219], v157 offset:7168
	global_load_lds_dwordx4 v[220:221], off
	s_add_i32 m0, s42, 0xe000
	v_lshl_add_u64 v[220:221], s[30:31], 0, v[142:143]
	global_load_lds_dwordx4 v[220:221], off
	s_waitcnt vmcnt(8)
	s_waitcnt lgkmcnt(0)
	s_barrier
	s_setprio 1
	s_waitcnt lgkmcnt(0)
	v_mfma_f32_16x16x32_bf16 v[124:127], v[148:151], v[188:191], 0
	v_mfma_f32_16x16x32_bf16 v[120:123], v[164:167], v[188:191], 0
	v_mfma_f32_16x16x32_bf16 v[108:111], v[148:151], v[196:199], 0
	v_mfma_f32_16x16x32_bf16 v[104:107], v[164:167], v[196:199], 0
	v_mfma_f32_16x16x32_bf16 v[92:95], v[148:151], v[204:207], 0
	v_mfma_f32_16x16x32_bf16 v[88:91], v[164:167], v[204:207], 0
	v_mfma_f32_16x16x32_bf16 v[76:79], v[148:151], v[212:215], 0
	v_mfma_f32_16x16x32_bf16 v[72:75], v[164:167], v[212:215], 0
	v_mfma_f32_16x16x32_bf16 v[124:127], v[160:163], v[192:195], v[124:127]
	v_mfma_f32_16x16x32_bf16 v[120:123], v[168:171], v[192:195], v[120:123]
	v_mfma_f32_16x16x32_bf16 v[108:111], v[160:163], v[200:203], v[108:111]
	v_mfma_f32_16x16x32_bf16 v[104:107], v[168:171], v[200:203], v[104:107]
	v_mfma_f32_16x16x32_bf16 v[92:95], v[160:163], v[208:211], v[92:95]
	v_mfma_f32_16x16x32_bf16 v[88:91], v[168:171], v[208:211], v[88:91]
	v_mfma_f32_16x16x32_bf16 v[76:79], v[160:163], v[216:219], v[76:79]
	v_mfma_f32_16x16x32_bf16 v[72:75], v[168:171], v[216:219], v[72:75]
	v_mfma_f32_16x16x32_bf16 v[116:119], v[172:175], v[188:191], 0
	v_mfma_f32_16x16x32_bf16 v[112:115], v[180:183], v[188:191], 0
	v_mfma_f32_16x16x32_bf16 v[100:103], v[172:175], v[196:199], 0
	v_mfma_f32_16x16x32_bf16 v[96:99], v[180:183], v[196:199], 0
	v_mfma_f32_16x16x32_bf16 v[84:87], v[172:175], v[204:207], 0
	v_mfma_f32_16x16x32_bf16 v[80:83], v[180:183], v[204:207], 0
	v_mfma_f32_16x16x32_bf16 v[68:71], v[172:175], v[212:215], 0
	v_mfma_f32_16x16x32_bf16 v[64:67], v[180:183], v[212:215], 0
	v_mfma_f32_16x16x32_bf16 v[116:119], v[176:179], v[192:195], v[116:119]
	v_mfma_f32_16x16x32_bf16 v[112:115], v[184:187], v[192:195], v[112:115]
	v_mfma_f32_16x16x32_bf16 v[100:103], v[176:179], v[200:203], v[100:103]
	v_mfma_f32_16x16x32_bf16 v[96:99], v[184:187], v[200:203], v[96:99]
	v_mfma_f32_16x16x32_bf16 v[84:87], v[176:179], v[208:211], v[84:87]
	v_mfma_f32_16x16x32_bf16 v[80:83], v[184:187], v[208:211], v[80:83]
	v_mfma_f32_16x16x32_bf16 v[68:71], v[176:179], v[216:219], v[68:71]
	v_mfma_f32_16x16x32_bf16 v[64:67], v[184:187], v[216:219], v[64:67]
	s_setprio 0
	s_barrier
	s_add_i32 s34, s56, s41
	v_lshl_add_u64 v[220:221], s[36:37], 0, v[134:135]
	s_mov_b32 m0, s34
	ds_read_b128 v[188:191], v157 offset:16384
	ds_read_b128 v[192:195], v157 offset:17408
	ds_read_b128 v[196:199], v157 offset:18432
	ds_read_b128 v[200:203], v157 offset:19456
	ds_read_b128 v[204:207], v157 offset:20480
	ds_read_b128 v[208:211], v157 offset:21504
	ds_read_b128 v[212:215], v157 offset:22528
	ds_read_b128 v[216:219], v157 offset:23552
	global_load_lds_dwordx4 v[220:221], off
	s_add_i32 m0, s34, 0x2000
	s_add_u32 s34, s36, 0xb0000
	v_lshl_add_u64 v[222:223], s[36:37], 0, v[138:139]
	s_addc_u32 s35, s37, 0
	s_add_i32 s65, s57, s41
	global_load_lds_dwordx4 v[222:223], off
	v_lshl_add_u64 v[224:225], s[34:35], 0, v[134:135]
	s_mov_b32 m0, s65
	v_lshl_add_u64 v[226:227], s[38:39], 0, v[136:137]
	global_load_lds_dwordx4 v[224:225], off
	s_add_i32 m0, s65, 0x2000
	v_lshl_add_u64 v[224:225], s[34:35], 0, v[138:139]
	global_load_lds_dwordx4 v[224:225], off
	s_mov_b32 m0, s42
	v_lshl_add_u64 v[224:225], s[38:39], 0, v[132:133]
	global_load_lds_dwordx4 v[224:225], off
	s_mov_b32 m0, s43
	s_nop 0
	global_load_lds_dwordx4 v[226:227], off
	s_waitcnt vmcnt(8)
	s_waitcnt lgkmcnt(0)
	s_barrier
	s_setprio 1
	s_waitcnt lgkmcnt(0)
	v_mfma_f32_16x16x32_bf16 v[60:63], v[148:151], v[188:191], 0
	v_mfma_f32_16x16x32_bf16 v[56:59], v[164:167], v[188:191], 0
	v_mfma_f32_16x16x32_bf16 v[44:47], v[148:151], v[196:199], 0
	v_mfma_f32_16x16x32_bf16 v[40:43], v[164:167], v[196:199], 0
	v_mfma_f32_16x16x32_bf16 v[28:31], v[148:151], v[204:207], 0
	v_mfma_f32_16x16x32_bf16 v[24:27], v[164:167], v[204:207], 0
	v_mfma_f32_16x16x32_bf16 v[12:15], v[148:151], v[212:215], 0
	v_mfma_f32_16x16x32_bf16 v[8:11], v[164:167], v[212:215], 0
	v_mfma_f32_16x16x32_bf16 v[60:63], v[160:163], v[192:195], v[60:63]
	v_mfma_f32_16x16x32_bf16 v[56:59], v[168:171], v[192:195], v[56:59]
	v_mfma_f32_16x16x32_bf16 v[44:47], v[160:163], v[200:203], v[44:47]
	v_mfma_f32_16x16x32_bf16 v[40:43], v[168:171], v[200:203], v[40:43]
	v_mfma_f32_16x16x32_bf16 v[28:31], v[160:163], v[208:211], v[28:31]
	v_mfma_f32_16x16x32_bf16 v[24:27], v[168:171], v[208:211], v[24:27]
	v_mfma_f32_16x16x32_bf16 v[12:15], v[160:163], v[216:219], v[12:15]
	v_mfma_f32_16x16x32_bf16 v[8:11], v[168:171], v[216:219], v[8:11]
	v_mfma_f32_16x16x32_bf16 v[52:55], v[172:175], v[188:191], 0
	v_mfma_f32_16x16x32_bf16 v[48:51], v[180:183], v[188:191], 0
	v_mfma_f32_16x16x32_bf16 v[36:39], v[172:175], v[196:199], 0
	v_mfma_f32_16x16x32_bf16 v[32:35], v[180:183], v[196:199], 0
	v_mfma_f32_16x16x32_bf16 v[20:23], v[172:175], v[204:207], 0
	v_mfma_f32_16x16x32_bf16 v[16:19], v[180:183], v[204:207], 0
	v_mfma_f32_16x16x32_bf16 v[4:7], v[172:175], v[212:215], 0
	v_mfma_f32_16x16x32_bf16 v[0:3], v[180:183], v[212:215], 0
	v_mfma_f32_16x16x32_bf16 v[52:55], v[176:179], v[192:195], v[52:55]
	v_mfma_f32_16x16x32_bf16 v[48:51], v[184:187], v[192:195], v[48:51]
	v_mfma_f32_16x16x32_bf16 v[36:39], v[176:179], v[200:203], v[36:39]
	v_mfma_f32_16x16x32_bf16 v[32:35], v[184:187], v[200:203], v[32:35]
	v_mfma_f32_16x16x32_bf16 v[20:23], v[176:179], v[208:211], v[20:23]
	v_mfma_f32_16x16x32_bf16 v[16:19], v[184:187], v[208:211], v[16:19]
	v_mfma_f32_16x16x32_bf16 v[4:7], v[176:179], v[216:219], v[4:7]
	v_mfma_f32_16x16x32_bf16 v[0:3], v[184:187], v[216:219], v[0:3]
	s_setprio 0
	s_barrier
	s_add_i32 s65, 0, 0x18000
	v_add_u32_e32 v159, s65, v152
	s_add_i32 s66, 0, 0x1c000
	ds_read_b128 v[148:151], v159
	ds_read_b128 v[160:163], v159 offset:1024
	ds_read_b128 v[164:167], v159 offset:2048
	ds_read_b128 v[168:171], v159 offset:3072
	v_add_u32_e32 v159, s66, v152
	ds_read_b128 v[172:175], v159
	ds_read_b128 v[176:179], v159 offset:1024
	ds_read_b128 v[180:183], v159 offset:2048
	ds_read_b128 v[184:187], v159 offset:3072
	s_add_u32 s34, s38, 0xb0000
	s_addc_u32 s35, s39, 0
	s_mov_b32 m0, s48
	v_lshl_add_u64 v[228:229], s[34:35], 0, v[132:133]
	ds_read_b128 v[188:191], v157 offset:32768
	ds_read_b128 v[192:195], v157 offset:33792
	ds_read_b128 v[196:199], v157 offset:34816
	ds_read_b128 v[200:203], v157 offset:35840
	ds_read_b128 v[204:207], v157 offset:36864
	ds_read_b128 v[208:211], v157 offset:37888
	ds_read_b128 v[212:215], v157 offset:38912
	ds_read_b128 v[216:219], v157 offset:39936
	global_load_lds_dwordx4 v[228:229], off
	s_mov_b32 m0, s49
	v_lshl_add_u64 v[228:229], s[34:35], 0, v[136:137]
	global_load_lds_dwordx4 v[228:229], off
	s_waitcnt vmcnt(8)
	s_waitcnt lgkmcnt(0)
	s_barrier
	s_setprio 1
	s_waitcnt lgkmcnt(0)
	v_mfma_f32_16x16x32_bf16 v[124:127], v[148:151], v[188:191], v[124:127]
	v_mfma_f32_16x16x32_bf16 v[120:123], v[164:167], v[188:191], v[120:123]
	v_mfma_f32_16x16x32_bf16 v[108:111], v[148:151], v[196:199], v[108:111]
	v_mfma_f32_16x16x32_bf16 v[104:107], v[164:167], v[196:199], v[104:107]
	v_mfma_f32_16x16x32_bf16 v[92:95], v[148:151], v[204:207], v[92:95]
	v_mfma_f32_16x16x32_bf16 v[88:91], v[164:167], v[204:207], v[88:91]
	v_mfma_f32_16x16x32_bf16 v[76:79], v[148:151], v[212:215], v[76:79]
	v_mfma_f32_16x16x32_bf16 v[72:75], v[164:167], v[212:215], v[72:75]
	v_mfma_f32_16x16x32_bf16 v[124:127], v[160:163], v[192:195], v[124:127]
	v_mfma_f32_16x16x32_bf16 v[120:123], v[168:171], v[192:195], v[120:123]
	v_mfma_f32_16x16x32_bf16 v[108:111], v[160:163], v[200:203], v[108:111]
	v_mfma_f32_16x16x32_bf16 v[104:107], v[168:171], v[200:203], v[104:107]
	v_mfma_f32_16x16x32_bf16 v[92:95], v[160:163], v[208:211], v[92:95]
	v_mfma_f32_16x16x32_bf16 v[88:91], v[168:171], v[208:211], v[88:91]
	v_mfma_f32_16x16x32_bf16 v[76:79], v[160:163], v[216:219], v[76:79]
	v_mfma_f32_16x16x32_bf16 v[72:75], v[168:171], v[216:219], v[72:75]
	v_mfma_f32_16x16x32_bf16 v[116:119], v[172:175], v[188:191], v[116:119]
	v_mfma_f32_16x16x32_bf16 v[112:115], v[180:183], v[188:191], v[112:115]
	v_mfma_f32_16x16x32_bf16 v[100:103], v[172:175], v[196:199], v[100:103]
	v_mfma_f32_16x16x32_bf16 v[96:99], v[180:183], v[196:199], v[96:99]
	v_mfma_f32_16x16x32_bf16 v[84:87], v[172:175], v[204:207], v[84:87]
	v_mfma_f32_16x16x32_bf16 v[80:83], v[180:183], v[204:207], v[80:83]
	v_mfma_f32_16x16x32_bf16 v[68:71], v[172:175], v[212:215], v[68:71]
	v_mfma_f32_16x16x32_bf16 v[64:67], v[180:183], v[212:215], v[64:67]
	v_mfma_f32_16x16x32_bf16 v[116:119], v[176:179], v[192:195], v[116:119]
	v_mfma_f32_16x16x32_bf16 v[112:115], v[184:187], v[192:195], v[112:115]
	v_mfma_f32_16x16x32_bf16 v[100:103], v[176:179], v[200:203], v[100:103]
	v_mfma_f32_16x16x32_bf16 v[96:99], v[184:187], v[200:203], v[96:99]
	v_mfma_f32_16x16x32_bf16 v[84:87], v[176:179], v[208:211], v[84:87]
	v_mfma_f32_16x16x32_bf16 v[80:83], v[184:187], v[208:211], v[80:83]
	v_mfma_f32_16x16x32_bf16 v[68:71], v[176:179], v[216:219], v[68:71]
	v_mfma_f32_16x16x32_bf16 v[64:67], v[184:187], v[216:219], v[64:67]
	s_setprio 0
	s_barrier
	s_add_i32 s34, s65, s41
	v_lshl_add_u64 v[220:221], v[220:221], 0, s[22:23]
	s_mov_b32 m0, s34
	ds_read_b128 v[188:191], v157 offset:49152
	ds_read_b128 v[192:195], v157 offset:50176
	ds_read_b128 v[196:199], v157 offset:51200
	ds_read_b128 v[200:203], v157 offset:52224
	ds_read_b128 v[204:207], v157 offset:53248
	ds_read_b128 v[208:211], v157 offset:54272
	ds_read_b128 v[212:215], v157 offset:55296
	ds_read_b128 v[216:219], v157 offset:56320
	global_load_lds_dwordx4 v[220:221], off
	s_add_i32 m0, s34, 0x2000
	s_add_u32 s34, s36, 0xb0080
	v_lshl_add_u64 v[220:221], v[222:223], 0, s[22:23]
	s_addc_u32 s35, s37, 0
	s_add_i32 s36, s66, s41
	global_load_lds_dwordx4 v[220:221], off
	s_mov_b32 m0, s36
	v_lshl_add_u64 v[220:221], s[34:35], 0, v[134:135]
	global_load_lds_dwordx4 v[220:221], off
	s_add_i32 m0, s36, 0x2000
	v_lshl_add_u64 v[220:221], s[34:35], 0, v[138:139]
	global_load_lds_dwordx4 v[220:221], off
	s_mov_b32 m0, s51
	v_lshl_add_u64 v[220:221], v[224:225], 0, s[22:23]
	global_load_lds_dwordx4 v[220:221], off
	s_mov_b32 m0, s52
	v_lshl_add_u64 v[220:221], v[226:227], 0, s[22:23]
	global_load_lds_dwordx4 v[220:221], off
	s_waitcnt vmcnt(8)
	s_waitcnt lgkmcnt(0)
	s_barrier
	s_setprio 1
	s_waitcnt lgkmcnt(0)
	v_mfma_f32_16x16x32_bf16 v[60:63], v[148:151], v[188:191], v[60:63]
	v_mfma_f32_16x16x32_bf16 v[56:59], v[164:167], v[188:191], v[56:59]
	v_mfma_f32_16x16x32_bf16 v[44:47], v[148:151], v[196:199], v[44:47]
	v_mfma_f32_16x16x32_bf16 v[40:43], v[164:167], v[196:199], v[40:43]
	v_mfma_f32_16x16x32_bf16 v[28:31], v[148:151], v[204:207], v[28:31]
	v_mfma_f32_16x16x32_bf16 v[24:27], v[164:167], v[204:207], v[24:27]
	v_mfma_f32_16x16x32_bf16 v[12:15], v[148:151], v[212:215], v[12:15]
	v_mfma_f32_16x16x32_bf16 v[8:11], v[164:167], v[212:215], v[8:11]
	v_mfma_f32_16x16x32_bf16 v[60:63], v[160:163], v[192:195], v[60:63]
	v_mfma_f32_16x16x32_bf16 v[56:59], v[168:171], v[192:195], v[56:59]
	v_mfma_f32_16x16x32_bf16 v[44:47], v[160:163], v[200:203], v[44:47]
	v_mfma_f32_16x16x32_bf16 v[40:43], v[168:171], v[200:203], v[40:43]
	v_mfma_f32_16x16x32_bf16 v[28:31], v[160:163], v[208:211], v[28:31]
	v_mfma_f32_16x16x32_bf16 v[24:27], v[168:171], v[208:211], v[24:27]
	v_mfma_f32_16x16x32_bf16 v[12:15], v[160:163], v[216:219], v[12:15]
	v_mfma_f32_16x16x32_bf16 v[8:11], v[168:171], v[216:219], v[8:11]
	v_mfma_f32_16x16x32_bf16 v[52:55], v[172:175], v[188:191], v[52:55]
	v_mfma_f32_16x16x32_bf16 v[48:51], v[180:183], v[188:191], v[48:51]
	v_mfma_f32_16x16x32_bf16 v[36:39], v[172:175], v[196:199], v[36:39]
	v_mfma_f32_16x16x32_bf16 v[32:35], v[180:183], v[196:199], v[32:35]
	v_mfma_f32_16x16x32_bf16 v[20:23], v[172:175], v[204:207], v[20:23]
	v_mfma_f32_16x16x32_bf16 v[16:19], v[180:183], v[204:207], v[16:19]
	v_mfma_f32_16x16x32_bf16 v[4:7], v[172:175], v[212:215], v[4:7]
	v_mfma_f32_16x16x32_bf16 v[0:3], v[180:183], v[212:215], v[0:3]
	v_mfma_f32_16x16x32_bf16 v[52:55], v[176:179], v[192:195], v[52:55]
	v_mfma_f32_16x16x32_bf16 v[48:51], v[184:187], v[192:195], v[48:51]
	v_mfma_f32_16x16x32_bf16 v[36:39], v[176:179], v[200:203], v[36:39]
	v_mfma_f32_16x16x32_bf16 v[32:35], v[184:187], v[200:203], v[32:35]
	v_mfma_f32_16x16x32_bf16 v[20:23], v[176:179], v[208:211], v[20:23]
	v_mfma_f32_16x16x32_bf16 v[16:19], v[184:187], v[208:211], v[16:19]
	v_mfma_f32_16x16x32_bf16 v[4:7], v[176:179], v[216:219], v[4:7]
	v_mfma_f32_16x16x32_bf16 v[0:3], v[184:187], v[216:219], v[0:3]
	s_setprio 0
	s_barrier
	s_add_i32 s64, s64, 2
	s_add_u32 s30, s30, 0x100
	s_addc_u32 s31, s31, 0
	s_add_u32 s13, s13, 0x100
	s_addc_u32 s63, s63, 0
.LBB0_1145:
	ds_read_b128 v[148:151], v154
	ds_read_b128 v[160:163], v154 offset:1024
	ds_read_b128 v[164:167], v154 offset:2048
	ds_read_b128 v[168:171], v154 offset:3072
	ds_read_b128 v[172:175], v155
	ds_read_b128 v[176:179], v155 offset:1024
	ds_read_b128 v[180:183], v155 offset:2048
	ds_read_b128 v[184:187], v155 offset:3072
	s_add_u32 s34, s30, 0xfff50080
	s_addc_u32 s35, s31, -1
	s_cmp_eq_u32 s64, 40
	s_cselect_b32 s39, s1, s35
	s_cselect_b32 s38, s0, s34
	s_cselect_b32 s37, s29, s63
	s_cselect_b32 s36, s28, s13
	v_lshl_add_u64 v[220:221], s[30:31], 0, v[140:141]
	s_add_i32 m0, s42, 0xc000
	ds_read_b128 v[188:191], v157
	ds_read_b128 v[192:195], v157 offset:1024
	ds_read_b128 v[196:199], v157 offset:2048
	ds_read_b128 v[200:203], v157 offset:3072
	ds_read_b128 v[204:207], v157 offset:4096
	ds_read_b128 v[208:211], v157 offset:5120
	ds_read_b128 v[212:215], v157 offset:6144
	ds_read_b128 v[216:219], v157 offset:7168
	global_load_lds_dwordx4 v[220:221], off
	s_add_i32 m0, s42, 0xe000
	v_lshl_add_u64 v[220:221], s[30:31], 0, v[142:143]
	global_load_lds_dwordx4 v[220:221], off
	s_waitcnt vmcnt(8)
	s_waitcnt lgkmcnt(0)
	s_barrier
	s_setprio 1
	s_waitcnt lgkmcnt(0)
	v_mfma_f32_16x16x32_bf16 v[124:127], v[148:151], v[188:191], v[124:127]
	v_mfma_f32_16x16x32_bf16 v[120:123], v[164:167], v[188:191], v[120:123]
	v_mfma_f32_16x16x32_bf16 v[108:111], v[148:151], v[196:199], v[108:111]
	v_mfma_f32_16x16x32_bf16 v[104:107], v[164:167], v[196:199], v[104:107]
	v_mfma_f32_16x16x32_bf16 v[92:95], v[148:151], v[204:207], v[92:95]
	v_mfma_f32_16x16x32_bf16 v[88:91], v[164:167], v[204:207], v[88:91]
	v_mfma_f32_16x16x32_bf16 v[76:79], v[148:151], v[212:215], v[76:79]
	v_mfma_f32_16x16x32_bf16 v[72:75], v[164:167], v[212:215], v[72:75]
	v_mfma_f32_16x16x32_bf16 v[124:127], v[160:163], v[192:195], v[124:127]
	v_mfma_f32_16x16x32_bf16 v[120:123], v[168:171], v[192:195], v[120:123]
	v_mfma_f32_16x16x32_bf16 v[108:111], v[160:163], v[200:203], v[108:111]
	v_mfma_f32_16x16x32_bf16 v[104:107], v[168:171], v[200:203], v[104:107]
	v_mfma_f32_16x16x32_bf16 v[92:95], v[160:163], v[208:211], v[92:95]
	v_mfma_f32_16x16x32_bf16 v[88:91], v[168:171], v[208:211], v[88:91]
	v_mfma_f32_16x16x32_bf16 v[76:79], v[160:163], v[216:219], v[76:79]
	v_mfma_f32_16x16x32_bf16 v[72:75], v[168:171], v[216:219], v[72:75]
	v_mfma_f32_16x16x32_bf16 v[116:119], v[172:175], v[188:191], v[116:119]
	v_mfma_f32_16x16x32_bf16 v[112:115], v[180:183], v[188:191], v[112:115]
	v_mfma_f32_16x16x32_bf16 v[100:103], v[172:175], v[196:199], v[100:103]
	v_mfma_f32_16x16x32_bf16 v[96:99], v[180:183], v[196:199], v[96:99]
	v_mfma_f32_16x16x32_bf16 v[84:87], v[172:175], v[204:207], v[84:87]
	v_mfma_f32_16x16x32_bf16 v[80:83], v[180:183], v[204:207], v[80:83]
	v_mfma_f32_16x16x32_bf16 v[68:71], v[172:175], v[212:215], v[68:71]
	v_mfma_f32_16x16x32_bf16 v[64:67], v[180:183], v[212:215], v[64:67]
	v_mfma_f32_16x16x32_bf16 v[116:119], v[176:179], v[192:195], v[116:119]
	v_mfma_f32_16x16x32_bf16 v[112:115], v[184:187], v[192:195], v[112:115]
	v_mfma_f32_16x16x32_bf16 v[100:103], v[176:179], v[200:203], v[100:103]
	v_mfma_f32_16x16x32_bf16 v[96:99], v[184:187], v[200:203], v[96:99]
	v_mfma_f32_16x16x32_bf16 v[84:87], v[176:179], v[208:211], v[84:87]
	v_mfma_f32_16x16x32_bf16 v[80:83], v[184:187], v[208:211], v[80:83]
	v_mfma_f32_16x16x32_bf16 v[68:71], v[176:179], v[216:219], v[68:71]
	v_mfma_f32_16x16x32_bf16 v[64:67], v[184:187], v[216:219], v[64:67]
	s_setprio 0
	s_barrier
	s_add_i32 s34, s56, s41
	v_lshl_add_u64 v[220:221], s[36:37], 0, v[134:135]
	s_mov_b32 m0, s34
	ds_read_b128 v[188:191], v157 offset:16384
	ds_read_b128 v[192:195], v157 offset:17408
	ds_read_b128 v[196:199], v157 offset:18432
	ds_read_b128 v[200:203], v157 offset:19456
	ds_read_b128 v[204:207], v157 offset:20480
	ds_read_b128 v[208:211], v157 offset:21504
	ds_read_b128 v[212:215], v157 offset:22528
	ds_read_b128 v[216:219], v157 offset:23552
	global_load_lds_dwordx4 v[220:221], off
	s_add_i32 m0, s34, 0x2000
	s_add_u32 s34, s36, 0xb0000
	v_lshl_add_u64 v[222:223], s[36:37], 0, v[138:139]
	s_addc_u32 s35, s37, 0
	s_add_i32 s65, s57, s41
	global_load_lds_dwordx4 v[222:223], off
	v_lshl_add_u64 v[224:225], s[34:35], 0, v[134:135]
	s_mov_b32 m0, s65
	v_lshl_add_u64 v[226:227], s[38:39], 0, v[136:137]
	global_load_lds_dwordx4 v[224:225], off
	s_add_i32 m0, s65, 0x2000
	v_lshl_add_u64 v[224:225], s[34:35], 0, v[138:139]
	global_load_lds_dwordx4 v[224:225], off
	s_mov_b32 m0, s42
	v_lshl_add_u64 v[224:225], s[38:39], 0, v[132:133]
	global_load_lds_dwordx4 v[224:225], off
	s_mov_b32 m0, s43
	s_nop 0
	global_load_lds_dwordx4 v[226:227], off
	s_waitcnt vmcnt(8)
	s_waitcnt lgkmcnt(0)
	s_barrier
	s_setprio 1
	s_waitcnt lgkmcnt(0)
	v_mfma_f32_16x16x32_bf16 v[60:63], v[148:151], v[188:191], v[60:63]
	v_mfma_f32_16x16x32_bf16 v[56:59], v[164:167], v[188:191], v[56:59]
	v_mfma_f32_16x16x32_bf16 v[44:47], v[148:151], v[196:199], v[44:47]
	v_mfma_f32_16x16x32_bf16 v[40:43], v[164:167], v[196:199], v[40:43]
	v_mfma_f32_16x16x32_bf16 v[28:31], v[148:151], v[204:207], v[28:31]
	v_mfma_f32_16x16x32_bf16 v[24:27], v[164:167], v[204:207], v[24:27]
	v_mfma_f32_16x16x32_bf16 v[12:15], v[148:151], v[212:215], v[12:15]
	v_mfma_f32_16x16x32_bf16 v[8:11], v[164:167], v[212:215], v[8:11]
	v_mfma_f32_16x16x32_bf16 v[60:63], v[160:163], v[192:195], v[60:63]
	v_mfma_f32_16x16x32_bf16 v[56:59], v[168:171], v[192:195], v[56:59]
	v_mfma_f32_16x16x32_bf16 v[44:47], v[160:163], v[200:203], v[44:47]
	v_mfma_f32_16x16x32_bf16 v[40:43], v[168:171], v[200:203], v[40:43]
	v_mfma_f32_16x16x32_bf16 v[28:31], v[160:163], v[208:211], v[28:31]
	v_mfma_f32_16x16x32_bf16 v[24:27], v[168:171], v[208:211], v[24:27]
	v_mfma_f32_16x16x32_bf16 v[12:15], v[160:163], v[216:219], v[12:15]
	v_mfma_f32_16x16x32_bf16 v[8:11], v[168:171], v[216:219], v[8:11]
	v_mfma_f32_16x16x32_bf16 v[52:55], v[172:175], v[188:191], v[52:55]
	v_mfma_f32_16x16x32_bf16 v[48:51], v[180:183], v[188:191], v[48:51]
	v_mfma_f32_16x16x32_bf16 v[36:39], v[172:175], v[196:199], v[36:39]
	v_mfma_f32_16x16x32_bf16 v[32:35], v[180:183], v[196:199], v[32:35]
	v_mfma_f32_16x16x32_bf16 v[20:23], v[172:175], v[204:207], v[20:23]
	v_mfma_f32_16x16x32_bf16 v[16:19], v[180:183], v[204:207], v[16:19]
	v_mfma_f32_16x16x32_bf16 v[4:7], v[172:175], v[212:215], v[4:7]
	v_mfma_f32_16x16x32_bf16 v[0:3], v[180:183], v[212:215], v[0:3]
	v_mfma_f32_16x16x32_bf16 v[52:55], v[176:179], v[192:195], v[52:55]
	v_mfma_f32_16x16x32_bf16 v[48:51], v[184:187], v[192:195], v[48:51]
	v_mfma_f32_16x16x32_bf16 v[36:39], v[176:179], v[200:203], v[36:39]
	v_mfma_f32_16x16x32_bf16 v[32:35], v[184:187], v[200:203], v[32:35]
	v_mfma_f32_16x16x32_bf16 v[20:23], v[176:179], v[208:211], v[20:23]
	v_mfma_f32_16x16x32_bf16 v[16:19], v[184:187], v[208:211], v[16:19]
	v_mfma_f32_16x16x32_bf16 v[4:7], v[176:179], v[216:219], v[4:7]
	v_mfma_f32_16x16x32_bf16 v[0:3], v[184:187], v[216:219], v[0:3]
	s_setprio 0
	s_barrier
	s_add_i32 s65, 0, 0x18000
	v_add_u32_e32 v159, s65, v152
	s_add_i32 s66, 0, 0x1c000
	ds_read_b128 v[148:151], v159
	ds_read_b128 v[160:163], v159 offset:1024
	ds_read_b128 v[164:167], v159 offset:2048
	ds_read_b128 v[168:171], v159 offset:3072
	v_add_u32_e32 v159, s66, v152
	ds_read_b128 v[172:175], v159
	ds_read_b128 v[176:179], v159 offset:1024
	ds_read_b128 v[180:183], v159 offset:2048
	ds_read_b128 v[184:187], v159 offset:3072
	s_add_u32 s34, s38, 0xb0000
	s_addc_u32 s35, s39, 0
	s_mov_b32 m0, s48
	v_lshl_add_u64 v[228:229], s[34:35], 0, v[132:133]
	ds_read_b128 v[188:191], v157 offset:32768
	ds_read_b128 v[192:195], v157 offset:33792
	ds_read_b128 v[196:199], v157 offset:34816
	ds_read_b128 v[200:203], v157 offset:35840
	ds_read_b128 v[204:207], v157 offset:36864
	ds_read_b128 v[208:211], v157 offset:37888
	ds_read_b128 v[212:215], v157 offset:38912
	ds_read_b128 v[216:219], v157 offset:39936
	global_load_lds_dwordx4 v[228:229], off
	s_mov_b32 m0, s49
	v_lshl_add_u64 v[228:229], s[34:35], 0, v[136:137]
	global_load_lds_dwordx4 v[228:229], off
	s_waitcnt vmcnt(8)
	s_waitcnt lgkmcnt(0)
	s_barrier
	s_setprio 1
	s_waitcnt lgkmcnt(0)
	v_mfma_f32_16x16x32_bf16 v[124:127], v[148:151], v[188:191], v[124:127]
	v_mfma_f32_16x16x32_bf16 v[120:123], v[164:167], v[188:191], v[120:123]
	v_mfma_f32_16x16x32_bf16 v[108:111], v[148:151], v[196:199], v[108:111]
	v_mfma_f32_16x16x32_bf16 v[104:107], v[164:167], v[196:199], v[104:107]
	v_mfma_f32_16x16x32_bf16 v[92:95], v[148:151], v[204:207], v[92:95]
	v_mfma_f32_16x16x32_bf16 v[88:91], v[164:167], v[204:207], v[88:91]
	v_mfma_f32_16x16x32_bf16 v[76:79], v[148:151], v[212:215], v[76:79]
	v_mfma_f32_16x16x32_bf16 v[72:75], v[164:167], v[212:215], v[72:75]
	v_mfma_f32_16x16x32_bf16 v[124:127], v[160:163], v[192:195], v[124:127]
	v_mfma_f32_16x16x32_bf16 v[120:123], v[168:171], v[192:195], v[120:123]
	v_mfma_f32_16x16x32_bf16 v[108:111], v[160:163], v[200:203], v[108:111]
	v_mfma_f32_16x16x32_bf16 v[104:107], v[168:171], v[200:203], v[104:107]
	v_mfma_f32_16x16x32_bf16 v[92:95], v[160:163], v[208:211], v[92:95]
	v_mfma_f32_16x16x32_bf16 v[88:91], v[168:171], v[208:211], v[88:91]
	v_mfma_f32_16x16x32_bf16 v[76:79], v[160:163], v[216:219], v[76:79]
	v_mfma_f32_16x16x32_bf16 v[72:75], v[168:171], v[216:219], v[72:75]
	v_mfma_f32_16x16x32_bf16 v[116:119], v[172:175], v[188:191], v[116:119]
	v_mfma_f32_16x16x32_bf16 v[112:115], v[180:183], v[188:191], v[112:115]
	v_mfma_f32_16x16x32_bf16 v[100:103], v[172:175], v[196:199], v[100:103]
	v_mfma_f32_16x16x32_bf16 v[96:99], v[180:183], v[196:199], v[96:99]
	v_mfma_f32_16x16x32_bf16 v[84:87], v[172:175], v[204:207], v[84:87]
	v_mfma_f32_16x16x32_bf16 v[80:83], v[180:183], v[204:207], v[80:83]
	v_mfma_f32_16x16x32_bf16 v[68:71], v[172:175], v[212:215], v[68:71]
	v_mfma_f32_16x16x32_bf16 v[64:67], v[180:183], v[212:215], v[64:67]
	v_mfma_f32_16x16x32_bf16 v[116:119], v[176:179], v[192:195], v[116:119]
	v_mfma_f32_16x16x32_bf16 v[112:115], v[184:187], v[192:195], v[112:115]
	v_mfma_f32_16x16x32_bf16 v[100:103], v[176:179], v[200:203], v[100:103]
	v_mfma_f32_16x16x32_bf16 v[96:99], v[184:187], v[200:203], v[96:99]
	v_mfma_f32_16x16x32_bf16 v[84:87], v[176:179], v[208:211], v[84:87]
	v_mfma_f32_16x16x32_bf16 v[80:83], v[184:187], v[208:211], v[80:83]
	v_mfma_f32_16x16x32_bf16 v[68:71], v[176:179], v[216:219], v[68:71]
	v_mfma_f32_16x16x32_bf16 v[64:67], v[184:187], v[216:219], v[64:67]
	s_setprio 0
	s_barrier
	s_add_i32 s34, s65, s41
	v_lshl_add_u64 v[220:221], v[220:221], 0, s[22:23]
	s_mov_b32 m0, s34
	ds_read_b128 v[188:191], v157 offset:49152
	ds_read_b128 v[192:195], v157 offset:50176
	ds_read_b128 v[196:199], v157 offset:51200
	ds_read_b128 v[200:203], v157 offset:52224
	ds_read_b128 v[204:207], v157 offset:53248
	ds_read_b128 v[208:211], v157 offset:54272
	ds_read_b128 v[212:215], v157 offset:55296
	ds_read_b128 v[216:219], v157 offset:56320
	global_load_lds_dwordx4 v[220:221], off
	s_add_i32 m0, s34, 0x2000
	s_add_u32 s34, s36, 0xb0080
	v_lshl_add_u64 v[220:221], v[222:223], 0, s[22:23]
	s_addc_u32 s35, s37, 0
	s_add_i32 s36, s66, s41
	global_load_lds_dwordx4 v[220:221], off
	s_mov_b32 m0, s36
	v_lshl_add_u64 v[220:221], s[34:35], 0, v[134:135]
	global_load_lds_dwordx4 v[220:221], off
	s_add_i32 m0, s36, 0x2000
	v_lshl_add_u64 v[220:221], s[34:35], 0, v[138:139]
	global_load_lds_dwordx4 v[220:221], off
	s_mov_b32 m0, s51
	v_lshl_add_u64 v[220:221], v[224:225], 0, s[22:23]
	global_load_lds_dwordx4 v[220:221], off
	s_mov_b32 m0, s52
	v_lshl_add_u64 v[220:221], v[226:227], 0, s[22:23]
	global_load_lds_dwordx4 v[220:221], off
	s_waitcnt vmcnt(8)
	s_waitcnt lgkmcnt(0)
	s_barrier
	s_setprio 1
	s_waitcnt lgkmcnt(0)
	v_mfma_f32_16x16x32_bf16 v[60:63], v[148:151], v[188:191], v[60:63]
	v_mfma_f32_16x16x32_bf16 v[56:59], v[164:167], v[188:191], v[56:59]
	v_mfma_f32_16x16x32_bf16 v[44:47], v[148:151], v[196:199], v[44:47]
	v_mfma_f32_16x16x32_bf16 v[40:43], v[164:167], v[196:199], v[40:43]
	v_mfma_f32_16x16x32_bf16 v[28:31], v[148:151], v[204:207], v[28:31]
	v_mfma_f32_16x16x32_bf16 v[24:27], v[164:167], v[204:207], v[24:27]
	v_mfma_f32_16x16x32_bf16 v[12:15], v[148:151], v[212:215], v[12:15]
	v_mfma_f32_16x16x32_bf16 v[8:11], v[164:167], v[212:215], v[8:11]
	v_mfma_f32_16x16x32_bf16 v[60:63], v[160:163], v[192:195], v[60:63]
	v_mfma_f32_16x16x32_bf16 v[56:59], v[168:171], v[192:195], v[56:59]
	v_mfma_f32_16x16x32_bf16 v[44:47], v[160:163], v[200:203], v[44:47]
	v_mfma_f32_16x16x32_bf16 v[40:43], v[168:171], v[200:203], v[40:43]
	v_mfma_f32_16x16x32_bf16 v[28:31], v[160:163], v[208:211], v[28:31]
	v_mfma_f32_16x16x32_bf16 v[24:27], v[168:171], v[208:211], v[24:27]
	v_mfma_f32_16x16x32_bf16 v[12:15], v[160:163], v[216:219], v[12:15]
	v_mfma_f32_16x16x32_bf16 v[8:11], v[168:171], v[216:219], v[8:11]
	v_mfma_f32_16x16x32_bf16 v[52:55], v[172:175], v[188:191], v[52:55]
	v_mfma_f32_16x16x32_bf16 v[48:51], v[180:183], v[188:191], v[48:51]
	v_mfma_f32_16x16x32_bf16 v[36:39], v[172:175], v[196:199], v[36:39]
	v_mfma_f32_16x16x32_bf16 v[32:35], v[180:183], v[196:199], v[32:35]
	v_mfma_f32_16x16x32_bf16 v[20:23], v[172:175], v[204:207], v[20:23]
	v_mfma_f32_16x16x32_bf16 v[16:19], v[180:183], v[204:207], v[16:19]
	v_mfma_f32_16x16x32_bf16 v[4:7], v[172:175], v[212:215], v[4:7]
	v_mfma_f32_16x16x32_bf16 v[0:3], v[180:183], v[212:215], v[0:3]
	v_mfma_f32_16x16x32_bf16 v[52:55], v[176:179], v[192:195], v[52:55]
	v_mfma_f32_16x16x32_bf16 v[48:51], v[184:187], v[192:195], v[48:51]
	v_mfma_f32_16x16x32_bf16 v[36:39], v[176:179], v[200:203], v[36:39]
	v_mfma_f32_16x16x32_bf16 v[32:35], v[184:187], v[200:203], v[32:35]
	v_mfma_f32_16x16x32_bf16 v[20:23], v[176:179], v[208:211], v[20:23]
	v_mfma_f32_16x16x32_bf16 v[16:19], v[184:187], v[208:211], v[16:19]
	v_mfma_f32_16x16x32_bf16 v[4:7], v[176:179], v[216:219], v[4:7]
	v_mfma_f32_16x16x32_bf16 v[0:3], v[184:187], v[216:219], v[0:3]
	s_setprio 0
	s_cmp_eq_u32 s64, s98
	s_cbranch_scc1 .Lmy_nobar_11
	s_barrier

.Lmy_nobar2_12:
	ds_read_b128 v[148:151], v155
	ds_read_b128 v[160:163], v155 offset:1024
	ds_read_b128 v[164:167], v155 offset:2048
	ds_read_b128 v[168:171], v155 offset:3072
	ds_read_b128 v[172:175], v157
	ds_read_b128 v[176:179], v157 offset:1024
	ds_read_b128 v[180:183], v157 offset:2048
	ds_read_b128 v[184:187], v157 offset:3072
	s_add_u32 s34, s36, 0xfffc0080
	s_addc_u32 s35, s37, -1
	s_cmp_eq_u32 s77, 12
	s_cselect_b32 s41, s23, s35
	s_cselect_b32 s40, s64, s34
	s_cselect_b32 s39, s11, s67
	s_cselect_b32 s38, s65, s66
	v_lshl_add_u64 v[220:221], s[36:37], 0, v[140:141]
	s_add_i32 m0, s31, 0xc000
	ds_read_b128 v[188:191], v158
	ds_read_b128 v[192:195], v158 offset:1024
	ds_read_b128 v[196:199], v158 offset:2048
	ds_read_b128 v[200:203], v158 offset:3072
	ds_read_b128 v[204:207], v158 offset:4096
	ds_read_b128 v[208:211], v158 offset:5120
	ds_read_b128 v[212:215], v158 offset:6144
	ds_read_b128 v[216:219], v158 offset:7168
	global_load_lds_dwordx4 v[220:221], off
	s_add_i32 m0, s31, 0xe000
	v_lshl_add_u64 v[220:221], s[36:37], 0, v[142:143]
	global_load_lds_dwordx4 v[220:221], off
	s_waitcnt vmcnt(8)
	s_waitcnt lgkmcnt(0)
	s_barrier
	s_setprio 1
	s_waitcnt lgkmcnt(0)
	v_mfma_f32_16x16x32_bf16 v[124:127], v[148:151], v[188:191], 0
	v_mfma_f32_16x16x32_bf16 v[120:123], v[164:167], v[188:191], 0
	v_mfma_f32_16x16x32_bf16 v[108:111], v[148:151], v[196:199], 0
	v_mfma_f32_16x16x32_bf16 v[104:107], v[164:167], v[196:199], 0
	v_mfma_f32_16x16x32_bf16 v[92:95], v[148:151], v[204:207], 0
	v_mfma_f32_16x16x32_bf16 v[88:91], v[164:167], v[204:207], 0
	v_mfma_f32_16x16x32_bf16 v[76:79], v[148:151], v[212:215], 0
	v_mfma_f32_16x16x32_bf16 v[72:75], v[164:167], v[212:215], 0
	v_mfma_f32_16x16x32_bf16 v[124:127], v[160:163], v[192:195], v[124:127]
	v_mfma_f32_16x16x32_bf16 v[120:123], v[168:171], v[192:195], v[120:123]
	v_mfma_f32_16x16x32_bf16 v[108:111], v[160:163], v[200:203], v[108:111]
	v_mfma_f32_16x16x32_bf16 v[104:107], v[168:171], v[200:203], v[104:107]
	v_mfma_f32_16x16x32_bf16 v[92:95], v[160:163], v[208:211], v[92:95]
	v_mfma_f32_16x16x32_bf16 v[88:91], v[168:171], v[208:211], v[88:91]
	v_mfma_f32_16x16x32_bf16 v[76:79], v[160:163], v[216:219], v[76:79]
	v_mfma_f32_16x16x32_bf16 v[72:75], v[168:171], v[216:219], v[72:75]
	v_mfma_f32_16x16x32_bf16 v[116:119], v[172:175], v[188:191], 0
	v_mfma_f32_16x16x32_bf16 v[112:115], v[180:183], v[188:191], 0
	v_mfma_f32_16x16x32_bf16 v[100:103], v[172:175], v[196:199], 0
	v_mfma_f32_16x16x32_bf16 v[96:99], v[180:183], v[196:199], 0
	v_mfma_f32_16x16x32_bf16 v[84:87], v[172:175], v[204:207], 0
	v_mfma_f32_16x16x32_bf16 v[80:83], v[180:183], v[204:207], 0
	v_mfma_f32_16x16x32_bf16 v[68:71], v[172:175], v[212:215], 0
	v_mfma_f32_16x16x32_bf16 v[64:67], v[180:183], v[212:215], 0
	v_mfma_f32_16x16x32_bf16 v[116:119], v[176:179], v[192:195], v[116:119]
	v_mfma_f32_16x16x32_bf16 v[112:115], v[184:187], v[192:195], v[112:115]
	v_mfma_f32_16x16x32_bf16 v[100:103], v[176:179], v[200:203], v[100:103]
	v_mfma_f32_16x16x32_bf16 v[96:99], v[184:187], v[200:203], v[96:99]
	v_mfma_f32_16x16x32_bf16 v[84:87], v[176:179], v[208:211], v[84:87]
	v_mfma_f32_16x16x32_bf16 v[80:83], v[184:187], v[208:211], v[80:83]
	v_mfma_f32_16x16x32_bf16 v[68:71], v[176:179], v[216:219], v[68:71]
	v_mfma_f32_16x16x32_bf16 v[64:67], v[184:187], v[216:219], v[64:67]
	s_setprio 0
	s_barrier
	s_add_i32 s34, s55, s48
	v_lshl_add_u64 v[220:221], s[38:39], 0, v[136:137]
	s_mov_b32 m0, s34
	ds_read_b128 v[188:191], v158 offset:16384
	ds_read_b128 v[192:195], v158 offset:17408
	ds_read_b128 v[196:199], v158 offset:18432
	ds_read_b128 v[200:203], v158 offset:19456
	ds_read_b128 v[204:207], v158 offset:20480
	ds_read_b128 v[208:211], v158 offset:21504
	ds_read_b128 v[212:215], v158 offset:22528
	ds_read_b128 v[216:219], v158 offset:23552
	global_load_lds_dwordx4 v[220:221], off
	s_add_i32 m0, s34, 0x2000
	s_add_u32 s34, s38, 0x40000
	v_lshl_add_u64 v[222:223], s[38:39], 0, v[132:133]
	s_addc_u32 s35, s39, 0
	s_add_i32 s79, s56, s48
	global_load_lds_dwordx4 v[222:223], off
	v_lshl_add_u64 v[224:225], s[34:35], 0, v[136:137]
	s_mov_b32 m0, s79
	v_lshl_add_u64 v[226:227], s[40:41], 0, v[134:135]
	global_load_lds_dwordx4 v[224:225], off
	s_add_i32 m0, s79, 0x2000
	v_lshl_add_u64 v[224:225], s[34:35], 0, v[132:133]
	global_load_lds_dwordx4 v[224:225], off
	s_mov_b32 m0, s31
	v_lshl_add_u64 v[224:225], s[40:41], 0, v[138:139]
	global_load_lds_dwordx4 v[224:225], off
	s_mov_b32 m0, s52
	s_nop 0
	global_load_lds_dwordx4 v[226:227], off
	s_waitcnt vmcnt(8)
	s_waitcnt lgkmcnt(0)
	s_barrier
	s_setprio 1
	s_waitcnt lgkmcnt(0)
	v_mfma_f32_16x16x32_bf16 v[60:63], v[148:151], v[188:191], 0
	v_mfma_f32_16x16x32_bf16 v[56:59], v[164:167], v[188:191], 0
	v_mfma_f32_16x16x32_bf16 v[44:47], v[148:151], v[196:199], 0
	v_mfma_f32_16x16x32_bf16 v[40:43], v[164:167], v[196:199], 0
	v_mfma_f32_16x16x32_bf16 v[28:31], v[148:151], v[204:207], 0
	v_mfma_f32_16x16x32_bf16 v[24:27], v[164:167], v[204:207], 0
	v_mfma_f32_16x16x32_bf16 v[12:15], v[148:151], v[212:215], 0
	v_mfma_f32_16x16x32_bf16 v[8:11], v[164:167], v[212:215], 0
	v_mfma_f32_16x16x32_bf16 v[60:63], v[160:163], v[192:195], v[60:63]
	v_mfma_f32_16x16x32_bf16 v[56:59], v[168:171], v[192:195], v[56:59]
	v_mfma_f32_16x16x32_bf16 v[44:47], v[160:163], v[200:203], v[44:47]
	v_mfma_f32_16x16x32_bf16 v[40:43], v[168:171], v[200:203], v[40:43]
	v_mfma_f32_16x16x32_bf16 v[28:31], v[160:163], v[208:211], v[28:31]
	v_mfma_f32_16x16x32_bf16 v[24:27], v[168:171], v[208:211], v[24:27]
	v_mfma_f32_16x16x32_bf16 v[12:15], v[160:163], v[216:219], v[12:15]
	v_mfma_f32_16x16x32_bf16 v[8:11], v[168:171], v[216:219], v[8:11]
	v_mfma_f32_16x16x32_bf16 v[52:55], v[172:175], v[188:191], 0
	v_mfma_f32_16x16x32_bf16 v[48:51], v[180:183], v[188:191], 0
	v_mfma_f32_16x16x32_bf16 v[36:39], v[172:175], v[196:199], 0
	v_mfma_f32_16x16x32_bf16 v[32:35], v[180:183], v[196:199], 0
	v_mfma_f32_16x16x32_bf16 v[20:23], v[172:175], v[204:207], 0
	v_mfma_f32_16x16x32_bf16 v[16:19], v[180:183], v[204:207], 0
	v_mfma_f32_16x16x32_bf16 v[4:7], v[172:175], v[212:215], 0
	v_mfma_f32_16x16x32_bf16 v[0:3], v[180:183], v[212:215], 0
	v_mfma_f32_16x16x32_bf16 v[52:55], v[176:179], v[192:195], v[52:55]
	v_mfma_f32_16x16x32_bf16 v[48:51], v[184:187], v[192:195], v[48:51]
	v_mfma_f32_16x16x32_bf16 v[36:39], v[176:179], v[200:203], v[36:39]
	v_mfma_f32_16x16x32_bf16 v[32:35], v[184:187], v[200:203], v[32:35]
	v_mfma_f32_16x16x32_bf16 v[20:23], v[176:179], v[208:211], v[20:23]
	v_mfma_f32_16x16x32_bf16 v[16:19], v[184:187], v[208:211], v[16:19]
	v_mfma_f32_16x16x32_bf16 v[4:7], v[176:179], v[216:219], v[4:7]
	v_mfma_f32_16x16x32_bf16 v[0:3], v[184:187], v[216:219], v[0:3]
	s_setprio 0
	s_barrier
	s_add_i32 s79, 0, 0x18000
	v_add_u32_e32 v159, s79, v152
	s_add_i32 s81, 0, 0x1c000
	ds_read_b128 v[148:151], v159
	ds_read_b128 v[160:163], v159 offset:1024
	ds_read_b128 v[164:167], v159 offset:2048
	ds_read_b128 v[168:171], v159 offset:3072
	v_add_u32_e32 v159, s81, v152
	ds_read_b128 v[172:175], v159
	ds_read_b128 v[176:179], v159 offset:1024
	ds_read_b128 v[180:183], v159 offset:2048
	ds_read_b128 v[184:187], v159 offset:3072
	s_add_u32 s34, s40, 0x40000
	s_addc_u32 s35, s41, 0
	s_mov_b32 m0, s53
	v_lshl_add_u64 v[228:229], s[34:35], 0, v[138:139]
	ds_read_b128 v[188:191], v158 offset:32768
	ds_read_b128 v[192:195], v158 offset:33792
	ds_read_b128 v[196:199], v158 offset:34816
	ds_read_b128 v[200:203], v158 offset:35840
	ds_read_b128 v[204:207], v158 offset:36864
	ds_read_b128 v[208:211], v158 offset:37888
	ds_read_b128 v[212:215], v158 offset:38912
	ds_read_b128 v[216:219], v158 offset:39936
	global_load_lds_dwordx4 v[228:229], off
	s_mov_b32 m0, s54
	v_lshl_add_u64 v[228:229], s[34:35], 0, v[134:135]
	global_load_lds_dwordx4 v[228:229], off
	s_waitcnt vmcnt(8)
	s_waitcnt lgkmcnt(0)
	s_barrier
	s_setprio 1
	s_waitcnt lgkmcnt(0)
	v_mfma_f32_16x16x32_bf16 v[124:127], v[148:151], v[188:191], v[124:127]
	v_mfma_f32_16x16x32_bf16 v[120:123], v[164:167], v[188:191], v[120:123]
	v_mfma_f32_16x16x32_bf16 v[108:111], v[148:151], v[196:199], v[108:111]
	v_mfma_f32_16x16x32_bf16 v[104:107], v[164:167], v[196:199], v[104:107]
	v_mfma_f32_16x16x32_bf16 v[92:95], v[148:151], v[204:207], v[92:95]
	v_mfma_f32_16x16x32_bf16 v[88:91], v[164:167], v[204:207], v[88:91]
	v_mfma_f32_16x16x32_bf16 v[76:79], v[148:151], v[212:215], v[76:79]
	v_mfma_f32_16x16x32_bf16 v[72:75], v[164:167], v[212:215], v[72:75]
	v_mfma_f32_16x16x32_bf16 v[124:127], v[160:163], v[192:195], v[124:127]
	v_mfma_f32_16x16x32_bf16 v[120:123], v[168:171], v[192:195], v[120:123]
	v_mfma_f32_16x16x32_bf16 v[108:111], v[160:163], v[200:203], v[108:111]
	v_mfma_f32_16x16x32_bf16 v[104:107], v[168:171], v[200:203], v[104:107]
	v_mfma_f32_16x16x32_bf16 v[92:95], v[160:163], v[208:211], v[92:95]
	v_mfma_f32_16x16x32_bf16 v[88:91], v[168:171], v[208:211], v[88:91]
	v_mfma_f32_16x16x32_bf16 v[76:79], v[160:163], v[216:219], v[76:79]
	v_mfma_f32_16x16x32_bf16 v[72:75], v[168:171], v[216:219], v[72:75]
	v_mfma_f32_16x16x32_bf16 v[116:119], v[172:175], v[188:191], v[116:119]
	v_mfma_f32_16x16x32_bf16 v[112:115], v[180:183], v[188:191], v[112:115]
	v_mfma_f32_16x16x32_bf16 v[100:103], v[172:175], v[196:199], v[100:103]
	v_mfma_f32_16x16x32_bf16 v[96:99], v[180:183], v[196:199], v[96:99]
	v_mfma_f32_16x16x32_bf16 v[84:87], v[172:175], v[204:207], v[84:87]
	v_mfma_f32_16x16x32_bf16 v[80:83], v[180:183], v[204:207], v[80:83]
	v_mfma_f32_16x16x32_bf16 v[68:71], v[172:175], v[212:215], v[68:71]
	v_mfma_f32_16x16x32_bf16 v[64:67], v[180:183], v[212:215], v[64:67]
	v_mfma_f32_16x16x32_bf16 v[116:119], v[176:179], v[192:195], v[116:119]
	v_mfma_f32_16x16x32_bf16 v[112:115], v[184:187], v[192:195], v[112:115]
	v_mfma_f32_16x16x32_bf16 v[100:103], v[176:179], v[200:203], v[100:103]
	v_mfma_f32_16x16x32_bf16 v[96:99], v[184:187], v[200:203], v[96:99]
	v_mfma_f32_16x16x32_bf16 v[84:87], v[176:179], v[208:211], v[84:87]
	v_mfma_f32_16x16x32_bf16 v[80:83], v[184:187], v[208:211], v[80:83]
	v_mfma_f32_16x16x32_bf16 v[68:71], v[176:179], v[216:219], v[68:71]
	v_mfma_f32_16x16x32_bf16 v[64:67], v[184:187], v[216:219], v[64:67]
	s_setprio 0
	s_barrier
	s_add_i32 s34, s79, s48
	v_lshl_add_u64 v[220:221], v[220:221], 0, s[6:7]
	s_mov_b32 m0, s34
	ds_read_b128 v[188:191], v158 offset:49152
	ds_read_b128 v[192:195], v158 offset:50176
	ds_read_b128 v[196:199], v158 offset:51200
	ds_read_b128 v[200:203], v158 offset:52224
	ds_read_b128 v[204:207], v158 offset:53248
	ds_read_b128 v[208:211], v158 offset:54272
	ds_read_b128 v[212:215], v158 offset:55296
	ds_read_b128 v[216:219], v158 offset:56320
	global_load_lds_dwordx4 v[220:221], off
	s_add_i32 m0, s34, 0x2000
	s_add_u32 s34, s38, 0x40080
	v_lshl_add_u64 v[220:221], v[222:223], 0, s[6:7]
	s_addc_u32 s35, s39, 0
	s_add_i32 s38, s81, s48
	global_load_lds_dwordx4 v[220:221], off
	s_mov_b32 m0, s38
	v_lshl_add_u64 v[220:221], s[34:35], 0, v[136:137]
	global_load_lds_dwordx4 v[220:221], off
	s_add_i32 m0, s38, 0x2000
	v_lshl_add_u64 v[220:221], s[34:35], 0, v[132:133]
	global_load_lds_dwordx4 v[220:221], off
	s_mov_b32 m0, s12
	v_lshl_add_u64 v[220:221], v[224:225], 0, s[6:7]
	global_load_lds_dwordx4 v[220:221], off
	s_mov_b32 m0, s13
	v_lshl_add_u64 v[220:221], v[226:227], 0, s[6:7]
	global_load_lds_dwordx4 v[220:221], off
	s_waitcnt vmcnt(8)
	s_waitcnt lgkmcnt(0)
	s_barrier
	s_setprio 1
	s_waitcnt lgkmcnt(0)
	v_mfma_f32_16x16x32_bf16 v[60:63], v[148:151], v[188:191], v[60:63]
	v_mfma_f32_16x16x32_bf16 v[56:59], v[164:167], v[188:191], v[56:59]
	v_mfma_f32_16x16x32_bf16 v[44:47], v[148:151], v[196:199], v[44:47]
	v_mfma_f32_16x16x32_bf16 v[40:43], v[164:167], v[196:199], v[40:43]
	v_mfma_f32_16x16x32_bf16 v[28:31], v[148:151], v[204:207], v[28:31]
	v_mfma_f32_16x16x32_bf16 v[24:27], v[164:167], v[204:207], v[24:27]
	v_mfma_f32_16x16x32_bf16 v[12:15], v[148:151], v[212:215], v[12:15]
	v_mfma_f32_16x16x32_bf16 v[8:11], v[164:167], v[212:215], v[8:11]
	v_mfma_f32_16x16x32_bf16 v[60:63], v[160:163], v[192:195], v[60:63]
	v_mfma_f32_16x16x32_bf16 v[56:59], v[168:171], v[192:195], v[56:59]
	v_mfma_f32_16x16x32_bf16 v[44:47], v[160:163], v[200:203], v[44:47]
	v_mfma_f32_16x16x32_bf16 v[40:43], v[168:171], v[200:203], v[40:43]
	v_mfma_f32_16x16x32_bf16 v[28:31], v[160:163], v[208:211], v[28:31]
	v_mfma_f32_16x16x32_bf16 v[24:27], v[168:171], v[208:211], v[24:27]
	v_mfma_f32_16x16x32_bf16 v[12:15], v[160:163], v[216:219], v[12:15]
	v_mfma_f32_16x16x32_bf16 v[8:11], v[168:171], v[216:219], v[8:11]
	v_mfma_f32_16x16x32_bf16 v[52:55], v[172:175], v[188:191], v[52:55]
	v_mfma_f32_16x16x32_bf16 v[48:51], v[180:183], v[188:191], v[48:51]
	v_mfma_f32_16x16x32_bf16 v[36:39], v[172:175], v[196:199], v[36:39]
	v_mfma_f32_16x16x32_bf16 v[32:35], v[180:183], v[196:199], v[32:35]
	v_mfma_f32_16x16x32_bf16 v[20:23], v[172:175], v[204:207], v[20:23]
	v_mfma_f32_16x16x32_bf16 v[16:19], v[180:183], v[204:207], v[16:19]
	v_mfma_f32_16x16x32_bf16 v[4:7], v[172:175], v[212:215], v[4:7]
	v_mfma_f32_16x16x32_bf16 v[0:3], v[180:183], v[212:215], v[0:3]
	v_mfma_f32_16x16x32_bf16 v[52:55], v[176:179], v[192:195], v[52:55]
	v_mfma_f32_16x16x32_bf16 v[48:51], v[184:187], v[192:195], v[48:51]
	v_mfma_f32_16x16x32_bf16 v[36:39], v[176:179], v[200:203], v[36:39]
	v_mfma_f32_16x16x32_bf16 v[32:35], v[184:187], v[200:203], v[32:35]
	v_mfma_f32_16x16x32_bf16 v[20:23], v[176:179], v[208:211], v[20:23]
	v_mfma_f32_16x16x32_bf16 v[16:19], v[184:187], v[208:211], v[16:19]
	v_mfma_f32_16x16x32_bf16 v[4:7], v[176:179], v[216:219], v[4:7]
	v_mfma_f32_16x16x32_bf16 v[0:3], v[184:187], v[216:219], v[0:3]
	s_setprio 0
	s_barrier
	s_add_i32 s77, s77, 2
	s_add_u32 s36, s36, 0x100
	s_addc_u32 s37, s37, 0
	s_add_u32 s66, s66, 0x100
	s_addc_u32 s67, s67, 0
.LBB0_1235:
	ds_read_b128 v[148:151], v155
	ds_read_b128 v[160:163], v155 offset:1024
	ds_read_b128 v[164:167], v155 offset:2048
	ds_read_b128 v[168:171], v155 offset:3072
	ds_read_b128 v[172:175], v157
	ds_read_b128 v[176:179], v157 offset:1024
	ds_read_b128 v[180:183], v157 offset:2048
	ds_read_b128 v[184:187], v157 offset:3072
	s_add_u32 s34, s36, 0xfffc0080
	s_addc_u32 s35, s37, -1
	s_cmp_eq_u32 s77, 12
	s_cselect_b32 s41, s23, s35
	s_cselect_b32 s40, s64, s34
	s_cselect_b32 s39, s11, s67
	s_cselect_b32 s38, s65, s66
	v_lshl_add_u64 v[220:221], s[36:37], 0, v[140:141]
	s_add_i32 m0, s31, 0xc000
	ds_read_b128 v[188:191], v158
	ds_read_b128 v[192:195], v158 offset:1024
	ds_read_b128 v[196:199], v158 offset:2048
	ds_read_b128 v[200:203], v158 offset:3072
	ds_read_b128 v[204:207], v158 offset:4096
	ds_read_b128 v[208:211], v158 offset:5120
	ds_read_b128 v[212:215], v158 offset:6144
	ds_read_b128 v[216:219], v158 offset:7168
	global_load_lds_dwordx4 v[220:221], off
	s_add_i32 m0, s31, 0xe000
	v_lshl_add_u64 v[220:221], s[36:37], 0, v[142:143]
	global_load_lds_dwordx4 v[220:221], off
	s_waitcnt vmcnt(8)
	s_waitcnt lgkmcnt(0)
	s_barrier
	s_setprio 1
	s_waitcnt lgkmcnt(0)
	v_mfma_f32_16x16x32_bf16 v[124:127], v[148:151], v[188:191], v[124:127]
	v_mfma_f32_16x16x32_bf16 v[120:123], v[164:167], v[188:191], v[120:123]
	v_mfma_f32_16x16x32_bf16 v[108:111], v[148:151], v[196:199], v[108:111]
	v_mfma_f32_16x16x32_bf16 v[104:107], v[164:167], v[196:199], v[104:107]
	v_mfma_f32_16x16x32_bf16 v[92:95], v[148:151], v[204:207], v[92:95]
	v_mfma_f32_16x16x32_bf16 v[88:91], v[164:167], v[204:207], v[88:91]
	v_mfma_f32_16x16x32_bf16 v[76:79], v[148:151], v[212:215], v[76:79]
	v_mfma_f32_16x16x32_bf16 v[72:75], v[164:167], v[212:215], v[72:75]
	v_mfma_f32_16x16x32_bf16 v[124:127], v[160:163], v[192:195], v[124:127]
	v_mfma_f32_16x16x32_bf16 v[120:123], v[168:171], v[192:195], v[120:123]
	v_mfma_f32_16x16x32_bf16 v[108:111], v[160:163], v[200:203], v[108:111]
	v_mfma_f32_16x16x32_bf16 v[104:107], v[168:171], v[200:203], v[104:107]
	v_mfma_f32_16x16x32_bf16 v[92:95], v[160:163], v[208:211], v[92:95]
	v_mfma_f32_16x16x32_bf16 v[88:91], v[168:171], v[208:211], v[88:91]
	v_mfma_f32_16x16x32_bf16 v[76:79], v[160:163], v[216:219], v[76:79]
	v_mfma_f32_16x16x32_bf16 v[72:75], v[168:171], v[216:219], v[72:75]
	v_mfma_f32_16x16x32_bf16 v[116:119], v[172:175], v[188:191], v[116:119]
	v_mfma_f32_16x16x32_bf16 v[112:115], v[180:183], v[188:191], v[112:115]
	v_mfma_f32_16x16x32_bf16 v[100:103], v[172:175], v[196:199], v[100:103]
	v_mfma_f32_16x16x32_bf16 v[96:99], v[180:183], v[196:199], v[96:99]
	v_mfma_f32_16x16x32_bf16 v[84:87], v[172:175], v[204:207], v[84:87]
	v_mfma_f32_16x16x32_bf16 v[80:83], v[180:183], v[204:207], v[80:83]
	v_mfma_f32_16x16x32_bf16 v[68:71], v[172:175], v[212:215], v[68:71]
	v_mfma_f32_16x16x32_bf16 v[64:67], v[180:183], v[212:215], v[64:67]
	v_mfma_f32_16x16x32_bf16 v[116:119], v[176:179], v[192:195], v[116:119]
	v_mfma_f32_16x16x32_bf16 v[112:115], v[184:187], v[192:195], v[112:115]
	v_mfma_f32_16x16x32_bf16 v[100:103], v[176:179], v[200:203], v[100:103]
	v_mfma_f32_16x16x32_bf16 v[96:99], v[184:187], v[200:203], v[96:99]
	v_mfma_f32_16x16x32_bf16 v[84:87], v[176:179], v[208:211], v[84:87]
	v_mfma_f32_16x16x32_bf16 v[80:83], v[184:187], v[208:211], v[80:83]
	v_mfma_f32_16x16x32_bf16 v[68:71], v[176:179], v[216:219], v[68:71]
	v_mfma_f32_16x16x32_bf16 v[64:67], v[184:187], v[216:219], v[64:67]
	s_setprio 0
	s_barrier
	s_add_i32 s34, s55, s48
	v_lshl_add_u64 v[220:221], s[38:39], 0, v[136:137]
	s_mov_b32 m0, s34
	ds_read_b128 v[188:191], v158 offset:16384
	ds_read_b128 v[192:195], v158 offset:17408
	ds_read_b128 v[196:199], v158 offset:18432
	ds_read_b128 v[200:203], v158 offset:19456
	ds_read_b128 v[204:207], v158 offset:20480
	ds_read_b128 v[208:211], v158 offset:21504
	ds_read_b128 v[212:215], v158 offset:22528
	ds_read_b128 v[216:219], v158 offset:23552
	global_load_lds_dwordx4 v[220:221], off
	s_add_i32 m0, s34, 0x2000
	s_add_u32 s34, s38, 0x40000
	v_lshl_add_u64 v[222:223], s[38:39], 0, v[132:133]
	s_addc_u32 s35, s39, 0
	s_add_i32 s79, s56, s48
	global_load_lds_dwordx4 v[222:223], off
	v_lshl_add_u64 v[224:225], s[34:35], 0, v[136:137]
	s_mov_b32 m0, s79
	v_lshl_add_u64 v[226:227], s[40:41], 0, v[134:135]
	global_load_lds_dwordx4 v[224:225], off
	s_add_i32 m0, s79, 0x2000
	v_lshl_add_u64 v[224:225], s[34:35], 0, v[132:133]
	global_load_lds_dwordx4 v[224:225], off
	s_mov_b32 m0, s31
	v_lshl_add_u64 v[224:225], s[40:41], 0, v[138:139]
	global_load_lds_dwordx4 v[224:225], off
	s_mov_b32 m0, s52
	s_nop 0
	global_load_lds_dwordx4 v[226:227], off
	s_waitcnt vmcnt(8)
	s_waitcnt lgkmcnt(0)
	s_barrier
	s_setprio 1
	s_waitcnt lgkmcnt(0)
	v_mfma_f32_16x16x32_bf16 v[60:63], v[148:151], v[188:191], v[60:63]
	v_mfma_f32_16x16x32_bf16 v[56:59], v[164:167], v[188:191], v[56:59]
	v_mfma_f32_16x16x32_bf16 v[44:47], v[148:151], v[196:199], v[44:47]
	v_mfma_f32_16x16x32_bf16 v[40:43], v[164:167], v[196:199], v[40:43]
	v_mfma_f32_16x16x32_bf16 v[28:31], v[148:151], v[204:207], v[28:31]
	v_mfma_f32_16x16x32_bf16 v[24:27], v[164:167], v[204:207], v[24:27]
	v_mfma_f32_16x16x32_bf16 v[12:15], v[148:151], v[212:215], v[12:15]
	v_mfma_f32_16x16x32_bf16 v[8:11], v[164:167], v[212:215], v[8:11]
	v_mfma_f32_16x16x32_bf16 v[60:63], v[160:163], v[192:195], v[60:63]
	v_mfma_f32_16x16x32_bf16 v[56:59], v[168:171], v[192:195], v[56:59]
	v_mfma_f32_16x16x32_bf16 v[44:47], v[160:163], v[200:203], v[44:47]
	v_mfma_f32_16x16x32_bf16 v[40:43], v[168:171], v[200:203], v[40:43]
	v_mfma_f32_16x16x32_bf16 v[28:31], v[160:163], v[208:211], v[28:31]
	v_mfma_f32_16x16x32_bf16 v[24:27], v[168:171], v[208:211], v[24:27]
	v_mfma_f32_16x16x32_bf16 v[12:15], v[160:163], v[216:219], v[12:15]
	v_mfma_f32_16x16x32_bf16 v[8:11], v[168:171], v[216:219], v[8:11]
	v_mfma_f32_16x16x32_bf16 v[52:55], v[172:175], v[188:191], v[52:55]
	v_mfma_f32_16x16x32_bf16 v[48:51], v[180:183], v[188:191], v[48:51]
	v_mfma_f32_16x16x32_bf16 v[36:39], v[172:175], v[196:199], v[36:39]
	v_mfma_f32_16x16x32_bf16 v[32:35], v[180:183], v[196:199], v[32:35]
	v_mfma_f32_16x16x32_bf16 v[20:23], v[172:175], v[204:207], v[20:23]
	v_mfma_f32_16x16x32_bf16 v[16:19], v[180:183], v[204:207], v[16:19]
	v_mfma_f32_16x16x32_bf16 v[4:7], v[172:175], v[212:215], v[4:7]
	v_mfma_f32_16x16x32_bf16 v[0:3], v[180:183], v[212:215], v[0:3]
	v_mfma_f32_16x16x32_bf16 v[52:55], v[176:179], v[192:195], v[52:55]
	v_mfma_f32_16x16x32_bf16 v[48:51], v[184:187], v[192:195], v[48:51]
	v_mfma_f32_16x16x32_bf16 v[36:39], v[176:179], v[200:203], v[36:39]
	v_mfma_f32_16x16x32_bf16 v[32:35], v[184:187], v[200:203], v[32:35]
	v_mfma_f32_16x16x32_bf16 v[20:23], v[176:179], v[208:211], v[20:23]
	v_mfma_f32_16x16x32_bf16 v[16:19], v[184:187], v[208:211], v[16:19]
	v_mfma_f32_16x16x32_bf16 v[4:7], v[176:179], v[216:219], v[4:7]
	v_mfma_f32_16x16x32_bf16 v[0:3], v[184:187], v[216:219], v[0:3]
	s_setprio 0
	s_barrier
	s_add_i32 s79, 0, 0x18000
	v_add_u32_e32 v159, s79, v152
	s_add_i32 s81, 0, 0x1c000
	ds_read_b128 v[148:151], v159
	ds_read_b128 v[160:163], v159 offset:1024
	ds_read_b128 v[164:167], v159 offset:2048
	ds_read_b128 v[168:171], v159 offset:3072
	v_add_u32_e32 v159, s81, v152
	ds_read_b128 v[172:175], v159
	ds_read_b128 v[176:179], v159 offset:1024
	ds_read_b128 v[180:183], v159 offset:2048
	ds_read_b128 v[184:187], v159 offset:3072
	s_add_u32 s34, s40, 0x40000
	s_addc_u32 s35, s41, 0
	s_mov_b32 m0, s53
	v_lshl_add_u64 v[228:229], s[34:35], 0, v[138:139]
	ds_read_b128 v[188:191], v158 offset:32768
	ds_read_b128 v[192:195], v158 offset:33792
	ds_read_b128 v[196:199], v158 offset:34816
	ds_read_b128 v[200:203], v158 offset:35840
	ds_read_b128 v[204:207], v158 offset:36864
	ds_read_b128 v[208:211], v158 offset:37888
	ds_read_b128 v[212:215], v158 offset:38912
	ds_read_b128 v[216:219], v158 offset:39936
	global_load_lds_dwordx4 v[228:229], off
	s_mov_b32 m0, s54
	v_lshl_add_u64 v[228:229], s[34:35], 0, v[134:135]
	global_load_lds_dwordx4 v[228:229], off
	s_waitcnt vmcnt(8)
	s_waitcnt lgkmcnt(0)
	s_barrier
	s_setprio 1
	s_waitcnt lgkmcnt(0)
	v_mfma_f32_16x16x32_bf16 v[124:127], v[148:151], v[188:191], v[124:127]
	v_mfma_f32_16x16x32_bf16 v[120:123], v[164:167], v[188:191], v[120:123]
	v_mfma_f32_16x16x32_bf16 v[108:111], v[148:151], v[196:199], v[108:111]
	v_mfma_f32_16x16x32_bf16 v[104:107], v[164:167], v[196:199], v[104:107]
	v_mfma_f32_16x16x32_bf16 v[92:95], v[148:151], v[204:207], v[92:95]
	v_mfma_f32_16x16x32_bf16 v[88:91], v[164:167], v[204:207], v[88:91]
	v_mfma_f32_16x16x32_bf16 v[76:79], v[148:151], v[212:215], v[76:79]
	v_mfma_f32_16x16x32_bf16 v[72:75], v[164:167], v[212:215], v[72:75]
	v_mfma_f32_16x16x32_bf16 v[124:127], v[160:163], v[192:195], v[124:127]
	v_mfma_f32_16x16x32_bf16 v[120:123], v[168:171], v[192:195], v[120:123]
	v_mfma_f32_16x16x32_bf16 v[108:111], v[160:163], v[200:203], v[108:111]
	v_mfma_f32_16x16x32_bf16 v[104:107], v[168:171], v[200:203], v[104:107]
	v_mfma_f32_16x16x32_bf16 v[92:95], v[160:163], v[208:211], v[92:95]
	v_mfma_f32_16x16x32_bf16 v[88:91], v[168:171], v[208:211], v[88:91]
	v_mfma_f32_16x16x32_bf16 v[76:79], v[160:163], v[216:219], v[76:79]
	v_mfma_f32_16x16x32_bf16 v[72:75], v[168:171], v[216:219], v[72:75]
	v_mfma_f32_16x16x32_bf16 v[116:119], v[172:175], v[188:191], v[116:119]
	v_mfma_f32_16x16x32_bf16 v[112:115], v[180:183], v[188:191], v[112:115]
	v_mfma_f32_16x16x32_bf16 v[100:103], v[172:175], v[196:199], v[100:103]
	v_mfma_f32_16x16x32_bf16 v[96:99], v[180:183], v[196:199], v[96:99]
	v_mfma_f32_16x16x32_bf16 v[84:87], v[172:175], v[204:207], v[84:87]
	v_mfma_f32_16x16x32_bf16 v[80:83], v[180:183], v[204:207], v[80:83]
	v_mfma_f32_16x16x32_bf16 v[68:71], v[172:175], v[212:215], v[68:71]
	v_mfma_f32_16x16x32_bf16 v[64:67], v[180:183], v[212:215], v[64:67]
	v_mfma_f32_16x16x32_bf16 v[116:119], v[176:179], v[192:195], v[116:119]
	v_mfma_f32_16x16x32_bf16 v[112:115], v[184:187], v[192:195], v[112:115]
	v_mfma_f32_16x16x32_bf16 v[100:103], v[176:179], v[200:203], v[100:103]
	v_mfma_f32_16x16x32_bf16 v[96:99], v[184:187], v[200:203], v[96:99]
	v_mfma_f32_16x16x32_bf16 v[84:87], v[176:179], v[208:211], v[84:87]
	v_mfma_f32_16x16x32_bf16 v[80:83], v[184:187], v[208:211], v[80:83]
	v_mfma_f32_16x16x32_bf16 v[68:71], v[176:179], v[216:219], v[68:71]
	v_mfma_f32_16x16x32_bf16 v[64:67], v[184:187], v[216:219], v[64:67]
	s_setprio 0
	s_barrier
	s_add_i32 s34, s79, s48
	v_lshl_add_u64 v[220:221], v[220:221], 0, s[6:7]
	s_mov_b32 m0, s34
	ds_read_b128 v[188:191], v158 offset:49152
	ds_read_b128 v[192:195], v158 offset:50176
	ds_read_b128 v[196:199], v158 offset:51200
	ds_read_b128 v[200:203], v158 offset:52224
	ds_read_b128 v[204:207], v158 offset:53248
	ds_read_b128 v[208:211], v158 offset:54272
	ds_read_b128 v[212:215], v158 offset:55296
	ds_read_b128 v[216:219], v158 offset:56320
	global_load_lds_dwordx4 v[220:221], off
	s_add_i32 m0, s34, 0x2000
	s_add_u32 s34, s38, 0x40080
	v_lshl_add_u64 v[220:221], v[222:223], 0, s[6:7]
	s_addc_u32 s35, s39, 0
	s_add_i32 s38, s81, s48
	global_load_lds_dwordx4 v[220:221], off
	s_mov_b32 m0, s38
	v_lshl_add_u64 v[220:221], s[34:35], 0, v[136:137]
	global_load_lds_dwordx4 v[220:221], off
	s_add_i32 m0, s38, 0x2000
	v_lshl_add_u64 v[220:221], s[34:35], 0, v[132:133]
	global_load_lds_dwordx4 v[220:221], off
	s_mov_b32 m0, s12
	v_lshl_add_u64 v[220:221], v[224:225], 0, s[6:7]
	global_load_lds_dwordx4 v[220:221], off
	s_mov_b32 m0, s13
	v_lshl_add_u64 v[220:221], v[226:227], 0, s[6:7]
	global_load_lds_dwordx4 v[220:221], off
	s_waitcnt vmcnt(8)
	s_waitcnt lgkmcnt(0)
	s_barrier
	s_setprio 1
	s_waitcnt lgkmcnt(0)
	v_mfma_f32_16x16x32_bf16 v[60:63], v[148:151], v[188:191], v[60:63]
	v_mfma_f32_16x16x32_bf16 v[56:59], v[164:167], v[188:191], v[56:59]
	v_mfma_f32_16x16x32_bf16 v[44:47], v[148:151], v[196:199], v[44:47]
	v_mfma_f32_16x16x32_bf16 v[40:43], v[164:167], v[196:199], v[40:43]
	v_mfma_f32_16x16x32_bf16 v[28:31], v[148:151], v[204:207], v[28:31]
	v_mfma_f32_16x16x32_bf16 v[24:27], v[164:167], v[204:207], v[24:27]
	v_mfma_f32_16x16x32_bf16 v[12:15], v[148:151], v[212:215], v[12:15]
	v_mfma_f32_16x16x32_bf16 v[8:11], v[164:167], v[212:215], v[8:11]
	v_mfma_f32_16x16x32_bf16 v[60:63], v[160:163], v[192:195], v[60:63]
	v_mfma_f32_16x16x32_bf16 v[56:59], v[168:171], v[192:195], v[56:59]
	v_mfma_f32_16x16x32_bf16 v[44:47], v[160:163], v[200:203], v[44:47]
	v_mfma_f32_16x16x32_bf16 v[40:43], v[168:171], v[200:203], v[40:43]
	v_mfma_f32_16x16x32_bf16 v[28:31], v[160:163], v[208:211], v[28:31]
	v_mfma_f32_16x16x32_bf16 v[24:27], v[168:171], v[208:211], v[24:27]
	v_mfma_f32_16x16x32_bf16 v[12:15], v[160:163], v[216:219], v[12:15]
	v_mfma_f32_16x16x32_bf16 v[8:11], v[168:171], v[216:219], v[8:11]
	v_mfma_f32_16x16x32_bf16 v[52:55], v[172:175], v[188:191], v[52:55]
	v_mfma_f32_16x16x32_bf16 v[48:51], v[180:183], v[188:191], v[48:51]
	v_mfma_f32_16x16x32_bf16 v[36:39], v[172:175], v[196:199], v[36:39]
	v_mfma_f32_16x16x32_bf16 v[32:35], v[180:183], v[196:199], v[32:35]
	v_mfma_f32_16x16x32_bf16 v[20:23], v[172:175], v[204:207], v[20:23]
	v_mfma_f32_16x16x32_bf16 v[16:19], v[180:183], v[204:207], v[16:19]
	v_mfma_f32_16x16x32_bf16 v[4:7], v[172:175], v[212:215], v[4:7]
	v_mfma_f32_16x16x32_bf16 v[0:3], v[180:183], v[212:215], v[0:3]
	v_mfma_f32_16x16x32_bf16 v[52:55], v[176:179], v[192:195], v[52:55]
	v_mfma_f32_16x16x32_bf16 v[48:51], v[184:187], v[192:195], v[48:51]
	v_mfma_f32_16x16x32_bf16 v[36:39], v[176:179], v[200:203], v[36:39]
	v_mfma_f32_16x16x32_bf16 v[32:35], v[184:187], v[200:203], v[32:35]
	v_mfma_f32_16x16x32_bf16 v[20:23], v[176:179], v[208:211], v[20:23]
	v_mfma_f32_16x16x32_bf16 v[16:19], v[184:187], v[208:211], v[16:19]
	v_mfma_f32_16x16x32_bf16 v[4:7], v[176:179], v[216:219], v[4:7]
	v_mfma_f32_16x16x32_bf16 v[0:3], v[184:187], v[216:219], v[0:3]
	s_setprio 0
	s_cmp_eq_u32 s77, s98
	s_cbranch_scc1 .Lmy_nobar_12
	s_barrier

.Lmy_nobar2_16:
	ds_read_b128 v[146:149], v153
	ds_read_b128 v[158:161], v153 offset:1024
	ds_read_b128 v[162:165], v153 offset:2048
	ds_read_b128 v[166:169], v153 offset:3072
	ds_read_b128 v[170:173], v154
	ds_read_b128 v[174:177], v154 offset:1024
	ds_read_b128 v[178:181], v154 offset:2048
	ds_read_b128 v[182:185], v154 offset:3072
	s_add_u32 s34, s40, 0xfffc0080
	s_addc_u32 s35, s41, -1
	s_cmp_eq_u32 s62, 12
	s_cselect_b32 s45, s12, s35
	s_cselect_b32 s44, s13, s34
	s_cselect_b32 s43, s27, s61
	s_cselect_b32 s42, s29, s39
	v_lshl_add_u64 v[218:219], s[40:41], 0, v[138:139]
	s_add_i32 m0, s48, 0xc000
	ds_read_b128 v[186:189], v155
	ds_read_b128 v[190:193], v155 offset:1024
	ds_read_b128 v[194:197], v155 offset:2048
	ds_read_b128 v[198:201], v155 offset:3072
	ds_read_b128 v[202:205], v155 offset:4096
	ds_read_b128 v[206:209], v155 offset:5120
	ds_read_b128 v[210:213], v155 offset:6144
	ds_read_b128 v[214:217], v155 offset:7168
	global_load_lds_dwordx4 v[218:219], off
	s_add_i32 m0, s48, 0xe000
	v_lshl_add_u64 v[218:219], s[40:41], 0, v[140:141]
	global_load_lds_dwordx4 v[218:219], off
	s_waitcnt vmcnt(8)
	s_waitcnt lgkmcnt(0)
	s_barrier
	s_setprio 1
	s_waitcnt lgkmcnt(0)
	v_mfma_f32_16x16x32_bf16 v[124:127], v[146:149], v[186:189], 0
	v_mfma_f32_16x16x32_bf16 v[120:123], v[162:165], v[186:189], 0
	v_mfma_f32_16x16x32_bf16 v[108:111], v[146:149], v[194:197], 0
	v_mfma_f32_16x16x32_bf16 v[104:107], v[162:165], v[194:197], 0
	v_mfma_f32_16x16x32_bf16 v[92:95], v[146:149], v[202:205], 0
	v_mfma_f32_16x16x32_bf16 v[88:91], v[162:165], v[202:205], 0
	v_mfma_f32_16x16x32_bf16 v[76:79], v[146:149], v[210:213], 0
	v_mfma_f32_16x16x32_bf16 v[72:75], v[162:165], v[210:213], 0
	v_mfma_f32_16x16x32_bf16 v[124:127], v[158:161], v[190:193], v[124:127]
	v_mfma_f32_16x16x32_bf16 v[120:123], v[166:169], v[190:193], v[120:123]
	v_mfma_f32_16x16x32_bf16 v[108:111], v[158:161], v[198:201], v[108:111]
	v_mfma_f32_16x16x32_bf16 v[104:107], v[166:169], v[198:201], v[104:107]
	v_mfma_f32_16x16x32_bf16 v[92:95], v[158:161], v[206:209], v[92:95]
	v_mfma_f32_16x16x32_bf16 v[88:91], v[166:169], v[206:209], v[88:91]
	v_mfma_f32_16x16x32_bf16 v[76:79], v[158:161], v[214:217], v[76:79]
	v_mfma_f32_16x16x32_bf16 v[72:75], v[166:169], v[214:217], v[72:75]
	v_mfma_f32_16x16x32_bf16 v[116:119], v[170:173], v[186:189], 0
	v_mfma_f32_16x16x32_bf16 v[112:115], v[178:181], v[186:189], 0
	v_mfma_f32_16x16x32_bf16 v[100:103], v[170:173], v[194:197], 0
	v_mfma_f32_16x16x32_bf16 v[96:99], v[178:181], v[194:197], 0
	v_mfma_f32_16x16x32_bf16 v[84:87], v[170:173], v[202:205], 0
	v_mfma_f32_16x16x32_bf16 v[80:83], v[178:181], v[202:205], 0
	v_mfma_f32_16x16x32_bf16 v[68:71], v[170:173], v[210:213], 0
	v_mfma_f32_16x16x32_bf16 v[64:67], v[178:181], v[210:213], 0
	v_mfma_f32_16x16x32_bf16 v[116:119], v[174:177], v[190:193], v[116:119]
	v_mfma_f32_16x16x32_bf16 v[112:115], v[182:185], v[190:193], v[112:115]
	v_mfma_f32_16x16x32_bf16 v[100:103], v[174:177], v[198:201], v[100:103]
	v_mfma_f32_16x16x32_bf16 v[96:99], v[182:185], v[198:201], v[96:99]
	v_mfma_f32_16x16x32_bf16 v[84:87], v[174:177], v[206:209], v[84:87]
	v_mfma_f32_16x16x32_bf16 v[80:83], v[182:185], v[206:209], v[80:83]
	v_mfma_f32_16x16x32_bf16 v[68:71], v[174:177], v[214:217], v[68:71]
	v_mfma_f32_16x16x32_bf16 v[64:67], v[182:185], v[214:217], v[64:67]
	s_setprio 0
	s_barrier
	s_add_i32 s34, s58, s47
	v_lshl_add_u64 v[218:219], s[42:43], 0, v[132:133]
	s_mov_b32 m0, s34
	ds_read_b128 v[186:189], v155 offset:16384
	ds_read_b128 v[190:193], v155 offset:17408
	ds_read_b128 v[194:197], v155 offset:18432
	ds_read_b128 v[198:201], v155 offset:19456
	ds_read_b128 v[202:205], v155 offset:20480
	ds_read_b128 v[206:209], v155 offset:21504
	ds_read_b128 v[210:213], v155 offset:22528
	ds_read_b128 v[214:217], v155 offset:23552
	global_load_lds_dwordx4 v[218:219], off
	s_add_i32 m0, s34, 0x2000
	s_add_u32 s34, s42, 0x40000
	v_lshl_add_u64 v[220:221], s[42:43], 0, v[136:137]
	s_addc_u32 s35, s43, 0
	s_add_i32 s63, s59, s47
	global_load_lds_dwordx4 v[220:221], off
	v_lshl_add_u64 v[222:223], s[34:35], 0, v[132:133]
	s_mov_b32 m0, s63
	v_lshl_add_u64 v[224:225], s[44:45], 0, v[134:135]
	global_load_lds_dwordx4 v[222:223], off
	s_add_i32 m0, s63, 0x2000
	v_lshl_add_u64 v[222:223], s[34:35], 0, v[136:137]
	global_load_lds_dwordx4 v[222:223], off
	s_mov_b32 m0, s48
	v_lshl_add_u64 v[222:223], s[44:45], 0, v[130:131]
	global_load_lds_dwordx4 v[222:223], off
	s_mov_b32 m0, s49
	s_nop 0
	global_load_lds_dwordx4 v[224:225], off
	s_waitcnt vmcnt(8)
	s_waitcnt lgkmcnt(0)
	s_barrier
	s_setprio 1
	s_waitcnt lgkmcnt(0)
	v_mfma_f32_16x16x32_bf16 v[60:63], v[146:149], v[186:189], 0
	v_mfma_f32_16x16x32_bf16 v[56:59], v[162:165], v[186:189], 0
	v_mfma_f32_16x16x32_bf16 v[44:47], v[146:149], v[194:197], 0
	v_mfma_f32_16x16x32_bf16 v[40:43], v[162:165], v[194:197], 0
	v_mfma_f32_16x16x32_bf16 v[28:31], v[146:149], v[202:205], 0
	v_mfma_f32_16x16x32_bf16 v[24:27], v[162:165], v[202:205], 0
	v_mfma_f32_16x16x32_bf16 v[12:15], v[146:149], v[210:213], 0
	v_mfma_f32_16x16x32_bf16 v[8:11], v[162:165], v[210:213], 0
	v_mfma_f32_16x16x32_bf16 v[60:63], v[158:161], v[190:193], v[60:63]
	v_mfma_f32_16x16x32_bf16 v[56:59], v[166:169], v[190:193], v[56:59]
	v_mfma_f32_16x16x32_bf16 v[44:47], v[158:161], v[198:201], v[44:47]
	v_mfma_f32_16x16x32_bf16 v[40:43], v[166:169], v[198:201], v[40:43]
	v_mfma_f32_16x16x32_bf16 v[28:31], v[158:161], v[206:209], v[28:31]
	v_mfma_f32_16x16x32_bf16 v[24:27], v[166:169], v[206:209], v[24:27]
	v_mfma_f32_16x16x32_bf16 v[12:15], v[158:161], v[214:217], v[12:15]
	v_mfma_f32_16x16x32_bf16 v[8:11], v[166:169], v[214:217], v[8:11]
	v_mfma_f32_16x16x32_bf16 v[52:55], v[170:173], v[186:189], 0
	v_mfma_f32_16x16x32_bf16 v[48:51], v[178:181], v[186:189], 0
	v_mfma_f32_16x16x32_bf16 v[36:39], v[170:173], v[194:197], 0
	v_mfma_f32_16x16x32_bf16 v[32:35], v[178:181], v[194:197], 0
	v_mfma_f32_16x16x32_bf16 v[20:23], v[170:173], v[202:205], 0
	v_mfma_f32_16x16x32_bf16 v[16:19], v[178:181], v[202:205], 0
	v_mfma_f32_16x16x32_bf16 v[4:7], v[170:173], v[210:213], 0
	v_mfma_f32_16x16x32_bf16 v[0:3], v[178:181], v[210:213], 0
	v_mfma_f32_16x16x32_bf16 v[52:55], v[174:177], v[190:193], v[52:55]
	v_mfma_f32_16x16x32_bf16 v[48:51], v[182:185], v[190:193], v[48:51]
	v_mfma_f32_16x16x32_bf16 v[36:39], v[174:177], v[198:201], v[36:39]
	v_mfma_f32_16x16x32_bf16 v[32:35], v[182:185], v[198:201], v[32:35]
	v_mfma_f32_16x16x32_bf16 v[20:23], v[174:177], v[206:209], v[20:23]
	v_mfma_f32_16x16x32_bf16 v[16:19], v[182:185], v[206:209], v[16:19]
	v_mfma_f32_16x16x32_bf16 v[4:7], v[174:177], v[214:217], v[4:7]
	v_mfma_f32_16x16x32_bf16 v[0:3], v[182:185], v[214:217], v[0:3]
	s_setprio 0
	s_barrier
	s_add_i32 s63, 0, 0x18000
	s_add_i32 s64, 0, 0x1c000
	v_add_u32_e32 v166, s63, v151
	v_add_u32_e32 v182, s64, v151
	ds_read_b128 v[146:149], v166
	ds_read_b128 v[158:161], v166 offset:1024
	ds_read_b128 v[162:165], v166 offset:2048
	ds_read_b128 v[166:169], v166 offset:3072
	ds_read_b128 v[170:173], v182
	ds_read_b128 v[174:177], v182 offset:1024
	ds_read_b128 v[178:181], v182 offset:2048
	ds_read_b128 v[182:185], v182 offset:3072
	s_add_u32 s34, s44, 0x40000
	s_addc_u32 s35, s45, 0
	s_mov_b32 m0, s50
	v_lshl_add_u64 v[226:227], s[34:35], 0, v[130:131]
	ds_read_b128 v[186:189], v155 offset:32768
	ds_read_b128 v[190:193], v155 offset:33792
	ds_read_b128 v[194:197], v155 offset:34816
	ds_read_b128 v[198:201], v155 offset:35840
	ds_read_b128 v[202:205], v155 offset:36864
	ds_read_b128 v[206:209], v155 offset:37888
	ds_read_b128 v[210:213], v155 offset:38912
	ds_read_b128 v[214:217], v155 offset:39936
	global_load_lds_dwordx4 v[226:227], off
	s_mov_b32 m0, s51
	v_lshl_add_u64 v[226:227], s[34:35], 0, v[134:135]
	global_load_lds_dwordx4 v[226:227], off
	s_waitcnt vmcnt(8)
	s_waitcnt lgkmcnt(0)
	s_barrier
	s_setprio 1
	s_waitcnt lgkmcnt(0)
	v_mfma_f32_16x16x32_bf16 v[124:127], v[146:149], v[186:189], v[124:127]
	v_mfma_f32_16x16x32_bf16 v[120:123], v[162:165], v[186:189], v[120:123]
	v_mfma_f32_16x16x32_bf16 v[108:111], v[146:149], v[194:197], v[108:111]
	v_mfma_f32_16x16x32_bf16 v[104:107], v[162:165], v[194:197], v[104:107]
	v_mfma_f32_16x16x32_bf16 v[92:95], v[146:149], v[202:205], v[92:95]
	v_mfma_f32_16x16x32_bf16 v[88:91], v[162:165], v[202:205], v[88:91]
	v_mfma_f32_16x16x32_bf16 v[76:79], v[146:149], v[210:213], v[76:79]
	v_mfma_f32_16x16x32_bf16 v[72:75], v[162:165], v[210:213], v[72:75]
	v_mfma_f32_16x16x32_bf16 v[124:127], v[158:161], v[190:193], v[124:127]
	v_mfma_f32_16x16x32_bf16 v[120:123], v[166:169], v[190:193], v[120:123]
	v_mfma_f32_16x16x32_bf16 v[108:111], v[158:161], v[198:201], v[108:111]
	v_mfma_f32_16x16x32_bf16 v[104:107], v[166:169], v[198:201], v[104:107]
	v_mfma_f32_16x16x32_bf16 v[92:95], v[158:161], v[206:209], v[92:95]
	v_mfma_f32_16x16x32_bf16 v[88:91], v[166:169], v[206:209], v[88:91]
	v_mfma_f32_16x16x32_bf16 v[76:79], v[158:161], v[214:217], v[76:79]
	v_mfma_f32_16x16x32_bf16 v[72:75], v[166:169], v[214:217], v[72:75]
	v_mfma_f32_16x16x32_bf16 v[116:119], v[170:173], v[186:189], v[116:119]
	v_mfma_f32_16x16x32_bf16 v[112:115], v[178:181], v[186:189], v[112:115]
	v_mfma_f32_16x16x32_bf16 v[100:103], v[170:173], v[194:197], v[100:103]
	v_mfma_f32_16x16x32_bf16 v[96:99], v[178:181], v[194:197], v[96:99]
	v_mfma_f32_16x16x32_bf16 v[84:87], v[170:173], v[202:205], v[84:87]
	v_mfma_f32_16x16x32_bf16 v[80:83], v[178:181], v[202:205], v[80:83]
	v_mfma_f32_16x16x32_bf16 v[68:71], v[170:173], v[210:213], v[68:71]
	v_mfma_f32_16x16x32_bf16 v[64:67], v[178:181], v[210:213], v[64:67]
	v_mfma_f32_16x16x32_bf16 v[116:119], v[174:177], v[190:193], v[116:119]
	v_mfma_f32_16x16x32_bf16 v[112:115], v[182:185], v[190:193], v[112:115]
	v_mfma_f32_16x16x32_bf16 v[100:103], v[174:177], v[198:201], v[100:103]
	v_mfma_f32_16x16x32_bf16 v[96:99], v[182:185], v[198:201], v[96:99]
	v_mfma_f32_16x16x32_bf16 v[84:87], v[174:177], v[206:209], v[84:87]
	v_mfma_f32_16x16x32_bf16 v[80:83], v[182:185], v[206:209], v[80:83]
	v_mfma_f32_16x16x32_bf16 v[68:71], v[174:177], v[214:217], v[68:71]
	v_mfma_f32_16x16x32_bf16 v[64:67], v[182:185], v[214:217], v[64:67]
	s_setprio 0
	s_barrier
	s_add_i32 s34, s63, s47
	v_lshl_add_u64 v[218:219], v[218:219], 0, s[10:11]
	s_mov_b32 m0, s34
	ds_read_b128 v[186:189], v155 offset:49152
	ds_read_b128 v[190:193], v155 offset:50176
	ds_read_b128 v[194:197], v155 offset:51200
	ds_read_b128 v[198:201], v155 offset:52224
	ds_read_b128 v[202:205], v155 offset:53248
	ds_read_b128 v[206:209], v155 offset:54272
	ds_read_b128 v[210:213], v155 offset:55296
	ds_read_b128 v[214:217], v155 offset:56320
	global_load_lds_dwordx4 v[218:219], off
	s_add_i32 m0, s34, 0x2000
	s_add_u32 s34, s42, 0x40080
	v_lshl_add_u64 v[218:219], v[220:221], 0, s[10:11]
	s_addc_u32 s35, s43, 0
	s_add_i32 s42, s64, s47
	global_load_lds_dwordx4 v[218:219], off
	s_mov_b32 m0, s42
	v_lshl_add_u64 v[218:219], s[34:35], 0, v[132:133]
	global_load_lds_dwordx4 v[218:219], off
	s_add_i32 m0, s42, 0x2000
	v_lshl_add_u64 v[218:219], s[34:35], 0, v[136:137]
	global_load_lds_dwordx4 v[218:219], off
	s_mov_b32 m0, s53
	v_lshl_add_u64 v[218:219], v[222:223], 0, s[10:11]
	global_load_lds_dwordx4 v[218:219], off
	s_mov_b32 m0, s54
	v_lshl_add_u64 v[218:219], v[224:225], 0, s[10:11]
	global_load_lds_dwordx4 v[218:219], off
	s_waitcnt vmcnt(8)
	s_waitcnt lgkmcnt(0)
	s_barrier
	s_setprio 1
	s_waitcnt lgkmcnt(0)
	v_mfma_f32_16x16x32_bf16 v[60:63], v[146:149], v[186:189], v[60:63]
	v_mfma_f32_16x16x32_bf16 v[56:59], v[162:165], v[186:189], v[56:59]
	v_mfma_f32_16x16x32_bf16 v[44:47], v[146:149], v[194:197], v[44:47]
	v_mfma_f32_16x16x32_bf16 v[40:43], v[162:165], v[194:197], v[40:43]
	v_mfma_f32_16x16x32_bf16 v[28:31], v[146:149], v[202:205], v[28:31]
	v_mfma_f32_16x16x32_bf16 v[24:27], v[162:165], v[202:205], v[24:27]
	v_mfma_f32_16x16x32_bf16 v[12:15], v[146:149], v[210:213], v[12:15]
	v_mfma_f32_16x16x32_bf16 v[8:11], v[162:165], v[210:213], v[8:11]
	v_mfma_f32_16x16x32_bf16 v[60:63], v[158:161], v[190:193], v[60:63]
	v_mfma_f32_16x16x32_bf16 v[56:59], v[166:169], v[190:193], v[56:59]
	v_mfma_f32_16x16x32_bf16 v[44:47], v[158:161], v[198:201], v[44:47]
	v_mfma_f32_16x16x32_bf16 v[40:43], v[166:169], v[198:201], v[40:43]
	v_mfma_f32_16x16x32_bf16 v[28:31], v[158:161], v[206:209], v[28:31]
	v_mfma_f32_16x16x32_bf16 v[24:27], v[166:169], v[206:209], v[24:27]
	v_mfma_f32_16x16x32_bf16 v[12:15], v[158:161], v[214:217], v[12:15]
	v_mfma_f32_16x16x32_bf16 v[8:11], v[166:169], v[214:217], v[8:11]
	v_mfma_f32_16x16x32_bf16 v[52:55], v[170:173], v[186:189], v[52:55]
	v_mfma_f32_16x16x32_bf16 v[48:51], v[178:181], v[186:189], v[48:51]
	v_mfma_f32_16x16x32_bf16 v[36:39], v[170:173], v[194:197], v[36:39]
	v_mfma_f32_16x16x32_bf16 v[32:35], v[178:181], v[194:197], v[32:35]
	v_mfma_f32_16x16x32_bf16 v[20:23], v[170:173], v[202:205], v[20:23]
	v_mfma_f32_16x16x32_bf16 v[16:19], v[178:181], v[202:205], v[16:19]
	v_mfma_f32_16x16x32_bf16 v[4:7], v[170:173], v[210:213], v[4:7]
	v_mfma_f32_16x16x32_bf16 v[0:3], v[178:181], v[210:213], v[0:3]
	v_mfma_f32_16x16x32_bf16 v[52:55], v[174:177], v[190:193], v[52:55]
	v_mfma_f32_16x16x32_bf16 v[48:51], v[182:185], v[190:193], v[48:51]
	v_mfma_f32_16x16x32_bf16 v[36:39], v[174:177], v[198:201], v[36:39]
	v_mfma_f32_16x16x32_bf16 v[32:35], v[182:185], v[198:201], v[32:35]
	v_mfma_f32_16x16x32_bf16 v[20:23], v[174:177], v[206:209], v[20:23]
	v_mfma_f32_16x16x32_bf16 v[16:19], v[182:185], v[206:209], v[16:19]
	v_mfma_f32_16x16x32_bf16 v[4:7], v[174:177], v[214:217], v[4:7]
	v_mfma_f32_16x16x32_bf16 v[0:3], v[182:185], v[214:217], v[0:3]
	s_setprio 0
	s_barrier
	s_add_i32 s62, s62, 2
	s_add_u32 s40, s40, 0x100
	s_addc_u32 s41, s41, 0
	s_add_u32 s39, s39, 0x100
	s_addc_u32 s61, s61, 0
.LBB0_1557:
	ds_read_b128 v[146:149], v153
	ds_read_b128 v[158:161], v153 offset:1024
	ds_read_b128 v[162:165], v153 offset:2048
	ds_read_b128 v[166:169], v153 offset:3072
	ds_read_b128 v[170:173], v154
	ds_read_b128 v[174:177], v154 offset:1024
	ds_read_b128 v[178:181], v154 offset:2048
	ds_read_b128 v[182:185], v154 offset:3072
	s_add_u32 s34, s40, 0xfffc0080
	s_addc_u32 s35, s41, -1
	s_cmp_eq_u32 s62, 12
	s_cselect_b32 s45, s12, s35
	s_cselect_b32 s44, s13, s34
	s_cselect_b32 s43, s27, s61
	s_cselect_b32 s42, s29, s39
	v_lshl_add_u64 v[218:219], s[40:41], 0, v[138:139]
	s_add_i32 m0, s48, 0xc000
	ds_read_b128 v[186:189], v155
	ds_read_b128 v[190:193], v155 offset:1024
	ds_read_b128 v[194:197], v155 offset:2048
	ds_read_b128 v[198:201], v155 offset:3072
	ds_read_b128 v[202:205], v155 offset:4096
	ds_read_b128 v[206:209], v155 offset:5120
	ds_read_b128 v[210:213], v155 offset:6144
	ds_read_b128 v[214:217], v155 offset:7168
	global_load_lds_dwordx4 v[218:219], off
	s_add_i32 m0, s48, 0xe000
	v_lshl_add_u64 v[218:219], s[40:41], 0, v[140:141]
	global_load_lds_dwordx4 v[218:219], off
	s_waitcnt vmcnt(8)
	s_waitcnt lgkmcnt(0)
	s_barrier
	s_setprio 1
	s_waitcnt lgkmcnt(0)
	v_mfma_f32_16x16x32_bf16 v[124:127], v[146:149], v[186:189], v[124:127]
	v_mfma_f32_16x16x32_bf16 v[120:123], v[162:165], v[186:189], v[120:123]
	v_mfma_f32_16x16x32_bf16 v[108:111], v[146:149], v[194:197], v[108:111]
	v_mfma_f32_16x16x32_bf16 v[104:107], v[162:165], v[194:197], v[104:107]
	v_mfma_f32_16x16x32_bf16 v[92:95], v[146:149], v[202:205], v[92:95]
	v_mfma_f32_16x16x32_bf16 v[88:91], v[162:165], v[202:205], v[88:91]
	v_mfma_f32_16x16x32_bf16 v[76:79], v[146:149], v[210:213], v[76:79]
	v_mfma_f32_16x16x32_bf16 v[72:75], v[162:165], v[210:213], v[72:75]
	v_mfma_f32_16x16x32_bf16 v[124:127], v[158:161], v[190:193], v[124:127]
	v_mfma_f32_16x16x32_bf16 v[120:123], v[166:169], v[190:193], v[120:123]
	v_mfma_f32_16x16x32_bf16 v[108:111], v[158:161], v[198:201], v[108:111]
	v_mfma_f32_16x16x32_bf16 v[104:107], v[166:169], v[198:201], v[104:107]
	v_mfma_f32_16x16x32_bf16 v[92:95], v[158:161], v[206:209], v[92:95]
	v_mfma_f32_16x16x32_bf16 v[88:91], v[166:169], v[206:209], v[88:91]
	v_mfma_f32_16x16x32_bf16 v[76:79], v[158:161], v[214:217], v[76:79]
	v_mfma_f32_16x16x32_bf16 v[72:75], v[166:169], v[214:217], v[72:75]
	v_mfma_f32_16x16x32_bf16 v[116:119], v[170:173], v[186:189], v[116:119]
	v_mfma_f32_16x16x32_bf16 v[112:115], v[178:181], v[186:189], v[112:115]
	v_mfma_f32_16x16x32_bf16 v[100:103], v[170:173], v[194:197], v[100:103]
	v_mfma_f32_16x16x32_bf16 v[96:99], v[178:181], v[194:197], v[96:99]
	v_mfma_f32_16x16x32_bf16 v[84:87], v[170:173], v[202:205], v[84:87]
	v_mfma_f32_16x16x32_bf16 v[80:83], v[178:181], v[202:205], v[80:83]
	v_mfma_f32_16x16x32_bf16 v[68:71], v[170:173], v[210:213], v[68:71]
	v_mfma_f32_16x16x32_bf16 v[64:67], v[178:181], v[210:213], v[64:67]
	v_mfma_f32_16x16x32_bf16 v[116:119], v[174:177], v[190:193], v[116:119]
	v_mfma_f32_16x16x32_bf16 v[112:115], v[182:185], v[190:193], v[112:115]
	v_mfma_f32_16x16x32_bf16 v[100:103], v[174:177], v[198:201], v[100:103]
	v_mfma_f32_16x16x32_bf16 v[96:99], v[182:185], v[198:201], v[96:99]
	v_mfma_f32_16x16x32_bf16 v[84:87], v[174:177], v[206:209], v[84:87]
	v_mfma_f32_16x16x32_bf16 v[80:83], v[182:185], v[206:209], v[80:83]
	v_mfma_f32_16x16x32_bf16 v[68:71], v[174:177], v[214:217], v[68:71]
	v_mfma_f32_16x16x32_bf16 v[64:67], v[182:185], v[214:217], v[64:67]
	s_setprio 0
	s_barrier
	s_add_i32 s34, s58, s47
	v_lshl_add_u64 v[218:219], s[42:43], 0, v[132:133]
	s_mov_b32 m0, s34
	ds_read_b128 v[186:189], v155 offset:16384
	ds_read_b128 v[190:193], v155 offset:17408
	ds_read_b128 v[194:197], v155 offset:18432
	ds_read_b128 v[198:201], v155 offset:19456
	ds_read_b128 v[202:205], v155 offset:20480
	ds_read_b128 v[206:209], v155 offset:21504
	ds_read_b128 v[210:213], v155 offset:22528
	ds_read_b128 v[214:217], v155 offset:23552
	global_load_lds_dwordx4 v[218:219], off
	s_add_i32 m0, s34, 0x2000
	s_add_u32 s34, s42, 0x40000
	v_lshl_add_u64 v[220:221], s[42:43], 0, v[136:137]
	s_addc_u32 s35, s43, 0
	s_add_i32 s63, s59, s47
	global_load_lds_dwordx4 v[220:221], off
	v_lshl_add_u64 v[222:223], s[34:35], 0, v[132:133]
	s_mov_b32 m0, s63
	v_lshl_add_u64 v[224:225], s[44:45], 0, v[134:135]
	global_load_lds_dwordx4 v[222:223], off
	s_add_i32 m0, s63, 0x2000
	v_lshl_add_u64 v[222:223], s[34:35], 0, v[136:137]
	global_load_lds_dwordx4 v[222:223], off
	s_mov_b32 m0, s48
	v_lshl_add_u64 v[222:223], s[44:45], 0, v[130:131]
	global_load_lds_dwordx4 v[222:223], off
	s_mov_b32 m0, s49
	s_nop 0
	global_load_lds_dwordx4 v[224:225], off
	s_waitcnt vmcnt(8)
	s_waitcnt lgkmcnt(0)
	s_barrier
	s_setprio 1
	s_waitcnt lgkmcnt(0)
	v_mfma_f32_16x16x32_bf16 v[60:63], v[146:149], v[186:189], v[60:63]
	v_mfma_f32_16x16x32_bf16 v[56:59], v[162:165], v[186:189], v[56:59]
	v_mfma_f32_16x16x32_bf16 v[44:47], v[146:149], v[194:197], v[44:47]
	v_mfma_f32_16x16x32_bf16 v[40:43], v[162:165], v[194:197], v[40:43]
	v_mfma_f32_16x16x32_bf16 v[28:31], v[146:149], v[202:205], v[28:31]
	v_mfma_f32_16x16x32_bf16 v[24:27], v[162:165], v[202:205], v[24:27]
	v_mfma_f32_16x16x32_bf16 v[12:15], v[146:149], v[210:213], v[12:15]
	v_mfma_f32_16x16x32_bf16 v[8:11], v[162:165], v[210:213], v[8:11]
	v_mfma_f32_16x16x32_bf16 v[60:63], v[158:161], v[190:193], v[60:63]
	v_mfma_f32_16x16x32_bf16 v[56:59], v[166:169], v[190:193], v[56:59]
	v_mfma_f32_16x16x32_bf16 v[44:47], v[158:161], v[198:201], v[44:47]
	v_mfma_f32_16x16x32_bf16 v[40:43], v[166:169], v[198:201], v[40:43]
	v_mfma_f32_16x16x32_bf16 v[28:31], v[158:161], v[206:209], v[28:31]
	v_mfma_f32_16x16x32_bf16 v[24:27], v[166:169], v[206:209], v[24:27]
	v_mfma_f32_16x16x32_bf16 v[12:15], v[158:161], v[214:217], v[12:15]
	v_mfma_f32_16x16x32_bf16 v[8:11], v[166:169], v[214:217], v[8:11]
	v_mfma_f32_16x16x32_bf16 v[52:55], v[170:173], v[186:189], v[52:55]
	v_mfma_f32_16x16x32_bf16 v[48:51], v[178:181], v[186:189], v[48:51]
	v_mfma_f32_16x16x32_bf16 v[36:39], v[170:173], v[194:197], v[36:39]
	v_mfma_f32_16x16x32_bf16 v[32:35], v[178:181], v[194:197], v[32:35]
	v_mfma_f32_16x16x32_bf16 v[20:23], v[170:173], v[202:205], v[20:23]
	v_mfma_f32_16x16x32_bf16 v[16:19], v[178:181], v[202:205], v[16:19]
	v_mfma_f32_16x16x32_bf16 v[4:7], v[170:173], v[210:213], v[4:7]
	v_mfma_f32_16x16x32_bf16 v[0:3], v[178:181], v[210:213], v[0:3]
	v_mfma_f32_16x16x32_bf16 v[52:55], v[174:177], v[190:193], v[52:55]
	v_mfma_f32_16x16x32_bf16 v[48:51], v[182:185], v[190:193], v[48:51]
	v_mfma_f32_16x16x32_bf16 v[36:39], v[174:177], v[198:201], v[36:39]
	v_mfma_f32_16x16x32_bf16 v[32:35], v[182:185], v[198:201], v[32:35]
	v_mfma_f32_16x16x32_bf16 v[20:23], v[174:177], v[206:209], v[20:23]
	v_mfma_f32_16x16x32_bf16 v[16:19], v[182:185], v[206:209], v[16:19]
	v_mfma_f32_16x16x32_bf16 v[4:7], v[174:177], v[214:217], v[4:7]
	v_mfma_f32_16x16x32_bf16 v[0:3], v[182:185], v[214:217], v[0:3]
	s_setprio 0
	s_barrier
	s_add_i32 s63, 0, 0x18000
	s_add_i32 s64, 0, 0x1c000
	v_add_u32_e32 v166, s63, v151
	v_add_u32_e32 v182, s64, v151
	ds_read_b128 v[146:149], v166
	ds_read_b128 v[158:161], v166 offset:1024
	ds_read_b128 v[162:165], v166 offset:2048
	ds_read_b128 v[166:169], v166 offset:3072
	ds_read_b128 v[170:173], v182
	ds_read_b128 v[174:177], v182 offset:1024
	ds_read_b128 v[178:181], v182 offset:2048
	ds_read_b128 v[182:185], v182 offset:3072
	s_add_u32 s34, s44, 0x40000
	s_addc_u32 s35, s45, 0
	s_mov_b32 m0, s50
	v_lshl_add_u64 v[226:227], s[34:35], 0, v[130:131]
	ds_read_b128 v[186:189], v155 offset:32768
	ds_read_b128 v[190:193], v155 offset:33792
	ds_read_b128 v[194:197], v155 offset:34816
	ds_read_b128 v[198:201], v155 offset:35840
	ds_read_b128 v[202:205], v155 offset:36864
	ds_read_b128 v[206:209], v155 offset:37888
	ds_read_b128 v[210:213], v155 offset:38912
	ds_read_b128 v[214:217], v155 offset:39936
	global_load_lds_dwordx4 v[226:227], off
	s_mov_b32 m0, s51
	v_lshl_add_u64 v[226:227], s[34:35], 0, v[134:135]
	global_load_lds_dwordx4 v[226:227], off
	s_waitcnt vmcnt(8)
	s_waitcnt lgkmcnt(0)
	s_barrier
	s_setprio 1
	s_waitcnt lgkmcnt(0)
	v_mfma_f32_16x16x32_bf16 v[124:127], v[146:149], v[186:189], v[124:127]
	v_mfma_f32_16x16x32_bf16 v[120:123], v[162:165], v[186:189], v[120:123]
	v_mfma_f32_16x16x32_bf16 v[108:111], v[146:149], v[194:197], v[108:111]
	v_mfma_f32_16x16x32_bf16 v[104:107], v[162:165], v[194:197], v[104:107]
	v_mfma_f32_16x16x32_bf16 v[92:95], v[146:149], v[202:205], v[92:95]
	v_mfma_f32_16x16x32_bf16 v[88:91], v[162:165], v[202:205], v[88:91]
	v_mfma_f32_16x16x32_bf16 v[76:79], v[146:149], v[210:213], v[76:79]
	v_mfma_f32_16x16x32_bf16 v[72:75], v[162:165], v[210:213], v[72:75]
	v_mfma_f32_16x16x32_bf16 v[124:127], v[158:161], v[190:193], v[124:127]
	v_mfma_f32_16x16x32_bf16 v[120:123], v[166:169], v[190:193], v[120:123]
	v_mfma_f32_16x16x32_bf16 v[108:111], v[158:161], v[198:201], v[108:111]
	v_mfma_f32_16x16x32_bf16 v[104:107], v[166:169], v[198:201], v[104:107]
	v_mfma_f32_16x16x32_bf16 v[92:95], v[158:161], v[206:209], v[92:95]
	v_mfma_f32_16x16x32_bf16 v[88:91], v[166:169], v[206:209], v[88:91]
	v_mfma_f32_16x16x32_bf16 v[76:79], v[158:161], v[214:217], v[76:79]
	v_mfma_f32_16x16x32_bf16 v[72:75], v[166:169], v[214:217], v[72:75]
	v_mfma_f32_16x16x32_bf16 v[116:119], v[170:173], v[186:189], v[116:119]
	v_mfma_f32_16x16x32_bf16 v[112:115], v[178:181], v[186:189], v[112:115]
	v_mfma_f32_16x16x32_bf16 v[100:103], v[170:173], v[194:197], v[100:103]
	v_mfma_f32_16x16x32_bf16 v[96:99], v[178:181], v[194:197], v[96:99]
	v_mfma_f32_16x16x32_bf16 v[84:87], v[170:173], v[202:205], v[84:87]
	v_mfma_f32_16x16x32_bf16 v[80:83], v[178:181], v[202:205], v[80:83]
	v_mfma_f32_16x16x32_bf16 v[68:71], v[170:173], v[210:213], v[68:71]
	v_mfma_f32_16x16x32_bf16 v[64:67], v[178:181], v[210:213], v[64:67]
	v_mfma_f32_16x16x32_bf16 v[116:119], v[174:177], v[190:193], v[116:119]
	v_mfma_f32_16x16x32_bf16 v[112:115], v[182:185], v[190:193], v[112:115]
	v_mfma_f32_16x16x32_bf16 v[100:103], v[174:177], v[198:201], v[100:103]
	v_mfma_f32_16x16x32_bf16 v[96:99], v[182:185], v[198:201], v[96:99]
	v_mfma_f32_16x16x32_bf16 v[84:87], v[174:177], v[206:209], v[84:87]
	v_mfma_f32_16x16x32_bf16 v[80:83], v[182:185], v[206:209], v[80:83]
	v_mfma_f32_16x16x32_bf16 v[68:71], v[174:177], v[214:217], v[68:71]
	v_mfma_f32_16x16x32_bf16 v[64:67], v[182:185], v[214:217], v[64:67]
	s_setprio 0
	s_barrier
	s_add_i32 s34, s63, s47
	v_lshl_add_u64 v[218:219], v[218:219], 0, s[10:11]
	s_mov_b32 m0, s34
	ds_read_b128 v[186:189], v155 offset:49152
	ds_read_b128 v[190:193], v155 offset:50176
	ds_read_b128 v[194:197], v155 offset:51200
	ds_read_b128 v[198:201], v155 offset:52224
	ds_read_b128 v[202:205], v155 offset:53248
	ds_read_b128 v[206:209], v155 offset:54272
	ds_read_b128 v[210:213], v155 offset:55296
	ds_read_b128 v[214:217], v155 offset:56320
	global_load_lds_dwordx4 v[218:219], off
	s_add_i32 m0, s34, 0x2000
	s_add_u32 s34, s42, 0x40080
	v_lshl_add_u64 v[218:219], v[220:221], 0, s[10:11]
	s_addc_u32 s35, s43, 0
	s_add_i32 s42, s64, s47
	global_load_lds_dwordx4 v[218:219], off
	s_mov_b32 m0, s42
	v_lshl_add_u64 v[218:219], s[34:35], 0, v[132:133]
	global_load_lds_dwordx4 v[218:219], off
	s_add_i32 m0, s42, 0x2000
	v_lshl_add_u64 v[218:219], s[34:35], 0, v[136:137]
	global_load_lds_dwordx4 v[218:219], off
	s_mov_b32 m0, s53
	v_lshl_add_u64 v[218:219], v[222:223], 0, s[10:11]
	global_load_lds_dwordx4 v[218:219], off
	s_mov_b32 m0, s54
	v_lshl_add_u64 v[218:219], v[224:225], 0, s[10:11]
	global_load_lds_dwordx4 v[218:219], off
	s_waitcnt vmcnt(8)
	s_waitcnt lgkmcnt(0)
	s_barrier
	s_setprio 1
	s_waitcnt lgkmcnt(0)
	v_mfma_f32_16x16x32_bf16 v[60:63], v[146:149], v[186:189], v[60:63]
	v_mfma_f32_16x16x32_bf16 v[56:59], v[162:165], v[186:189], v[56:59]
	v_mfma_f32_16x16x32_bf16 v[44:47], v[146:149], v[194:197], v[44:47]
	v_mfma_f32_16x16x32_bf16 v[40:43], v[162:165], v[194:197], v[40:43]
	v_mfma_f32_16x16x32_bf16 v[28:31], v[146:149], v[202:205], v[28:31]
	v_mfma_f32_16x16x32_bf16 v[24:27], v[162:165], v[202:205], v[24:27]
	v_mfma_f32_16x16x32_bf16 v[12:15], v[146:149], v[210:213], v[12:15]
	v_mfma_f32_16x16x32_bf16 v[8:11], v[162:165], v[210:213], v[8:11]
	v_mfma_f32_16x16x32_bf16 v[60:63], v[158:161], v[190:193], v[60:63]
	v_mfma_f32_16x16x32_bf16 v[56:59], v[166:169], v[190:193], v[56:59]
	v_mfma_f32_16x16x32_bf16 v[44:47], v[158:161], v[198:201], v[44:47]
	v_mfma_f32_16x16x32_bf16 v[40:43], v[166:169], v[198:201], v[40:43]
	v_mfma_f32_16x16x32_bf16 v[28:31], v[158:161], v[206:209], v[28:31]
	v_mfma_f32_16x16x32_bf16 v[24:27], v[166:169], v[206:209], v[24:27]
	v_mfma_f32_16x16x32_bf16 v[12:15], v[158:161], v[214:217], v[12:15]
	v_mfma_f32_16x16x32_bf16 v[8:11], v[166:169], v[214:217], v[8:11]
	v_mfma_f32_16x16x32_bf16 v[52:55], v[170:173], v[186:189], v[52:55]
	v_mfma_f32_16x16x32_bf16 v[48:51], v[178:181], v[186:189], v[48:51]
	v_mfma_f32_16x16x32_bf16 v[36:39], v[170:173], v[194:197], v[36:39]
	v_mfma_f32_16x16x32_bf16 v[32:35], v[178:181], v[194:197], v[32:35]
	v_mfma_f32_16x16x32_bf16 v[20:23], v[170:173], v[202:205], v[20:23]
	v_mfma_f32_16x16x32_bf16 v[16:19], v[178:181], v[202:205], v[16:19]
	v_mfma_f32_16x16x32_bf16 v[4:7], v[170:173], v[210:213], v[4:7]
	v_mfma_f32_16x16x32_bf16 v[0:3], v[178:181], v[210:213], v[0:3]
	v_mfma_f32_16x16x32_bf16 v[52:55], v[174:177], v[190:193], v[52:55]
	v_mfma_f32_16x16x32_bf16 v[48:51], v[182:185], v[190:193], v[48:51]
	v_mfma_f32_16x16x32_bf16 v[36:39], v[174:177], v[198:201], v[36:39]
	v_mfma_f32_16x16x32_bf16 v[32:35], v[182:185], v[198:201], v[32:35]
	v_mfma_f32_16x16x32_bf16 v[20:23], v[174:177], v[206:209], v[20:23]
	v_mfma_f32_16x16x32_bf16 v[16:19], v[182:185], v[206:209], v[16:19]
	v_mfma_f32_16x16x32_bf16 v[4:7], v[174:177], v[214:217], v[4:7]
	v_mfma_f32_16x16x32_bf16 v[0:3], v[182:185], v[214:217], v[0:3]
	s_setprio 0
	s_cmp_eq_u32 s62, s98
	s_cbranch_scc1 .Lmy_nobar_16
	s_barrier

.Lmy_nobar2_17:
	ds_read_b128 v[146:149], v154
	ds_read_b128 v[158:161], v154 offset:1024
	ds_read_b128 v[162:165], v154 offset:2048
	ds_read_b128 v[166:169], v154 offset:3072
	ds_read_b128 v[170:173], v155
	ds_read_b128 v[174:177], v155 offset:1024
	ds_read_b128 v[178:181], v155 offset:2048
	ds_read_b128 v[182:185], v155 offset:3072
	s_add_u32 s34, s36, 0xfffc0080
	s_addc_u32 s35, s37, -1
	s_cmp_eq_u32 s62, 12
	s_cselect_b32 s41, s23, s35
	s_cselect_b32 s40, s58, s34
	s_cselect_b32 s39, s11, s61
	s_cselect_b32 s38, s59, s60
	v_lshl_add_u64 v[218:219], s[36:37], 0, v[138:139]
	s_add_i32 m0, s31, 0xc000
	ds_read_b128 v[186:189], v157
	ds_read_b128 v[190:193], v157 offset:1024
	ds_read_b128 v[194:197], v157 offset:2048
	ds_read_b128 v[198:201], v157 offset:3072
	ds_read_b128 v[202:205], v157 offset:4096
	ds_read_b128 v[206:209], v157 offset:5120
	ds_read_b128 v[210:213], v157 offset:6144
	ds_read_b128 v[214:217], v157 offset:7168
	global_load_lds_dwordx4 v[218:219], off
	s_add_i32 m0, s31, 0xe000
	v_lshl_add_u64 v[218:219], s[36:37], 0, v[140:141]
	global_load_lds_dwordx4 v[218:219], off
	s_waitcnt vmcnt(8)
	s_waitcnt lgkmcnt(0)
	s_barrier
	s_setprio 1
	s_waitcnt lgkmcnt(0)
	v_mfma_f32_16x16x32_bf16 v[124:127], v[146:149], v[186:189], 0
	v_mfma_f32_16x16x32_bf16 v[120:123], v[162:165], v[186:189], 0
	v_mfma_f32_16x16x32_bf16 v[108:111], v[146:149], v[194:197], 0
	v_mfma_f32_16x16x32_bf16 v[104:107], v[162:165], v[194:197], 0
	v_mfma_f32_16x16x32_bf16 v[92:95], v[146:149], v[202:205], 0
	v_mfma_f32_16x16x32_bf16 v[88:91], v[162:165], v[202:205], 0
	v_mfma_f32_16x16x32_bf16 v[76:79], v[146:149], v[210:213], 0
	v_mfma_f32_16x16x32_bf16 v[72:75], v[162:165], v[210:213], 0
	v_mfma_f32_16x16x32_bf16 v[124:127], v[158:161], v[190:193], v[124:127]
	v_mfma_f32_16x16x32_bf16 v[120:123], v[166:169], v[190:193], v[120:123]
	v_mfma_f32_16x16x32_bf16 v[108:111], v[158:161], v[198:201], v[108:111]
	v_mfma_f32_16x16x32_bf16 v[104:107], v[166:169], v[198:201], v[104:107]
	v_mfma_f32_16x16x32_bf16 v[92:95], v[158:161], v[206:209], v[92:95]
	v_mfma_f32_16x16x32_bf16 v[88:91], v[166:169], v[206:209], v[88:91]
	v_mfma_f32_16x16x32_bf16 v[76:79], v[158:161], v[214:217], v[76:79]
	v_mfma_f32_16x16x32_bf16 v[72:75], v[166:169], v[214:217], v[72:75]
	v_mfma_f32_16x16x32_bf16 v[116:119], v[170:173], v[186:189], 0
	v_mfma_f32_16x16x32_bf16 v[112:115], v[178:181], v[186:189], 0
	v_mfma_f32_16x16x32_bf16 v[100:103], v[170:173], v[194:197], 0
	v_mfma_f32_16x16x32_bf16 v[96:99], v[178:181], v[194:197], 0
	v_mfma_f32_16x16x32_bf16 v[84:87], v[170:173], v[202:205], 0
	v_mfma_f32_16x16x32_bf16 v[80:83], v[178:181], v[202:205], 0
	v_mfma_f32_16x16x32_bf16 v[68:71], v[170:173], v[210:213], 0
	v_mfma_f32_16x16x32_bf16 v[64:67], v[178:181], v[210:213], 0
	v_mfma_f32_16x16x32_bf16 v[116:119], v[174:177], v[190:193], v[116:119]
	v_mfma_f32_16x16x32_bf16 v[112:115], v[182:185], v[190:193], v[112:115]
	v_mfma_f32_16x16x32_bf16 v[100:103], v[174:177], v[198:201], v[100:103]
	v_mfma_f32_16x16x32_bf16 v[96:99], v[182:185], v[198:201], v[96:99]
	v_mfma_f32_16x16x32_bf16 v[84:87], v[174:177], v[206:209], v[84:87]
	v_mfma_f32_16x16x32_bf16 v[80:83], v[182:185], v[206:209], v[80:83]
	v_mfma_f32_16x16x32_bf16 v[68:71], v[174:177], v[214:217], v[68:71]
	v_mfma_f32_16x16x32_bf16 v[64:67], v[182:185], v[214:217], v[64:67]
	s_setprio 0
	s_barrier
	s_add_i32 s34, s53, s44
	v_lshl_add_u64 v[218:219], s[38:39], 0, v[134:135]
	s_mov_b32 m0, s34
	ds_read_b128 v[186:189], v157 offset:16384
	ds_read_b128 v[190:193], v157 offset:17408
	ds_read_b128 v[194:197], v157 offset:18432
	ds_read_b128 v[198:201], v157 offset:19456
	ds_read_b128 v[202:205], v157 offset:20480
	ds_read_b128 v[206:209], v157 offset:21504
	ds_read_b128 v[210:213], v157 offset:22528
	ds_read_b128 v[214:217], v157 offset:23552
	global_load_lds_dwordx4 v[218:219], off
	s_add_i32 m0, s34, 0x2000
	s_add_u32 s34, s38, 0x40000
	v_lshl_add_u64 v[220:221], s[38:39], 0, v[130:131]
	s_addc_u32 s35, s39, 0
	s_add_i32 s63, s54, s44
	global_load_lds_dwordx4 v[220:221], off
	v_lshl_add_u64 v[222:223], s[34:35], 0, v[134:135]
	s_mov_b32 m0, s63
	v_lshl_add_u64 v[224:225], s[40:41], 0, v[132:133]
	global_load_lds_dwordx4 v[222:223], off
	s_add_i32 m0, s63, 0x2000
	v_lshl_add_u64 v[222:223], s[34:35], 0, v[130:131]
	global_load_lds_dwordx4 v[222:223], off
	s_mov_b32 m0, s31
	v_lshl_add_u64 v[222:223], s[40:41], 0, v[136:137]
	global_load_lds_dwordx4 v[222:223], off
	s_mov_b32 m0, s48
	s_nop 0
	global_load_lds_dwordx4 v[224:225], off
	s_waitcnt vmcnt(8)
	s_waitcnt lgkmcnt(0)
	s_barrier
	s_setprio 1
	s_waitcnt lgkmcnt(0)
	v_mfma_f32_16x16x32_bf16 v[60:63], v[146:149], v[186:189], 0
	v_mfma_f32_16x16x32_bf16 v[56:59], v[162:165], v[186:189], 0
	v_mfma_f32_16x16x32_bf16 v[44:47], v[146:149], v[194:197], 0
	v_mfma_f32_16x16x32_bf16 v[40:43], v[162:165], v[194:197], 0
	v_mfma_f32_16x16x32_bf16 v[28:31], v[146:149], v[202:205], 0
	v_mfma_f32_16x16x32_bf16 v[24:27], v[162:165], v[202:205], 0
	v_mfma_f32_16x16x32_bf16 v[12:15], v[146:149], v[210:213], 0
	v_mfma_f32_16x16x32_bf16 v[8:11], v[162:165], v[210:213], 0
	v_mfma_f32_16x16x32_bf16 v[60:63], v[158:161], v[190:193], v[60:63]
	v_mfma_f32_16x16x32_bf16 v[56:59], v[166:169], v[190:193], v[56:59]
	v_mfma_f32_16x16x32_bf16 v[44:47], v[158:161], v[198:201], v[44:47]
	v_mfma_f32_16x16x32_bf16 v[40:43], v[166:169], v[198:201], v[40:43]
	v_mfma_f32_16x16x32_bf16 v[28:31], v[158:161], v[206:209], v[28:31]
	v_mfma_f32_16x16x32_bf16 v[24:27], v[166:169], v[206:209], v[24:27]
	v_mfma_f32_16x16x32_bf16 v[12:15], v[158:161], v[214:217], v[12:15]
	v_mfma_f32_16x16x32_bf16 v[8:11], v[166:169], v[214:217], v[8:11]
	v_mfma_f32_16x16x32_bf16 v[52:55], v[170:173], v[186:189], 0
	v_mfma_f32_16x16x32_bf16 v[48:51], v[178:181], v[186:189], 0
	v_mfma_f32_16x16x32_bf16 v[36:39], v[170:173], v[194:197], 0
	v_mfma_f32_16x16x32_bf16 v[32:35], v[178:181], v[194:197], 0
	v_mfma_f32_16x16x32_bf16 v[20:23], v[170:173], v[202:205], 0
	v_mfma_f32_16x16x32_bf16 v[16:19], v[178:181], v[202:205], 0
	v_mfma_f32_16x16x32_bf16 v[4:7], v[170:173], v[210:213], 0
	v_mfma_f32_16x16x32_bf16 v[0:3], v[178:181], v[210:213], 0
	v_mfma_f32_16x16x32_bf16 v[52:55], v[174:177], v[190:193], v[52:55]
	v_mfma_f32_16x16x32_bf16 v[48:51], v[182:185], v[190:193], v[48:51]
	v_mfma_f32_16x16x32_bf16 v[36:39], v[174:177], v[198:201], v[36:39]
	v_mfma_f32_16x16x32_bf16 v[32:35], v[182:185], v[198:201], v[32:35]
	v_mfma_f32_16x16x32_bf16 v[20:23], v[174:177], v[206:209], v[20:23]
	v_mfma_f32_16x16x32_bf16 v[16:19], v[182:185], v[206:209], v[16:19]
	v_mfma_f32_16x16x32_bf16 v[4:7], v[174:177], v[214:217], v[4:7]
	v_mfma_f32_16x16x32_bf16 v[0:3], v[182:185], v[214:217], v[0:3]
	s_setprio 0
	s_barrier
	s_add_i32 s63, 0, 0x18000
	s_add_i32 s64, 0, 0x1c000
	v_add_u32_e32 v166, s63, v151
	v_add_u32_e32 v182, s64, v151
	ds_read_b128 v[146:149], v166
	ds_read_b128 v[158:161], v166 offset:1024
	ds_read_b128 v[162:165], v166 offset:2048
	ds_read_b128 v[166:169], v166 offset:3072
	ds_read_b128 v[170:173], v182
	ds_read_b128 v[174:177], v182 offset:1024
	ds_read_b128 v[178:181], v182 offset:2048
	ds_read_b128 v[182:185], v182 offset:3072
	s_add_u32 s34, s40, 0x40000
	s_addc_u32 s35, s41, 0
	s_mov_b32 m0, s49
	v_lshl_add_u64 v[226:227], s[34:35], 0, v[136:137]
	ds_read_b128 v[186:189], v157 offset:32768
	ds_read_b128 v[190:193], v157 offset:33792
	ds_read_b128 v[194:197], v157 offset:34816
	ds_read_b128 v[198:201], v157 offset:35840
	ds_read_b128 v[202:205], v157 offset:36864
	ds_read_b128 v[206:209], v157 offset:37888
	ds_read_b128 v[210:213], v157 offset:38912
	ds_read_b128 v[214:217], v157 offset:39936
	global_load_lds_dwordx4 v[226:227], off
	s_mov_b32 m0, s50
	v_lshl_add_u64 v[226:227], s[34:35], 0, v[132:133]
	global_load_lds_dwordx4 v[226:227], off
	s_waitcnt vmcnt(8)
	s_waitcnt lgkmcnt(0)
	s_barrier
	s_setprio 1
	s_waitcnt lgkmcnt(0)
	v_mfma_f32_16x16x32_bf16 v[124:127], v[146:149], v[186:189], v[124:127]
	v_mfma_f32_16x16x32_bf16 v[120:123], v[162:165], v[186:189], v[120:123]
	v_mfma_f32_16x16x32_bf16 v[108:111], v[146:149], v[194:197], v[108:111]
	v_mfma_f32_16x16x32_bf16 v[104:107], v[162:165], v[194:197], v[104:107]
	v_mfma_f32_16x16x32_bf16 v[92:95], v[146:149], v[202:205], v[92:95]
	v_mfma_f32_16x16x32_bf16 v[88:91], v[162:165], v[202:205], v[88:91]
	v_mfma_f32_16x16x32_bf16 v[76:79], v[146:149], v[210:213], v[76:79]
	v_mfma_f32_16x16x32_bf16 v[72:75], v[162:165], v[210:213], v[72:75]
	v_mfma_f32_16x16x32_bf16 v[124:127], v[158:161], v[190:193], v[124:127]
	v_mfma_f32_16x16x32_bf16 v[120:123], v[166:169], v[190:193], v[120:123]
	v_mfma_f32_16x16x32_bf16 v[108:111], v[158:161], v[198:201], v[108:111]
	v_mfma_f32_16x16x32_bf16 v[104:107], v[166:169], v[198:201], v[104:107]
	v_mfma_f32_16x16x32_bf16 v[92:95], v[158:161], v[206:209], v[92:95]
	v_mfma_f32_16x16x32_bf16 v[88:91], v[166:169], v[206:209], v[88:91]
	v_mfma_f32_16x16x32_bf16 v[76:79], v[158:161], v[214:217], v[76:79]
	v_mfma_f32_16x16x32_bf16 v[72:75], v[166:169], v[214:217], v[72:75]
	v_mfma_f32_16x16x32_bf16 v[116:119], v[170:173], v[186:189], v[116:119]
	v_mfma_f32_16x16x32_bf16 v[112:115], v[178:181], v[186:189], v[112:115]
	v_mfma_f32_16x16x32_bf16 v[100:103], v[170:173], v[194:197], v[100:103]
	v_mfma_f32_16x16x32_bf16 v[96:99], v[178:181], v[194:197], v[96:99]
	v_mfma_f32_16x16x32_bf16 v[84:87], v[170:173], v[202:205], v[84:87]
	v_mfma_f32_16x16x32_bf16 v[80:83], v[178:181], v[202:205], v[80:83]
	v_mfma_f32_16x16x32_bf16 v[68:71], v[170:173], v[210:213], v[68:71]
	v_mfma_f32_16x16x32_bf16 v[64:67], v[178:181], v[210:213], v[64:67]
	v_mfma_f32_16x16x32_bf16 v[116:119], v[174:177], v[190:193], v[116:119]
	v_mfma_f32_16x16x32_bf16 v[112:115], v[182:185], v[190:193], v[112:115]
	v_mfma_f32_16x16x32_bf16 v[100:103], v[174:177], v[198:201], v[100:103]
	v_mfma_f32_16x16x32_bf16 v[96:99], v[182:185], v[198:201], v[96:99]
	v_mfma_f32_16x16x32_bf16 v[84:87], v[174:177], v[206:209], v[84:87]
	v_mfma_f32_16x16x32_bf16 v[80:83], v[182:185], v[206:209], v[80:83]
	v_mfma_f32_16x16x32_bf16 v[68:71], v[174:177], v[214:217], v[68:71]
	v_mfma_f32_16x16x32_bf16 v[64:67], v[182:185], v[214:217], v[64:67]
	s_setprio 0
	s_barrier
	s_add_i32 s34, s63, s44
	v_lshl_add_u64 v[218:219], v[218:219], 0, s[6:7]
	s_mov_b32 m0, s34
	ds_read_b128 v[186:189], v157 offset:49152
	ds_read_b128 v[190:193], v157 offset:50176
	ds_read_b128 v[194:197], v157 offset:51200
	ds_read_b128 v[198:201], v157 offset:52224
	ds_read_b128 v[202:205], v157 offset:53248
	ds_read_b128 v[206:209], v157 offset:54272
	ds_read_b128 v[210:213], v157 offset:55296
	ds_read_b128 v[214:217], v157 offset:56320
	global_load_lds_dwordx4 v[218:219], off
	s_add_i32 m0, s34, 0x2000
	s_add_u32 s34, s38, 0x40080
	v_lshl_add_u64 v[218:219], v[220:221], 0, s[6:7]
	s_addc_u32 s35, s39, 0
	s_add_i32 s38, s64, s44
	global_load_lds_dwordx4 v[218:219], off
	s_mov_b32 m0, s38
	v_lshl_add_u64 v[218:219], s[34:35], 0, v[134:135]
	global_load_lds_dwordx4 v[218:219], off
	s_add_i32 m0, s38, 0x2000
	v_lshl_add_u64 v[218:219], s[34:35], 0, v[130:131]
	global_load_lds_dwordx4 v[218:219], off
	s_mov_b32 m0, s51
	v_lshl_add_u64 v[218:219], v[222:223], 0, s[6:7]
	global_load_lds_dwordx4 v[218:219], off
	s_mov_b32 m0, s52
	v_lshl_add_u64 v[218:219], v[224:225], 0, s[6:7]
	global_load_lds_dwordx4 v[218:219], off
	s_waitcnt vmcnt(8)
	s_waitcnt lgkmcnt(0)
	s_barrier
	s_setprio 1
	s_waitcnt lgkmcnt(0)
	v_mfma_f32_16x16x32_bf16 v[60:63], v[146:149], v[186:189], v[60:63]
	v_mfma_f32_16x16x32_bf16 v[56:59], v[162:165], v[186:189], v[56:59]
	v_mfma_f32_16x16x32_bf16 v[44:47], v[146:149], v[194:197], v[44:47]
	v_mfma_f32_16x16x32_bf16 v[40:43], v[162:165], v[194:197], v[40:43]
	v_mfma_f32_16x16x32_bf16 v[28:31], v[146:149], v[202:205], v[28:31]
	v_mfma_f32_16x16x32_bf16 v[24:27], v[162:165], v[202:205], v[24:27]
	v_mfma_f32_16x16x32_bf16 v[12:15], v[146:149], v[210:213], v[12:15]
	v_mfma_f32_16x16x32_bf16 v[8:11], v[162:165], v[210:213], v[8:11]
	v_mfma_f32_16x16x32_bf16 v[60:63], v[158:161], v[190:193], v[60:63]
	v_mfma_f32_16x16x32_bf16 v[56:59], v[166:169], v[190:193], v[56:59]
	v_mfma_f32_16x16x32_bf16 v[44:47], v[158:161], v[198:201], v[44:47]
	v_mfma_f32_16x16x32_bf16 v[40:43], v[166:169], v[198:201], v[40:43]
	v_mfma_f32_16x16x32_bf16 v[28:31], v[158:161], v[206:209], v[28:31]
	v_mfma_f32_16x16x32_bf16 v[24:27], v[166:169], v[206:209], v[24:27]
	v_mfma_f32_16x16x32_bf16 v[12:15], v[158:161], v[214:217], v[12:15]
	v_mfma_f32_16x16x32_bf16 v[8:11], v[166:169], v[214:217], v[8:11]
	v_mfma_f32_16x16x32_bf16 v[52:55], v[170:173], v[186:189], v[52:55]
	v_mfma_f32_16x16x32_bf16 v[48:51], v[178:181], v[186:189], v[48:51]
	v_mfma_f32_16x16x32_bf16 v[36:39], v[170:173], v[194:197], v[36:39]
	v_mfma_f32_16x16x32_bf16 v[32:35], v[178:181], v[194:197], v[32:35]
	v_mfma_f32_16x16x32_bf16 v[20:23], v[170:173], v[202:205], v[20:23]
	v_mfma_f32_16x16x32_bf16 v[16:19], v[178:181], v[202:205], v[16:19]
	v_mfma_f32_16x16x32_bf16 v[4:7], v[170:173], v[210:213], v[4:7]
	v_mfma_f32_16x16x32_bf16 v[0:3], v[178:181], v[210:213], v[0:3]
	v_mfma_f32_16x16x32_bf16 v[52:55], v[174:177], v[190:193], v[52:55]
	v_mfma_f32_16x16x32_bf16 v[48:51], v[182:185], v[190:193], v[48:51]
	v_mfma_f32_16x16x32_bf16 v[36:39], v[174:177], v[198:201], v[36:39]
	v_mfma_f32_16x16x32_bf16 v[32:35], v[182:185], v[198:201], v[32:35]
	v_mfma_f32_16x16x32_bf16 v[20:23], v[174:177], v[206:209], v[20:23]
	v_mfma_f32_16x16x32_bf16 v[16:19], v[182:185], v[206:209], v[16:19]
	v_mfma_f32_16x16x32_bf16 v[4:7], v[174:177], v[214:217], v[4:7]
	v_mfma_f32_16x16x32_bf16 v[0:3], v[182:185], v[214:217], v[0:3]
	s_setprio 0
	s_barrier
	s_add_i32 s62, s62, 2
	s_add_u32 s36, s36, 0x100
	s_addc_u32 s37, s37, 0
	s_add_u32 s60, s60, 0x100
	s_addc_u32 s61, s61, 0
.LBB0_1647:
	ds_read_b128 v[146:149], v154
	ds_read_b128 v[158:161], v154 offset:1024
	ds_read_b128 v[162:165], v154 offset:2048
	ds_read_b128 v[166:169], v154 offset:3072
	ds_read_b128 v[170:173], v155
	ds_read_b128 v[174:177], v155 offset:1024
	ds_read_b128 v[178:181], v155 offset:2048
	ds_read_b128 v[182:185], v155 offset:3072
	s_add_u32 s34, s36, 0xfffc0080
	s_addc_u32 s35, s37, -1
	s_cmp_eq_u32 s62, 12
	s_cselect_b32 s41, s23, s35
	s_cselect_b32 s40, s58, s34
	s_cselect_b32 s39, s11, s61
	s_cselect_b32 s38, s59, s60
	v_lshl_add_u64 v[218:219], s[36:37], 0, v[138:139]
	s_add_i32 m0, s31, 0xc000
	ds_read_b128 v[186:189], v157
	ds_read_b128 v[190:193], v157 offset:1024
	ds_read_b128 v[194:197], v157 offset:2048
	ds_read_b128 v[198:201], v157 offset:3072
	ds_read_b128 v[202:205], v157 offset:4096
	ds_read_b128 v[206:209], v157 offset:5120
	ds_read_b128 v[210:213], v157 offset:6144
	ds_read_b128 v[214:217], v157 offset:7168
	global_load_lds_dwordx4 v[218:219], off
	s_add_i32 m0, s31, 0xe000
	v_lshl_add_u64 v[218:219], s[36:37], 0, v[140:141]
	global_load_lds_dwordx4 v[218:219], off
	s_waitcnt vmcnt(8)
	s_waitcnt lgkmcnt(0)
	s_barrier
	s_setprio 1
	s_waitcnt lgkmcnt(0)
	v_mfma_f32_16x16x32_bf16 v[124:127], v[146:149], v[186:189], v[124:127]
	v_mfma_f32_16x16x32_bf16 v[120:123], v[162:165], v[186:189], v[120:123]
	v_mfma_f32_16x16x32_bf16 v[108:111], v[146:149], v[194:197], v[108:111]
	v_mfma_f32_16x16x32_bf16 v[104:107], v[162:165], v[194:197], v[104:107]
	v_mfma_f32_16x16x32_bf16 v[92:95], v[146:149], v[202:205], v[92:95]
	v_mfma_f32_16x16x32_bf16 v[88:91], v[162:165], v[202:205], v[88:91]
	v_mfma_f32_16x16x32_bf16 v[76:79], v[146:149], v[210:213], v[76:79]
	v_mfma_f32_16x16x32_bf16 v[72:75], v[162:165], v[210:213], v[72:75]
	v_mfma_f32_16x16x32_bf16 v[124:127], v[158:161], v[190:193], v[124:127]
	v_mfma_f32_16x16x32_bf16 v[120:123], v[166:169], v[190:193], v[120:123]
	v_mfma_f32_16x16x32_bf16 v[108:111], v[158:161], v[198:201], v[108:111]
	v_mfma_f32_16x16x32_bf16 v[104:107], v[166:169], v[198:201], v[104:107]
	v_mfma_f32_16x16x32_bf16 v[92:95], v[158:161], v[206:209], v[92:95]
	v_mfma_f32_16x16x32_bf16 v[88:91], v[166:169], v[206:209], v[88:91]
	v_mfma_f32_16x16x32_bf16 v[76:79], v[158:161], v[214:217], v[76:79]
	v_mfma_f32_16x16x32_bf16 v[72:75], v[166:169], v[214:217], v[72:75]
	v_mfma_f32_16x16x32_bf16 v[116:119], v[170:173], v[186:189], v[116:119]
	v_mfma_f32_16x16x32_bf16 v[112:115], v[178:181], v[186:189], v[112:115]
	v_mfma_f32_16x16x32_bf16 v[100:103], v[170:173], v[194:197], v[100:103]
	v_mfma_f32_16x16x32_bf16 v[96:99], v[178:181], v[194:197], v[96:99]
	v_mfma_f32_16x16x32_bf16 v[84:87], v[170:173], v[202:205], v[84:87]
	v_mfma_f32_16x16x32_bf16 v[80:83], v[178:181], v[202:205], v[80:83]
	v_mfma_f32_16x16x32_bf16 v[68:71], v[170:173], v[210:213], v[68:71]
	v_mfma_f32_16x16x32_bf16 v[64:67], v[178:181], v[210:213], v[64:67]
	v_mfma_f32_16x16x32_bf16 v[116:119], v[174:177], v[190:193], v[116:119]
	v_mfma_f32_16x16x32_bf16 v[112:115], v[182:185], v[190:193], v[112:115]
	v_mfma_f32_16x16x32_bf16 v[100:103], v[174:177], v[198:201], v[100:103]
	v_mfma_f32_16x16x32_bf16 v[96:99], v[182:185], v[198:201], v[96:99]
	v_mfma_f32_16x16x32_bf16 v[84:87], v[174:177], v[206:209], v[84:87]
	v_mfma_f32_16x16x32_bf16 v[80:83], v[182:185], v[206:209], v[80:83]
	v_mfma_f32_16x16x32_bf16 v[68:71], v[174:177], v[214:217], v[68:71]
	v_mfma_f32_16x16x32_bf16 v[64:67], v[182:185], v[214:217], v[64:67]
	s_setprio 0
	s_barrier
	s_add_i32 s34, s53, s44
	v_lshl_add_u64 v[218:219], s[38:39], 0, v[134:135]
	s_mov_b32 m0, s34
	ds_read_b128 v[186:189], v157 offset:16384
	ds_read_b128 v[190:193], v157 offset:17408
	ds_read_b128 v[194:197], v157 offset:18432
	ds_read_b128 v[198:201], v157 offset:19456
	ds_read_b128 v[202:205], v157 offset:20480
	ds_read_b128 v[206:209], v157 offset:21504
	ds_read_b128 v[210:213], v157 offset:22528
	ds_read_b128 v[214:217], v157 offset:23552
	global_load_lds_dwordx4 v[218:219], off
	s_add_i32 m0, s34, 0x2000
	s_add_u32 s34, s38, 0x40000
	v_lshl_add_u64 v[220:221], s[38:39], 0, v[130:131]
	s_addc_u32 s35, s39, 0
	s_add_i32 s63, s54, s44
	global_load_lds_dwordx4 v[220:221], off
	v_lshl_add_u64 v[222:223], s[34:35], 0, v[134:135]
	s_mov_b32 m0, s63
	v_lshl_add_u64 v[224:225], s[40:41], 0, v[132:133]
	global_load_lds_dwordx4 v[222:223], off
	s_add_i32 m0, s63, 0x2000
	v_lshl_add_u64 v[222:223], s[34:35], 0, v[130:131]
	global_load_lds_dwordx4 v[222:223], off
	s_mov_b32 m0, s31
	v_lshl_add_u64 v[222:223], s[40:41], 0, v[136:137]
	global_load_lds_dwordx4 v[222:223], off
	s_mov_b32 m0, s48
	s_nop 0
	global_load_lds_dwordx4 v[224:225], off
	s_waitcnt vmcnt(8)
	s_waitcnt lgkmcnt(0)
	s_barrier
	s_setprio 1
	s_waitcnt lgkmcnt(0)
	v_mfma_f32_16x16x32_bf16 v[60:63], v[146:149], v[186:189], v[60:63]
	v_mfma_f32_16x16x32_bf16 v[56:59], v[162:165], v[186:189], v[56:59]
	v_mfma_f32_16x16x32_bf16 v[44:47], v[146:149], v[194:197], v[44:47]
	v_mfma_f32_16x16x32_bf16 v[40:43], v[162:165], v[194:197], v[40:43]
	v_mfma_f32_16x16x32_bf16 v[28:31], v[146:149], v[202:205], v[28:31]
	v_mfma_f32_16x16x32_bf16 v[24:27], v[162:165], v[202:205], v[24:27]
	v_mfma_f32_16x16x32_bf16 v[12:15], v[146:149], v[210:213], v[12:15]
	v_mfma_f32_16x16x32_bf16 v[8:11], v[162:165], v[210:213], v[8:11]
	v_mfma_f32_16x16x32_bf16 v[60:63], v[158:161], v[190:193], v[60:63]
	v_mfma_f32_16x16x32_bf16 v[56:59], v[166:169], v[190:193], v[56:59]
	v_mfma_f32_16x16x32_bf16 v[44:47], v[158:161], v[198:201], v[44:47]
	v_mfma_f32_16x16x32_bf16 v[40:43], v[166:169], v[198:201], v[40:43]
	v_mfma_f32_16x16x32_bf16 v[28:31], v[158:161], v[206:209], v[28:31]
	v_mfma_f32_16x16x32_bf16 v[24:27], v[166:169], v[206:209], v[24:27]
	v_mfma_f32_16x16x32_bf16 v[12:15], v[158:161], v[214:217], v[12:15]
	v_mfma_f32_16x16x32_bf16 v[8:11], v[166:169], v[214:217], v[8:11]
	v_mfma_f32_16x16x32_bf16 v[52:55], v[170:173], v[186:189], v[52:55]
	v_mfma_f32_16x16x32_bf16 v[48:51], v[178:181], v[186:189], v[48:51]
	v_mfma_f32_16x16x32_bf16 v[36:39], v[170:173], v[194:197], v[36:39]
	v_mfma_f32_16x16x32_bf16 v[32:35], v[178:181], v[194:197], v[32:35]
	v_mfma_f32_16x16x32_bf16 v[20:23], v[170:173], v[202:205], v[20:23]
	v_mfma_f32_16x16x32_bf16 v[16:19], v[178:181], v[202:205], v[16:19]
	v_mfma_f32_16x16x32_bf16 v[4:7], v[170:173], v[210:213], v[4:7]
	v_mfma_f32_16x16x32_bf16 v[0:3], v[178:181], v[210:213], v[0:3]
	v_mfma_f32_16x16x32_bf16 v[52:55], v[174:177], v[190:193], v[52:55]
	v_mfma_f32_16x16x32_bf16 v[48:51], v[182:185], v[190:193], v[48:51]
	v_mfma_f32_16x16x32_bf16 v[36:39], v[174:177], v[198:201], v[36:39]
	v_mfma_f32_16x16x32_bf16 v[32:35], v[182:185], v[198:201], v[32:35]
	v_mfma_f32_16x16x32_bf16 v[20:23], v[174:177], v[206:209], v[20:23]
	v_mfma_f32_16x16x32_bf16 v[16:19], v[182:185], v[206:209], v[16:19]
	v_mfma_f32_16x16x32_bf16 v[4:7], v[174:177], v[214:217], v[4:7]
	v_mfma_f32_16x16x32_bf16 v[0:3], v[182:185], v[214:217], v[0:3]
	s_setprio 0
	s_barrier
	s_add_i32 s63, 0, 0x18000
	s_add_i32 s64, 0, 0x1c000
	v_add_u32_e32 v166, s63, v151
	v_add_u32_e32 v182, s64, v151
	ds_read_b128 v[146:149], v166
	ds_read_b128 v[158:161], v166 offset:1024
	ds_read_b128 v[162:165], v166 offset:2048
	ds_read_b128 v[166:169], v166 offset:3072
	ds_read_b128 v[170:173], v182
	ds_read_b128 v[174:177], v182 offset:1024
	ds_read_b128 v[178:181], v182 offset:2048
	ds_read_b128 v[182:185], v182 offset:3072
	s_add_u32 s34, s40, 0x40000
	s_addc_u32 s35, s41, 0
	s_mov_b32 m0, s49
	v_lshl_add_u64 v[226:227], s[34:35], 0, v[136:137]
	ds_read_b128 v[186:189], v157 offset:32768
	ds_read_b128 v[190:193], v157 offset:33792
	ds_read_b128 v[194:197], v157 offset:34816
	ds_read_b128 v[198:201], v157 offset:35840
	ds_read_b128 v[202:205], v157 offset:36864
	ds_read_b128 v[206:209], v157 offset:37888
	ds_read_b128 v[210:213], v157 offset:38912
	ds_read_b128 v[214:217], v157 offset:39936
	global_load_lds_dwordx4 v[226:227], off
	s_mov_b32 m0, s50
	v_lshl_add_u64 v[226:227], s[34:35], 0, v[132:133]
	global_load_lds_dwordx4 v[226:227], off
	s_waitcnt vmcnt(8)
	s_waitcnt lgkmcnt(0)
	s_barrier
	s_setprio 1
	s_waitcnt lgkmcnt(0)
	v_mfma_f32_16x16x32_bf16 v[124:127], v[146:149], v[186:189], v[124:127]
	v_mfma_f32_16x16x32_bf16 v[120:123], v[162:165], v[186:189], v[120:123]
	v_mfma_f32_16x16x32_bf16 v[108:111], v[146:149], v[194:197], v[108:111]
	v_mfma_f32_16x16x32_bf16 v[104:107], v[162:165], v[194:197], v[104:107]
	v_mfma_f32_16x16x32_bf16 v[92:95], v[146:149], v[202:205], v[92:95]
	v_mfma_f32_16x16x32_bf16 v[88:91], v[162:165], v[202:205], v[88:91]
	v_mfma_f32_16x16x32_bf16 v[76:79], v[146:149], v[210:213], v[76:79]
	v_mfma_f32_16x16x32_bf16 v[72:75], v[162:165], v[210:213], v[72:75]
	v_mfma_f32_16x16x32_bf16 v[124:127], v[158:161], v[190:193], v[124:127]
	v_mfma_f32_16x16x32_bf16 v[120:123], v[166:169], v[190:193], v[120:123]
	v_mfma_f32_16x16x32_bf16 v[108:111], v[158:161], v[198:201], v[108:111]
	v_mfma_f32_16x16x32_bf16 v[104:107], v[166:169], v[198:201], v[104:107]
	v_mfma_f32_16x16x32_bf16 v[92:95], v[158:161], v[206:209], v[92:95]
	v_mfma_f32_16x16x32_bf16 v[88:91], v[166:169], v[206:209], v[88:91]
	v_mfma_f32_16x16x32_bf16 v[76:79], v[158:161], v[214:217], v[76:79]
	v_mfma_f32_16x16x32_bf16 v[72:75], v[166:169], v[214:217], v[72:75]
	v_mfma_f32_16x16x32_bf16 v[116:119], v[170:173], v[186:189], v[116:119]
	v_mfma_f32_16x16x32_bf16 v[112:115], v[178:181], v[186:189], v[112:115]
	v_mfma_f32_16x16x32_bf16 v[100:103], v[170:173], v[194:197], v[100:103]
	v_mfma_f32_16x16x32_bf16 v[96:99], v[178:181], v[194:197], v[96:99]
	v_mfma_f32_16x16x32_bf16 v[84:87], v[170:173], v[202:205], v[84:87]
	v_mfma_f32_16x16x32_bf16 v[80:83], v[178:181], v[202:205], v[80:83]
	v_mfma_f32_16x16x32_bf16 v[68:71], v[170:173], v[210:213], v[68:71]
	v_mfma_f32_16x16x32_bf16 v[64:67], v[178:181], v[210:213], v[64:67]
	v_mfma_f32_16x16x32_bf16 v[116:119], v[174:177], v[190:193], v[116:119]
	v_mfma_f32_16x16x32_bf16 v[112:115], v[182:185], v[190:193], v[112:115]
	v_mfma_f32_16x16x32_bf16 v[100:103], v[174:177], v[198:201], v[100:103]
	v_mfma_f32_16x16x32_bf16 v[96:99], v[182:185], v[198:201], v[96:99]
	v_mfma_f32_16x16x32_bf16 v[84:87], v[174:177], v[206:209], v[84:87]
	v_mfma_f32_16x16x32_bf16 v[80:83], v[182:185], v[206:209], v[80:83]
	v_mfma_f32_16x16x32_bf16 v[68:71], v[174:177], v[214:217], v[68:71]
	v_mfma_f32_16x16x32_bf16 v[64:67], v[182:185], v[214:217], v[64:67]
	s_setprio 0
	s_barrier
	s_add_i32 s34, s63, s44
	v_lshl_add_u64 v[218:219], v[218:219], 0, s[6:7]
	s_mov_b32 m0, s34
	ds_read_b128 v[186:189], v157 offset:49152
	ds_read_b128 v[190:193], v157 offset:50176
	ds_read_b128 v[194:197], v157 offset:51200
	ds_read_b128 v[198:201], v157 offset:52224
	ds_read_b128 v[202:205], v157 offset:53248
	ds_read_b128 v[206:209], v157 offset:54272
	ds_read_b128 v[210:213], v157 offset:55296
	ds_read_b128 v[214:217], v157 offset:56320
	global_load_lds_dwordx4 v[218:219], off
	s_add_i32 m0, s34, 0x2000
	s_add_u32 s34, s38, 0x40080
	v_lshl_add_u64 v[218:219], v[220:221], 0, s[6:7]
	s_addc_u32 s35, s39, 0
	s_add_i32 s38, s64, s44
	global_load_lds_dwordx4 v[218:219], off
	s_mov_b32 m0, s38
	v_lshl_add_u64 v[218:219], s[34:35], 0, v[134:135]
	global_load_lds_dwordx4 v[218:219], off
	s_add_i32 m0, s38, 0x2000
	v_lshl_add_u64 v[218:219], s[34:35], 0, v[130:131]
	global_load_lds_dwordx4 v[218:219], off
	s_mov_b32 m0, s51
	v_lshl_add_u64 v[218:219], v[222:223], 0, s[6:7]
	global_load_lds_dwordx4 v[218:219], off
	s_mov_b32 m0, s52
	v_lshl_add_u64 v[218:219], v[224:225], 0, s[6:7]
	global_load_lds_dwordx4 v[218:219], off
	s_waitcnt vmcnt(8)
	s_waitcnt lgkmcnt(0)
	s_barrier
	s_setprio 1
	s_waitcnt lgkmcnt(0)
	v_mfma_f32_16x16x32_bf16 v[60:63], v[146:149], v[186:189], v[60:63]
	v_mfma_f32_16x16x32_bf16 v[56:59], v[162:165], v[186:189], v[56:59]
	v_mfma_f32_16x16x32_bf16 v[44:47], v[146:149], v[194:197], v[44:47]
	v_mfma_f32_16x16x32_bf16 v[40:43], v[162:165], v[194:197], v[40:43]
	v_mfma_f32_16x16x32_bf16 v[28:31], v[146:149], v[202:205], v[28:31]
	v_mfma_f32_16x16x32_bf16 v[24:27], v[162:165], v[202:205], v[24:27]
	v_mfma_f32_16x16x32_bf16 v[12:15], v[146:149], v[210:213], v[12:15]
	v_mfma_f32_16x16x32_bf16 v[8:11], v[162:165], v[210:213], v[8:11]
	v_mfma_f32_16x16x32_bf16 v[60:63], v[158:161], v[190:193], v[60:63]
	v_mfma_f32_16x16x32_bf16 v[56:59], v[166:169], v[190:193], v[56:59]
	v_mfma_f32_16x16x32_bf16 v[44:47], v[158:161], v[198:201], v[44:47]
	v_mfma_f32_16x16x32_bf16 v[40:43], v[166:169], v[198:201], v[40:43]
	v_mfma_f32_16x16x32_bf16 v[28:31], v[158:161], v[206:209], v[28:31]
	v_mfma_f32_16x16x32_bf16 v[24:27], v[166:169], v[206:209], v[24:27]
	v_mfma_f32_16x16x32_bf16 v[12:15], v[158:161], v[214:217], v[12:15]
	v_mfma_f32_16x16x32_bf16 v[8:11], v[166:169], v[214:217], v[8:11]
	v_mfma_f32_16x16x32_bf16 v[52:55], v[170:173], v[186:189], v[52:55]
	v_mfma_f32_16x16x32_bf16 v[48:51], v[178:181], v[186:189], v[48:51]
	v_mfma_f32_16x16x32_bf16 v[36:39], v[170:173], v[194:197], v[36:39]
	v_mfma_f32_16x16x32_bf16 v[32:35], v[178:181], v[194:197], v[32:35]
	v_mfma_f32_16x16x32_bf16 v[20:23], v[170:173], v[202:205], v[20:23]
	v_mfma_f32_16x16x32_bf16 v[16:19], v[178:181], v[202:205], v[16:19]
	v_mfma_f32_16x16x32_bf16 v[4:7], v[170:173], v[210:213], v[4:7]
	v_mfma_f32_16x16x32_bf16 v[0:3], v[178:181], v[210:213], v[0:3]
	v_mfma_f32_16x16x32_bf16 v[52:55], v[174:177], v[190:193], v[52:55]
	v_mfma_f32_16x16x32_bf16 v[48:51], v[182:185], v[190:193], v[48:51]
	v_mfma_f32_16x16x32_bf16 v[36:39], v[174:177], v[198:201], v[36:39]
	v_mfma_f32_16x16x32_bf16 v[32:35], v[182:185], v[198:201], v[32:35]
	v_mfma_f32_16x16x32_bf16 v[20:23], v[174:177], v[206:209], v[20:23]
	v_mfma_f32_16x16x32_bf16 v[16:19], v[182:185], v[206:209], v[16:19]
	v_mfma_f32_16x16x32_bf16 v[4:7], v[174:177], v[214:217], v[4:7]
	v_mfma_f32_16x16x32_bf16 v[0:3], v[182:185], v[214:217], v[0:3]
	s_setprio 0
	s_cmp_eq_u32 s62, s98
	s_cbranch_scc1 .Lmy_nobar_17
	s_barrier

.Lmy_nobar2_18:
	ds_read_b128 v[146:149], v153
	ds_read_b128 v[158:161], v153 offset:1024
	ds_read_b128 v[162:165], v153 offset:2048
	ds_read_b128 v[166:169], v153 offset:3072
	ds_read_b128 v[170:173], v154
	ds_read_b128 v[174:177], v154 offset:1024
	ds_read_b128 v[178:181], v154 offset:2048
	ds_read_b128 v[182:185], v154 offset:3072
	s_add_u32 s34, s30, 0xfff50080
	s_addc_u32 s35, s31, -1
	s_cmp_eq_u32 s58, 40
	s_cselect_b32 s39, s1, s35
	s_cselect_b32 s38, s0, s34
	s_cselect_b32 s37, s29, s57
	s_cselect_b32 s36, s28, s13
	v_lshl_add_u64 v[218:219], s[30:31], 0, v[138:139]
	s_add_i32 m0, s42, 0xc000
	ds_read_b128 v[186:189], v155
	ds_read_b128 v[190:193], v155 offset:1024
	ds_read_b128 v[194:197], v155 offset:2048
	ds_read_b128 v[198:201], v155 offset:3072
	ds_read_b128 v[202:205], v155 offset:4096
	ds_read_b128 v[206:209], v155 offset:5120
	ds_read_b128 v[210:213], v155 offset:6144
	ds_read_b128 v[214:217], v155 offset:7168
	global_load_lds_dwordx4 v[218:219], off
	s_add_i32 m0, s42, 0xe000
	v_lshl_add_u64 v[218:219], s[30:31], 0, v[140:141]
	global_load_lds_dwordx4 v[218:219], off
	s_waitcnt vmcnt(8)
	s_waitcnt lgkmcnt(0)
	s_barrier
	s_setprio 1
	s_waitcnt lgkmcnt(0)
	v_mfma_f32_16x16x32_bf16 v[124:127], v[146:149], v[186:189], 0
	v_mfma_f32_16x16x32_bf16 v[120:123], v[162:165], v[186:189], 0
	v_mfma_f32_16x16x32_bf16 v[108:111], v[146:149], v[194:197], 0
	v_mfma_f32_16x16x32_bf16 v[104:107], v[162:165], v[194:197], 0
	v_mfma_f32_16x16x32_bf16 v[92:95], v[146:149], v[202:205], 0
	v_mfma_f32_16x16x32_bf16 v[88:91], v[162:165], v[202:205], 0
	v_mfma_f32_16x16x32_bf16 v[76:79], v[146:149], v[210:213], 0
	v_mfma_f32_16x16x32_bf16 v[72:75], v[162:165], v[210:213], 0
	v_mfma_f32_16x16x32_bf16 v[124:127], v[158:161], v[190:193], v[124:127]
	v_mfma_f32_16x16x32_bf16 v[120:123], v[166:169], v[190:193], v[120:123]
	v_mfma_f32_16x16x32_bf16 v[108:111], v[158:161], v[198:201], v[108:111]
	v_mfma_f32_16x16x32_bf16 v[104:107], v[166:169], v[198:201], v[104:107]
	v_mfma_f32_16x16x32_bf16 v[92:95], v[158:161], v[206:209], v[92:95]
	v_mfma_f32_16x16x32_bf16 v[88:91], v[166:169], v[206:209], v[88:91]
	v_mfma_f32_16x16x32_bf16 v[76:79], v[158:161], v[214:217], v[76:79]
	v_mfma_f32_16x16x32_bf16 v[72:75], v[166:169], v[214:217], v[72:75]
	v_mfma_f32_16x16x32_bf16 v[116:119], v[170:173], v[186:189], 0
	v_mfma_f32_16x16x32_bf16 v[112:115], v[178:181], v[186:189], 0
	v_mfma_f32_16x16x32_bf16 v[100:103], v[170:173], v[194:197], 0
	v_mfma_f32_16x16x32_bf16 v[96:99], v[178:181], v[194:197], 0
	v_mfma_f32_16x16x32_bf16 v[84:87], v[170:173], v[202:205], 0
	v_mfma_f32_16x16x32_bf16 v[80:83], v[178:181], v[202:205], 0
	v_mfma_f32_16x16x32_bf16 v[68:71], v[170:173], v[210:213], 0
	v_mfma_f32_16x16x32_bf16 v[64:67], v[178:181], v[210:213], 0
	v_mfma_f32_16x16x32_bf16 v[116:119], v[174:177], v[190:193], v[116:119]
	v_mfma_f32_16x16x32_bf16 v[112:115], v[182:185], v[190:193], v[112:115]
	v_mfma_f32_16x16x32_bf16 v[100:103], v[174:177], v[198:201], v[100:103]
	v_mfma_f32_16x16x32_bf16 v[96:99], v[182:185], v[198:201], v[96:99]
	v_mfma_f32_16x16x32_bf16 v[84:87], v[174:177], v[206:209], v[84:87]
	v_mfma_f32_16x16x32_bf16 v[80:83], v[182:185], v[206:209], v[80:83]
	v_mfma_f32_16x16x32_bf16 v[68:71], v[174:177], v[214:217], v[68:71]
	v_mfma_f32_16x16x32_bf16 v[64:67], v[182:185], v[214:217], v[64:67]
	s_setprio 0
	s_barrier
	s_add_i32 s34, s52, s41
	v_lshl_add_u64 v[218:219], s[36:37], 0, v[132:133]
	s_mov_b32 m0, s34
	ds_read_b128 v[186:189], v155 offset:16384
	ds_read_b128 v[190:193], v155 offset:17408
	ds_read_b128 v[194:197], v155 offset:18432
	ds_read_b128 v[198:201], v155 offset:19456
	ds_read_b128 v[202:205], v155 offset:20480
	ds_read_b128 v[206:209], v155 offset:21504
	ds_read_b128 v[210:213], v155 offset:22528
	ds_read_b128 v[214:217], v155 offset:23552
	global_load_lds_dwordx4 v[218:219], off
	s_add_i32 m0, s34, 0x2000
	s_add_u32 s34, s36, 0xb0000
	v_lshl_add_u64 v[220:221], s[36:37], 0, v[136:137]
	s_addc_u32 s35, s37, 0
	s_add_i32 s59, s53, s41
	global_load_lds_dwordx4 v[220:221], off
	v_lshl_add_u64 v[222:223], s[34:35], 0, v[132:133]
	s_mov_b32 m0, s59
	v_lshl_add_u64 v[224:225], s[38:39], 0, v[134:135]
	global_load_lds_dwordx4 v[222:223], off
	s_add_i32 m0, s59, 0x2000
	v_lshl_add_u64 v[222:223], s[34:35], 0, v[136:137]
	global_load_lds_dwordx4 v[222:223], off
	s_mov_b32 m0, s42
	v_lshl_add_u64 v[222:223], s[38:39], 0, v[130:131]
	global_load_lds_dwordx4 v[222:223], off
	s_mov_b32 m0, s43
	s_nop 0
	global_load_lds_dwordx4 v[224:225], off
	s_waitcnt vmcnt(8)
	s_waitcnt lgkmcnt(0)
	s_barrier
	s_setprio 1
	s_waitcnt lgkmcnt(0)
	v_mfma_f32_16x16x32_bf16 v[60:63], v[146:149], v[186:189], 0
	v_mfma_f32_16x16x32_bf16 v[56:59], v[162:165], v[186:189], 0
	v_mfma_f32_16x16x32_bf16 v[44:47], v[146:149], v[194:197], 0
	v_mfma_f32_16x16x32_bf16 v[40:43], v[162:165], v[194:197], 0
	v_mfma_f32_16x16x32_bf16 v[28:31], v[146:149], v[202:205], 0
	v_mfma_f32_16x16x32_bf16 v[24:27], v[162:165], v[202:205], 0
	v_mfma_f32_16x16x32_bf16 v[12:15], v[146:149], v[210:213], 0
	v_mfma_f32_16x16x32_bf16 v[8:11], v[162:165], v[210:213], 0
	v_mfma_f32_16x16x32_bf16 v[60:63], v[158:161], v[190:193], v[60:63]
	v_mfma_f32_16x16x32_bf16 v[56:59], v[166:169], v[190:193], v[56:59]
	v_mfma_f32_16x16x32_bf16 v[44:47], v[158:161], v[198:201], v[44:47]
	v_mfma_f32_16x16x32_bf16 v[40:43], v[166:169], v[198:201], v[40:43]
	v_mfma_f32_16x16x32_bf16 v[28:31], v[158:161], v[206:209], v[28:31]
	v_mfma_f32_16x16x32_bf16 v[24:27], v[166:169], v[206:209], v[24:27]
	v_mfma_f32_16x16x32_bf16 v[12:15], v[158:161], v[214:217], v[12:15]
	v_mfma_f32_16x16x32_bf16 v[8:11], v[166:169], v[214:217], v[8:11]
	v_mfma_f32_16x16x32_bf16 v[52:55], v[170:173], v[186:189], 0
	v_mfma_f32_16x16x32_bf16 v[48:51], v[178:181], v[186:189], 0
	v_mfma_f32_16x16x32_bf16 v[36:39], v[170:173], v[194:197], 0
	v_mfma_f32_16x16x32_bf16 v[32:35], v[178:181], v[194:197], 0
	v_mfma_f32_16x16x32_bf16 v[20:23], v[170:173], v[202:205], 0
	v_mfma_f32_16x16x32_bf16 v[16:19], v[178:181], v[202:205], 0
	v_mfma_f32_16x16x32_bf16 v[4:7], v[170:173], v[210:213], 0
	v_mfma_f32_16x16x32_bf16 v[0:3], v[178:181], v[210:213], 0
	v_mfma_f32_16x16x32_bf16 v[52:55], v[174:177], v[190:193], v[52:55]
	v_mfma_f32_16x16x32_bf16 v[48:51], v[182:185], v[190:193], v[48:51]
	v_mfma_f32_16x16x32_bf16 v[36:39], v[174:177], v[198:201], v[36:39]
	v_mfma_f32_16x16x32_bf16 v[32:35], v[182:185], v[198:201], v[32:35]
	v_mfma_f32_16x16x32_bf16 v[20:23], v[174:177], v[206:209], v[20:23]
	v_mfma_f32_16x16x32_bf16 v[16:19], v[182:185], v[206:209], v[16:19]
	v_mfma_f32_16x16x32_bf16 v[4:7], v[174:177], v[214:217], v[4:7]
	v_mfma_f32_16x16x32_bf16 v[0:3], v[182:185], v[214:217], v[0:3]
	s_setprio 0
	s_barrier
	s_add_i32 s59, 0, 0x18000
	s_add_i32 s60, 0, 0x1c000
	v_add_u32_e32 v166, s59, v151
	v_add_u32_e32 v182, s60, v151
	ds_read_b128 v[146:149], v166
	ds_read_b128 v[158:161], v166 offset:1024
	ds_read_b128 v[162:165], v166 offset:2048
	ds_read_b128 v[166:169], v166 offset:3072
	ds_read_b128 v[170:173], v182
	ds_read_b128 v[174:177], v182 offset:1024
	ds_read_b128 v[178:181], v182 offset:2048
	ds_read_b128 v[182:185], v182 offset:3072
	s_add_u32 s34, s38, 0xb0000
	s_addc_u32 s35, s39, 0
	s_mov_b32 m0, s44
	v_lshl_add_u64 v[226:227], s[34:35], 0, v[130:131]
	ds_read_b128 v[186:189], v155 offset:32768
	ds_read_b128 v[190:193], v155 offset:33792
	ds_read_b128 v[194:197], v155 offset:34816
	ds_read_b128 v[198:201], v155 offset:35840
	ds_read_b128 v[202:205], v155 offset:36864
	ds_read_b128 v[206:209], v155 offset:37888
	ds_read_b128 v[210:213], v155 offset:38912
	ds_read_b128 v[214:217], v155 offset:39936
	global_load_lds_dwordx4 v[226:227], off
	s_mov_b32 m0, s45
	v_lshl_add_u64 v[226:227], s[34:35], 0, v[134:135]
	global_load_lds_dwordx4 v[226:227], off
	s_waitcnt vmcnt(8)
	s_waitcnt lgkmcnt(0)
	s_barrier
	s_setprio 1
	s_waitcnt lgkmcnt(0)
	v_mfma_f32_16x16x32_bf16 v[124:127], v[146:149], v[186:189], v[124:127]
	v_mfma_f32_16x16x32_bf16 v[120:123], v[162:165], v[186:189], v[120:123]
	v_mfma_f32_16x16x32_bf16 v[108:111], v[146:149], v[194:197], v[108:111]
	v_mfma_f32_16x16x32_bf16 v[104:107], v[162:165], v[194:197], v[104:107]
	v_mfma_f32_16x16x32_bf16 v[92:95], v[146:149], v[202:205], v[92:95]
	v_mfma_f32_16x16x32_bf16 v[88:91], v[162:165], v[202:205], v[88:91]
	v_mfma_f32_16x16x32_bf16 v[76:79], v[146:149], v[210:213], v[76:79]
	v_mfma_f32_16x16x32_bf16 v[72:75], v[162:165], v[210:213], v[72:75]
	v_mfma_f32_16x16x32_bf16 v[124:127], v[158:161], v[190:193], v[124:127]
	v_mfma_f32_16x16x32_bf16 v[120:123], v[166:169], v[190:193], v[120:123]
	v_mfma_f32_16x16x32_bf16 v[108:111], v[158:161], v[198:201], v[108:111]
	v_mfma_f32_16x16x32_bf16 v[104:107], v[166:169], v[198:201], v[104:107]
	v_mfma_f32_16x16x32_bf16 v[92:95], v[158:161], v[206:209], v[92:95]
	v_mfma_f32_16x16x32_bf16 v[88:91], v[166:169], v[206:209], v[88:91]
	v_mfma_f32_16x16x32_bf16 v[76:79], v[158:161], v[214:217], v[76:79]
	v_mfma_f32_16x16x32_bf16 v[72:75], v[166:169], v[214:217], v[72:75]
	v_mfma_f32_16x16x32_bf16 v[116:119], v[170:173], v[186:189], v[116:119]
	v_mfma_f32_16x16x32_bf16 v[112:115], v[178:181], v[186:189], v[112:115]
	v_mfma_f32_16x16x32_bf16 v[100:103], v[170:173], v[194:197], v[100:103]
	v_mfma_f32_16x16x32_bf16 v[96:99], v[178:181], v[194:197], v[96:99]
	v_mfma_f32_16x16x32_bf16 v[84:87], v[170:173], v[202:205], v[84:87]
	v_mfma_f32_16x16x32_bf16 v[80:83], v[178:181], v[202:205], v[80:83]
	v_mfma_f32_16x16x32_bf16 v[68:71], v[170:173], v[210:213], v[68:71]
	v_mfma_f32_16x16x32_bf16 v[64:67], v[178:181], v[210:213], v[64:67]
	v_mfma_f32_16x16x32_bf16 v[116:119], v[174:177], v[190:193], v[116:119]
	v_mfma_f32_16x16x32_bf16 v[112:115], v[182:185], v[190:193], v[112:115]
	v_mfma_f32_16x16x32_bf16 v[100:103], v[174:177], v[198:201], v[100:103]
	v_mfma_f32_16x16x32_bf16 v[96:99], v[182:185], v[198:201], v[96:99]
	v_mfma_f32_16x16x32_bf16 v[84:87], v[174:177], v[206:209], v[84:87]
	v_mfma_f32_16x16x32_bf16 v[80:83], v[182:185], v[206:209], v[80:83]
	v_mfma_f32_16x16x32_bf16 v[68:71], v[174:177], v[214:217], v[68:71]
	v_mfma_f32_16x16x32_bf16 v[64:67], v[182:185], v[214:217], v[64:67]
	s_setprio 0
	s_barrier
	s_add_i32 s34, s59, s41
	v_lshl_add_u64 v[218:219], v[218:219], 0, s[22:23]
	s_mov_b32 m0, s34
	ds_read_b128 v[186:189], v155 offset:49152
	ds_read_b128 v[190:193], v155 offset:50176
	ds_read_b128 v[194:197], v155 offset:51200
	ds_read_b128 v[198:201], v155 offset:52224
	ds_read_b128 v[202:205], v155 offset:53248
	ds_read_b128 v[206:209], v155 offset:54272
	ds_read_b128 v[210:213], v155 offset:55296
	ds_read_b128 v[214:217], v155 offset:56320
	global_load_lds_dwordx4 v[218:219], off
	s_add_i32 m0, s34, 0x2000
	s_add_u32 s34, s36, 0xb0080
	v_lshl_add_u64 v[218:219], v[220:221], 0, s[22:23]
	s_addc_u32 s35, s37, 0
	s_add_i32 s36, s60, s41
	global_load_lds_dwordx4 v[218:219], off
	s_mov_b32 m0, s36
	v_lshl_add_u64 v[218:219], s[34:35], 0, v[132:133]
	global_load_lds_dwordx4 v[218:219], off
	s_add_i32 m0, s36, 0x2000
	v_lshl_add_u64 v[218:219], s[34:35], 0, v[136:137]
	global_load_lds_dwordx4 v[218:219], off
	s_mov_b32 m0, s47
	v_lshl_add_u64 v[218:219], v[222:223], 0, s[22:23]
	global_load_lds_dwordx4 v[218:219], off
	s_mov_b32 m0, s48
	v_lshl_add_u64 v[218:219], v[224:225], 0, s[22:23]
	global_load_lds_dwordx4 v[218:219], off
	s_waitcnt vmcnt(8)
	s_waitcnt lgkmcnt(0)
	s_barrier
	s_setprio 1
	s_waitcnt lgkmcnt(0)
	v_mfma_f32_16x16x32_bf16 v[60:63], v[146:149], v[186:189], v[60:63]
	v_mfma_f32_16x16x32_bf16 v[56:59], v[162:165], v[186:189], v[56:59]
	v_mfma_f32_16x16x32_bf16 v[44:47], v[146:149], v[194:197], v[44:47]
	v_mfma_f32_16x16x32_bf16 v[40:43], v[162:165], v[194:197], v[40:43]
	v_mfma_f32_16x16x32_bf16 v[28:31], v[146:149], v[202:205], v[28:31]
	v_mfma_f32_16x16x32_bf16 v[24:27], v[162:165], v[202:205], v[24:27]
	v_mfma_f32_16x16x32_bf16 v[12:15], v[146:149], v[210:213], v[12:15]
	v_mfma_f32_16x16x32_bf16 v[8:11], v[162:165], v[210:213], v[8:11]
	v_mfma_f32_16x16x32_bf16 v[60:63], v[158:161], v[190:193], v[60:63]
	v_mfma_f32_16x16x32_bf16 v[56:59], v[166:169], v[190:193], v[56:59]
	v_mfma_f32_16x16x32_bf16 v[44:47], v[158:161], v[198:201], v[44:47]
	v_mfma_f32_16x16x32_bf16 v[40:43], v[166:169], v[198:201], v[40:43]
	v_mfma_f32_16x16x32_bf16 v[28:31], v[158:161], v[206:209], v[28:31]
	v_mfma_f32_16x16x32_bf16 v[24:27], v[166:169], v[206:209], v[24:27]
	v_mfma_f32_16x16x32_bf16 v[12:15], v[158:161], v[214:217], v[12:15]
	v_mfma_f32_16x16x32_bf16 v[8:11], v[166:169], v[214:217], v[8:11]
	v_mfma_f32_16x16x32_bf16 v[52:55], v[170:173], v[186:189], v[52:55]
	v_mfma_f32_16x16x32_bf16 v[48:51], v[178:181], v[186:189], v[48:51]
	v_mfma_f32_16x16x32_bf16 v[36:39], v[170:173], v[194:197], v[36:39]
	v_mfma_f32_16x16x32_bf16 v[32:35], v[178:181], v[194:197], v[32:35]
	v_mfma_f32_16x16x32_bf16 v[20:23], v[170:173], v[202:205], v[20:23]
	v_mfma_f32_16x16x32_bf16 v[16:19], v[178:181], v[202:205], v[16:19]
	v_mfma_f32_16x16x32_bf16 v[4:7], v[170:173], v[210:213], v[4:7]
	v_mfma_f32_16x16x32_bf16 v[0:3], v[178:181], v[210:213], v[0:3]
	v_mfma_f32_16x16x32_bf16 v[52:55], v[174:177], v[190:193], v[52:55]
	v_mfma_f32_16x16x32_bf16 v[48:51], v[182:185], v[190:193], v[48:51]
	v_mfma_f32_16x16x32_bf16 v[36:39], v[174:177], v[198:201], v[36:39]
	v_mfma_f32_16x16x32_bf16 v[32:35], v[182:185], v[198:201], v[32:35]
	v_mfma_f32_16x16x32_bf16 v[20:23], v[174:177], v[206:209], v[20:23]
	v_mfma_f32_16x16x32_bf16 v[16:19], v[182:185], v[206:209], v[16:19]
	v_mfma_f32_16x16x32_bf16 v[4:7], v[174:177], v[214:217], v[4:7]
	v_mfma_f32_16x16x32_bf16 v[0:3], v[182:185], v[214:217], v[0:3]
	s_setprio 0
	s_barrier
	s_add_i32 s58, s58, 2
	s_add_u32 s30, s30, 0x100
	s_addc_u32 s31, s31, 0
	s_add_u32 s13, s13, 0x100
	s_addc_u32 s57, s57, 0
.LBB0_1733:
	ds_read_b128 v[146:149], v153
	ds_read_b128 v[158:161], v153 offset:1024
	ds_read_b128 v[162:165], v153 offset:2048
	ds_read_b128 v[166:169], v153 offset:3072
	ds_read_b128 v[170:173], v154
	ds_read_b128 v[174:177], v154 offset:1024
	ds_read_b128 v[178:181], v154 offset:2048
	ds_read_b128 v[182:185], v154 offset:3072
	s_add_u32 s34, s30, 0xfff50080
	s_addc_u32 s35, s31, -1
	s_cmp_eq_u32 s58, 40
	s_cselect_b32 s39, s1, s35
	s_cselect_b32 s38, s0, s34
	s_cselect_b32 s37, s29, s57
	s_cselect_b32 s36, s28, s13
	v_lshl_add_u64 v[218:219], s[30:31], 0, v[138:139]
	s_add_i32 m0, s42, 0xc000
	ds_read_b128 v[186:189], v155
	ds_read_b128 v[190:193], v155 offset:1024
	ds_read_b128 v[194:197], v155 offset:2048
	ds_read_b128 v[198:201], v155 offset:3072
	ds_read_b128 v[202:205], v155 offset:4096
	ds_read_b128 v[206:209], v155 offset:5120
	ds_read_b128 v[210:213], v155 offset:6144
	ds_read_b128 v[214:217], v155 offset:7168
	global_load_lds_dwordx4 v[218:219], off
	s_add_i32 m0, s42, 0xe000
	v_lshl_add_u64 v[218:219], s[30:31], 0, v[140:141]
	global_load_lds_dwordx4 v[218:219], off
	s_waitcnt vmcnt(8)
	s_waitcnt lgkmcnt(0)
	s_barrier
	s_setprio 1
	s_waitcnt lgkmcnt(0)
	v_mfma_f32_16x16x32_bf16 v[124:127], v[146:149], v[186:189], v[124:127]
	v_mfma_f32_16x16x32_bf16 v[120:123], v[162:165], v[186:189], v[120:123]
	v_mfma_f32_16x16x32_bf16 v[108:111], v[146:149], v[194:197], v[108:111]
	v_mfma_f32_16x16x32_bf16 v[104:107], v[162:165], v[194:197], v[104:107]
	v_mfma_f32_16x16x32_bf16 v[92:95], v[146:149], v[202:205], v[92:95]
	v_mfma_f32_16x16x32_bf16 v[88:91], v[162:165], v[202:205], v[88:91]
	v_mfma_f32_16x16x32_bf16 v[76:79], v[146:149], v[210:213], v[76:79]
	v_mfma_f32_16x16x32_bf16 v[72:75], v[162:165], v[210:213], v[72:75]
	v_mfma_f32_16x16x32_bf16 v[124:127], v[158:161], v[190:193], v[124:127]
	v_mfma_f32_16x16x32_bf16 v[120:123], v[166:169], v[190:193], v[120:123]
	v_mfma_f32_16x16x32_bf16 v[108:111], v[158:161], v[198:201], v[108:111]
	v_mfma_f32_16x16x32_bf16 v[104:107], v[166:169], v[198:201], v[104:107]
	v_mfma_f32_16x16x32_bf16 v[92:95], v[158:161], v[206:209], v[92:95]
	v_mfma_f32_16x16x32_bf16 v[88:91], v[166:169], v[206:209], v[88:91]
	v_mfma_f32_16x16x32_bf16 v[76:79], v[158:161], v[214:217], v[76:79]
	v_mfma_f32_16x16x32_bf16 v[72:75], v[166:169], v[214:217], v[72:75]
	v_mfma_f32_16x16x32_bf16 v[116:119], v[170:173], v[186:189], v[116:119]
	v_mfma_f32_16x16x32_bf16 v[112:115], v[178:181], v[186:189], v[112:115]
	v_mfma_f32_16x16x32_bf16 v[100:103], v[170:173], v[194:197], v[100:103]
	v_mfma_f32_16x16x32_bf16 v[96:99], v[178:181], v[194:197], v[96:99]
	v_mfma_f32_16x16x32_bf16 v[84:87], v[170:173], v[202:205], v[84:87]
	v_mfma_f32_16x16x32_bf16 v[80:83], v[178:181], v[202:205], v[80:83]
	v_mfma_f32_16x16x32_bf16 v[68:71], v[170:173], v[210:213], v[68:71]
	v_mfma_f32_16x16x32_bf16 v[64:67], v[178:181], v[210:213], v[64:67]
	v_mfma_f32_16x16x32_bf16 v[116:119], v[174:177], v[190:193], v[116:119]
	v_mfma_f32_16x16x32_bf16 v[112:115], v[182:185], v[190:193], v[112:115]
	v_mfma_f32_16x16x32_bf16 v[100:103], v[174:177], v[198:201], v[100:103]
	v_mfma_f32_16x16x32_bf16 v[96:99], v[182:185], v[198:201], v[96:99]
	v_mfma_f32_16x16x32_bf16 v[84:87], v[174:177], v[206:209], v[84:87]
	v_mfma_f32_16x16x32_bf16 v[80:83], v[182:185], v[206:209], v[80:83]
	v_mfma_f32_16x16x32_bf16 v[68:71], v[174:177], v[214:217], v[68:71]
	v_mfma_f32_16x16x32_bf16 v[64:67], v[182:185], v[214:217], v[64:67]
	s_setprio 0
	s_barrier
	s_add_i32 s34, s52, s41
	v_lshl_add_u64 v[218:219], s[36:37], 0, v[132:133]
	s_mov_b32 m0, s34
	ds_read_b128 v[186:189], v155 offset:16384
	ds_read_b128 v[190:193], v155 offset:17408
	ds_read_b128 v[194:197], v155 offset:18432
	ds_read_b128 v[198:201], v155 offset:19456
	ds_read_b128 v[202:205], v155 offset:20480
	ds_read_b128 v[206:209], v155 offset:21504
	ds_read_b128 v[210:213], v155 offset:22528
	ds_read_b128 v[214:217], v155 offset:23552
	global_load_lds_dwordx4 v[218:219], off
	s_add_i32 m0, s34, 0x2000
	s_add_u32 s34, s36, 0xb0000
	v_lshl_add_u64 v[220:221], s[36:37], 0, v[136:137]
	s_addc_u32 s35, s37, 0
	s_add_i32 s59, s53, s41
	global_load_lds_dwordx4 v[220:221], off
	v_lshl_add_u64 v[222:223], s[34:35], 0, v[132:133]
	s_mov_b32 m0, s59
	v_lshl_add_u64 v[224:225], s[38:39], 0, v[134:135]
	global_load_lds_dwordx4 v[222:223], off
	s_add_i32 m0, s59, 0x2000
	v_lshl_add_u64 v[222:223], s[34:35], 0, v[136:137]
	global_load_lds_dwordx4 v[222:223], off
	s_mov_b32 m0, s42
	v_lshl_add_u64 v[222:223], s[38:39], 0, v[130:131]
	global_load_lds_dwordx4 v[222:223], off
	s_mov_b32 m0, s43
	s_nop 0
	global_load_lds_dwordx4 v[224:225], off
	s_waitcnt vmcnt(8)
	s_waitcnt lgkmcnt(0)
	s_barrier
	s_setprio 1
	s_waitcnt lgkmcnt(0)
	v_mfma_f32_16x16x32_bf16 v[60:63], v[146:149], v[186:189], v[60:63]
	v_mfma_f32_16x16x32_bf16 v[56:59], v[162:165], v[186:189], v[56:59]
	v_mfma_f32_16x16x32_bf16 v[44:47], v[146:149], v[194:197], v[44:47]
	v_mfma_f32_16x16x32_bf16 v[40:43], v[162:165], v[194:197], v[40:43]
	v_mfma_f32_16x16x32_bf16 v[28:31], v[146:149], v[202:205], v[28:31]
	v_mfma_f32_16x16x32_bf16 v[24:27], v[162:165], v[202:205], v[24:27]
	v_mfma_f32_16x16x32_bf16 v[12:15], v[146:149], v[210:213], v[12:15]
	v_mfma_f32_16x16x32_bf16 v[8:11], v[162:165], v[210:213], v[8:11]
	v_mfma_f32_16x16x32_bf16 v[60:63], v[158:161], v[190:193], v[60:63]
	v_mfma_f32_16x16x32_bf16 v[56:59], v[166:169], v[190:193], v[56:59]
	v_mfma_f32_16x16x32_bf16 v[44:47], v[158:161], v[198:201], v[44:47]
	v_mfma_f32_16x16x32_bf16 v[40:43], v[166:169], v[198:201], v[40:43]
	v_mfma_f32_16x16x32_bf16 v[28:31], v[158:161], v[206:209], v[28:31]
	v_mfma_f32_16x16x32_bf16 v[24:27], v[166:169], v[206:209], v[24:27]
	v_mfma_f32_16x16x32_bf16 v[12:15], v[158:161], v[214:217], v[12:15]
	v_mfma_f32_16x16x32_bf16 v[8:11], v[166:169], v[214:217], v[8:11]
	v_mfma_f32_16x16x32_bf16 v[52:55], v[170:173], v[186:189], v[52:55]
	v_mfma_f32_16x16x32_bf16 v[48:51], v[178:181], v[186:189], v[48:51]
	v_mfma_f32_16x16x32_bf16 v[36:39], v[170:173], v[194:197], v[36:39]
	v_mfma_f32_16x16x32_bf16 v[32:35], v[178:181], v[194:197], v[32:35]
	v_mfma_f32_16x16x32_bf16 v[20:23], v[170:173], v[202:205], v[20:23]
	v_mfma_f32_16x16x32_bf16 v[16:19], v[178:181], v[202:205], v[16:19]
	v_mfma_f32_16x16x32_bf16 v[4:7], v[170:173], v[210:213], v[4:7]
	v_mfma_f32_16x16x32_bf16 v[0:3], v[178:181], v[210:213], v[0:3]
	v_mfma_f32_16x16x32_bf16 v[52:55], v[174:177], v[190:193], v[52:55]
	v_mfma_f32_16x16x32_bf16 v[48:51], v[182:185], v[190:193], v[48:51]
	v_mfma_f32_16x16x32_bf16 v[36:39], v[174:177], v[198:201], v[36:39]
	v_mfma_f32_16x16x32_bf16 v[32:35], v[182:185], v[198:201], v[32:35]
	v_mfma_f32_16x16x32_bf16 v[20:23], v[174:177], v[206:209], v[20:23]
	v_mfma_f32_16x16x32_bf16 v[16:19], v[182:185], v[206:209], v[16:19]
	v_mfma_f32_16x16x32_bf16 v[4:7], v[174:177], v[214:217], v[4:7]
	v_mfma_f32_16x16x32_bf16 v[0:3], v[182:185], v[214:217], v[0:3]
	s_setprio 0
	s_barrier
	s_add_i32 s59, 0, 0x18000
	s_add_i32 s60, 0, 0x1c000
	v_add_u32_e32 v166, s59, v151
	v_add_u32_e32 v182, s60, v151
	ds_read_b128 v[146:149], v166
	ds_read_b128 v[158:161], v166 offset:1024
	ds_read_b128 v[162:165], v166 offset:2048
	ds_read_b128 v[166:169], v166 offset:3072
	ds_read_b128 v[170:173], v182
	ds_read_b128 v[174:177], v182 offset:1024
	ds_read_b128 v[178:181], v182 offset:2048
	ds_read_b128 v[182:185], v182 offset:3072
	s_add_u32 s34, s38, 0xb0000
	s_addc_u32 s35, s39, 0
	s_mov_b32 m0, s44
	v_lshl_add_u64 v[226:227], s[34:35], 0, v[130:131]
	ds_read_b128 v[186:189], v155 offset:32768
	ds_read_b128 v[190:193], v155 offset:33792
	ds_read_b128 v[194:197], v155 offset:34816
	ds_read_b128 v[198:201], v155 offset:35840
	ds_read_b128 v[202:205], v155 offset:36864
	ds_read_b128 v[206:209], v155 offset:37888
	ds_read_b128 v[210:213], v155 offset:38912
	ds_read_b128 v[214:217], v155 offset:39936
	global_load_lds_dwordx4 v[226:227], off
	s_mov_b32 m0, s45
	v_lshl_add_u64 v[226:227], s[34:35], 0, v[134:135]
	global_load_lds_dwordx4 v[226:227], off
	s_waitcnt vmcnt(8)
	s_waitcnt lgkmcnt(0)
	s_barrier
	s_setprio 1
	s_waitcnt lgkmcnt(0)
	v_mfma_f32_16x16x32_bf16 v[124:127], v[146:149], v[186:189], v[124:127]
	v_mfma_f32_16x16x32_bf16 v[120:123], v[162:165], v[186:189], v[120:123]
	v_mfma_f32_16x16x32_bf16 v[108:111], v[146:149], v[194:197], v[108:111]
	v_mfma_f32_16x16x32_bf16 v[104:107], v[162:165], v[194:197], v[104:107]
	v_mfma_f32_16x16x32_bf16 v[92:95], v[146:149], v[202:205], v[92:95]
	v_mfma_f32_16x16x32_bf16 v[88:91], v[162:165], v[202:205], v[88:91]
	v_mfma_f32_16x16x32_bf16 v[76:79], v[146:149], v[210:213], v[76:79]
	v_mfma_f32_16x16x32_bf16 v[72:75], v[162:165], v[210:213], v[72:75]
	v_mfma_f32_16x16x32_bf16 v[124:127], v[158:161], v[190:193], v[124:127]
	v_mfma_f32_16x16x32_bf16 v[120:123], v[166:169], v[190:193], v[120:123]
	v_mfma_f32_16x16x32_bf16 v[108:111], v[158:161], v[198:201], v[108:111]
	v_mfma_f32_16x16x32_bf16 v[104:107], v[166:169], v[198:201], v[104:107]
	v_mfma_f32_16x16x32_bf16 v[92:95], v[158:161], v[206:209], v[92:95]
	v_mfma_f32_16x16x32_bf16 v[88:91], v[166:169], v[206:209], v[88:91]
	v_mfma_f32_16x16x32_bf16 v[76:79], v[158:161], v[214:217], v[76:79]
	v_mfma_f32_16x16x32_bf16 v[72:75], v[166:169], v[214:217], v[72:75]
	v_mfma_f32_16x16x32_bf16 v[116:119], v[170:173], v[186:189], v[116:119]
	v_mfma_f32_16x16x32_bf16 v[112:115], v[178:181], v[186:189], v[112:115]
	v_mfma_f32_16x16x32_bf16 v[100:103], v[170:173], v[194:197], v[100:103]
	v_mfma_f32_16x16x32_bf16 v[96:99], v[178:181], v[194:197], v[96:99]
	v_mfma_f32_16x16x32_bf16 v[84:87], v[170:173], v[202:205], v[84:87]
	v_mfma_f32_16x16x32_bf16 v[80:83], v[178:181], v[202:205], v[80:83]
	v_mfma_f32_16x16x32_bf16 v[68:71], v[170:173], v[210:213], v[68:71]
	v_mfma_f32_16x16x32_bf16 v[64:67], v[178:181], v[210:213], v[64:67]
	v_mfma_f32_16x16x32_bf16 v[116:119], v[174:177], v[190:193], v[116:119]
	v_mfma_f32_16x16x32_bf16 v[112:115], v[182:185], v[190:193], v[112:115]
	v_mfma_f32_16x16x32_bf16 v[100:103], v[174:177], v[198:201], v[100:103]
	v_mfma_f32_16x16x32_bf16 v[96:99], v[182:185], v[198:201], v[96:99]
	v_mfma_f32_16x16x32_bf16 v[84:87], v[174:177], v[206:209], v[84:87]
	v_mfma_f32_16x16x32_bf16 v[80:83], v[182:185], v[206:209], v[80:83]
	v_mfma_f32_16x16x32_bf16 v[68:71], v[174:177], v[214:217], v[68:71]
	v_mfma_f32_16x16x32_bf16 v[64:67], v[182:185], v[214:217], v[64:67]
	s_setprio 0
	s_barrier
	s_add_i32 s34, s59, s41
	v_lshl_add_u64 v[218:219], v[218:219], 0, s[22:23]
	s_mov_b32 m0, s34
	ds_read_b128 v[186:189], v155 offset:49152
	ds_read_b128 v[190:193], v155 offset:50176
	ds_read_b128 v[194:197], v155 offset:51200
	ds_read_b128 v[198:201], v155 offset:52224
	ds_read_b128 v[202:205], v155 offset:53248
	ds_read_b128 v[206:209], v155 offset:54272
	ds_read_b128 v[210:213], v155 offset:55296
	ds_read_b128 v[214:217], v155 offset:56320
	global_load_lds_dwordx4 v[218:219], off
	s_add_i32 m0, s34, 0x2000
	s_add_u32 s34, s36, 0xb0080
	v_lshl_add_u64 v[218:219], v[220:221], 0, s[22:23]
	s_addc_u32 s35, s37, 0
	s_add_i32 s36, s60, s41
	global_load_lds_dwordx4 v[218:219], off
	s_mov_b32 m0, s36
	v_lshl_add_u64 v[218:219], s[34:35], 0, v[132:133]
	global_load_lds_dwordx4 v[218:219], off
	s_add_i32 m0, s36, 0x2000
	v_lshl_add_u64 v[218:219], s[34:35], 0, v[136:137]
	global_load_lds_dwordx4 v[218:219], off
	s_mov_b32 m0, s47
	v_lshl_add_u64 v[218:219], v[222:223], 0, s[22:23]
	global_load_lds_dwordx4 v[218:219], off
	s_mov_b32 m0, s48
	v_lshl_add_u64 v[218:219], v[224:225], 0, s[22:23]
	global_load_lds_dwordx4 v[218:219], off
	s_waitcnt vmcnt(8)
	s_waitcnt lgkmcnt(0)
	s_barrier
	s_setprio 1
	s_waitcnt lgkmcnt(0)
	v_mfma_f32_16x16x32_bf16 v[60:63], v[146:149], v[186:189], v[60:63]
	v_mfma_f32_16x16x32_bf16 v[56:59], v[162:165], v[186:189], v[56:59]
	v_mfma_f32_16x16x32_bf16 v[44:47], v[146:149], v[194:197], v[44:47]
	v_mfma_f32_16x16x32_bf16 v[40:43], v[162:165], v[194:197], v[40:43]
	v_mfma_f32_16x16x32_bf16 v[28:31], v[146:149], v[202:205], v[28:31]
	v_mfma_f32_16x16x32_bf16 v[24:27], v[162:165], v[202:205], v[24:27]
	v_mfma_f32_16x16x32_bf16 v[12:15], v[146:149], v[210:213], v[12:15]
	v_mfma_f32_16x16x32_bf16 v[8:11], v[162:165], v[210:213], v[8:11]
	v_mfma_f32_16x16x32_bf16 v[60:63], v[158:161], v[190:193], v[60:63]
	v_mfma_f32_16x16x32_bf16 v[56:59], v[166:169], v[190:193], v[56:59]
	v_mfma_f32_16x16x32_bf16 v[44:47], v[158:161], v[198:201], v[44:47]
	v_mfma_f32_16x16x32_bf16 v[40:43], v[166:169], v[198:201], v[40:43]
	v_mfma_f32_16x16x32_bf16 v[28:31], v[158:161], v[206:209], v[28:31]
	v_mfma_f32_16x16x32_bf16 v[24:27], v[166:169], v[206:209], v[24:27]
	v_mfma_f32_16x16x32_bf16 v[12:15], v[158:161], v[214:217], v[12:15]
	v_mfma_f32_16x16x32_bf16 v[8:11], v[166:169], v[214:217], v[8:11]
	v_mfma_f32_16x16x32_bf16 v[52:55], v[170:173], v[186:189], v[52:55]
	v_mfma_f32_16x16x32_bf16 v[48:51], v[178:181], v[186:189], v[48:51]
	v_mfma_f32_16x16x32_bf16 v[36:39], v[170:173], v[194:197], v[36:39]
	v_mfma_f32_16x16x32_bf16 v[32:35], v[178:181], v[194:197], v[32:35]
	v_mfma_f32_16x16x32_bf16 v[20:23], v[170:173], v[202:205], v[20:23]
	v_mfma_f32_16x16x32_bf16 v[16:19], v[178:181], v[202:205], v[16:19]
	v_mfma_f32_16x16x32_bf16 v[4:7], v[170:173], v[210:213], v[4:7]
	v_mfma_f32_16x16x32_bf16 v[0:3], v[178:181], v[210:213], v[0:3]
	v_mfma_f32_16x16x32_bf16 v[52:55], v[174:177], v[190:193], v[52:55]
	v_mfma_f32_16x16x32_bf16 v[48:51], v[182:185], v[190:193], v[48:51]
	v_mfma_f32_16x16x32_bf16 v[36:39], v[174:177], v[198:201], v[36:39]
	v_mfma_f32_16x16x32_bf16 v[32:35], v[182:185], v[198:201], v[32:35]
	v_mfma_f32_16x16x32_bf16 v[20:23], v[174:177], v[206:209], v[20:23]
	v_mfma_f32_16x16x32_bf16 v[16:19], v[182:185], v[206:209], v[16:19]
	v_mfma_f32_16x16x32_bf16 v[4:7], v[174:177], v[214:217], v[4:7]
	v_mfma_f32_16x16x32_bf16 v[0:3], v[182:185], v[214:217], v[0:3]
	s_setprio 0
	s_cmp_eq_u32 s58, s98
	s_cbranch_scc1 .Lmy_nobar_18
	s_barrier

.Lmy_nobar2_19:
	ds_read_b128 v[150:153], v157
	ds_read_b128 v[160:163], v157 offset:1024
	ds_read_b128 v[164:167], v157 offset:2048
	ds_read_b128 v[168:171], v157 offset:3072
	ds_read_b128 v[172:175], v158
	ds_read_b128 v[176:179], v158 offset:1024
	ds_read_b128 v[180:183], v158 offset:2048
	ds_read_b128 v[184:187], v158 offset:3072
	s_add_u32 s34, s42, 0xfffc0080
	s_addc_u32 s35, s43, -1
	s_cmp_eq_u32 s65, 12
	s_cselect_b32 s47, s7, s35
	s_cselect_b32 s46, s8, s34
	s_cselect_b32 s45, s12, s37
	s_cselect_b32 s44, s13, s31
	v_lshl_add_u64 v[220:221], s[42:43], 0, v[142:143]
	s_add_i32 m0, s53, 0xc000
	ds_read_b128 v[188:191], v159
	ds_read_b128 v[192:195], v159 offset:1024
	ds_read_b128 v[196:199], v159 offset:2048
	ds_read_b128 v[200:203], v159 offset:3072
	ds_read_b128 v[204:207], v159 offset:4096
	ds_read_b128 v[208:211], v159 offset:5120
	ds_read_b128 v[212:215], v159 offset:6144
	ds_read_b128 v[216:219], v159 offset:7168
	global_load_lds_dwordx4 v[220:221], off
	s_add_i32 m0, s53, 0xe000
	v_lshl_add_u64 v[220:221], s[42:43], 0, v[144:145]
	global_load_lds_dwordx4 v[220:221], off
	s_waitcnt vmcnt(8)
	s_waitcnt lgkmcnt(0)
	s_barrier
	s_setprio 1
	s_waitcnt lgkmcnt(0)
	v_mfma_f32_16x16x32_bf16 v[124:127], v[150:153], v[188:191], 0
	v_mfma_f32_16x16x32_bf16 v[120:123], v[164:167], v[188:191], 0
	v_mfma_f32_16x16x32_bf16 v[108:111], v[150:153], v[196:199], 0
	v_mfma_f32_16x16x32_bf16 v[104:107], v[164:167], v[196:199], 0
	v_mfma_f32_16x16x32_bf16 v[92:95], v[150:153], v[204:207], 0
	v_mfma_f32_16x16x32_bf16 v[88:91], v[164:167], v[204:207], 0
	v_mfma_f32_16x16x32_bf16 v[76:79], v[150:153], v[212:215], 0
	v_mfma_f32_16x16x32_bf16 v[72:75], v[164:167], v[212:215], 0
	v_mfma_f32_16x16x32_bf16 v[124:127], v[160:163], v[192:195], v[124:127]
	v_mfma_f32_16x16x32_bf16 v[120:123], v[168:171], v[192:195], v[120:123]
	v_mfma_f32_16x16x32_bf16 v[108:111], v[160:163], v[200:203], v[108:111]
	v_mfma_f32_16x16x32_bf16 v[104:107], v[168:171], v[200:203], v[104:107]
	v_mfma_f32_16x16x32_bf16 v[92:95], v[160:163], v[208:211], v[92:95]
	v_mfma_f32_16x16x32_bf16 v[88:91], v[168:171], v[208:211], v[88:91]
	v_mfma_f32_16x16x32_bf16 v[76:79], v[160:163], v[216:219], v[76:79]
	v_mfma_f32_16x16x32_bf16 v[72:75], v[168:171], v[216:219], v[72:75]
	v_mfma_f32_16x16x32_bf16 v[116:119], v[172:175], v[188:191], 0
	v_mfma_f32_16x16x32_bf16 v[112:115], v[180:183], v[188:191], 0
	v_mfma_f32_16x16x32_bf16 v[100:103], v[172:175], v[196:199], 0
	v_mfma_f32_16x16x32_bf16 v[96:99], v[180:183], v[196:199], 0
	v_mfma_f32_16x16x32_bf16 v[84:87], v[172:175], v[204:207], 0
	v_mfma_f32_16x16x32_bf16 v[80:83], v[180:183], v[204:207], 0
	v_mfma_f32_16x16x32_bf16 v[68:71], v[172:175], v[212:215], 0
	v_mfma_f32_16x16x32_bf16 v[64:67], v[180:183], v[212:215], 0
	v_mfma_f32_16x16x32_bf16 v[116:119], v[176:179], v[192:195], v[116:119]
	v_mfma_f32_16x16x32_bf16 v[112:115], v[184:187], v[192:195], v[112:115]
	v_mfma_f32_16x16x32_bf16 v[100:103], v[176:179], v[200:203], v[100:103]
	v_mfma_f32_16x16x32_bf16 v[96:99], v[184:187], v[200:203], v[96:99]
	v_mfma_f32_16x16x32_bf16 v[84:87], v[176:179], v[208:211], v[84:87]
	v_mfma_f32_16x16x32_bf16 v[80:83], v[184:187], v[208:211], v[80:83]
	v_mfma_f32_16x16x32_bf16 v[68:71], v[176:179], v[216:219], v[68:71]
	v_mfma_f32_16x16x32_bf16 v[64:67], v[184:187], v[216:219], v[64:67]
	s_setprio 0
	s_barrier
	s_add_i32 s34, s61, s50
	v_lshl_add_u64 v[220:221], s[44:45], 0, v[134:135]
	s_mov_b32 m0, s34
	ds_read_b128 v[188:191], v159 offset:16384
	ds_read_b128 v[192:195], v159 offset:17408
	ds_read_b128 v[196:199], v159 offset:18432
	ds_read_b128 v[200:203], v159 offset:19456
	ds_read_b128 v[204:207], v159 offset:20480
	ds_read_b128 v[208:211], v159 offset:21504
	ds_read_b128 v[212:215], v159 offset:22528
	ds_read_b128 v[216:219], v159 offset:23552
	global_load_lds_dwordx4 v[220:221], off
	s_add_i32 m0, s34, 0x2000
	s_add_u32 s34, s44, 0x40000
	v_lshl_add_u64 v[222:223], s[44:45], 0, v[138:139]
	s_addc_u32 s35, s45, 0
	s_add_i32 s66, s62, s50
	global_load_lds_dwordx4 v[222:223], off
	v_lshl_add_u64 v[224:225], s[34:35], 0, v[134:135]
	s_mov_b32 m0, s66
	v_lshl_add_u64 v[226:227], s[46:47], 0, v[136:137]
	global_load_lds_dwordx4 v[224:225], off
	s_add_i32 m0, s66, 0x2000
	v_lshl_add_u64 v[224:225], s[34:35], 0, v[138:139]
	global_load_lds_dwordx4 v[224:225], off
	s_mov_b32 m0, s53
	v_lshl_add_u64 v[224:225], s[46:47], 0, v[132:133]
	global_load_lds_dwordx4 v[224:225], off
	s_mov_b32 m0, s54
	s_nop 0
	global_load_lds_dwordx4 v[226:227], off
	s_waitcnt vmcnt(8)
	s_waitcnt lgkmcnt(0)
	s_barrier
	s_setprio 1
	s_waitcnt lgkmcnt(0)
	v_mfma_f32_16x16x32_bf16 v[60:63], v[150:153], v[188:191], 0
	v_mfma_f32_16x16x32_bf16 v[56:59], v[164:167], v[188:191], 0
	v_mfma_f32_16x16x32_bf16 v[44:47], v[150:153], v[196:199], 0
	v_mfma_f32_16x16x32_bf16 v[40:43], v[164:167], v[196:199], 0
	v_mfma_f32_16x16x32_bf16 v[28:31], v[150:153], v[204:207], 0
	v_mfma_f32_16x16x32_bf16 v[24:27], v[164:167], v[204:207], 0
	v_mfma_f32_16x16x32_bf16 v[12:15], v[150:153], v[212:215], 0
	v_mfma_f32_16x16x32_bf16 v[8:11], v[164:167], v[212:215], 0
	v_mfma_f32_16x16x32_bf16 v[60:63], v[160:163], v[192:195], v[60:63]
	v_mfma_f32_16x16x32_bf16 v[56:59], v[168:171], v[192:195], v[56:59]
	v_mfma_f32_16x16x32_bf16 v[44:47], v[160:163], v[200:203], v[44:47]
	v_mfma_f32_16x16x32_bf16 v[40:43], v[168:171], v[200:203], v[40:43]
	v_mfma_f32_16x16x32_bf16 v[28:31], v[160:163], v[208:211], v[28:31]
	v_mfma_f32_16x16x32_bf16 v[24:27], v[168:171], v[208:211], v[24:27]
	v_mfma_f32_16x16x32_bf16 v[12:15], v[160:163], v[216:219], v[12:15]
	v_mfma_f32_16x16x32_bf16 v[8:11], v[168:171], v[216:219], v[8:11]
	v_mfma_f32_16x16x32_bf16 v[52:55], v[172:175], v[188:191], 0
	v_mfma_f32_16x16x32_bf16 v[48:51], v[180:183], v[188:191], 0
	v_mfma_f32_16x16x32_bf16 v[36:39], v[172:175], v[196:199], 0
	v_mfma_f32_16x16x32_bf16 v[32:35], v[180:183], v[196:199], 0
	v_mfma_f32_16x16x32_bf16 v[20:23], v[172:175], v[204:207], 0
	v_mfma_f32_16x16x32_bf16 v[16:19], v[180:183], v[204:207], 0
	v_mfma_f32_16x16x32_bf16 v[4:7], v[172:175], v[212:215], 0
	v_mfma_f32_16x16x32_bf16 v[0:3], v[180:183], v[212:215], 0
	v_mfma_f32_16x16x32_bf16 v[52:55], v[176:179], v[192:195], v[52:55]
	v_mfma_f32_16x16x32_bf16 v[48:51], v[184:187], v[192:195], v[48:51]
	v_mfma_f32_16x16x32_bf16 v[36:39], v[176:179], v[200:203], v[36:39]
	v_mfma_f32_16x16x32_bf16 v[32:35], v[184:187], v[200:203], v[32:35]
	v_mfma_f32_16x16x32_bf16 v[20:23], v[176:179], v[208:211], v[20:23]
	v_mfma_f32_16x16x32_bf16 v[16:19], v[184:187], v[208:211], v[16:19]
	v_mfma_f32_16x16x32_bf16 v[4:7], v[176:179], v[216:219], v[4:7]
	v_mfma_f32_16x16x32_bf16 v[0:3], v[184:187], v[216:219], v[0:3]
	s_setprio 0
	s_barrier
	s_add_i32 s66, 0, 0x18000
	v_add_u32_e32 v140, s66, v154
	s_add_i32 s67, 0, 0x1c000
	ds_read_b128 v[150:153], v140
	ds_read_b128 v[160:163], v140 offset:1024
	ds_read_b128 v[164:167], v140 offset:2048
	ds_read_b128 v[168:171], v140 offset:3072
	v_add_u32_e32 v140, s67, v154
	ds_read_b128 v[172:175], v140
	ds_read_b128 v[176:179], v140 offset:1024
	ds_read_b128 v[180:183], v140 offset:2048
	ds_read_b128 v[184:187], v140 offset:3072
	s_add_u32 s34, s46, 0x40000
	s_addc_u32 s35, s47, 0
	s_mov_b32 m0, s55
	v_lshl_add_u64 v[228:229], s[34:35], 0, v[132:133]
	ds_read_b128 v[188:191], v159 offset:32768
	ds_read_b128 v[192:195], v159 offset:33792
	ds_read_b128 v[196:199], v159 offset:34816
	ds_read_b128 v[200:203], v159 offset:35840
	ds_read_b128 v[204:207], v159 offset:36864
	ds_read_b128 v[208:211], v159 offset:37888
	ds_read_b128 v[212:215], v159 offset:38912
	ds_read_b128 v[216:219], v159 offset:39936
	global_load_lds_dwordx4 v[228:229], off
	s_mov_b32 m0, s56
	v_lshl_add_u64 v[228:229], s[34:35], 0, v[136:137]
	global_load_lds_dwordx4 v[228:229], off
	s_waitcnt vmcnt(8)
	s_waitcnt lgkmcnt(0)
	s_barrier
	s_setprio 1
	s_waitcnt lgkmcnt(0)
	v_mfma_f32_16x16x32_bf16 v[124:127], v[150:153], v[188:191], v[124:127]
	v_mfma_f32_16x16x32_bf16 v[120:123], v[164:167], v[188:191], v[120:123]
	v_mfma_f32_16x16x32_bf16 v[108:111], v[150:153], v[196:199], v[108:111]
	v_mfma_f32_16x16x32_bf16 v[104:107], v[164:167], v[196:199], v[104:107]
	v_mfma_f32_16x16x32_bf16 v[92:95], v[150:153], v[204:207], v[92:95]
	v_mfma_f32_16x16x32_bf16 v[88:91], v[164:167], v[204:207], v[88:91]
	v_mfma_f32_16x16x32_bf16 v[76:79], v[150:153], v[212:215], v[76:79]
	v_mfma_f32_16x16x32_bf16 v[72:75], v[164:167], v[212:215], v[72:75]
	v_mfma_f32_16x16x32_bf16 v[124:127], v[160:163], v[192:195], v[124:127]
	v_mfma_f32_16x16x32_bf16 v[120:123], v[168:171], v[192:195], v[120:123]
	v_mfma_f32_16x16x32_bf16 v[108:111], v[160:163], v[200:203], v[108:111]
	v_mfma_f32_16x16x32_bf16 v[104:107], v[168:171], v[200:203], v[104:107]
	v_mfma_f32_16x16x32_bf16 v[92:95], v[160:163], v[208:211], v[92:95]
	v_mfma_f32_16x16x32_bf16 v[88:91], v[168:171], v[208:211], v[88:91]
	v_mfma_f32_16x16x32_bf16 v[76:79], v[160:163], v[216:219], v[76:79]
	v_mfma_f32_16x16x32_bf16 v[72:75], v[168:171], v[216:219], v[72:75]
	v_mfma_f32_16x16x32_bf16 v[116:119], v[172:175], v[188:191], v[116:119]
	v_mfma_f32_16x16x32_bf16 v[112:115], v[180:183], v[188:191], v[112:115]
	v_mfma_f32_16x16x32_bf16 v[100:103], v[172:175], v[196:199], v[100:103]
	v_mfma_f32_16x16x32_bf16 v[96:99], v[180:183], v[196:199], v[96:99]
	v_mfma_f32_16x16x32_bf16 v[84:87], v[172:175], v[204:207], v[84:87]
	v_mfma_f32_16x16x32_bf16 v[80:83], v[180:183], v[204:207], v[80:83]
	v_mfma_f32_16x16x32_bf16 v[68:71], v[172:175], v[212:215], v[68:71]
	v_mfma_f32_16x16x32_bf16 v[64:67], v[180:183], v[212:215], v[64:67]
	v_mfma_f32_16x16x32_bf16 v[116:119], v[176:179], v[192:195], v[116:119]
	v_mfma_f32_16x16x32_bf16 v[112:115], v[184:187], v[192:195], v[112:115]
	v_mfma_f32_16x16x32_bf16 v[100:103], v[176:179], v[200:203], v[100:103]
	v_mfma_f32_16x16x32_bf16 v[96:99], v[184:187], v[200:203], v[96:99]
	v_mfma_f32_16x16x32_bf16 v[84:87], v[176:179], v[208:211], v[84:87]
	v_mfma_f32_16x16x32_bf16 v[80:83], v[184:187], v[208:211], v[80:83]
	v_mfma_f32_16x16x32_bf16 v[68:71], v[176:179], v[216:219], v[68:71]
	v_mfma_f32_16x16x32_bf16 v[64:67], v[184:187], v[216:219], v[64:67]
	s_setprio 0
	s_barrier
	s_add_i32 s34, s66, s50
	v_lshl_add_u64 v[220:221], v[220:221], 0, s[26:27]
	s_mov_b32 m0, s34
	ds_read_b128 v[188:191], v159 offset:49152
	ds_read_b128 v[192:195], v159 offset:50176
	ds_read_b128 v[196:199], v159 offset:51200
	ds_read_b128 v[200:203], v159 offset:52224
	ds_read_b128 v[204:207], v159 offset:53248
	ds_read_b128 v[208:211], v159 offset:54272
	ds_read_b128 v[212:215], v159 offset:55296
	ds_read_b128 v[216:219], v159 offset:56320
	global_load_lds_dwordx4 v[220:221], off
	s_add_i32 m0, s34, 0x2000
	s_add_u32 s34, s44, 0x40080
	v_lshl_add_u64 v[220:221], v[222:223], 0, s[26:27]
	s_addc_u32 s35, s45, 0
	s_add_i32 s44, s67, s50
	global_load_lds_dwordx4 v[220:221], off
	s_mov_b32 m0, s44
	v_lshl_add_u64 v[220:221], s[34:35], 0, v[134:135]
	global_load_lds_dwordx4 v[220:221], off
	s_add_i32 m0, s44, 0x2000
	v_lshl_add_u64 v[220:221], s[34:35], 0, v[138:139]
	global_load_lds_dwordx4 v[220:221], off
	s_mov_b32 m0, s58
	v_lshl_add_u64 v[220:221], v[224:225], 0, s[26:27]
	global_load_lds_dwordx4 v[220:221], off
	s_mov_b32 m0, s59
	v_lshl_add_u64 v[220:221], v[226:227], 0, s[26:27]
	global_load_lds_dwordx4 v[220:221], off
	s_waitcnt vmcnt(8)
	s_waitcnt lgkmcnt(0)
	s_barrier
	s_setprio 1
	s_waitcnt lgkmcnt(0)
	v_mfma_f32_16x16x32_bf16 v[60:63], v[150:153], v[188:191], v[60:63]
	v_mfma_f32_16x16x32_bf16 v[56:59], v[164:167], v[188:191], v[56:59]
	v_mfma_f32_16x16x32_bf16 v[44:47], v[150:153], v[196:199], v[44:47]
	v_mfma_f32_16x16x32_bf16 v[40:43], v[164:167], v[196:199], v[40:43]
	v_mfma_f32_16x16x32_bf16 v[28:31], v[150:153], v[204:207], v[28:31]
	v_mfma_f32_16x16x32_bf16 v[24:27], v[164:167], v[204:207], v[24:27]
	v_mfma_f32_16x16x32_bf16 v[12:15], v[150:153], v[212:215], v[12:15]
	v_mfma_f32_16x16x32_bf16 v[8:11], v[164:167], v[212:215], v[8:11]
	v_mfma_f32_16x16x32_bf16 v[60:63], v[160:163], v[192:195], v[60:63]
	v_mfma_f32_16x16x32_bf16 v[56:59], v[168:171], v[192:195], v[56:59]
	v_mfma_f32_16x16x32_bf16 v[44:47], v[160:163], v[200:203], v[44:47]
	v_mfma_f32_16x16x32_bf16 v[40:43], v[168:171], v[200:203], v[40:43]
	v_mfma_f32_16x16x32_bf16 v[28:31], v[160:163], v[208:211], v[28:31]
	v_mfma_f32_16x16x32_bf16 v[24:27], v[168:171], v[208:211], v[24:27]
	v_mfma_f32_16x16x32_bf16 v[12:15], v[160:163], v[216:219], v[12:15]
	v_mfma_f32_16x16x32_bf16 v[8:11], v[168:171], v[216:219], v[8:11]
	v_mfma_f32_16x16x32_bf16 v[52:55], v[172:175], v[188:191], v[52:55]
	v_mfma_f32_16x16x32_bf16 v[48:51], v[180:183], v[188:191], v[48:51]
	v_mfma_f32_16x16x32_bf16 v[36:39], v[172:175], v[196:199], v[36:39]
	v_mfma_f32_16x16x32_bf16 v[32:35], v[180:183], v[196:199], v[32:35]
	v_mfma_f32_16x16x32_bf16 v[20:23], v[172:175], v[204:207], v[20:23]
	v_mfma_f32_16x16x32_bf16 v[16:19], v[180:183], v[204:207], v[16:19]
	v_mfma_f32_16x16x32_bf16 v[4:7], v[172:175], v[212:215], v[4:7]
	v_mfma_f32_16x16x32_bf16 v[0:3], v[180:183], v[212:215], v[0:3]
	v_mfma_f32_16x16x32_bf16 v[52:55], v[176:179], v[192:195], v[52:55]
	v_mfma_f32_16x16x32_bf16 v[48:51], v[184:187], v[192:195], v[48:51]
	v_mfma_f32_16x16x32_bf16 v[36:39], v[176:179], v[200:203], v[36:39]
	v_mfma_f32_16x16x32_bf16 v[32:35], v[184:187], v[200:203], v[32:35]
	v_mfma_f32_16x16x32_bf16 v[20:23], v[176:179], v[208:211], v[20:23]
	v_mfma_f32_16x16x32_bf16 v[16:19], v[184:187], v[208:211], v[16:19]
	v_mfma_f32_16x16x32_bf16 v[4:7], v[176:179], v[216:219], v[4:7]
	v_mfma_f32_16x16x32_bf16 v[0:3], v[184:187], v[216:219], v[0:3]
	s_setprio 0
	s_barrier
	s_add_i32 s65, s65, 2
	s_add_u32 s42, s42, 0x100
	s_addc_u32 s43, s43, 0
	s_add_u32 s31, s31, 0x100
	s_addc_u32 s37, s37, 0
.LBB0_1826:
	ds_read_b128 v[150:153], v157
	ds_read_b128 v[160:163], v157 offset:1024
	ds_read_b128 v[164:167], v157 offset:2048
	ds_read_b128 v[168:171], v157 offset:3072
	ds_read_b128 v[172:175], v158
	ds_read_b128 v[176:179], v158 offset:1024
	ds_read_b128 v[180:183], v158 offset:2048
	ds_read_b128 v[184:187], v158 offset:3072
	s_add_u32 s34, s42, 0xfffc0080
	s_addc_u32 s35, s43, -1
	s_cmp_eq_u32 s65, 12
	s_cselect_b32 s47, s7, s35
	s_cselect_b32 s46, s8, s34
	s_cselect_b32 s45, s12, s37
	s_cselect_b32 s44, s13, s31
	v_lshl_add_u64 v[220:221], s[42:43], 0, v[142:143]
	s_add_i32 m0, s53, 0xc000
	ds_read_b128 v[188:191], v159
	ds_read_b128 v[192:195], v159 offset:1024
	ds_read_b128 v[196:199], v159 offset:2048
	ds_read_b128 v[200:203], v159 offset:3072
	ds_read_b128 v[204:207], v159 offset:4096
	ds_read_b128 v[208:211], v159 offset:5120
	ds_read_b128 v[212:215], v159 offset:6144
	ds_read_b128 v[216:219], v159 offset:7168
	global_load_lds_dwordx4 v[220:221], off
	s_add_i32 m0, s53, 0xe000
	v_lshl_add_u64 v[220:221], s[42:43], 0, v[144:145]
	global_load_lds_dwordx4 v[220:221], off
	s_waitcnt vmcnt(8)
	s_waitcnt lgkmcnt(0)
	s_barrier
	s_setprio 1
	s_waitcnt lgkmcnt(0)
	v_mfma_f32_16x16x32_bf16 v[124:127], v[150:153], v[188:191], v[124:127]
	v_mfma_f32_16x16x32_bf16 v[120:123], v[164:167], v[188:191], v[120:123]
	v_mfma_f32_16x16x32_bf16 v[108:111], v[150:153], v[196:199], v[108:111]
	v_mfma_f32_16x16x32_bf16 v[104:107], v[164:167], v[196:199], v[104:107]
	v_mfma_f32_16x16x32_bf16 v[92:95], v[150:153], v[204:207], v[92:95]
	v_mfma_f32_16x16x32_bf16 v[88:91], v[164:167], v[204:207], v[88:91]
	v_mfma_f32_16x16x32_bf16 v[76:79], v[150:153], v[212:215], v[76:79]
	v_mfma_f32_16x16x32_bf16 v[72:75], v[164:167], v[212:215], v[72:75]
	v_mfma_f32_16x16x32_bf16 v[124:127], v[160:163], v[192:195], v[124:127]
	v_mfma_f32_16x16x32_bf16 v[120:123], v[168:171], v[192:195], v[120:123]
	v_mfma_f32_16x16x32_bf16 v[108:111], v[160:163], v[200:203], v[108:111]
	v_mfma_f32_16x16x32_bf16 v[104:107], v[168:171], v[200:203], v[104:107]
	v_mfma_f32_16x16x32_bf16 v[92:95], v[160:163], v[208:211], v[92:95]
	v_mfma_f32_16x16x32_bf16 v[88:91], v[168:171], v[208:211], v[88:91]
	v_mfma_f32_16x16x32_bf16 v[76:79], v[160:163], v[216:219], v[76:79]
	v_mfma_f32_16x16x32_bf16 v[72:75], v[168:171], v[216:219], v[72:75]
	v_mfma_f32_16x16x32_bf16 v[116:119], v[172:175], v[188:191], v[116:119]
	v_mfma_f32_16x16x32_bf16 v[112:115], v[180:183], v[188:191], v[112:115]
	v_mfma_f32_16x16x32_bf16 v[100:103], v[172:175], v[196:199], v[100:103]
	v_mfma_f32_16x16x32_bf16 v[96:99], v[180:183], v[196:199], v[96:99]
	v_mfma_f32_16x16x32_bf16 v[84:87], v[172:175], v[204:207], v[84:87]
	v_mfma_f32_16x16x32_bf16 v[80:83], v[180:183], v[204:207], v[80:83]
	v_mfma_f32_16x16x32_bf16 v[68:71], v[172:175], v[212:215], v[68:71]
	v_mfma_f32_16x16x32_bf16 v[64:67], v[180:183], v[212:215], v[64:67]
	v_mfma_f32_16x16x32_bf16 v[116:119], v[176:179], v[192:195], v[116:119]
	v_mfma_f32_16x16x32_bf16 v[112:115], v[184:187], v[192:195], v[112:115]
	v_mfma_f32_16x16x32_bf16 v[100:103], v[176:179], v[200:203], v[100:103]
	v_mfma_f32_16x16x32_bf16 v[96:99], v[184:187], v[200:203], v[96:99]
	v_mfma_f32_16x16x32_bf16 v[84:87], v[176:179], v[208:211], v[84:87]
	v_mfma_f32_16x16x32_bf16 v[80:83], v[184:187], v[208:211], v[80:83]
	v_mfma_f32_16x16x32_bf16 v[68:71], v[176:179], v[216:219], v[68:71]
	v_mfma_f32_16x16x32_bf16 v[64:67], v[184:187], v[216:219], v[64:67]
	s_setprio 0
	s_barrier
	s_add_i32 s34, s61, s50
	v_lshl_add_u64 v[220:221], s[44:45], 0, v[134:135]
	s_mov_b32 m0, s34
	ds_read_b128 v[188:191], v159 offset:16384
	ds_read_b128 v[192:195], v159 offset:17408
	ds_read_b128 v[196:199], v159 offset:18432
	ds_read_b128 v[200:203], v159 offset:19456
	ds_read_b128 v[204:207], v159 offset:20480
	ds_read_b128 v[208:211], v159 offset:21504
	ds_read_b128 v[212:215], v159 offset:22528
	ds_read_b128 v[216:219], v159 offset:23552
	global_load_lds_dwordx4 v[220:221], off
	s_add_i32 m0, s34, 0x2000
	s_add_u32 s34, s44, 0x40000
	v_lshl_add_u64 v[222:223], s[44:45], 0, v[138:139]
	s_addc_u32 s35, s45, 0
	s_add_i32 s66, s62, s50
	global_load_lds_dwordx4 v[222:223], off
	v_lshl_add_u64 v[224:225], s[34:35], 0, v[134:135]
	s_mov_b32 m0, s66
	v_lshl_add_u64 v[226:227], s[46:47], 0, v[136:137]
	global_load_lds_dwordx4 v[224:225], off
	s_add_i32 m0, s66, 0x2000
	v_lshl_add_u64 v[224:225], s[34:35], 0, v[138:139]
	global_load_lds_dwordx4 v[224:225], off
	s_mov_b32 m0, s53
	v_lshl_add_u64 v[224:225], s[46:47], 0, v[132:133]
	global_load_lds_dwordx4 v[224:225], off
	s_mov_b32 m0, s54
	s_nop 0
	global_load_lds_dwordx4 v[226:227], off
	s_waitcnt vmcnt(8)
	s_waitcnt lgkmcnt(0)
	s_barrier
	s_setprio 1
	s_waitcnt lgkmcnt(0)
	v_mfma_f32_16x16x32_bf16 v[60:63], v[150:153], v[188:191], v[60:63]
	v_mfma_f32_16x16x32_bf16 v[56:59], v[164:167], v[188:191], v[56:59]
	v_mfma_f32_16x16x32_bf16 v[44:47], v[150:153], v[196:199], v[44:47]
	v_mfma_f32_16x16x32_bf16 v[40:43], v[164:167], v[196:199], v[40:43]
	v_mfma_f32_16x16x32_bf16 v[28:31], v[150:153], v[204:207], v[28:31]
	v_mfma_f32_16x16x32_bf16 v[24:27], v[164:167], v[204:207], v[24:27]
	v_mfma_f32_16x16x32_bf16 v[12:15], v[150:153], v[212:215], v[12:15]
	v_mfma_f32_16x16x32_bf16 v[8:11], v[164:167], v[212:215], v[8:11]
	v_mfma_f32_16x16x32_bf16 v[60:63], v[160:163], v[192:195], v[60:63]
	v_mfma_f32_16x16x32_bf16 v[56:59], v[168:171], v[192:195], v[56:59]
	v_mfma_f32_16x16x32_bf16 v[44:47], v[160:163], v[200:203], v[44:47]
	v_mfma_f32_16x16x32_bf16 v[40:43], v[168:171], v[200:203], v[40:43]
	v_mfma_f32_16x16x32_bf16 v[28:31], v[160:163], v[208:211], v[28:31]
	v_mfma_f32_16x16x32_bf16 v[24:27], v[168:171], v[208:211], v[24:27]
	v_mfma_f32_16x16x32_bf16 v[12:15], v[160:163], v[216:219], v[12:15]
	v_mfma_f32_16x16x32_bf16 v[8:11], v[168:171], v[216:219], v[8:11]
	v_mfma_f32_16x16x32_bf16 v[52:55], v[172:175], v[188:191], v[52:55]
	v_mfma_f32_16x16x32_bf16 v[48:51], v[180:183], v[188:191], v[48:51]
	v_mfma_f32_16x16x32_bf16 v[36:39], v[172:175], v[196:199], v[36:39]
	v_mfma_f32_16x16x32_bf16 v[32:35], v[180:183], v[196:199], v[32:35]
	v_mfma_f32_16x16x32_bf16 v[20:23], v[172:175], v[204:207], v[20:23]
	v_mfma_f32_16x16x32_bf16 v[16:19], v[180:183], v[204:207], v[16:19]
	v_mfma_f32_16x16x32_bf16 v[4:7], v[172:175], v[212:215], v[4:7]
	v_mfma_f32_16x16x32_bf16 v[0:3], v[180:183], v[212:215], v[0:3]
	v_mfma_f32_16x16x32_bf16 v[52:55], v[176:179], v[192:195], v[52:55]
	v_mfma_f32_16x16x32_bf16 v[48:51], v[184:187], v[192:195], v[48:51]
	v_mfma_f32_16x16x32_bf16 v[36:39], v[176:179], v[200:203], v[36:39]
	v_mfma_f32_16x16x32_bf16 v[32:35], v[184:187], v[200:203], v[32:35]
	v_mfma_f32_16x16x32_bf16 v[20:23], v[176:179], v[208:211], v[20:23]
	v_mfma_f32_16x16x32_bf16 v[16:19], v[184:187], v[208:211], v[16:19]
	v_mfma_f32_16x16x32_bf16 v[4:7], v[176:179], v[216:219], v[4:7]
	v_mfma_f32_16x16x32_bf16 v[0:3], v[184:187], v[216:219], v[0:3]
	s_setprio 0
	s_barrier
	s_add_i32 s66, 0, 0x18000
	v_add_u32_e32 v140, s66, v154
	s_add_i32 s67, 0, 0x1c000
	ds_read_b128 v[150:153], v140
	ds_read_b128 v[160:163], v140 offset:1024
	ds_read_b128 v[164:167], v140 offset:2048
	ds_read_b128 v[168:171], v140 offset:3072
	v_add_u32_e32 v140, s67, v154
	ds_read_b128 v[172:175], v140
	ds_read_b128 v[176:179], v140 offset:1024
	ds_read_b128 v[180:183], v140 offset:2048
	ds_read_b128 v[184:187], v140 offset:3072
	s_add_u32 s34, s46, 0x40000
	s_addc_u32 s35, s47, 0
	s_mov_b32 m0, s55
	v_lshl_add_u64 v[228:229], s[34:35], 0, v[132:133]
	ds_read_b128 v[188:191], v159 offset:32768
	ds_read_b128 v[192:195], v159 offset:33792
	ds_read_b128 v[196:199], v159 offset:34816
	ds_read_b128 v[200:203], v159 offset:35840
	ds_read_b128 v[204:207], v159 offset:36864
	ds_read_b128 v[208:211], v159 offset:37888
	ds_read_b128 v[212:215], v159 offset:38912
	ds_read_b128 v[216:219], v159 offset:39936
	global_load_lds_dwordx4 v[228:229], off
	s_mov_b32 m0, s56
	v_lshl_add_u64 v[228:229], s[34:35], 0, v[136:137]
	global_load_lds_dwordx4 v[228:229], off
	s_waitcnt vmcnt(8)
	s_waitcnt lgkmcnt(0)
	s_barrier
	s_setprio 1
	s_waitcnt lgkmcnt(0)
	v_mfma_f32_16x16x32_bf16 v[124:127], v[150:153], v[188:191], v[124:127]
	v_mfma_f32_16x16x32_bf16 v[120:123], v[164:167], v[188:191], v[120:123]
	v_mfma_f32_16x16x32_bf16 v[108:111], v[150:153], v[196:199], v[108:111]
	v_mfma_f32_16x16x32_bf16 v[104:107], v[164:167], v[196:199], v[104:107]
	v_mfma_f32_16x16x32_bf16 v[92:95], v[150:153], v[204:207], v[92:95]
	v_mfma_f32_16x16x32_bf16 v[88:91], v[164:167], v[204:207], v[88:91]
	v_mfma_f32_16x16x32_bf16 v[76:79], v[150:153], v[212:215], v[76:79]
	v_mfma_f32_16x16x32_bf16 v[72:75], v[164:167], v[212:215], v[72:75]
	v_mfma_f32_16x16x32_bf16 v[124:127], v[160:163], v[192:195], v[124:127]
	v_mfma_f32_16x16x32_bf16 v[120:123], v[168:171], v[192:195], v[120:123]
	v_mfma_f32_16x16x32_bf16 v[108:111], v[160:163], v[200:203], v[108:111]
	v_mfma_f32_16x16x32_bf16 v[104:107], v[168:171], v[200:203], v[104:107]
	v_mfma_f32_16x16x32_bf16 v[92:95], v[160:163], v[208:211], v[92:95]
	v_mfma_f32_16x16x32_bf16 v[88:91], v[168:171], v[208:211], v[88:91]
	v_mfma_f32_16x16x32_bf16 v[76:79], v[160:163], v[216:219], v[76:79]
	v_mfma_f32_16x16x32_bf16 v[72:75], v[168:171], v[216:219], v[72:75]
	v_mfma_f32_16x16x32_bf16 v[116:119], v[172:175], v[188:191], v[116:119]
	v_mfma_f32_16x16x32_bf16 v[112:115], v[180:183], v[188:191], v[112:115]
	v_mfma_f32_16x16x32_bf16 v[100:103], v[172:175], v[196:199], v[100:103]
	v_mfma_f32_16x16x32_bf16 v[96:99], v[180:183], v[196:199], v[96:99]
	v_mfma_f32_16x16x32_bf16 v[84:87], v[172:175], v[204:207], v[84:87]
	v_mfma_f32_16x16x32_bf16 v[80:83], v[180:183], v[204:207], v[80:83]
	v_mfma_f32_16x16x32_bf16 v[68:71], v[172:175], v[212:215], v[68:71]
	v_mfma_f32_16x16x32_bf16 v[64:67], v[180:183], v[212:215], v[64:67]
	v_mfma_f32_16x16x32_bf16 v[116:119], v[176:179], v[192:195], v[116:119]
	v_mfma_f32_16x16x32_bf16 v[112:115], v[184:187], v[192:195], v[112:115]
	v_mfma_f32_16x16x32_bf16 v[100:103], v[176:179], v[200:203], v[100:103]
	v_mfma_f32_16x16x32_bf16 v[96:99], v[184:187], v[200:203], v[96:99]
	v_mfma_f32_16x16x32_bf16 v[84:87], v[176:179], v[208:211], v[84:87]
	v_mfma_f32_16x16x32_bf16 v[80:83], v[184:187], v[208:211], v[80:83]
	v_mfma_f32_16x16x32_bf16 v[68:71], v[176:179], v[216:219], v[68:71]
	v_mfma_f32_16x16x32_bf16 v[64:67], v[184:187], v[216:219], v[64:67]
	s_setprio 0
	s_barrier
	s_add_i32 s34, s66, s50
	v_lshl_add_u64 v[220:221], v[220:221], 0, s[26:27]
	s_mov_b32 m0, s34
	ds_read_b128 v[188:191], v159 offset:49152
	ds_read_b128 v[192:195], v159 offset:50176
	ds_read_b128 v[196:199], v159 offset:51200
	ds_read_b128 v[200:203], v159 offset:52224
	ds_read_b128 v[204:207], v159 offset:53248
	ds_read_b128 v[208:211], v159 offset:54272
	ds_read_b128 v[212:215], v159 offset:55296
	ds_read_b128 v[216:219], v159 offset:56320
	global_load_lds_dwordx4 v[220:221], off
	s_add_i32 m0, s34, 0x2000
	s_add_u32 s34, s44, 0x40080
	v_lshl_add_u64 v[220:221], v[222:223], 0, s[26:27]
	s_addc_u32 s35, s45, 0
	s_add_i32 s44, s67, s50
	global_load_lds_dwordx4 v[220:221], off
	s_mov_b32 m0, s44
	v_lshl_add_u64 v[220:221], s[34:35], 0, v[134:135]
	global_load_lds_dwordx4 v[220:221], off
	s_add_i32 m0, s44, 0x2000
	v_lshl_add_u64 v[220:221], s[34:35], 0, v[138:139]
	global_load_lds_dwordx4 v[220:221], off
	s_mov_b32 m0, s58
	v_lshl_add_u64 v[220:221], v[224:225], 0, s[26:27]
	global_load_lds_dwordx4 v[220:221], off
	s_mov_b32 m0, s59
	v_lshl_add_u64 v[220:221], v[226:227], 0, s[26:27]
	global_load_lds_dwordx4 v[220:221], off
	s_waitcnt vmcnt(8)
	s_waitcnt lgkmcnt(0)
	s_barrier
	s_setprio 1
	s_waitcnt lgkmcnt(0)
	v_mfma_f32_16x16x32_bf16 v[60:63], v[150:153], v[188:191], v[60:63]
	v_mfma_f32_16x16x32_bf16 v[56:59], v[164:167], v[188:191], v[56:59]
	v_mfma_f32_16x16x32_bf16 v[44:47], v[150:153], v[196:199], v[44:47]
	v_mfma_f32_16x16x32_bf16 v[40:43], v[164:167], v[196:199], v[40:43]
	v_mfma_f32_16x16x32_bf16 v[28:31], v[150:153], v[204:207], v[28:31]
	v_mfma_f32_16x16x32_bf16 v[24:27], v[164:167], v[204:207], v[24:27]
	v_mfma_f32_16x16x32_bf16 v[12:15], v[150:153], v[212:215], v[12:15]
	v_mfma_f32_16x16x32_bf16 v[8:11], v[164:167], v[212:215], v[8:11]
	v_mfma_f32_16x16x32_bf16 v[60:63], v[160:163], v[192:195], v[60:63]
	v_mfma_f32_16x16x32_bf16 v[56:59], v[168:171], v[192:195], v[56:59]
	v_mfma_f32_16x16x32_bf16 v[44:47], v[160:163], v[200:203], v[44:47]
	v_mfma_f32_16x16x32_bf16 v[40:43], v[168:171], v[200:203], v[40:43]
	v_mfma_f32_16x16x32_bf16 v[28:31], v[160:163], v[208:211], v[28:31]
	v_mfma_f32_16x16x32_bf16 v[24:27], v[168:171], v[208:211], v[24:27]
	v_mfma_f32_16x16x32_bf16 v[12:15], v[160:163], v[216:219], v[12:15]
	v_mfma_f32_16x16x32_bf16 v[8:11], v[168:171], v[216:219], v[8:11]
	v_mfma_f32_16x16x32_bf16 v[52:55], v[172:175], v[188:191], v[52:55]
	v_mfma_f32_16x16x32_bf16 v[48:51], v[180:183], v[188:191], v[48:51]
	v_mfma_f32_16x16x32_bf16 v[36:39], v[172:175], v[196:199], v[36:39]
	v_mfma_f32_16x16x32_bf16 v[32:35], v[180:183], v[196:199], v[32:35]
	v_mfma_f32_16x16x32_bf16 v[20:23], v[172:175], v[204:207], v[20:23]
	v_mfma_f32_16x16x32_bf16 v[16:19], v[180:183], v[204:207], v[16:19]
	v_mfma_f32_16x16x32_bf16 v[4:7], v[172:175], v[212:215], v[4:7]
	v_mfma_f32_16x16x32_bf16 v[0:3], v[180:183], v[212:215], v[0:3]
	v_mfma_f32_16x16x32_bf16 v[52:55], v[176:179], v[192:195], v[52:55]
	v_mfma_f32_16x16x32_bf16 v[48:51], v[184:187], v[192:195], v[48:51]
	v_mfma_f32_16x16x32_bf16 v[36:39], v[176:179], v[200:203], v[36:39]
	v_mfma_f32_16x16x32_bf16 v[32:35], v[184:187], v[200:203], v[32:35]
	v_mfma_f32_16x16x32_bf16 v[20:23], v[176:179], v[208:211], v[20:23]
	v_mfma_f32_16x16x32_bf16 v[16:19], v[184:187], v[208:211], v[16:19]
	v_mfma_f32_16x16x32_bf16 v[4:7], v[176:179], v[216:219], v[4:7]
	v_mfma_f32_16x16x32_bf16 v[0:3], v[184:187], v[216:219], v[0:3]
	s_setprio 0
	s_cmp_eq_u32 s65, s98
	s_cbranch_scc1 .Lmy_nobar_19
	s_barrier

.Lmy_nobar2_21:
	ds_read_b128 v[146:149], v153
	ds_read_b128 v[158:161], v153 offset:1024
	ds_read_b128 v[162:165], v153 offset:2048
	ds_read_b128 v[166:169], v153 offset:3072
	ds_read_b128 v[170:173], v154
	ds_read_b128 v[174:177], v154 offset:1024
	ds_read_b128 v[178:181], v154 offset:2048
	ds_read_b128 v[182:185], v154 offset:3072
	s_add_u32 s34, s38, 0xfffc0080
	s_addc_u32 s35, s39, -1
	s_cmp_eq_u32 s60, 12
	s_cselect_b32 s43, s12, s35
	s_cselect_b32 s42, s13, s34
	s_cselect_b32 s41, s25, s59
	s_cselect_b32 s40, s27, s37
	v_lshl_add_u64 v[218:219], s[38:39], 0, v[138:139]
	s_add_i32 m0, s46, 0xc000
	ds_read_b128 v[186:189], v155
	ds_read_b128 v[190:193], v155 offset:1024
	ds_read_b128 v[194:197], v155 offset:2048
	ds_read_b128 v[198:201], v155 offset:3072
	ds_read_b128 v[202:205], v155 offset:4096
	ds_read_b128 v[206:209], v155 offset:5120
	ds_read_b128 v[210:213], v155 offset:6144
	ds_read_b128 v[214:217], v155 offset:7168
	global_load_lds_dwordx4 v[218:219], off
	s_add_i32 m0, s46, 0xe000
	v_lshl_add_u64 v[218:219], s[38:39], 0, v[140:141]
	global_load_lds_dwordx4 v[218:219], off
	s_waitcnt vmcnt(8)
	s_waitcnt lgkmcnt(0)
	s_barrier
	s_setprio 1
	s_waitcnt lgkmcnt(0)
	v_mfma_f32_16x16x32_bf16 v[124:127], v[146:149], v[186:189], 0
	v_mfma_f32_16x16x32_bf16 v[120:123], v[162:165], v[186:189], 0
	v_mfma_f32_16x16x32_bf16 v[108:111], v[146:149], v[194:197], 0
	v_mfma_f32_16x16x32_bf16 v[104:107], v[162:165], v[194:197], 0
	v_mfma_f32_16x16x32_bf16 v[92:95], v[146:149], v[202:205], 0
	v_mfma_f32_16x16x32_bf16 v[88:91], v[162:165], v[202:205], 0
	v_mfma_f32_16x16x32_bf16 v[76:79], v[146:149], v[210:213], 0
	v_mfma_f32_16x16x32_bf16 v[72:75], v[162:165], v[210:213], 0
	v_mfma_f32_16x16x32_bf16 v[124:127], v[158:161], v[190:193], v[124:127]
	v_mfma_f32_16x16x32_bf16 v[120:123], v[166:169], v[190:193], v[120:123]
	v_mfma_f32_16x16x32_bf16 v[108:111], v[158:161], v[198:201], v[108:111]
	v_mfma_f32_16x16x32_bf16 v[104:107], v[166:169], v[198:201], v[104:107]
	v_mfma_f32_16x16x32_bf16 v[92:95], v[158:161], v[206:209], v[92:95]
	v_mfma_f32_16x16x32_bf16 v[88:91], v[166:169], v[206:209], v[88:91]
	v_mfma_f32_16x16x32_bf16 v[76:79], v[158:161], v[214:217], v[76:79]
	v_mfma_f32_16x16x32_bf16 v[72:75], v[166:169], v[214:217], v[72:75]
	v_mfma_f32_16x16x32_bf16 v[116:119], v[170:173], v[186:189], 0
	v_mfma_f32_16x16x32_bf16 v[112:115], v[178:181], v[186:189], 0
	v_mfma_f32_16x16x32_bf16 v[100:103], v[170:173], v[194:197], 0
	v_mfma_f32_16x16x32_bf16 v[96:99], v[178:181], v[194:197], 0
	v_mfma_f32_16x16x32_bf16 v[84:87], v[170:173], v[202:205], 0
	v_mfma_f32_16x16x32_bf16 v[80:83], v[178:181], v[202:205], 0
	v_mfma_f32_16x16x32_bf16 v[68:71], v[170:173], v[210:213], 0
	v_mfma_f32_16x16x32_bf16 v[64:67], v[178:181], v[210:213], 0
	v_mfma_f32_16x16x32_bf16 v[116:119], v[174:177], v[190:193], v[116:119]
	v_mfma_f32_16x16x32_bf16 v[112:115], v[182:185], v[190:193], v[112:115]
	v_mfma_f32_16x16x32_bf16 v[100:103], v[174:177], v[198:201], v[100:103]
	v_mfma_f32_16x16x32_bf16 v[96:99], v[182:185], v[198:201], v[96:99]
	v_mfma_f32_16x16x32_bf16 v[84:87], v[174:177], v[206:209], v[84:87]
	v_mfma_f32_16x16x32_bf16 v[80:83], v[182:185], v[206:209], v[80:83]
	v_mfma_f32_16x16x32_bf16 v[68:71], v[174:177], v[214:217], v[68:71]
	v_mfma_f32_16x16x32_bf16 v[64:67], v[182:185], v[214:217], v[64:67]
	s_setprio 0
	s_barrier
	s_add_i32 s34, s56, s45
	v_lshl_add_u64 v[218:219], s[40:41], 0, v[132:133]
	s_mov_b32 m0, s34
	ds_read_b128 v[186:189], v155 offset:16384
	ds_read_b128 v[190:193], v155 offset:17408
	ds_read_b128 v[194:197], v155 offset:18432
	ds_read_b128 v[198:201], v155 offset:19456
	ds_read_b128 v[202:205], v155 offset:20480
	ds_read_b128 v[206:209], v155 offset:21504
	ds_read_b128 v[210:213], v155 offset:22528
	ds_read_b128 v[214:217], v155 offset:23552
	global_load_lds_dwordx4 v[218:219], off
	s_add_i32 m0, s34, 0x2000
	s_add_u32 s34, s40, 0x40000
	v_lshl_add_u64 v[220:221], s[40:41], 0, v[136:137]
	s_addc_u32 s35, s41, 0
	s_add_i32 s61, s57, s45
	global_load_lds_dwordx4 v[220:221], off
	v_lshl_add_u64 v[222:223], s[34:35], 0, v[132:133]
	s_mov_b32 m0, s61
	v_lshl_add_u64 v[224:225], s[42:43], 0, v[134:135]
	global_load_lds_dwordx4 v[222:223], off
	s_add_i32 m0, s61, 0x2000
	v_lshl_add_u64 v[222:223], s[34:35], 0, v[136:137]
	global_load_lds_dwordx4 v[222:223], off
	s_mov_b32 m0, s46
	v_lshl_add_u64 v[222:223], s[42:43], 0, v[130:131]
	global_load_lds_dwordx4 v[222:223], off
	s_mov_b32 m0, s47
	s_nop 0
	global_load_lds_dwordx4 v[224:225], off
	s_waitcnt vmcnt(8)
	s_waitcnt lgkmcnt(0)
	s_barrier
	s_setprio 1
	s_waitcnt lgkmcnt(0)
	v_mfma_f32_16x16x32_bf16 v[60:63], v[146:149], v[186:189], 0
	v_mfma_f32_16x16x32_bf16 v[56:59], v[162:165], v[186:189], 0
	v_mfma_f32_16x16x32_bf16 v[44:47], v[146:149], v[194:197], 0
	v_mfma_f32_16x16x32_bf16 v[40:43], v[162:165], v[194:197], 0
	v_mfma_f32_16x16x32_bf16 v[28:31], v[146:149], v[202:205], 0
	v_mfma_f32_16x16x32_bf16 v[24:27], v[162:165], v[202:205], 0
	v_mfma_f32_16x16x32_bf16 v[12:15], v[146:149], v[210:213], 0
	v_mfma_f32_16x16x32_bf16 v[8:11], v[162:165], v[210:213], 0
	v_mfma_f32_16x16x32_bf16 v[60:63], v[158:161], v[190:193], v[60:63]
	v_mfma_f32_16x16x32_bf16 v[56:59], v[166:169], v[190:193], v[56:59]
	v_mfma_f32_16x16x32_bf16 v[44:47], v[158:161], v[198:201], v[44:47]
	v_mfma_f32_16x16x32_bf16 v[40:43], v[166:169], v[198:201], v[40:43]
	v_mfma_f32_16x16x32_bf16 v[28:31], v[158:161], v[206:209], v[28:31]
	v_mfma_f32_16x16x32_bf16 v[24:27], v[166:169], v[206:209], v[24:27]
	v_mfma_f32_16x16x32_bf16 v[12:15], v[158:161], v[214:217], v[12:15]
	v_mfma_f32_16x16x32_bf16 v[8:11], v[166:169], v[214:217], v[8:11]
	v_mfma_f32_16x16x32_bf16 v[52:55], v[170:173], v[186:189], 0
	v_mfma_f32_16x16x32_bf16 v[48:51], v[178:181], v[186:189], 0
	v_mfma_f32_16x16x32_bf16 v[36:39], v[170:173], v[194:197], 0
	v_mfma_f32_16x16x32_bf16 v[32:35], v[178:181], v[194:197], 0
	v_mfma_f32_16x16x32_bf16 v[20:23], v[170:173], v[202:205], 0
	v_mfma_f32_16x16x32_bf16 v[16:19], v[178:181], v[202:205], 0
	v_mfma_f32_16x16x32_bf16 v[4:7], v[170:173], v[210:213], 0
	v_mfma_f32_16x16x32_bf16 v[0:3], v[178:181], v[210:213], 0
	v_mfma_f32_16x16x32_bf16 v[52:55], v[174:177], v[190:193], v[52:55]
	v_mfma_f32_16x16x32_bf16 v[48:51], v[182:185], v[190:193], v[48:51]
	v_mfma_f32_16x16x32_bf16 v[36:39], v[174:177], v[198:201], v[36:39]
	v_mfma_f32_16x16x32_bf16 v[32:35], v[182:185], v[198:201], v[32:35]
	v_mfma_f32_16x16x32_bf16 v[20:23], v[174:177], v[206:209], v[20:23]
	v_mfma_f32_16x16x32_bf16 v[16:19], v[182:185], v[206:209], v[16:19]
	v_mfma_f32_16x16x32_bf16 v[4:7], v[174:177], v[214:217], v[4:7]
	v_mfma_f32_16x16x32_bf16 v[0:3], v[182:185], v[214:217], v[0:3]
	s_setprio 0
	s_barrier
	s_add_i32 s61, 0, 0x18000
	v_add_u32_e32 v157, s61, v151
	s_add_i32 s62, 0, 0x1c000
	ds_read_b128 v[146:149], v157
	ds_read_b128 v[158:161], v157 offset:1024
	ds_read_b128 v[162:165], v157 offset:2048
	ds_read_b128 v[166:169], v157 offset:3072
	v_add_u32_e32 v157, s62, v151
	ds_read_b128 v[170:173], v157
	ds_read_b128 v[174:177], v157 offset:1024
	ds_read_b128 v[178:181], v157 offset:2048
	ds_read_b128 v[182:185], v157 offset:3072
	s_add_u32 s34, s42, 0x40000
	s_addc_u32 s35, s43, 0
	s_mov_b32 m0, s48
	v_lshl_add_u64 v[226:227], s[34:35], 0, v[130:131]
	ds_read_b128 v[186:189], v155 offset:32768
	ds_read_b128 v[190:193], v155 offset:33792
	ds_read_b128 v[194:197], v155 offset:34816
	ds_read_b128 v[198:201], v155 offset:35840
	ds_read_b128 v[202:205], v155 offset:36864
	ds_read_b128 v[206:209], v155 offset:37888
	ds_read_b128 v[210:213], v155 offset:38912
	ds_read_b128 v[214:217], v155 offset:39936
	global_load_lds_dwordx4 v[226:227], off
	s_mov_b32 m0, s49
	v_lshl_add_u64 v[226:227], s[34:35], 0, v[134:135]
	global_load_lds_dwordx4 v[226:227], off
	s_waitcnt vmcnt(8)
	s_waitcnt lgkmcnt(0)
	s_barrier
	s_setprio 1
	s_waitcnt lgkmcnt(0)
	v_mfma_f32_16x16x32_bf16 v[124:127], v[146:149], v[186:189], v[124:127]
	v_mfma_f32_16x16x32_bf16 v[120:123], v[162:165], v[186:189], v[120:123]
	v_mfma_f32_16x16x32_bf16 v[108:111], v[146:149], v[194:197], v[108:111]
	v_mfma_f32_16x16x32_bf16 v[104:107], v[162:165], v[194:197], v[104:107]
	v_mfma_f32_16x16x32_bf16 v[92:95], v[146:149], v[202:205], v[92:95]
	v_mfma_f32_16x16x32_bf16 v[88:91], v[162:165], v[202:205], v[88:91]
	v_mfma_f32_16x16x32_bf16 v[76:79], v[146:149], v[210:213], v[76:79]
	v_mfma_f32_16x16x32_bf16 v[72:75], v[162:165], v[210:213], v[72:75]
	v_mfma_f32_16x16x32_bf16 v[124:127], v[158:161], v[190:193], v[124:127]
	v_mfma_f32_16x16x32_bf16 v[120:123], v[166:169], v[190:193], v[120:123]
	v_mfma_f32_16x16x32_bf16 v[108:111], v[158:161], v[198:201], v[108:111]
	v_mfma_f32_16x16x32_bf16 v[104:107], v[166:169], v[198:201], v[104:107]
	v_mfma_f32_16x16x32_bf16 v[92:95], v[158:161], v[206:209], v[92:95]
	v_mfma_f32_16x16x32_bf16 v[88:91], v[166:169], v[206:209], v[88:91]
	v_mfma_f32_16x16x32_bf16 v[76:79], v[158:161], v[214:217], v[76:79]
	v_mfma_f32_16x16x32_bf16 v[72:75], v[166:169], v[214:217], v[72:75]
	v_mfma_f32_16x16x32_bf16 v[116:119], v[170:173], v[186:189], v[116:119]
	v_mfma_f32_16x16x32_bf16 v[112:115], v[178:181], v[186:189], v[112:115]
	v_mfma_f32_16x16x32_bf16 v[100:103], v[170:173], v[194:197], v[100:103]
	v_mfma_f32_16x16x32_bf16 v[96:99], v[178:181], v[194:197], v[96:99]
	v_mfma_f32_16x16x32_bf16 v[84:87], v[170:173], v[202:205], v[84:87]
	v_mfma_f32_16x16x32_bf16 v[80:83], v[178:181], v[202:205], v[80:83]
	v_mfma_f32_16x16x32_bf16 v[68:71], v[170:173], v[210:213], v[68:71]
	v_mfma_f32_16x16x32_bf16 v[64:67], v[178:181], v[210:213], v[64:67]
	v_mfma_f32_16x16x32_bf16 v[116:119], v[174:177], v[190:193], v[116:119]
	v_mfma_f32_16x16x32_bf16 v[112:115], v[182:185], v[190:193], v[112:115]
	v_mfma_f32_16x16x32_bf16 v[100:103], v[174:177], v[198:201], v[100:103]
	v_mfma_f32_16x16x32_bf16 v[96:99], v[182:185], v[198:201], v[96:99]
	v_mfma_f32_16x16x32_bf16 v[84:87], v[174:177], v[206:209], v[84:87]
	v_mfma_f32_16x16x32_bf16 v[80:83], v[182:185], v[206:209], v[80:83]
	v_mfma_f32_16x16x32_bf16 v[68:71], v[174:177], v[214:217], v[68:71]
	v_mfma_f32_16x16x32_bf16 v[64:67], v[182:185], v[214:217], v[64:67]
	s_setprio 0
	s_barrier
	s_add_i32 s34, s61, s45
	v_lshl_add_u64 v[218:219], v[218:219], 0, s[10:11]
	s_mov_b32 m0, s34
	ds_read_b128 v[186:189], v155 offset:49152
	ds_read_b128 v[190:193], v155 offset:50176
	ds_read_b128 v[194:197], v155 offset:51200
	ds_read_b128 v[198:201], v155 offset:52224
	ds_read_b128 v[202:205], v155 offset:53248
	ds_read_b128 v[206:209], v155 offset:54272
	ds_read_b128 v[210:213], v155 offset:55296
	ds_read_b128 v[214:217], v155 offset:56320
	global_load_lds_dwordx4 v[218:219], off
	s_add_i32 m0, s34, 0x2000
	s_add_u32 s34, s40, 0x40080
	v_lshl_add_u64 v[218:219], v[220:221], 0, s[10:11]
	s_addc_u32 s35, s41, 0
	s_add_i32 s40, s62, s45
	global_load_lds_dwordx4 v[218:219], off
	s_mov_b32 m0, s40
	v_lshl_add_u64 v[218:219], s[34:35], 0, v[132:133]
	global_load_lds_dwordx4 v[218:219], off
	s_add_i32 m0, s40, 0x2000
	v_lshl_add_u64 v[218:219], s[34:35], 0, v[136:137]
	global_load_lds_dwordx4 v[218:219], off
	s_mov_b32 m0, s51
	v_lshl_add_u64 v[218:219], v[222:223], 0, s[10:11]
	global_load_lds_dwordx4 v[218:219], off
	s_mov_b32 m0, s52
	v_lshl_add_u64 v[218:219], v[224:225], 0, s[10:11]
	global_load_lds_dwordx4 v[218:219], off
	s_waitcnt vmcnt(8)
	s_waitcnt lgkmcnt(0)
	s_barrier
	s_setprio 1
	s_waitcnt lgkmcnt(0)
	v_mfma_f32_16x16x32_bf16 v[60:63], v[146:149], v[186:189], v[60:63]
	v_mfma_f32_16x16x32_bf16 v[56:59], v[162:165], v[186:189], v[56:59]
	v_mfma_f32_16x16x32_bf16 v[44:47], v[146:149], v[194:197], v[44:47]
	v_mfma_f32_16x16x32_bf16 v[40:43], v[162:165], v[194:197], v[40:43]
	v_mfma_f32_16x16x32_bf16 v[28:31], v[146:149], v[202:205], v[28:31]
	v_mfma_f32_16x16x32_bf16 v[24:27], v[162:165], v[202:205], v[24:27]
	v_mfma_f32_16x16x32_bf16 v[12:15], v[146:149], v[210:213], v[12:15]
	v_mfma_f32_16x16x32_bf16 v[8:11], v[162:165], v[210:213], v[8:11]
	v_mfma_f32_16x16x32_bf16 v[60:63], v[158:161], v[190:193], v[60:63]
	v_mfma_f32_16x16x32_bf16 v[56:59], v[166:169], v[190:193], v[56:59]
	v_mfma_f32_16x16x32_bf16 v[44:47], v[158:161], v[198:201], v[44:47]
	v_mfma_f32_16x16x32_bf16 v[40:43], v[166:169], v[198:201], v[40:43]
	v_mfma_f32_16x16x32_bf16 v[28:31], v[158:161], v[206:209], v[28:31]
	v_mfma_f32_16x16x32_bf16 v[24:27], v[166:169], v[206:209], v[24:27]
	v_mfma_f32_16x16x32_bf16 v[12:15], v[158:161], v[214:217], v[12:15]
	v_mfma_f32_16x16x32_bf16 v[8:11], v[166:169], v[214:217], v[8:11]
	v_mfma_f32_16x16x32_bf16 v[52:55], v[170:173], v[186:189], v[52:55]
	v_mfma_f32_16x16x32_bf16 v[48:51], v[178:181], v[186:189], v[48:51]
	v_mfma_f32_16x16x32_bf16 v[36:39], v[170:173], v[194:197], v[36:39]
	v_mfma_f32_16x16x32_bf16 v[32:35], v[178:181], v[194:197], v[32:35]
	v_mfma_f32_16x16x32_bf16 v[20:23], v[170:173], v[202:205], v[20:23]
	v_mfma_f32_16x16x32_bf16 v[16:19], v[178:181], v[202:205], v[16:19]
	v_mfma_f32_16x16x32_bf16 v[4:7], v[170:173], v[210:213], v[4:7]
	v_mfma_f32_16x16x32_bf16 v[0:3], v[178:181], v[210:213], v[0:3]
	v_mfma_f32_16x16x32_bf16 v[52:55], v[174:177], v[190:193], v[52:55]
	v_mfma_f32_16x16x32_bf16 v[48:51], v[182:185], v[190:193], v[48:51]
	v_mfma_f32_16x16x32_bf16 v[36:39], v[174:177], v[198:201], v[36:39]
	v_mfma_f32_16x16x32_bf16 v[32:35], v[182:185], v[198:201], v[32:35]
	v_mfma_f32_16x16x32_bf16 v[20:23], v[174:177], v[206:209], v[20:23]
	v_mfma_f32_16x16x32_bf16 v[16:19], v[182:185], v[206:209], v[16:19]
	v_mfma_f32_16x16x32_bf16 v[4:7], v[174:177], v[214:217], v[4:7]
	v_mfma_f32_16x16x32_bf16 v[0:3], v[182:185], v[214:217], v[0:3]
	s_setprio 0
	s_barrier
	s_add_i32 s60, s60, 2
	s_add_u32 s38, s38, 0x100
	s_addc_u32 s39, s39, 0
	s_add_u32 s37, s37, 0x100
	s_addc_u32 s59, s59, 0
.LBB0_2001:
	ds_read_b128 v[146:149], v153
	ds_read_b128 v[158:161], v153 offset:1024
	ds_read_b128 v[162:165], v153 offset:2048
	ds_read_b128 v[166:169], v153 offset:3072
	ds_read_b128 v[170:173], v154
	ds_read_b128 v[174:177], v154 offset:1024
	ds_read_b128 v[178:181], v154 offset:2048
	ds_read_b128 v[182:185], v154 offset:3072
	s_add_u32 s34, s38, 0xfffc0080
	s_addc_u32 s35, s39, -1
	s_cmp_eq_u32 s60, 12
	s_cselect_b32 s43, s12, s35
	s_cselect_b32 s42, s13, s34
	s_cselect_b32 s41, s25, s59
	s_cselect_b32 s40, s27, s37
	v_lshl_add_u64 v[218:219], s[38:39], 0, v[138:139]
	s_add_i32 m0, s46, 0xc000
	ds_read_b128 v[186:189], v155
	ds_read_b128 v[190:193], v155 offset:1024
	ds_read_b128 v[194:197], v155 offset:2048
	ds_read_b128 v[198:201], v155 offset:3072
	ds_read_b128 v[202:205], v155 offset:4096
	ds_read_b128 v[206:209], v155 offset:5120
	ds_read_b128 v[210:213], v155 offset:6144
	ds_read_b128 v[214:217], v155 offset:7168
	global_load_lds_dwordx4 v[218:219], off
	s_add_i32 m0, s46, 0xe000
	v_lshl_add_u64 v[218:219], s[38:39], 0, v[140:141]
	global_load_lds_dwordx4 v[218:219], off
	s_waitcnt vmcnt(8)
	s_waitcnt lgkmcnt(0)
	s_barrier
	s_setprio 1
	s_waitcnt lgkmcnt(0)
	v_mfma_f32_16x16x32_bf16 v[124:127], v[146:149], v[186:189], v[124:127]
	v_mfma_f32_16x16x32_bf16 v[120:123], v[162:165], v[186:189], v[120:123]
	v_mfma_f32_16x16x32_bf16 v[108:111], v[146:149], v[194:197], v[108:111]
	v_mfma_f32_16x16x32_bf16 v[104:107], v[162:165], v[194:197], v[104:107]
	v_mfma_f32_16x16x32_bf16 v[92:95], v[146:149], v[202:205], v[92:95]
	v_mfma_f32_16x16x32_bf16 v[88:91], v[162:165], v[202:205], v[88:91]
	v_mfma_f32_16x16x32_bf16 v[76:79], v[146:149], v[210:213], v[76:79]
	v_mfma_f32_16x16x32_bf16 v[72:75], v[162:165], v[210:213], v[72:75]
	v_mfma_f32_16x16x32_bf16 v[124:127], v[158:161], v[190:193], v[124:127]
	v_mfma_f32_16x16x32_bf16 v[120:123], v[166:169], v[190:193], v[120:123]
	v_mfma_f32_16x16x32_bf16 v[108:111], v[158:161], v[198:201], v[108:111]
	v_mfma_f32_16x16x32_bf16 v[104:107], v[166:169], v[198:201], v[104:107]
	v_mfma_f32_16x16x32_bf16 v[92:95], v[158:161], v[206:209], v[92:95]
	v_mfma_f32_16x16x32_bf16 v[88:91], v[166:169], v[206:209], v[88:91]
	v_mfma_f32_16x16x32_bf16 v[76:79], v[158:161], v[214:217], v[76:79]
	v_mfma_f32_16x16x32_bf16 v[72:75], v[166:169], v[214:217], v[72:75]
	v_mfma_f32_16x16x32_bf16 v[116:119], v[170:173], v[186:189], v[116:119]
	v_mfma_f32_16x16x32_bf16 v[112:115], v[178:181], v[186:189], v[112:115]
	v_mfma_f32_16x16x32_bf16 v[100:103], v[170:173], v[194:197], v[100:103]
	v_mfma_f32_16x16x32_bf16 v[96:99], v[178:181], v[194:197], v[96:99]
	v_mfma_f32_16x16x32_bf16 v[84:87], v[170:173], v[202:205], v[84:87]
	v_mfma_f32_16x16x32_bf16 v[80:83], v[178:181], v[202:205], v[80:83]
	v_mfma_f32_16x16x32_bf16 v[68:71], v[170:173], v[210:213], v[68:71]
	v_mfma_f32_16x16x32_bf16 v[64:67], v[178:181], v[210:213], v[64:67]
	v_mfma_f32_16x16x32_bf16 v[116:119], v[174:177], v[190:193], v[116:119]
	v_mfma_f32_16x16x32_bf16 v[112:115], v[182:185], v[190:193], v[112:115]
	v_mfma_f32_16x16x32_bf16 v[100:103], v[174:177], v[198:201], v[100:103]
	v_mfma_f32_16x16x32_bf16 v[96:99], v[182:185], v[198:201], v[96:99]
	v_mfma_f32_16x16x32_bf16 v[84:87], v[174:177], v[206:209], v[84:87]
	v_mfma_f32_16x16x32_bf16 v[80:83], v[182:185], v[206:209], v[80:83]
	v_mfma_f32_16x16x32_bf16 v[68:71], v[174:177], v[214:217], v[68:71]
	v_mfma_f32_16x16x32_bf16 v[64:67], v[182:185], v[214:217], v[64:67]
	s_setprio 0
	s_barrier
	s_add_i32 s34, s56, s45
	v_lshl_add_u64 v[218:219], s[40:41], 0, v[132:133]
	s_mov_b32 m0, s34
	ds_read_b128 v[186:189], v155 offset:16384
	ds_read_b128 v[190:193], v155 offset:17408
	ds_read_b128 v[194:197], v155 offset:18432
	ds_read_b128 v[198:201], v155 offset:19456
	ds_read_b128 v[202:205], v155 offset:20480
	ds_read_b128 v[206:209], v155 offset:21504
	ds_read_b128 v[210:213], v155 offset:22528
	ds_read_b128 v[214:217], v155 offset:23552
	global_load_lds_dwordx4 v[218:219], off
	s_add_i32 m0, s34, 0x2000
	s_add_u32 s34, s40, 0x40000
	v_lshl_add_u64 v[220:221], s[40:41], 0, v[136:137]
	s_addc_u32 s35, s41, 0
	s_add_i32 s61, s57, s45
	global_load_lds_dwordx4 v[220:221], off
	v_lshl_add_u64 v[222:223], s[34:35], 0, v[132:133]
	s_mov_b32 m0, s61
	v_lshl_add_u64 v[224:225], s[42:43], 0, v[134:135]
	global_load_lds_dwordx4 v[222:223], off
	s_add_i32 m0, s61, 0x2000
	v_lshl_add_u64 v[222:223], s[34:35], 0, v[136:137]
	global_load_lds_dwordx4 v[222:223], off
	s_mov_b32 m0, s46
	v_lshl_add_u64 v[222:223], s[42:43], 0, v[130:131]
	global_load_lds_dwordx4 v[222:223], off
	s_mov_b32 m0, s47
	s_nop 0
	global_load_lds_dwordx4 v[224:225], off
	s_waitcnt vmcnt(8)
	s_waitcnt lgkmcnt(0)
	s_barrier
	s_setprio 1
	s_waitcnt lgkmcnt(0)
	v_mfma_f32_16x16x32_bf16 v[60:63], v[146:149], v[186:189], v[60:63]
	v_mfma_f32_16x16x32_bf16 v[56:59], v[162:165], v[186:189], v[56:59]
	v_mfma_f32_16x16x32_bf16 v[44:47], v[146:149], v[194:197], v[44:47]
	v_mfma_f32_16x16x32_bf16 v[40:43], v[162:165], v[194:197], v[40:43]
	v_mfma_f32_16x16x32_bf16 v[28:31], v[146:149], v[202:205], v[28:31]
	v_mfma_f32_16x16x32_bf16 v[24:27], v[162:165], v[202:205], v[24:27]
	v_mfma_f32_16x16x32_bf16 v[12:15], v[146:149], v[210:213], v[12:15]
	v_mfma_f32_16x16x32_bf16 v[8:11], v[162:165], v[210:213], v[8:11]
	v_mfma_f32_16x16x32_bf16 v[60:63], v[158:161], v[190:193], v[60:63]
	v_mfma_f32_16x16x32_bf16 v[56:59], v[166:169], v[190:193], v[56:59]
	v_mfma_f32_16x16x32_bf16 v[44:47], v[158:161], v[198:201], v[44:47]
	v_mfma_f32_16x16x32_bf16 v[40:43], v[166:169], v[198:201], v[40:43]
	v_mfma_f32_16x16x32_bf16 v[28:31], v[158:161], v[206:209], v[28:31]
	v_mfma_f32_16x16x32_bf16 v[24:27], v[166:169], v[206:209], v[24:27]
	v_mfma_f32_16x16x32_bf16 v[12:15], v[158:161], v[214:217], v[12:15]
	v_mfma_f32_16x16x32_bf16 v[8:11], v[166:169], v[214:217], v[8:11]
	v_mfma_f32_16x16x32_bf16 v[52:55], v[170:173], v[186:189], v[52:55]
	v_mfma_f32_16x16x32_bf16 v[48:51], v[178:181], v[186:189], v[48:51]
	v_mfma_f32_16x16x32_bf16 v[36:39], v[170:173], v[194:197], v[36:39]
	v_mfma_f32_16x16x32_bf16 v[32:35], v[178:181], v[194:197], v[32:35]
	v_mfma_f32_16x16x32_bf16 v[20:23], v[170:173], v[202:205], v[20:23]
	v_mfma_f32_16x16x32_bf16 v[16:19], v[178:181], v[202:205], v[16:19]
	v_mfma_f32_16x16x32_bf16 v[4:7], v[170:173], v[210:213], v[4:7]
	v_mfma_f32_16x16x32_bf16 v[0:3], v[178:181], v[210:213], v[0:3]
	v_mfma_f32_16x16x32_bf16 v[52:55], v[174:177], v[190:193], v[52:55]
	v_mfma_f32_16x16x32_bf16 v[48:51], v[182:185], v[190:193], v[48:51]
	v_mfma_f32_16x16x32_bf16 v[36:39], v[174:177], v[198:201], v[36:39]
	v_mfma_f32_16x16x32_bf16 v[32:35], v[182:185], v[198:201], v[32:35]
	v_mfma_f32_16x16x32_bf16 v[20:23], v[174:177], v[206:209], v[20:23]
	v_mfma_f32_16x16x32_bf16 v[16:19], v[182:185], v[206:209], v[16:19]
	v_mfma_f32_16x16x32_bf16 v[4:7], v[174:177], v[214:217], v[4:7]
	v_mfma_f32_16x16x32_bf16 v[0:3], v[182:185], v[214:217], v[0:3]
	s_setprio 0
	s_barrier
	s_add_i32 s61, 0, 0x18000
	v_add_u32_e32 v157, s61, v151
	s_add_i32 s62, 0, 0x1c000
	ds_read_b128 v[146:149], v157
	ds_read_b128 v[158:161], v157 offset:1024
	ds_read_b128 v[162:165], v157 offset:2048
	ds_read_b128 v[166:169], v157 offset:3072
	v_add_u32_e32 v157, s62, v151
	ds_read_b128 v[170:173], v157
	ds_read_b128 v[174:177], v157 offset:1024
	ds_read_b128 v[178:181], v157 offset:2048
	ds_read_b128 v[182:185], v157 offset:3072
	s_add_u32 s34, s42, 0x40000
	s_addc_u32 s35, s43, 0
	s_mov_b32 m0, s48
	v_lshl_add_u64 v[226:227], s[34:35], 0, v[130:131]
	ds_read_b128 v[186:189], v155 offset:32768
	ds_read_b128 v[190:193], v155 offset:33792
	ds_read_b128 v[194:197], v155 offset:34816
	ds_read_b128 v[198:201], v155 offset:35840
	ds_read_b128 v[202:205], v155 offset:36864
	ds_read_b128 v[206:209], v155 offset:37888
	ds_read_b128 v[210:213], v155 offset:38912
	ds_read_b128 v[214:217], v155 offset:39936
	global_load_lds_dwordx4 v[226:227], off
	s_mov_b32 m0, s49
	v_lshl_add_u64 v[226:227], s[34:35], 0, v[134:135]
	global_load_lds_dwordx4 v[226:227], off
	s_waitcnt vmcnt(8)
	s_waitcnt lgkmcnt(0)
	s_barrier
	s_setprio 1
	s_waitcnt lgkmcnt(0)
	v_mfma_f32_16x16x32_bf16 v[124:127], v[146:149], v[186:189], v[124:127]
	v_mfma_f32_16x16x32_bf16 v[120:123], v[162:165], v[186:189], v[120:123]
	v_mfma_f32_16x16x32_bf16 v[108:111], v[146:149], v[194:197], v[108:111]
	v_mfma_f32_16x16x32_bf16 v[104:107], v[162:165], v[194:197], v[104:107]
	v_mfma_f32_16x16x32_bf16 v[92:95], v[146:149], v[202:205], v[92:95]
	v_mfma_f32_16x16x32_bf16 v[88:91], v[162:165], v[202:205], v[88:91]
	v_mfma_f32_16x16x32_bf16 v[76:79], v[146:149], v[210:213], v[76:79]
	v_mfma_f32_16x16x32_bf16 v[72:75], v[162:165], v[210:213], v[72:75]
	v_mfma_f32_16x16x32_bf16 v[124:127], v[158:161], v[190:193], v[124:127]
	v_mfma_f32_16x16x32_bf16 v[120:123], v[166:169], v[190:193], v[120:123]
	v_mfma_f32_16x16x32_bf16 v[108:111], v[158:161], v[198:201], v[108:111]
	v_mfma_f32_16x16x32_bf16 v[104:107], v[166:169], v[198:201], v[104:107]
	v_mfma_f32_16x16x32_bf16 v[92:95], v[158:161], v[206:209], v[92:95]
	v_mfma_f32_16x16x32_bf16 v[88:91], v[166:169], v[206:209], v[88:91]
	v_mfma_f32_16x16x32_bf16 v[76:79], v[158:161], v[214:217], v[76:79]
	v_mfma_f32_16x16x32_bf16 v[72:75], v[166:169], v[214:217], v[72:75]
	v_mfma_f32_16x16x32_bf16 v[116:119], v[170:173], v[186:189], v[116:119]
	v_mfma_f32_16x16x32_bf16 v[112:115], v[178:181], v[186:189], v[112:115]
	v_mfma_f32_16x16x32_bf16 v[100:103], v[170:173], v[194:197], v[100:103]
	v_mfma_f32_16x16x32_bf16 v[96:99], v[178:181], v[194:197], v[96:99]
	v_mfma_f32_16x16x32_bf16 v[84:87], v[170:173], v[202:205], v[84:87]
	v_mfma_f32_16x16x32_bf16 v[80:83], v[178:181], v[202:205], v[80:83]
	v_mfma_f32_16x16x32_bf16 v[68:71], v[170:173], v[210:213], v[68:71]
	v_mfma_f32_16x16x32_bf16 v[64:67], v[178:181], v[210:213], v[64:67]
	v_mfma_f32_16x16x32_bf16 v[116:119], v[174:177], v[190:193], v[116:119]
	v_mfma_f32_16x16x32_bf16 v[112:115], v[182:185], v[190:193], v[112:115]
	v_mfma_f32_16x16x32_bf16 v[100:103], v[174:177], v[198:201], v[100:103]
	v_mfma_f32_16x16x32_bf16 v[96:99], v[182:185], v[198:201], v[96:99]
	v_mfma_f32_16x16x32_bf16 v[84:87], v[174:177], v[206:209], v[84:87]
	v_mfma_f32_16x16x32_bf16 v[80:83], v[182:185], v[206:209], v[80:83]
	v_mfma_f32_16x16x32_bf16 v[68:71], v[174:177], v[214:217], v[68:71]
	v_mfma_f32_16x16x32_bf16 v[64:67], v[182:185], v[214:217], v[64:67]
	s_setprio 0
	s_barrier
	s_add_i32 s34, s61, s45
	v_lshl_add_u64 v[218:219], v[218:219], 0, s[10:11]
	s_mov_b32 m0, s34
	ds_read_b128 v[186:189], v155 offset:49152
	ds_read_b128 v[190:193], v155 offset:50176
	ds_read_b128 v[194:197], v155 offset:51200
	ds_read_b128 v[198:201], v155 offset:52224
	ds_read_b128 v[202:205], v155 offset:53248
	ds_read_b128 v[206:209], v155 offset:54272
	ds_read_b128 v[210:213], v155 offset:55296
	ds_read_b128 v[214:217], v155 offset:56320
	global_load_lds_dwordx4 v[218:219], off
	s_add_i32 m0, s34, 0x2000
	s_add_u32 s34, s40, 0x40080
	v_lshl_add_u64 v[218:219], v[220:221], 0, s[10:11]
	s_addc_u32 s35, s41, 0
	s_add_i32 s40, s62, s45
	global_load_lds_dwordx4 v[218:219], off
	s_mov_b32 m0, s40
	v_lshl_add_u64 v[218:219], s[34:35], 0, v[132:133]
	global_load_lds_dwordx4 v[218:219], off
	s_add_i32 m0, s40, 0x2000
	v_lshl_add_u64 v[218:219], s[34:35], 0, v[136:137]
	global_load_lds_dwordx4 v[218:219], off
	s_mov_b32 m0, s51
	v_lshl_add_u64 v[218:219], v[222:223], 0, s[10:11]
	global_load_lds_dwordx4 v[218:219], off
	s_mov_b32 m0, s52
	v_lshl_add_u64 v[218:219], v[224:225], 0, s[10:11]
	global_load_lds_dwordx4 v[218:219], off
	s_waitcnt vmcnt(8)
	s_waitcnt lgkmcnt(0)
	s_barrier
	s_setprio 1
	s_waitcnt lgkmcnt(0)
	v_mfma_f32_16x16x32_bf16 v[60:63], v[146:149], v[186:189], v[60:63]
	v_mfma_f32_16x16x32_bf16 v[56:59], v[162:165], v[186:189], v[56:59]
	v_mfma_f32_16x16x32_bf16 v[44:47], v[146:149], v[194:197], v[44:47]
	v_mfma_f32_16x16x32_bf16 v[40:43], v[162:165], v[194:197], v[40:43]
	v_mfma_f32_16x16x32_bf16 v[28:31], v[146:149], v[202:205], v[28:31]
	v_mfma_f32_16x16x32_bf16 v[24:27], v[162:165], v[202:205], v[24:27]
	v_mfma_f32_16x16x32_bf16 v[12:15], v[146:149], v[210:213], v[12:15]
	v_mfma_f32_16x16x32_bf16 v[8:11], v[162:165], v[210:213], v[8:11]
	v_mfma_f32_16x16x32_bf16 v[60:63], v[158:161], v[190:193], v[60:63]
	v_mfma_f32_16x16x32_bf16 v[56:59], v[166:169], v[190:193], v[56:59]
	v_mfma_f32_16x16x32_bf16 v[44:47], v[158:161], v[198:201], v[44:47]
	v_mfma_f32_16x16x32_bf16 v[40:43], v[166:169], v[198:201], v[40:43]
	v_mfma_f32_16x16x32_bf16 v[28:31], v[158:161], v[206:209], v[28:31]
	v_mfma_f32_16x16x32_bf16 v[24:27], v[166:169], v[206:209], v[24:27]
	v_mfma_f32_16x16x32_bf16 v[12:15], v[158:161], v[214:217], v[12:15]
	v_mfma_f32_16x16x32_bf16 v[8:11], v[166:169], v[214:217], v[8:11]
	v_mfma_f32_16x16x32_bf16 v[52:55], v[170:173], v[186:189], v[52:55]
	v_mfma_f32_16x16x32_bf16 v[48:51], v[178:181], v[186:189], v[48:51]
	v_mfma_f32_16x16x32_bf16 v[36:39], v[170:173], v[194:197], v[36:39]
	v_mfma_f32_16x16x32_bf16 v[32:35], v[178:181], v[194:197], v[32:35]
	v_mfma_f32_16x16x32_bf16 v[20:23], v[170:173], v[202:205], v[20:23]
	v_mfma_f32_16x16x32_bf16 v[16:19], v[178:181], v[202:205], v[16:19]
	v_mfma_f32_16x16x32_bf16 v[4:7], v[170:173], v[210:213], v[4:7]
	v_mfma_f32_16x16x32_bf16 v[0:3], v[178:181], v[210:213], v[0:3]
	v_mfma_f32_16x16x32_bf16 v[52:55], v[174:177], v[190:193], v[52:55]
	v_mfma_f32_16x16x32_bf16 v[48:51], v[182:185], v[190:193], v[48:51]
	v_mfma_f32_16x16x32_bf16 v[36:39], v[174:177], v[198:201], v[36:39]
	v_mfma_f32_16x16x32_bf16 v[32:35], v[182:185], v[198:201], v[32:35]
	v_mfma_f32_16x16x32_bf16 v[20:23], v[174:177], v[206:209], v[20:23]
	v_mfma_f32_16x16x32_bf16 v[16:19], v[182:185], v[206:209], v[16:19]
	v_mfma_f32_16x16x32_bf16 v[4:7], v[174:177], v[214:217], v[4:7]
	v_mfma_f32_16x16x32_bf16 v[0:3], v[182:185], v[214:217], v[0:3]
	s_setprio 0
	s_cmp_eq_u32 s60, s98
	s_cbranch_scc1 .Lmy_nobar_21
	s_barrier

.Lmy_nobar2_22:
	ds_read_b128 v[146:149], v153
	ds_read_b128 v[156:159], v153 offset:1024
	ds_read_b128 v[160:163], v153 offset:2048
	ds_read_b128 v[164:167], v153 offset:3072
	ds_read_b128 v[168:171], v154
	ds_read_b128 v[172:175], v154 offset:1024
	ds_read_b128 v[176:179], v154 offset:2048
	ds_read_b128 v[180:183], v154 offset:3072
	s_add_u32 s28, s26, 0xfffc0080
	s_addc_u32 s29, s27, -1
	s_cmp_eq_u32 s56, 12
	s_cselect_b32 s31, s19, s29
	s_cselect_b32 s30, s52, s28
	s_cselect_b32 s29, s11, s55
	s_cselect_b32 s28, s53, s54
	v_lshl_add_u64 v[216:217], s[26:27], 0, v[138:139]
	s_add_i32 m0, s25, 0xc000
	ds_read_b128 v[184:187], v155
	ds_read_b128 v[188:191], v155 offset:1024
	ds_read_b128 v[192:195], v155 offset:2048
	ds_read_b128 v[196:199], v155 offset:3072
	ds_read_b128 v[200:203], v155 offset:4096
	ds_read_b128 v[204:207], v155 offset:5120
	ds_read_b128 v[208:211], v155 offset:6144
	ds_read_b128 v[212:215], v155 offset:7168
	global_load_lds_dwordx4 v[216:217], off
	s_add_i32 m0, s25, 0xe000
	v_lshl_add_u64 v[216:217], s[26:27], 0, v[140:141]
	global_load_lds_dwordx4 v[216:217], off
	s_waitcnt vmcnt(8)
	s_waitcnt lgkmcnt(0)
	s_barrier
	s_setprio 1
	s_waitcnt lgkmcnt(0)
	v_mfma_f32_16x16x32_bf16 v[124:127], v[146:149], v[184:187], 0
	v_mfma_f32_16x16x32_bf16 v[120:123], v[160:163], v[184:187], 0
	v_mfma_f32_16x16x32_bf16 v[108:111], v[146:149], v[192:195], 0
	v_mfma_f32_16x16x32_bf16 v[104:107], v[160:163], v[192:195], 0
	v_mfma_f32_16x16x32_bf16 v[92:95], v[146:149], v[200:203], 0
	v_mfma_f32_16x16x32_bf16 v[88:91], v[160:163], v[200:203], 0
	v_mfma_f32_16x16x32_bf16 v[76:79], v[146:149], v[208:211], 0
	v_mfma_f32_16x16x32_bf16 v[72:75], v[160:163], v[208:211], 0
	v_mfma_f32_16x16x32_bf16 v[124:127], v[156:159], v[188:191], v[124:127]
	v_mfma_f32_16x16x32_bf16 v[120:123], v[164:167], v[188:191], v[120:123]
	v_mfma_f32_16x16x32_bf16 v[108:111], v[156:159], v[196:199], v[108:111]
	v_mfma_f32_16x16x32_bf16 v[104:107], v[164:167], v[196:199], v[104:107]
	v_mfma_f32_16x16x32_bf16 v[92:95], v[156:159], v[204:207], v[92:95]
	v_mfma_f32_16x16x32_bf16 v[88:91], v[164:167], v[204:207], v[88:91]
	v_mfma_f32_16x16x32_bf16 v[76:79], v[156:159], v[212:215], v[76:79]
	v_mfma_f32_16x16x32_bf16 v[72:75], v[164:167], v[212:215], v[72:75]
	v_mfma_f32_16x16x32_bf16 v[116:119], v[168:171], v[184:187], 0
	v_mfma_f32_16x16x32_bf16 v[112:115], v[176:179], v[184:187], 0
	v_mfma_f32_16x16x32_bf16 v[100:103], v[168:171], v[192:195], 0
	v_mfma_f32_16x16x32_bf16 v[96:99], v[176:179], v[192:195], 0
	v_mfma_f32_16x16x32_bf16 v[84:87], v[168:171], v[200:203], 0
	v_mfma_f32_16x16x32_bf16 v[80:83], v[176:179], v[200:203], 0
	v_mfma_f32_16x16x32_bf16 v[68:71], v[168:171], v[208:211], 0
	v_mfma_f32_16x16x32_bf16 v[64:67], v[176:179], v[208:211], 0
	v_mfma_f32_16x16x32_bf16 v[116:119], v[172:175], v[188:191], v[116:119]
	v_mfma_f32_16x16x32_bf16 v[112:115], v[180:183], v[188:191], v[112:115]
	v_mfma_f32_16x16x32_bf16 v[100:103], v[172:175], v[196:199], v[100:103]
	v_mfma_f32_16x16x32_bf16 v[96:99], v[180:183], v[196:199], v[96:99]
	v_mfma_f32_16x16x32_bf16 v[84:87], v[172:175], v[204:207], v[84:87]
	v_mfma_f32_16x16x32_bf16 v[80:83], v[180:183], v[204:207], v[80:83]
	v_mfma_f32_16x16x32_bf16 v[68:71], v[172:175], v[212:215], v[68:71]
	v_mfma_f32_16x16x32_bf16 v[64:67], v[180:183], v[212:215], v[64:67]
	s_setprio 0
	s_barrier
	s_add_i32 s34, s47, s38
	v_lshl_add_u64 v[216:217], s[28:29], 0, v[134:135]
	s_mov_b32 m0, s34
	ds_read_b128 v[184:187], v155 offset:16384
	ds_read_b128 v[188:191], v155 offset:17408
	ds_read_b128 v[192:195], v155 offset:18432
	ds_read_b128 v[196:199], v155 offset:19456
	ds_read_b128 v[200:203], v155 offset:20480
	ds_read_b128 v[204:207], v155 offset:21504
	ds_read_b128 v[208:211], v155 offset:22528
	ds_read_b128 v[212:215], v155 offset:23552
	global_load_lds_dwordx4 v[216:217], off
	s_add_i32 m0, s34, 0x2000
	s_add_u32 s34, s28, 0x40000
	v_lshl_add_u64 v[218:219], s[28:29], 0, v[130:131]
	s_addc_u32 s35, s29, 0
	s_add_i32 s57, s48, s38
	global_load_lds_dwordx4 v[218:219], off
	v_lshl_add_u64 v[220:221], s[34:35], 0, v[134:135]
	s_mov_b32 m0, s57
	v_lshl_add_u64 v[222:223], s[30:31], 0, v[132:133]
	global_load_lds_dwordx4 v[220:221], off
	s_add_i32 m0, s57, 0x2000
	v_lshl_add_u64 v[220:221], s[34:35], 0, v[130:131]
	global_load_lds_dwordx4 v[220:221], off
	s_mov_b32 m0, s25
	v_lshl_add_u64 v[220:221], s[30:31], 0, v[136:137]
	global_load_lds_dwordx4 v[220:221], off
	s_mov_b32 m0, s42
	s_nop 0
	global_load_lds_dwordx4 v[222:223], off
	s_waitcnt vmcnt(8)
	s_waitcnt lgkmcnt(0)
	s_barrier
	s_setprio 1
	s_waitcnt lgkmcnt(0)
	v_mfma_f32_16x16x32_bf16 v[60:63], v[146:149], v[184:187], 0
	v_mfma_f32_16x16x32_bf16 v[56:59], v[160:163], v[184:187], 0
	v_mfma_f32_16x16x32_bf16 v[44:47], v[146:149], v[192:195], 0
	v_mfma_f32_16x16x32_bf16 v[40:43], v[160:163], v[192:195], 0
	v_mfma_f32_16x16x32_bf16 v[28:31], v[146:149], v[200:203], 0
	v_mfma_f32_16x16x32_bf16 v[24:27], v[160:163], v[200:203], 0
	v_mfma_f32_16x16x32_bf16 v[12:15], v[146:149], v[208:211], 0
	v_mfma_f32_16x16x32_bf16 v[8:11], v[160:163], v[208:211], 0
	v_mfma_f32_16x16x32_bf16 v[60:63], v[156:159], v[188:191], v[60:63]
	v_mfma_f32_16x16x32_bf16 v[56:59], v[164:167], v[188:191], v[56:59]
	v_mfma_f32_16x16x32_bf16 v[44:47], v[156:159], v[196:199], v[44:47]
	v_mfma_f32_16x16x32_bf16 v[40:43], v[164:167], v[196:199], v[40:43]
	v_mfma_f32_16x16x32_bf16 v[28:31], v[156:159], v[204:207], v[28:31]
	v_mfma_f32_16x16x32_bf16 v[24:27], v[164:167], v[204:207], v[24:27]
	v_mfma_f32_16x16x32_bf16 v[12:15], v[156:159], v[212:215], v[12:15]
	v_mfma_f32_16x16x32_bf16 v[8:11], v[164:167], v[212:215], v[8:11]
	v_mfma_f32_16x16x32_bf16 v[52:55], v[168:171], v[184:187], 0
	v_mfma_f32_16x16x32_bf16 v[48:51], v[176:179], v[184:187], 0
	v_mfma_f32_16x16x32_bf16 v[36:39], v[168:171], v[192:195], 0
	v_mfma_f32_16x16x32_bf16 v[32:35], v[176:179], v[192:195], 0
	v_mfma_f32_16x16x32_bf16 v[20:23], v[168:171], v[200:203], 0
	v_mfma_f32_16x16x32_bf16 v[16:19], v[176:179], v[200:203], 0
	v_mfma_f32_16x16x32_bf16 v[4:7], v[168:171], v[208:211], 0
	v_mfma_f32_16x16x32_bf16 v[0:3], v[176:179], v[208:211], 0
	v_mfma_f32_16x16x32_bf16 v[52:55], v[172:175], v[188:191], v[52:55]
	v_mfma_f32_16x16x32_bf16 v[48:51], v[180:183], v[188:191], v[48:51]
	v_mfma_f32_16x16x32_bf16 v[36:39], v[172:175], v[196:199], v[36:39]
	v_mfma_f32_16x16x32_bf16 v[32:35], v[180:183], v[196:199], v[32:35]
	v_mfma_f32_16x16x32_bf16 v[20:23], v[172:175], v[204:207], v[20:23]
	v_mfma_f32_16x16x32_bf16 v[16:19], v[180:183], v[204:207], v[16:19]
	v_mfma_f32_16x16x32_bf16 v[4:7], v[172:175], v[212:215], v[4:7]
	v_mfma_f32_16x16x32_bf16 v[0:3], v[180:183], v[212:215], v[0:3]
	s_setprio 0
	s_barrier
	s_add_i32 s34, 0, 0x18000
	s_add_i32 s35, 0, 0x1c000
	v_add_u32_e32 v164, s34, v150
	v_add_u32_e32 v180, s35, v150
	ds_read_b128 v[146:149], v164
	ds_read_b128 v[156:159], v164 offset:1024
	ds_read_b128 v[160:163], v164 offset:2048
	ds_read_b128 v[164:167], v164 offset:3072
	ds_read_b128 v[168:171], v180
	ds_read_b128 v[172:175], v180 offset:1024
	ds_read_b128 v[176:179], v180 offset:2048
	ds_read_b128 v[180:183], v180 offset:3072
	s_add_u32 s30, s30, 0x40000
	s_addc_u32 s31, s31, 0
	s_mov_b32 m0, s43
	v_lshl_add_u64 v[224:225], s[30:31], 0, v[136:137]
	ds_read_b128 v[184:187], v155 offset:32768
	ds_read_b128 v[188:191], v155 offset:33792
	ds_read_b128 v[192:195], v155 offset:34816
	ds_read_b128 v[196:199], v155 offset:35840
	ds_read_b128 v[200:203], v155 offset:36864
	ds_read_b128 v[204:207], v155 offset:37888
	ds_read_b128 v[208:211], v155 offset:38912
	ds_read_b128 v[212:215], v155 offset:39936
	global_load_lds_dwordx4 v[224:225], off
	s_mov_b32 m0, s44
	v_lshl_add_u64 v[224:225], s[30:31], 0, v[132:133]
	global_load_lds_dwordx4 v[224:225], off
	s_waitcnt vmcnt(8)
	s_waitcnt lgkmcnt(0)
	s_barrier
	s_setprio 1
	s_waitcnt lgkmcnt(0)
	v_mfma_f32_16x16x32_bf16 v[124:127], v[146:149], v[184:187], v[124:127]
	v_mfma_f32_16x16x32_bf16 v[120:123], v[160:163], v[184:187], v[120:123]
	v_mfma_f32_16x16x32_bf16 v[108:111], v[146:149], v[192:195], v[108:111]
	v_mfma_f32_16x16x32_bf16 v[104:107], v[160:163], v[192:195], v[104:107]
	v_mfma_f32_16x16x32_bf16 v[92:95], v[146:149], v[200:203], v[92:95]
	v_mfma_f32_16x16x32_bf16 v[88:91], v[160:163], v[200:203], v[88:91]
	v_mfma_f32_16x16x32_bf16 v[76:79], v[146:149], v[208:211], v[76:79]
	v_mfma_f32_16x16x32_bf16 v[72:75], v[160:163], v[208:211], v[72:75]
	v_mfma_f32_16x16x32_bf16 v[124:127], v[156:159], v[188:191], v[124:127]
	v_mfma_f32_16x16x32_bf16 v[120:123], v[164:167], v[188:191], v[120:123]
	v_mfma_f32_16x16x32_bf16 v[108:111], v[156:159], v[196:199], v[108:111]
	v_mfma_f32_16x16x32_bf16 v[104:107], v[164:167], v[196:199], v[104:107]
	v_mfma_f32_16x16x32_bf16 v[92:95], v[156:159], v[204:207], v[92:95]
	v_mfma_f32_16x16x32_bf16 v[88:91], v[164:167], v[204:207], v[88:91]
	v_mfma_f32_16x16x32_bf16 v[76:79], v[156:159], v[212:215], v[76:79]
	v_mfma_f32_16x16x32_bf16 v[72:75], v[164:167], v[212:215], v[72:75]
	v_mfma_f32_16x16x32_bf16 v[116:119], v[168:171], v[184:187], v[116:119]
	v_mfma_f32_16x16x32_bf16 v[112:115], v[176:179], v[184:187], v[112:115]
	v_mfma_f32_16x16x32_bf16 v[100:103], v[168:171], v[192:195], v[100:103]
	v_mfma_f32_16x16x32_bf16 v[96:99], v[176:179], v[192:195], v[96:99]
	v_mfma_f32_16x16x32_bf16 v[84:87], v[168:171], v[200:203], v[84:87]
	v_mfma_f32_16x16x32_bf16 v[80:83], v[176:179], v[200:203], v[80:83]
	v_mfma_f32_16x16x32_bf16 v[68:71], v[168:171], v[208:211], v[68:71]
	v_mfma_f32_16x16x32_bf16 v[64:67], v[176:179], v[208:211], v[64:67]
	v_mfma_f32_16x16x32_bf16 v[116:119], v[172:175], v[188:191], v[116:119]
	v_mfma_f32_16x16x32_bf16 v[112:115], v[180:183], v[188:191], v[112:115]
	v_mfma_f32_16x16x32_bf16 v[100:103], v[172:175], v[196:199], v[100:103]
	v_mfma_f32_16x16x32_bf16 v[96:99], v[180:183], v[196:199], v[96:99]
	v_mfma_f32_16x16x32_bf16 v[84:87], v[172:175], v[204:207], v[84:87]
	v_mfma_f32_16x16x32_bf16 v[80:83], v[180:183], v[204:207], v[80:83]
	v_mfma_f32_16x16x32_bf16 v[68:71], v[172:175], v[212:215], v[68:71]
	v_mfma_f32_16x16x32_bf16 v[64:67], v[180:183], v[212:215], v[64:67]
	s_setprio 0
	s_barrier
	s_add_i32 s30, s34, s38
	v_lshl_add_u64 v[216:217], v[216:217], 0, s[6:7]
	s_mov_b32 m0, s30
	ds_read_b128 v[184:187], v155 offset:49152
	ds_read_b128 v[188:191], v155 offset:50176
	ds_read_b128 v[192:195], v155 offset:51200
	ds_read_b128 v[196:199], v155 offset:52224
	ds_read_b128 v[200:203], v155 offset:53248
	ds_read_b128 v[204:207], v155 offset:54272
	ds_read_b128 v[208:211], v155 offset:55296
	ds_read_b128 v[212:215], v155 offset:56320
	global_load_lds_dwordx4 v[216:217], off
	s_add_i32 m0, s30, 0x2000
	s_add_u32 s28, s28, 0x40080
	v_lshl_add_u64 v[216:217], v[218:219], 0, s[6:7]
	s_addc_u32 s29, s29, 0
	s_add_i32 s30, s35, s38
	global_load_lds_dwordx4 v[216:217], off
	s_mov_b32 m0, s30
	v_lshl_add_u64 v[216:217], s[28:29], 0, v[134:135]
	global_load_lds_dwordx4 v[216:217], off
	s_add_i32 m0, s30, 0x2000
	v_lshl_add_u64 v[216:217], s[28:29], 0, v[130:131]
	global_load_lds_dwordx4 v[216:217], off
	s_mov_b32 m0, s45
	v_lshl_add_u64 v[216:217], v[220:221], 0, s[6:7]
	global_load_lds_dwordx4 v[216:217], off
	s_mov_b32 m0, s46
	v_lshl_add_u64 v[216:217], v[222:223], 0, s[6:7]
	global_load_lds_dwordx4 v[216:217], off
	s_waitcnt vmcnt(8)
	s_waitcnt lgkmcnt(0)
	s_barrier
	s_setprio 1
	s_waitcnt lgkmcnt(0)
	v_mfma_f32_16x16x32_bf16 v[60:63], v[146:149], v[184:187], v[60:63]
	v_mfma_f32_16x16x32_bf16 v[56:59], v[160:163], v[184:187], v[56:59]
	v_mfma_f32_16x16x32_bf16 v[44:47], v[146:149], v[192:195], v[44:47]
	v_mfma_f32_16x16x32_bf16 v[40:43], v[160:163], v[192:195], v[40:43]
	v_mfma_f32_16x16x32_bf16 v[28:31], v[146:149], v[200:203], v[28:31]
	v_mfma_f32_16x16x32_bf16 v[24:27], v[160:163], v[200:203], v[24:27]
	v_mfma_f32_16x16x32_bf16 v[12:15], v[146:149], v[208:211], v[12:15]
	v_mfma_f32_16x16x32_bf16 v[8:11], v[160:163], v[208:211], v[8:11]
	v_mfma_f32_16x16x32_bf16 v[60:63], v[156:159], v[188:191], v[60:63]
	v_mfma_f32_16x16x32_bf16 v[56:59], v[164:167], v[188:191], v[56:59]
	v_mfma_f32_16x16x32_bf16 v[44:47], v[156:159], v[196:199], v[44:47]
	v_mfma_f32_16x16x32_bf16 v[40:43], v[164:167], v[196:199], v[40:43]
	v_mfma_f32_16x16x32_bf16 v[28:31], v[156:159], v[204:207], v[28:31]
	v_mfma_f32_16x16x32_bf16 v[24:27], v[164:167], v[204:207], v[24:27]
	v_mfma_f32_16x16x32_bf16 v[12:15], v[156:159], v[212:215], v[12:15]
	v_mfma_f32_16x16x32_bf16 v[8:11], v[164:167], v[212:215], v[8:11]
	v_mfma_f32_16x16x32_bf16 v[52:55], v[168:171], v[184:187], v[52:55]
	v_mfma_f32_16x16x32_bf16 v[48:51], v[176:179], v[184:187], v[48:51]
	v_mfma_f32_16x16x32_bf16 v[36:39], v[168:171], v[192:195], v[36:39]
	v_mfma_f32_16x16x32_bf16 v[32:35], v[176:179], v[192:195], v[32:35]
	v_mfma_f32_16x16x32_bf16 v[20:23], v[168:171], v[200:203], v[20:23]
	v_mfma_f32_16x16x32_bf16 v[16:19], v[176:179], v[200:203], v[16:19]
	v_mfma_f32_16x16x32_bf16 v[4:7], v[168:171], v[208:211], v[4:7]
	v_mfma_f32_16x16x32_bf16 v[0:3], v[176:179], v[208:211], v[0:3]
	v_mfma_f32_16x16x32_bf16 v[52:55], v[172:175], v[188:191], v[52:55]
	v_mfma_f32_16x16x32_bf16 v[48:51], v[180:183], v[188:191], v[48:51]
	v_mfma_f32_16x16x32_bf16 v[36:39], v[172:175], v[196:199], v[36:39]
	v_mfma_f32_16x16x32_bf16 v[32:35], v[180:183], v[196:199], v[32:35]
	v_mfma_f32_16x16x32_bf16 v[20:23], v[172:175], v[204:207], v[20:23]
	v_mfma_f32_16x16x32_bf16 v[16:19], v[180:183], v[204:207], v[16:19]
	v_mfma_f32_16x16x32_bf16 v[4:7], v[172:175], v[212:215], v[4:7]
	v_mfma_f32_16x16x32_bf16 v[0:3], v[180:183], v[212:215], v[0:3]
	s_setprio 0
	s_barrier
	s_add_i32 s56, s56, 2
	s_add_u32 s26, s26, 0x100
	s_addc_u32 s27, s27, 0
	s_add_u32 s54, s54, 0x100
	s_addc_u32 s55, s55, 0
.LBB0_2091:
	ds_read_b128 v[146:149], v153
	ds_read_b128 v[156:159], v153 offset:1024
	ds_read_b128 v[160:163], v153 offset:2048
	ds_read_b128 v[164:167], v153 offset:3072
	ds_read_b128 v[168:171], v154
	ds_read_b128 v[172:175], v154 offset:1024
	ds_read_b128 v[176:179], v154 offset:2048
	ds_read_b128 v[180:183], v154 offset:3072
	s_add_u32 s28, s26, 0xfffc0080
	s_addc_u32 s29, s27, -1
	s_cmp_eq_u32 s56, 12
	s_cselect_b32 s31, s19, s29
	s_cselect_b32 s30, s52, s28
	s_cselect_b32 s29, s11, s55
	s_cselect_b32 s28, s53, s54
	v_lshl_add_u64 v[216:217], s[26:27], 0, v[138:139]
	s_add_i32 m0, s25, 0xc000
	ds_read_b128 v[184:187], v155
	ds_read_b128 v[188:191], v155 offset:1024
	ds_read_b128 v[192:195], v155 offset:2048
	ds_read_b128 v[196:199], v155 offset:3072
	ds_read_b128 v[200:203], v155 offset:4096
	ds_read_b128 v[204:207], v155 offset:5120
	ds_read_b128 v[208:211], v155 offset:6144
	ds_read_b128 v[212:215], v155 offset:7168
	global_load_lds_dwordx4 v[216:217], off
	s_add_i32 m0, s25, 0xe000
	v_lshl_add_u64 v[216:217], s[26:27], 0, v[140:141]
	global_load_lds_dwordx4 v[216:217], off
	s_waitcnt vmcnt(8)
	s_waitcnt lgkmcnt(0)
	s_barrier
	s_setprio 1
	s_waitcnt lgkmcnt(0)
	v_mfma_f32_16x16x32_bf16 v[124:127], v[146:149], v[184:187], v[124:127]
	v_mfma_f32_16x16x32_bf16 v[120:123], v[160:163], v[184:187], v[120:123]
	v_mfma_f32_16x16x32_bf16 v[108:111], v[146:149], v[192:195], v[108:111]
	v_mfma_f32_16x16x32_bf16 v[104:107], v[160:163], v[192:195], v[104:107]
	v_mfma_f32_16x16x32_bf16 v[92:95], v[146:149], v[200:203], v[92:95]
	v_mfma_f32_16x16x32_bf16 v[88:91], v[160:163], v[200:203], v[88:91]
	v_mfma_f32_16x16x32_bf16 v[76:79], v[146:149], v[208:211], v[76:79]
	v_mfma_f32_16x16x32_bf16 v[72:75], v[160:163], v[208:211], v[72:75]
	v_mfma_f32_16x16x32_bf16 v[124:127], v[156:159], v[188:191], v[124:127]
	v_mfma_f32_16x16x32_bf16 v[120:123], v[164:167], v[188:191], v[120:123]
	v_mfma_f32_16x16x32_bf16 v[108:111], v[156:159], v[196:199], v[108:111]
	v_mfma_f32_16x16x32_bf16 v[104:107], v[164:167], v[196:199], v[104:107]
	v_mfma_f32_16x16x32_bf16 v[92:95], v[156:159], v[204:207], v[92:95]
	v_mfma_f32_16x16x32_bf16 v[88:91], v[164:167], v[204:207], v[88:91]
	v_mfma_f32_16x16x32_bf16 v[76:79], v[156:159], v[212:215], v[76:79]
	v_mfma_f32_16x16x32_bf16 v[72:75], v[164:167], v[212:215], v[72:75]
	v_mfma_f32_16x16x32_bf16 v[116:119], v[168:171], v[184:187], v[116:119]
	v_mfma_f32_16x16x32_bf16 v[112:115], v[176:179], v[184:187], v[112:115]
	v_mfma_f32_16x16x32_bf16 v[100:103], v[168:171], v[192:195], v[100:103]
	v_mfma_f32_16x16x32_bf16 v[96:99], v[176:179], v[192:195], v[96:99]
	v_mfma_f32_16x16x32_bf16 v[84:87], v[168:171], v[200:203], v[84:87]
	v_mfma_f32_16x16x32_bf16 v[80:83], v[176:179], v[200:203], v[80:83]
	v_mfma_f32_16x16x32_bf16 v[68:71], v[168:171], v[208:211], v[68:71]
	v_mfma_f32_16x16x32_bf16 v[64:67], v[176:179], v[208:211], v[64:67]
	v_mfma_f32_16x16x32_bf16 v[116:119], v[172:175], v[188:191], v[116:119]
	v_mfma_f32_16x16x32_bf16 v[112:115], v[180:183], v[188:191], v[112:115]
	v_mfma_f32_16x16x32_bf16 v[100:103], v[172:175], v[196:199], v[100:103]
	v_mfma_f32_16x16x32_bf16 v[96:99], v[180:183], v[196:199], v[96:99]
	v_mfma_f32_16x16x32_bf16 v[84:87], v[172:175], v[204:207], v[84:87]
	v_mfma_f32_16x16x32_bf16 v[80:83], v[180:183], v[204:207], v[80:83]
	v_mfma_f32_16x16x32_bf16 v[68:71], v[172:175], v[212:215], v[68:71]
	v_mfma_f32_16x16x32_bf16 v[64:67], v[180:183], v[212:215], v[64:67]
	s_setprio 0
	s_barrier
	s_add_i32 s34, s47, s38
	v_lshl_add_u64 v[216:217], s[28:29], 0, v[134:135]
	s_mov_b32 m0, s34
	ds_read_b128 v[184:187], v155 offset:16384
	ds_read_b128 v[188:191], v155 offset:17408
	ds_read_b128 v[192:195], v155 offset:18432
	ds_read_b128 v[196:199], v155 offset:19456
	ds_read_b128 v[200:203], v155 offset:20480
	ds_read_b128 v[204:207], v155 offset:21504
	ds_read_b128 v[208:211], v155 offset:22528
	ds_read_b128 v[212:215], v155 offset:23552
	global_load_lds_dwordx4 v[216:217], off
	s_add_i32 m0, s34, 0x2000
	s_add_u32 s34, s28, 0x40000
	v_lshl_add_u64 v[218:219], s[28:29], 0, v[130:131]
	s_addc_u32 s35, s29, 0
	s_add_i32 s57, s48, s38
	global_load_lds_dwordx4 v[218:219], off
	v_lshl_add_u64 v[220:221], s[34:35], 0, v[134:135]
	s_mov_b32 m0, s57
	v_lshl_add_u64 v[222:223], s[30:31], 0, v[132:133]
	global_load_lds_dwordx4 v[220:221], off
	s_add_i32 m0, s57, 0x2000
	v_lshl_add_u64 v[220:221], s[34:35], 0, v[130:131]
	global_load_lds_dwordx4 v[220:221], off
	s_mov_b32 m0, s25
	v_lshl_add_u64 v[220:221], s[30:31], 0, v[136:137]
	global_load_lds_dwordx4 v[220:221], off
	s_mov_b32 m0, s42
	s_nop 0
	global_load_lds_dwordx4 v[222:223], off
	s_waitcnt vmcnt(8)
	s_waitcnt lgkmcnt(0)
	s_barrier
	s_setprio 1
	s_waitcnt lgkmcnt(0)
	v_mfma_f32_16x16x32_bf16 v[60:63], v[146:149], v[184:187], v[60:63]
	v_mfma_f32_16x16x32_bf16 v[56:59], v[160:163], v[184:187], v[56:59]
	v_mfma_f32_16x16x32_bf16 v[44:47], v[146:149], v[192:195], v[44:47]
	v_mfma_f32_16x16x32_bf16 v[40:43], v[160:163], v[192:195], v[40:43]
	v_mfma_f32_16x16x32_bf16 v[28:31], v[146:149], v[200:203], v[28:31]
	v_mfma_f32_16x16x32_bf16 v[24:27], v[160:163], v[200:203], v[24:27]
	v_mfma_f32_16x16x32_bf16 v[12:15], v[146:149], v[208:211], v[12:15]
	v_mfma_f32_16x16x32_bf16 v[8:11], v[160:163], v[208:211], v[8:11]
	v_mfma_f32_16x16x32_bf16 v[60:63], v[156:159], v[188:191], v[60:63]
	v_mfma_f32_16x16x32_bf16 v[56:59], v[164:167], v[188:191], v[56:59]
	v_mfma_f32_16x16x32_bf16 v[44:47], v[156:159], v[196:199], v[44:47]
	v_mfma_f32_16x16x32_bf16 v[40:43], v[164:167], v[196:199], v[40:43]
	v_mfma_f32_16x16x32_bf16 v[28:31], v[156:159], v[204:207], v[28:31]
	v_mfma_f32_16x16x32_bf16 v[24:27], v[164:167], v[204:207], v[24:27]
	v_mfma_f32_16x16x32_bf16 v[12:15], v[156:159], v[212:215], v[12:15]
	v_mfma_f32_16x16x32_bf16 v[8:11], v[164:167], v[212:215], v[8:11]
	v_mfma_f32_16x16x32_bf16 v[52:55], v[168:171], v[184:187], v[52:55]
	v_mfma_f32_16x16x32_bf16 v[48:51], v[176:179], v[184:187], v[48:51]
	v_mfma_f32_16x16x32_bf16 v[36:39], v[168:171], v[192:195], v[36:39]
	v_mfma_f32_16x16x32_bf16 v[32:35], v[176:179], v[192:195], v[32:35]
	v_mfma_f32_16x16x32_bf16 v[20:23], v[168:171], v[200:203], v[20:23]
	v_mfma_f32_16x16x32_bf16 v[16:19], v[176:179], v[200:203], v[16:19]
	v_mfma_f32_16x16x32_bf16 v[4:7], v[168:171], v[208:211], v[4:7]
	v_mfma_f32_16x16x32_bf16 v[0:3], v[176:179], v[208:211], v[0:3]
	v_mfma_f32_16x16x32_bf16 v[52:55], v[172:175], v[188:191], v[52:55]
	v_mfma_f32_16x16x32_bf16 v[48:51], v[180:183], v[188:191], v[48:51]
	v_mfma_f32_16x16x32_bf16 v[36:39], v[172:175], v[196:199], v[36:39]
	v_mfma_f32_16x16x32_bf16 v[32:35], v[180:183], v[196:199], v[32:35]
	v_mfma_f32_16x16x32_bf16 v[20:23], v[172:175], v[204:207], v[20:23]
	v_mfma_f32_16x16x32_bf16 v[16:19], v[180:183], v[204:207], v[16:19]
	v_mfma_f32_16x16x32_bf16 v[4:7], v[172:175], v[212:215], v[4:7]
	v_mfma_f32_16x16x32_bf16 v[0:3], v[180:183], v[212:215], v[0:3]
	s_setprio 0
	s_barrier
	s_add_i32 s34, 0, 0x18000
	s_add_i32 s35, 0, 0x1c000
	v_add_u32_e32 v164, s34, v150
	v_add_u32_e32 v180, s35, v150
	ds_read_b128 v[146:149], v164
	ds_read_b128 v[156:159], v164 offset:1024
	ds_read_b128 v[160:163], v164 offset:2048
	ds_read_b128 v[164:167], v164 offset:3072
	ds_read_b128 v[168:171], v180
	ds_read_b128 v[172:175], v180 offset:1024
	ds_read_b128 v[176:179], v180 offset:2048
	ds_read_b128 v[180:183], v180 offset:3072
	s_add_u32 s30, s30, 0x40000
	s_addc_u32 s31, s31, 0
	s_mov_b32 m0, s43
	v_lshl_add_u64 v[224:225], s[30:31], 0, v[136:137]
	ds_read_b128 v[184:187], v155 offset:32768
	ds_read_b128 v[188:191], v155 offset:33792
	ds_read_b128 v[192:195], v155 offset:34816
	ds_read_b128 v[196:199], v155 offset:35840
	ds_read_b128 v[200:203], v155 offset:36864
	ds_read_b128 v[204:207], v155 offset:37888
	ds_read_b128 v[208:211], v155 offset:38912
	ds_read_b128 v[212:215], v155 offset:39936
	global_load_lds_dwordx4 v[224:225], off
	s_mov_b32 m0, s44
	v_lshl_add_u64 v[224:225], s[30:31], 0, v[132:133]
	global_load_lds_dwordx4 v[224:225], off
	s_waitcnt vmcnt(8)
	s_waitcnt lgkmcnt(0)
	s_barrier
	s_setprio 1
	s_waitcnt lgkmcnt(0)
	v_mfma_f32_16x16x32_bf16 v[124:127], v[146:149], v[184:187], v[124:127]
	v_mfma_f32_16x16x32_bf16 v[120:123], v[160:163], v[184:187], v[120:123]
	v_mfma_f32_16x16x32_bf16 v[108:111], v[146:149], v[192:195], v[108:111]
	v_mfma_f32_16x16x32_bf16 v[104:107], v[160:163], v[192:195], v[104:107]
	v_mfma_f32_16x16x32_bf16 v[92:95], v[146:149], v[200:203], v[92:95]
	v_mfma_f32_16x16x32_bf16 v[88:91], v[160:163], v[200:203], v[88:91]
	v_mfma_f32_16x16x32_bf16 v[76:79], v[146:149], v[208:211], v[76:79]
	v_mfma_f32_16x16x32_bf16 v[72:75], v[160:163], v[208:211], v[72:75]
	v_mfma_f32_16x16x32_bf16 v[124:127], v[156:159], v[188:191], v[124:127]
	v_mfma_f32_16x16x32_bf16 v[120:123], v[164:167], v[188:191], v[120:123]
	v_mfma_f32_16x16x32_bf16 v[108:111], v[156:159], v[196:199], v[108:111]
	v_mfma_f32_16x16x32_bf16 v[104:107], v[164:167], v[196:199], v[104:107]
	v_mfma_f32_16x16x32_bf16 v[92:95], v[156:159], v[204:207], v[92:95]
	v_mfma_f32_16x16x32_bf16 v[88:91], v[164:167], v[204:207], v[88:91]
	v_mfma_f32_16x16x32_bf16 v[76:79], v[156:159], v[212:215], v[76:79]
	v_mfma_f32_16x16x32_bf16 v[72:75], v[164:167], v[212:215], v[72:75]
	v_mfma_f32_16x16x32_bf16 v[116:119], v[168:171], v[184:187], v[116:119]
	v_mfma_f32_16x16x32_bf16 v[112:115], v[176:179], v[184:187], v[112:115]
	v_mfma_f32_16x16x32_bf16 v[100:103], v[168:171], v[192:195], v[100:103]
	v_mfma_f32_16x16x32_bf16 v[96:99], v[176:179], v[192:195], v[96:99]
	v_mfma_f32_16x16x32_bf16 v[84:87], v[168:171], v[200:203], v[84:87]
	v_mfma_f32_16x16x32_bf16 v[80:83], v[176:179], v[200:203], v[80:83]
	v_mfma_f32_16x16x32_bf16 v[68:71], v[168:171], v[208:211], v[68:71]
	v_mfma_f32_16x16x32_bf16 v[64:67], v[176:179], v[208:211], v[64:67]
	v_mfma_f32_16x16x32_bf16 v[116:119], v[172:175], v[188:191], v[116:119]
	v_mfma_f32_16x16x32_bf16 v[112:115], v[180:183], v[188:191], v[112:115]
	v_mfma_f32_16x16x32_bf16 v[100:103], v[172:175], v[196:199], v[100:103]
	v_mfma_f32_16x16x32_bf16 v[96:99], v[180:183], v[196:199], v[96:99]
	v_mfma_f32_16x16x32_bf16 v[84:87], v[172:175], v[204:207], v[84:87]
	v_mfma_f32_16x16x32_bf16 v[80:83], v[180:183], v[204:207], v[80:83]
	v_mfma_f32_16x16x32_bf16 v[68:71], v[172:175], v[212:215], v[68:71]
	v_mfma_f32_16x16x32_bf16 v[64:67], v[180:183], v[212:215], v[64:67]
	s_setprio 0
	s_barrier
	s_add_i32 s30, s34, s38
	v_lshl_add_u64 v[216:217], v[216:217], 0, s[6:7]
	s_mov_b32 m0, s30
	ds_read_b128 v[184:187], v155 offset:49152
	ds_read_b128 v[188:191], v155 offset:50176
	ds_read_b128 v[192:195], v155 offset:51200
	ds_read_b128 v[196:199], v155 offset:52224
	ds_read_b128 v[200:203], v155 offset:53248
	ds_read_b128 v[204:207], v155 offset:54272
	ds_read_b128 v[208:211], v155 offset:55296
	ds_read_b128 v[212:215], v155 offset:56320
	global_load_lds_dwordx4 v[216:217], off
	s_add_i32 m0, s30, 0x2000
	s_add_u32 s28, s28, 0x40080
	v_lshl_add_u64 v[216:217], v[218:219], 0, s[6:7]
	s_addc_u32 s29, s29, 0
	s_add_i32 s30, s35, s38
	global_load_lds_dwordx4 v[216:217], off
	s_mov_b32 m0, s30
	v_lshl_add_u64 v[216:217], s[28:29], 0, v[134:135]
	global_load_lds_dwordx4 v[216:217], off
	s_add_i32 m0, s30, 0x2000
	v_lshl_add_u64 v[216:217], s[28:29], 0, v[130:131]
	global_load_lds_dwordx4 v[216:217], off
	s_mov_b32 m0, s45
	v_lshl_add_u64 v[216:217], v[220:221], 0, s[6:7]
	global_load_lds_dwordx4 v[216:217], off
	s_mov_b32 m0, s46
	v_lshl_add_u64 v[216:217], v[222:223], 0, s[6:7]
	global_load_lds_dwordx4 v[216:217], off
	s_waitcnt vmcnt(8)
	s_waitcnt lgkmcnt(0)
	s_barrier
	s_setprio 1
	s_waitcnt lgkmcnt(0)
	v_mfma_f32_16x16x32_bf16 v[60:63], v[146:149], v[184:187], v[60:63]
	v_mfma_f32_16x16x32_bf16 v[56:59], v[160:163], v[184:187], v[56:59]
	v_mfma_f32_16x16x32_bf16 v[44:47], v[146:149], v[192:195], v[44:47]
	v_mfma_f32_16x16x32_bf16 v[40:43], v[160:163], v[192:195], v[40:43]
	v_mfma_f32_16x16x32_bf16 v[28:31], v[146:149], v[200:203], v[28:31]
	v_mfma_f32_16x16x32_bf16 v[24:27], v[160:163], v[200:203], v[24:27]
	v_mfma_f32_16x16x32_bf16 v[12:15], v[146:149], v[208:211], v[12:15]
	v_mfma_f32_16x16x32_bf16 v[8:11], v[160:163], v[208:211], v[8:11]
	v_mfma_f32_16x16x32_bf16 v[60:63], v[156:159], v[188:191], v[60:63]
	v_mfma_f32_16x16x32_bf16 v[56:59], v[164:167], v[188:191], v[56:59]
	v_mfma_f32_16x16x32_bf16 v[44:47], v[156:159], v[196:199], v[44:47]
	v_mfma_f32_16x16x32_bf16 v[40:43], v[164:167], v[196:199], v[40:43]
	v_mfma_f32_16x16x32_bf16 v[28:31], v[156:159], v[204:207], v[28:31]
	v_mfma_f32_16x16x32_bf16 v[24:27], v[164:167], v[204:207], v[24:27]
	v_mfma_f32_16x16x32_bf16 v[12:15], v[156:159], v[212:215], v[12:15]
	v_mfma_f32_16x16x32_bf16 v[8:11], v[164:167], v[212:215], v[8:11]
	v_mfma_f32_16x16x32_bf16 v[52:55], v[168:171], v[184:187], v[52:55]
	v_mfma_f32_16x16x32_bf16 v[48:51], v[176:179], v[184:187], v[48:51]
	v_mfma_f32_16x16x32_bf16 v[36:39], v[168:171], v[192:195], v[36:39]
	v_mfma_f32_16x16x32_bf16 v[32:35], v[176:179], v[192:195], v[32:35]
	v_mfma_f32_16x16x32_bf16 v[20:23], v[168:171], v[200:203], v[20:23]
	v_mfma_f32_16x16x32_bf16 v[16:19], v[176:179], v[200:203], v[16:19]
	v_mfma_f32_16x16x32_bf16 v[4:7], v[168:171], v[208:211], v[4:7]
	v_mfma_f32_16x16x32_bf16 v[0:3], v[176:179], v[208:211], v[0:3]
	v_mfma_f32_16x16x32_bf16 v[52:55], v[172:175], v[188:191], v[52:55]
	v_mfma_f32_16x16x32_bf16 v[48:51], v[180:183], v[188:191], v[48:51]
	v_mfma_f32_16x16x32_bf16 v[36:39], v[172:175], v[196:199], v[36:39]
	v_mfma_f32_16x16x32_bf16 v[32:35], v[180:183], v[196:199], v[32:35]
	v_mfma_f32_16x16x32_bf16 v[20:23], v[172:175], v[204:207], v[20:23]
	v_mfma_f32_16x16x32_bf16 v[16:19], v[180:183], v[204:207], v[16:19]
	v_mfma_f32_16x16x32_bf16 v[4:7], v[172:175], v[212:215], v[4:7]
	v_mfma_f32_16x16x32_bf16 v[0:3], v[180:183], v[212:215], v[0:3]
	s_setprio 0
	s_cmp_eq_u32 s56, s98
	s_cbranch_scc1 .Lmy_nobar_22
	s_barrier

.Lmy_nobar2_23:
	ds_read_b128 v[144:147], v153
	ds_read_b128 v[156:159], v153 offset:1024
	ds_read_b128 v[160:163], v153 offset:2048
	ds_read_b128 v[164:167], v153 offset:3072
	ds_read_b128 v[168:171], v154
	ds_read_b128 v[172:175], v154 offset:1024
	ds_read_b128 v[176:179], v154 offset:2048
	ds_read_b128 v[180:183], v154 offset:3072
	s_add_u32 s30, s28, 0xfff50080
	s_addc_u32 s31, s29, -1
	s_cmp_eq_u32 s56, 40
	s_cselect_b32 s37, s1, s31
	s_cselect_b32 s36, s0, s30
	s_cselect_b32 s31, s27, s55
	s_cselect_b32 s30, s26, s54
	v_lshl_add_u64 v[148:149], s[28:29], 0, v[128:129]
	s_add_i32 m0, s41, 0xc000
	ds_read_b128 v[184:187], v155
	ds_read_b128 v[188:191], v155 offset:1024
	ds_read_b128 v[192:195], v155 offset:2048
	ds_read_b128 v[196:199], v155 offset:3072
	ds_read_b128 v[200:203], v155 offset:4096
	ds_read_b128 v[204:207], v155 offset:5120
	ds_read_b128 v[208:211], v155 offset:6144
	ds_read_b128 v[212:215], v155 offset:7168
	global_load_lds_dwordx4 v[148:149], off
	s_add_i32 m0, s41, 0xe000
	v_lshl_add_u64 v[148:149], s[28:29], 0, v[138:139]
	global_load_lds_dwordx4 v[148:149], off
	s_waitcnt vmcnt(8)
	s_waitcnt lgkmcnt(0)
	s_barrier
	s_setprio 1
	s_waitcnt lgkmcnt(0)
	v_mfma_f32_16x16x32_bf16 v[124:127], v[144:147], v[184:187], 0
	v_mfma_f32_16x16x32_bf16 v[120:123], v[160:163], v[184:187], 0
	v_mfma_f32_16x16x32_bf16 v[108:111], v[144:147], v[192:195], 0
	v_mfma_f32_16x16x32_bf16 v[104:107], v[160:163], v[192:195], 0
	v_mfma_f32_16x16x32_bf16 v[92:95], v[144:147], v[200:203], 0
	v_mfma_f32_16x16x32_bf16 v[88:91], v[160:163], v[200:203], 0
	v_mfma_f32_16x16x32_bf16 v[76:79], v[144:147], v[208:211], 0
	v_mfma_f32_16x16x32_bf16 v[72:75], v[160:163], v[208:211], 0
	v_mfma_f32_16x16x32_bf16 v[124:127], v[156:159], v[188:191], v[124:127]
	v_mfma_f32_16x16x32_bf16 v[120:123], v[164:167], v[188:191], v[120:123]
	v_mfma_f32_16x16x32_bf16 v[108:111], v[156:159], v[196:199], v[108:111]
	v_mfma_f32_16x16x32_bf16 v[104:107], v[164:167], v[196:199], v[104:107]
	v_mfma_f32_16x16x32_bf16 v[92:95], v[156:159], v[204:207], v[92:95]
	v_mfma_f32_16x16x32_bf16 v[88:91], v[164:167], v[204:207], v[88:91]
	v_mfma_f32_16x16x32_bf16 v[76:79], v[156:159], v[212:215], v[76:79]
	v_mfma_f32_16x16x32_bf16 v[72:75], v[164:167], v[212:215], v[72:75]
	v_mfma_f32_16x16x32_bf16 v[116:119], v[168:171], v[184:187], 0
	v_mfma_f32_16x16x32_bf16 v[112:115], v[176:179], v[184:187], 0
	v_mfma_f32_16x16x32_bf16 v[100:103], v[168:171], v[192:195], 0
	v_mfma_f32_16x16x32_bf16 v[96:99], v[176:179], v[192:195], 0
	v_mfma_f32_16x16x32_bf16 v[84:87], v[168:171], v[200:203], 0
	v_mfma_f32_16x16x32_bf16 v[80:83], v[176:179], v[200:203], 0
	v_mfma_f32_16x16x32_bf16 v[68:71], v[168:171], v[208:211], 0
	v_mfma_f32_16x16x32_bf16 v[64:67], v[176:179], v[208:211], 0
	v_mfma_f32_16x16x32_bf16 v[116:119], v[172:175], v[188:191], v[116:119]
	v_mfma_f32_16x16x32_bf16 v[112:115], v[180:183], v[188:191], v[112:115]
	v_mfma_f32_16x16x32_bf16 v[100:103], v[172:175], v[196:199], v[100:103]
	v_mfma_f32_16x16x32_bf16 v[96:99], v[180:183], v[196:199], v[96:99]
	v_mfma_f32_16x16x32_bf16 v[84:87], v[172:175], v[204:207], v[84:87]
	v_mfma_f32_16x16x32_bf16 v[80:83], v[180:183], v[204:207], v[80:83]
	v_mfma_f32_16x16x32_bf16 v[68:71], v[172:175], v[212:215], v[68:71]
	v_mfma_f32_16x16x32_bf16 v[64:67], v[180:183], v[212:215], v[64:67]
	s_setprio 0
	s_barrier
	s_add_i32 s34, s50, s40
	v_lshl_add_u64 v[148:149], s[30:31], 0, v[132:133]
	s_mov_b32 m0, s34
	ds_read_b128 v[184:187], v155 offset:16384
	ds_read_b128 v[188:191], v155 offset:17408
	ds_read_b128 v[192:195], v155 offset:18432
	ds_read_b128 v[196:199], v155 offset:19456
	ds_read_b128 v[200:203], v155 offset:20480
	ds_read_b128 v[204:207], v155 offset:21504
	ds_read_b128 v[208:211], v155 offset:22528
	ds_read_b128 v[212:215], v155 offset:23552
	global_load_lds_dwordx4 v[148:149], off
	s_add_i32 m0, s34, 0x2000
	s_add_u32 s34, s30, 0xb0000
	v_lshl_add_u64 v[216:217], s[30:31], 0, v[136:137]
	s_addc_u32 s35, s31, 0
	s_add_i32 s57, s51, s40
	global_load_lds_dwordx4 v[216:217], off
	v_lshl_add_u64 v[218:219], s[34:35], 0, v[132:133]
	s_mov_b32 m0, s57
	v_lshl_add_u64 v[220:221], s[36:37], 0, v[134:135]
	global_load_lds_dwordx4 v[218:219], off
	s_add_i32 m0, s57, 0x2000
	v_lshl_add_u64 v[218:219], s[34:35], 0, v[136:137]
	global_load_lds_dwordx4 v[218:219], off
	s_mov_b32 m0, s41
	v_lshl_add_u64 v[218:219], s[36:37], 0, v[130:131]
	global_load_lds_dwordx4 v[218:219], off
	s_mov_b32 m0, s42
	s_nop 0
	global_load_lds_dwordx4 v[220:221], off
	s_waitcnt vmcnt(8)
	s_waitcnt lgkmcnt(0)
	s_barrier
	s_setprio 1
	s_waitcnt lgkmcnt(0)
	v_mfma_f32_16x16x32_bf16 v[60:63], v[144:147], v[184:187], 0
	v_mfma_f32_16x16x32_bf16 v[56:59], v[160:163], v[184:187], 0
	v_mfma_f32_16x16x32_bf16 v[44:47], v[144:147], v[192:195], 0
	v_mfma_f32_16x16x32_bf16 v[40:43], v[160:163], v[192:195], 0
	v_mfma_f32_16x16x32_bf16 v[28:31], v[144:147], v[200:203], 0
	v_mfma_f32_16x16x32_bf16 v[24:27], v[160:163], v[200:203], 0
	v_mfma_f32_16x16x32_bf16 v[12:15], v[144:147], v[208:211], 0
	v_mfma_f32_16x16x32_bf16 v[8:11], v[160:163], v[208:211], 0
	v_mfma_f32_16x16x32_bf16 v[60:63], v[156:159], v[188:191], v[60:63]
	v_mfma_f32_16x16x32_bf16 v[56:59], v[164:167], v[188:191], v[56:59]
	v_mfma_f32_16x16x32_bf16 v[44:47], v[156:159], v[196:199], v[44:47]
	v_mfma_f32_16x16x32_bf16 v[40:43], v[164:167], v[196:199], v[40:43]
	v_mfma_f32_16x16x32_bf16 v[28:31], v[156:159], v[204:207], v[28:31]
	v_mfma_f32_16x16x32_bf16 v[24:27], v[164:167], v[204:207], v[24:27]
	v_mfma_f32_16x16x32_bf16 v[12:15], v[156:159], v[212:215], v[12:15]
	v_mfma_f32_16x16x32_bf16 v[8:11], v[164:167], v[212:215], v[8:11]
	v_mfma_f32_16x16x32_bf16 v[52:55], v[168:171], v[184:187], 0
	v_mfma_f32_16x16x32_bf16 v[48:51], v[176:179], v[184:187], 0
	v_mfma_f32_16x16x32_bf16 v[36:39], v[168:171], v[192:195], 0
	v_mfma_f32_16x16x32_bf16 v[32:35], v[176:179], v[192:195], 0
	v_mfma_f32_16x16x32_bf16 v[20:23], v[168:171], v[200:203], 0
	v_mfma_f32_16x16x32_bf16 v[16:19], v[176:179], v[200:203], 0
	v_mfma_f32_16x16x32_bf16 v[4:7], v[168:171], v[208:211], 0
	v_mfma_f32_16x16x32_bf16 v[0:3], v[176:179], v[208:211], 0
	v_mfma_f32_16x16x32_bf16 v[52:55], v[172:175], v[188:191], v[52:55]
	v_mfma_f32_16x16x32_bf16 v[48:51], v[180:183], v[188:191], v[48:51]
	v_mfma_f32_16x16x32_bf16 v[36:39], v[172:175], v[196:199], v[36:39]
	v_mfma_f32_16x16x32_bf16 v[32:35], v[180:183], v[196:199], v[32:35]
	v_mfma_f32_16x16x32_bf16 v[20:23], v[172:175], v[204:207], v[20:23]
	v_mfma_f32_16x16x32_bf16 v[16:19], v[180:183], v[204:207], v[16:19]
	v_mfma_f32_16x16x32_bf16 v[4:7], v[172:175], v[212:215], v[4:7]
	v_mfma_f32_16x16x32_bf16 v[0:3], v[180:183], v[212:215], v[0:3]
	s_setprio 0
	s_barrier
	s_add_i32 s57, 0, 0x18000
	s_add_i32 s58, 0, 0x1c000
	v_add_u32_e32 v164, s57, v151
	v_add_u32_e32 v180, s58, v151
	ds_read_b128 v[144:147], v164
	ds_read_b128 v[156:159], v164 offset:1024
	ds_read_b128 v[160:163], v164 offset:2048
	ds_read_b128 v[164:167], v164 offset:3072
	ds_read_b128 v[168:171], v180
	ds_read_b128 v[172:175], v180 offset:1024
	ds_read_b128 v[176:179], v180 offset:2048
	ds_read_b128 v[180:183], v180 offset:3072
	s_add_u32 s34, s36, 0xb0000
	s_addc_u32 s35, s37, 0
	s_mov_b32 m0, s43
	v_lshl_add_u64 v[222:223], s[34:35], 0, v[130:131]
	ds_read_b128 v[184:187], v155 offset:32768
	ds_read_b128 v[188:191], v155 offset:33792
	ds_read_b128 v[192:195], v155 offset:34816
	ds_read_b128 v[196:199], v155 offset:35840
	ds_read_b128 v[200:203], v155 offset:36864
	ds_read_b128 v[204:207], v155 offset:37888
	ds_read_b128 v[208:211], v155 offset:38912
	ds_read_b128 v[212:215], v155 offset:39936
	global_load_lds_dwordx4 v[222:223], off
	s_mov_b32 m0, s44
	v_lshl_add_u64 v[222:223], s[34:35], 0, v[134:135]
	global_load_lds_dwordx4 v[222:223], off
	s_waitcnt vmcnt(8)
	s_waitcnt lgkmcnt(0)
	s_barrier
	s_setprio 1
	s_waitcnt lgkmcnt(0)
	v_mfma_f32_16x16x32_bf16 v[124:127], v[144:147], v[184:187], v[124:127]
	v_mfma_f32_16x16x32_bf16 v[120:123], v[160:163], v[184:187], v[120:123]
	v_mfma_f32_16x16x32_bf16 v[108:111], v[144:147], v[192:195], v[108:111]
	v_mfma_f32_16x16x32_bf16 v[104:107], v[160:163], v[192:195], v[104:107]
	v_mfma_f32_16x16x32_bf16 v[92:95], v[144:147], v[200:203], v[92:95]
	v_mfma_f32_16x16x32_bf16 v[88:91], v[160:163], v[200:203], v[88:91]
	v_mfma_f32_16x16x32_bf16 v[76:79], v[144:147], v[208:211], v[76:79]
	v_mfma_f32_16x16x32_bf16 v[72:75], v[160:163], v[208:211], v[72:75]
	v_mfma_f32_16x16x32_bf16 v[124:127], v[156:159], v[188:191], v[124:127]
	v_mfma_f32_16x16x32_bf16 v[120:123], v[164:167], v[188:191], v[120:123]
	v_mfma_f32_16x16x32_bf16 v[108:111], v[156:159], v[196:199], v[108:111]
	v_mfma_f32_16x16x32_bf16 v[104:107], v[164:167], v[196:199], v[104:107]
	v_mfma_f32_16x16x32_bf16 v[92:95], v[156:159], v[204:207], v[92:95]
	v_mfma_f32_16x16x32_bf16 v[88:91], v[164:167], v[204:207], v[88:91]
	v_mfma_f32_16x16x32_bf16 v[76:79], v[156:159], v[212:215], v[76:79]
	v_mfma_f32_16x16x32_bf16 v[72:75], v[164:167], v[212:215], v[72:75]
	v_mfma_f32_16x16x32_bf16 v[116:119], v[168:171], v[184:187], v[116:119]
	v_mfma_f32_16x16x32_bf16 v[112:115], v[176:179], v[184:187], v[112:115]
	v_mfma_f32_16x16x32_bf16 v[100:103], v[168:171], v[192:195], v[100:103]
	v_mfma_f32_16x16x32_bf16 v[96:99], v[176:179], v[192:195], v[96:99]
	v_mfma_f32_16x16x32_bf16 v[84:87], v[168:171], v[200:203], v[84:87]
	v_mfma_f32_16x16x32_bf16 v[80:83], v[176:179], v[200:203], v[80:83]
	v_mfma_f32_16x16x32_bf16 v[68:71], v[168:171], v[208:211], v[68:71]
	v_mfma_f32_16x16x32_bf16 v[64:67], v[176:179], v[208:211], v[64:67]
	v_mfma_f32_16x16x32_bf16 v[116:119], v[172:175], v[188:191], v[116:119]
	v_mfma_f32_16x16x32_bf16 v[112:115], v[180:183], v[188:191], v[112:115]
	v_mfma_f32_16x16x32_bf16 v[100:103], v[172:175], v[196:199], v[100:103]
	v_mfma_f32_16x16x32_bf16 v[96:99], v[180:183], v[196:199], v[96:99]
	v_mfma_f32_16x16x32_bf16 v[84:87], v[172:175], v[204:207], v[84:87]
	v_mfma_f32_16x16x32_bf16 v[80:83], v[180:183], v[204:207], v[80:83]
	v_mfma_f32_16x16x32_bf16 v[68:71], v[172:175], v[212:215], v[68:71]
	v_mfma_f32_16x16x32_bf16 v[64:67], v[180:183], v[212:215], v[64:67]
	s_setprio 0
	s_barrier
	s_add_i32 s34, s57, s40
	v_lshl_add_u64 v[148:149], v[148:149], 0, s[8:9]
	s_mov_b32 m0, s34
	ds_read_b128 v[184:187], v155 offset:49152
	ds_read_b128 v[188:191], v155 offset:50176
	ds_read_b128 v[192:195], v155 offset:51200
	ds_read_b128 v[196:199], v155 offset:52224
	ds_read_b128 v[200:203], v155 offset:53248
	ds_read_b128 v[204:207], v155 offset:54272
	ds_read_b128 v[208:211], v155 offset:55296
	ds_read_b128 v[212:215], v155 offset:56320
	global_load_lds_dwordx4 v[148:149], off
	s_add_i32 m0, s34, 0x2000
	s_add_u32 s30, s30, 0xb0080
	v_lshl_add_u64 v[148:149], v[216:217], 0, s[8:9]
	s_addc_u32 s31, s31, 0
	s_add_i32 s34, s58, s40
	global_load_lds_dwordx4 v[148:149], off
	s_mov_b32 m0, s34
	v_lshl_add_u64 v[148:149], s[30:31], 0, v[132:133]
	global_load_lds_dwordx4 v[148:149], off
	s_add_i32 m0, s34, 0x2000
	v_lshl_add_u64 v[148:149], s[30:31], 0, v[136:137]
	global_load_lds_dwordx4 v[148:149], off
	s_mov_b32 m0, s46
	v_lshl_add_u64 v[148:149], v[218:219], 0, s[8:9]
	global_load_lds_dwordx4 v[148:149], off
	s_mov_b32 m0, s47
	v_lshl_add_u64 v[148:149], v[220:221], 0, s[8:9]
	global_load_lds_dwordx4 v[148:149], off
	s_waitcnt vmcnt(8)
	s_waitcnt lgkmcnt(0)
	s_barrier
	s_setprio 1
	s_waitcnt lgkmcnt(0)
	v_mfma_f32_16x16x32_bf16 v[60:63], v[144:147], v[184:187], v[60:63]
	v_mfma_f32_16x16x32_bf16 v[56:59], v[160:163], v[184:187], v[56:59]
	v_mfma_f32_16x16x32_bf16 v[44:47], v[144:147], v[192:195], v[44:47]
	v_mfma_f32_16x16x32_bf16 v[40:43], v[160:163], v[192:195], v[40:43]
	v_mfma_f32_16x16x32_bf16 v[28:31], v[144:147], v[200:203], v[28:31]
	v_mfma_f32_16x16x32_bf16 v[24:27], v[160:163], v[200:203], v[24:27]
	v_mfma_f32_16x16x32_bf16 v[12:15], v[144:147], v[208:211], v[12:15]
	v_mfma_f32_16x16x32_bf16 v[8:11], v[160:163], v[208:211], v[8:11]
	v_mfma_f32_16x16x32_bf16 v[60:63], v[156:159], v[188:191], v[60:63]
	v_mfma_f32_16x16x32_bf16 v[56:59], v[164:167], v[188:191], v[56:59]
	v_mfma_f32_16x16x32_bf16 v[44:47], v[156:159], v[196:199], v[44:47]
	v_mfma_f32_16x16x32_bf16 v[40:43], v[164:167], v[196:199], v[40:43]
	v_mfma_f32_16x16x32_bf16 v[28:31], v[156:159], v[204:207], v[28:31]
	v_mfma_f32_16x16x32_bf16 v[24:27], v[164:167], v[204:207], v[24:27]
	v_mfma_f32_16x16x32_bf16 v[12:15], v[156:159], v[212:215], v[12:15]
	v_mfma_f32_16x16x32_bf16 v[8:11], v[164:167], v[212:215], v[8:11]
	v_mfma_f32_16x16x32_bf16 v[52:55], v[168:171], v[184:187], v[52:55]
	v_mfma_f32_16x16x32_bf16 v[48:51], v[176:179], v[184:187], v[48:51]
	v_mfma_f32_16x16x32_bf16 v[36:39], v[168:171], v[192:195], v[36:39]
	v_mfma_f32_16x16x32_bf16 v[32:35], v[176:179], v[192:195], v[32:35]
	v_mfma_f32_16x16x32_bf16 v[20:23], v[168:171], v[200:203], v[20:23]
	v_mfma_f32_16x16x32_bf16 v[16:19], v[176:179], v[200:203], v[16:19]
	v_mfma_f32_16x16x32_bf16 v[4:7], v[168:171], v[208:211], v[4:7]
	v_mfma_f32_16x16x32_bf16 v[0:3], v[176:179], v[208:211], v[0:3]
	v_mfma_f32_16x16x32_bf16 v[52:55], v[172:175], v[188:191], v[52:55]
	v_mfma_f32_16x16x32_bf16 v[48:51], v[180:183], v[188:191], v[48:51]
	v_mfma_f32_16x16x32_bf16 v[36:39], v[172:175], v[196:199], v[36:39]
	v_mfma_f32_16x16x32_bf16 v[32:35], v[180:183], v[196:199], v[32:35]
	v_mfma_f32_16x16x32_bf16 v[20:23], v[172:175], v[204:207], v[20:23]
	v_mfma_f32_16x16x32_bf16 v[16:19], v[180:183], v[204:207], v[16:19]
	v_mfma_f32_16x16x32_bf16 v[4:7], v[172:175], v[212:215], v[4:7]
	v_mfma_f32_16x16x32_bf16 v[0:3], v[180:183], v[212:215], v[0:3]
	s_setprio 0
	s_barrier
	s_add_i32 s56, s56, 2
	s_add_u32 s28, s28, 0x100
	s_addc_u32 s29, s29, 0
	s_add_u32 s54, s54, 0x100
	s_addc_u32 s55, s55, 0
.LBB0_2174:
	ds_read_b128 v[144:147], v153
	ds_read_b128 v[156:159], v153 offset:1024
	ds_read_b128 v[160:163], v153 offset:2048
	ds_read_b128 v[164:167], v153 offset:3072
	ds_read_b128 v[168:171], v154
	ds_read_b128 v[172:175], v154 offset:1024
	ds_read_b128 v[176:179], v154 offset:2048
	ds_read_b128 v[180:183], v154 offset:3072
	s_add_u32 s30, s28, 0xfff50080
	s_addc_u32 s31, s29, -1
	s_cmp_eq_u32 s56, 40
	s_cselect_b32 s37, s1, s31
	s_cselect_b32 s36, s0, s30
	s_cselect_b32 s31, s27, s55
	s_cselect_b32 s30, s26, s54
	v_lshl_add_u64 v[148:149], s[28:29], 0, v[128:129]
	s_add_i32 m0, s41, 0xc000
	ds_read_b128 v[184:187], v155
	ds_read_b128 v[188:191], v155 offset:1024
	ds_read_b128 v[192:195], v155 offset:2048
	ds_read_b128 v[196:199], v155 offset:3072
	ds_read_b128 v[200:203], v155 offset:4096
	ds_read_b128 v[204:207], v155 offset:5120
	ds_read_b128 v[208:211], v155 offset:6144
	ds_read_b128 v[212:215], v155 offset:7168
	global_load_lds_dwordx4 v[148:149], off
	s_add_i32 m0, s41, 0xe000
	v_lshl_add_u64 v[148:149], s[28:29], 0, v[138:139]
	global_load_lds_dwordx4 v[148:149], off
	s_waitcnt vmcnt(8)
	s_waitcnt lgkmcnt(0)
	s_barrier
	s_setprio 1
	s_waitcnt lgkmcnt(0)
	v_mfma_f32_16x16x32_bf16 v[124:127], v[144:147], v[184:187], v[124:127]
	v_mfma_f32_16x16x32_bf16 v[120:123], v[160:163], v[184:187], v[120:123]
	v_mfma_f32_16x16x32_bf16 v[108:111], v[144:147], v[192:195], v[108:111]
	v_mfma_f32_16x16x32_bf16 v[104:107], v[160:163], v[192:195], v[104:107]
	v_mfma_f32_16x16x32_bf16 v[92:95], v[144:147], v[200:203], v[92:95]
	v_mfma_f32_16x16x32_bf16 v[88:91], v[160:163], v[200:203], v[88:91]
	v_mfma_f32_16x16x32_bf16 v[76:79], v[144:147], v[208:211], v[76:79]
	v_mfma_f32_16x16x32_bf16 v[72:75], v[160:163], v[208:211], v[72:75]
	v_mfma_f32_16x16x32_bf16 v[124:127], v[156:159], v[188:191], v[124:127]
	v_mfma_f32_16x16x32_bf16 v[120:123], v[164:167], v[188:191], v[120:123]
	v_mfma_f32_16x16x32_bf16 v[108:111], v[156:159], v[196:199], v[108:111]
	v_mfma_f32_16x16x32_bf16 v[104:107], v[164:167], v[196:199], v[104:107]
	v_mfma_f32_16x16x32_bf16 v[92:95], v[156:159], v[204:207], v[92:95]
	v_mfma_f32_16x16x32_bf16 v[88:91], v[164:167], v[204:207], v[88:91]
	v_mfma_f32_16x16x32_bf16 v[76:79], v[156:159], v[212:215], v[76:79]
	v_mfma_f32_16x16x32_bf16 v[72:75], v[164:167], v[212:215], v[72:75]
	v_mfma_f32_16x16x32_bf16 v[116:119], v[168:171], v[184:187], v[116:119]
	v_mfma_f32_16x16x32_bf16 v[112:115], v[176:179], v[184:187], v[112:115]
	v_mfma_f32_16x16x32_bf16 v[100:103], v[168:171], v[192:195], v[100:103]
	v_mfma_f32_16x16x32_bf16 v[96:99], v[176:179], v[192:195], v[96:99]
	v_mfma_f32_16x16x32_bf16 v[84:87], v[168:171], v[200:203], v[84:87]
	v_mfma_f32_16x16x32_bf16 v[80:83], v[176:179], v[200:203], v[80:83]
	v_mfma_f32_16x16x32_bf16 v[68:71], v[168:171], v[208:211], v[68:71]
	v_mfma_f32_16x16x32_bf16 v[64:67], v[176:179], v[208:211], v[64:67]
	v_mfma_f32_16x16x32_bf16 v[116:119], v[172:175], v[188:191], v[116:119]
	v_mfma_f32_16x16x32_bf16 v[112:115], v[180:183], v[188:191], v[112:115]
	v_mfma_f32_16x16x32_bf16 v[100:103], v[172:175], v[196:199], v[100:103]
	v_mfma_f32_16x16x32_bf16 v[96:99], v[180:183], v[196:199], v[96:99]
	v_mfma_f32_16x16x32_bf16 v[84:87], v[172:175], v[204:207], v[84:87]
	v_mfma_f32_16x16x32_bf16 v[80:83], v[180:183], v[204:207], v[80:83]
	v_mfma_f32_16x16x32_bf16 v[68:71], v[172:175], v[212:215], v[68:71]
	v_mfma_f32_16x16x32_bf16 v[64:67], v[180:183], v[212:215], v[64:67]
	s_setprio 0
	s_barrier
	s_add_i32 s34, s50, s40
	v_lshl_add_u64 v[148:149], s[30:31], 0, v[132:133]
	s_mov_b32 m0, s34
	ds_read_b128 v[184:187], v155 offset:16384
	ds_read_b128 v[188:191], v155 offset:17408
	ds_read_b128 v[192:195], v155 offset:18432
	ds_read_b128 v[196:199], v155 offset:19456
	ds_read_b128 v[200:203], v155 offset:20480
	ds_read_b128 v[204:207], v155 offset:21504
	ds_read_b128 v[208:211], v155 offset:22528
	ds_read_b128 v[212:215], v155 offset:23552
	global_load_lds_dwordx4 v[148:149], off
	s_add_i32 m0, s34, 0x2000
	s_add_u32 s34, s30, 0xb0000
	v_lshl_add_u64 v[216:217], s[30:31], 0, v[136:137]
	s_addc_u32 s35, s31, 0
	s_add_i32 s57, s51, s40
	global_load_lds_dwordx4 v[216:217], off
	v_lshl_add_u64 v[218:219], s[34:35], 0, v[132:133]
	s_mov_b32 m0, s57
	v_lshl_add_u64 v[220:221], s[36:37], 0, v[134:135]
	global_load_lds_dwordx4 v[218:219], off
	s_add_i32 m0, s57, 0x2000
	v_lshl_add_u64 v[218:219], s[34:35], 0, v[136:137]
	global_load_lds_dwordx4 v[218:219], off
	s_mov_b32 m0, s41
	v_lshl_add_u64 v[218:219], s[36:37], 0, v[130:131]
	global_load_lds_dwordx4 v[218:219], off
	s_mov_b32 m0, s42
	s_nop 0
	global_load_lds_dwordx4 v[220:221], off
	s_waitcnt vmcnt(8)
	s_waitcnt lgkmcnt(0)
	s_barrier
	s_setprio 1
	s_waitcnt lgkmcnt(0)
	v_mfma_f32_16x16x32_bf16 v[60:63], v[144:147], v[184:187], v[60:63]
	v_mfma_f32_16x16x32_bf16 v[56:59], v[160:163], v[184:187], v[56:59]
	v_mfma_f32_16x16x32_bf16 v[44:47], v[144:147], v[192:195], v[44:47]
	v_mfma_f32_16x16x32_bf16 v[40:43], v[160:163], v[192:195], v[40:43]
	v_mfma_f32_16x16x32_bf16 v[28:31], v[144:147], v[200:203], v[28:31]
	v_mfma_f32_16x16x32_bf16 v[24:27], v[160:163], v[200:203], v[24:27]
	v_mfma_f32_16x16x32_bf16 v[12:15], v[144:147], v[208:211], v[12:15]
	v_mfma_f32_16x16x32_bf16 v[8:11], v[160:163], v[208:211], v[8:11]
	v_mfma_f32_16x16x32_bf16 v[60:63], v[156:159], v[188:191], v[60:63]
	v_mfma_f32_16x16x32_bf16 v[56:59], v[164:167], v[188:191], v[56:59]
	v_mfma_f32_16x16x32_bf16 v[44:47], v[156:159], v[196:199], v[44:47]
	v_mfma_f32_16x16x32_bf16 v[40:43], v[164:167], v[196:199], v[40:43]
	v_mfma_f32_16x16x32_bf16 v[28:31], v[156:159], v[204:207], v[28:31]
	v_mfma_f32_16x16x32_bf16 v[24:27], v[164:167], v[204:207], v[24:27]
	v_mfma_f32_16x16x32_bf16 v[12:15], v[156:159], v[212:215], v[12:15]
	v_mfma_f32_16x16x32_bf16 v[8:11], v[164:167], v[212:215], v[8:11]
	v_mfma_f32_16x16x32_bf16 v[52:55], v[168:171], v[184:187], v[52:55]
	v_mfma_f32_16x16x32_bf16 v[48:51], v[176:179], v[184:187], v[48:51]
	v_mfma_f32_16x16x32_bf16 v[36:39], v[168:171], v[192:195], v[36:39]
	v_mfma_f32_16x16x32_bf16 v[32:35], v[176:179], v[192:195], v[32:35]
	v_mfma_f32_16x16x32_bf16 v[20:23], v[168:171], v[200:203], v[20:23]
	v_mfma_f32_16x16x32_bf16 v[16:19], v[176:179], v[200:203], v[16:19]
	v_mfma_f32_16x16x32_bf16 v[4:7], v[168:171], v[208:211], v[4:7]
	v_mfma_f32_16x16x32_bf16 v[0:3], v[176:179], v[208:211], v[0:3]
	v_mfma_f32_16x16x32_bf16 v[52:55], v[172:175], v[188:191], v[52:55]
	v_mfma_f32_16x16x32_bf16 v[48:51], v[180:183], v[188:191], v[48:51]
	v_mfma_f32_16x16x32_bf16 v[36:39], v[172:175], v[196:199], v[36:39]
	v_mfma_f32_16x16x32_bf16 v[32:35], v[180:183], v[196:199], v[32:35]
	v_mfma_f32_16x16x32_bf16 v[20:23], v[172:175], v[204:207], v[20:23]
	v_mfma_f32_16x16x32_bf16 v[16:19], v[180:183], v[204:207], v[16:19]
	v_mfma_f32_16x16x32_bf16 v[4:7], v[172:175], v[212:215], v[4:7]
	v_mfma_f32_16x16x32_bf16 v[0:3], v[180:183], v[212:215], v[0:3]
	s_setprio 0
	s_barrier
	s_add_i32 s57, 0, 0x18000
	s_add_i32 s58, 0, 0x1c000
	v_add_u32_e32 v164, s57, v151
	v_add_u32_e32 v180, s58, v151
	ds_read_b128 v[144:147], v164
	ds_read_b128 v[156:159], v164 offset:1024
	ds_read_b128 v[160:163], v164 offset:2048
	ds_read_b128 v[164:167], v164 offset:3072
	ds_read_b128 v[168:171], v180
	ds_read_b128 v[172:175], v180 offset:1024
	ds_read_b128 v[176:179], v180 offset:2048
	ds_read_b128 v[180:183], v180 offset:3072
	s_add_u32 s34, s36, 0xb0000
	s_addc_u32 s35, s37, 0
	s_mov_b32 m0, s43
	v_lshl_add_u64 v[222:223], s[34:35], 0, v[130:131]
	ds_read_b128 v[184:187], v155 offset:32768
	ds_read_b128 v[188:191], v155 offset:33792
	ds_read_b128 v[192:195], v155 offset:34816
	ds_read_b128 v[196:199], v155 offset:35840
	ds_read_b128 v[200:203], v155 offset:36864
	ds_read_b128 v[204:207], v155 offset:37888
	ds_read_b128 v[208:211], v155 offset:38912
	ds_read_b128 v[212:215], v155 offset:39936
	global_load_lds_dwordx4 v[222:223], off
	s_mov_b32 m0, s44
	v_lshl_add_u64 v[222:223], s[34:35], 0, v[134:135]
	global_load_lds_dwordx4 v[222:223], off
	s_waitcnt vmcnt(8)
	s_waitcnt lgkmcnt(0)
	s_barrier
	s_setprio 1
	s_waitcnt lgkmcnt(0)
	v_mfma_f32_16x16x32_bf16 v[124:127], v[144:147], v[184:187], v[124:127]
	v_mfma_f32_16x16x32_bf16 v[120:123], v[160:163], v[184:187], v[120:123]
	v_mfma_f32_16x16x32_bf16 v[108:111], v[144:147], v[192:195], v[108:111]
	v_mfma_f32_16x16x32_bf16 v[104:107], v[160:163], v[192:195], v[104:107]
	v_mfma_f32_16x16x32_bf16 v[92:95], v[144:147], v[200:203], v[92:95]
	v_mfma_f32_16x16x32_bf16 v[88:91], v[160:163], v[200:203], v[88:91]
	v_mfma_f32_16x16x32_bf16 v[76:79], v[144:147], v[208:211], v[76:79]
	v_mfma_f32_16x16x32_bf16 v[72:75], v[160:163], v[208:211], v[72:75]
	v_mfma_f32_16x16x32_bf16 v[124:127], v[156:159], v[188:191], v[124:127]
	v_mfma_f32_16x16x32_bf16 v[120:123], v[164:167], v[188:191], v[120:123]
	v_mfma_f32_16x16x32_bf16 v[108:111], v[156:159], v[196:199], v[108:111]
	v_mfma_f32_16x16x32_bf16 v[104:107], v[164:167], v[196:199], v[104:107]
	v_mfma_f32_16x16x32_bf16 v[92:95], v[156:159], v[204:207], v[92:95]
	v_mfma_f32_16x16x32_bf16 v[88:91], v[164:167], v[204:207], v[88:91]
	v_mfma_f32_16x16x32_bf16 v[76:79], v[156:159], v[212:215], v[76:79]
	v_mfma_f32_16x16x32_bf16 v[72:75], v[164:167], v[212:215], v[72:75]
	v_mfma_f32_16x16x32_bf16 v[116:119], v[168:171], v[184:187], v[116:119]
	v_mfma_f32_16x16x32_bf16 v[112:115], v[176:179], v[184:187], v[112:115]
	v_mfma_f32_16x16x32_bf16 v[100:103], v[168:171], v[192:195], v[100:103]
	v_mfma_f32_16x16x32_bf16 v[96:99], v[176:179], v[192:195], v[96:99]
	v_mfma_f32_16x16x32_bf16 v[84:87], v[168:171], v[200:203], v[84:87]
	v_mfma_f32_16x16x32_bf16 v[80:83], v[176:179], v[200:203], v[80:83]
	v_mfma_f32_16x16x32_bf16 v[68:71], v[168:171], v[208:211], v[68:71]
	v_mfma_f32_16x16x32_bf16 v[64:67], v[176:179], v[208:211], v[64:67]
	v_mfma_f32_16x16x32_bf16 v[116:119], v[172:175], v[188:191], v[116:119]
	v_mfma_f32_16x16x32_bf16 v[112:115], v[180:183], v[188:191], v[112:115]
	v_mfma_f32_16x16x32_bf16 v[100:103], v[172:175], v[196:199], v[100:103]
	v_mfma_f32_16x16x32_bf16 v[96:99], v[180:183], v[196:199], v[96:99]
	v_mfma_f32_16x16x32_bf16 v[84:87], v[172:175], v[204:207], v[84:87]
	v_mfma_f32_16x16x32_bf16 v[80:83], v[180:183], v[204:207], v[80:83]
	v_mfma_f32_16x16x32_bf16 v[68:71], v[172:175], v[212:215], v[68:71]
	v_mfma_f32_16x16x32_bf16 v[64:67], v[180:183], v[212:215], v[64:67]
	s_setprio 0
	s_barrier
	s_add_i32 s34, s57, s40
	v_lshl_add_u64 v[148:149], v[148:149], 0, s[8:9]
	s_mov_b32 m0, s34
	ds_read_b128 v[184:187], v155 offset:49152
	ds_read_b128 v[188:191], v155 offset:50176
	ds_read_b128 v[192:195], v155 offset:51200
	ds_read_b128 v[196:199], v155 offset:52224
	ds_read_b128 v[200:203], v155 offset:53248
	ds_read_b128 v[204:207], v155 offset:54272
	ds_read_b128 v[208:211], v155 offset:55296
	ds_read_b128 v[212:215], v155 offset:56320
	global_load_lds_dwordx4 v[148:149], off
	s_add_i32 m0, s34, 0x2000
	s_add_u32 s30, s30, 0xb0080
	v_lshl_add_u64 v[148:149], v[216:217], 0, s[8:9]
	s_addc_u32 s31, s31, 0
	s_add_i32 s34, s58, s40
	global_load_lds_dwordx4 v[148:149], off
	s_mov_b32 m0, s34
	v_lshl_add_u64 v[148:149], s[30:31], 0, v[132:133]
	global_load_lds_dwordx4 v[148:149], off
	s_add_i32 m0, s34, 0x2000
	v_lshl_add_u64 v[148:149], s[30:31], 0, v[136:137]
	global_load_lds_dwordx4 v[148:149], off
	s_mov_b32 m0, s46
	v_lshl_add_u64 v[148:149], v[218:219], 0, s[8:9]
	global_load_lds_dwordx4 v[148:149], off
	s_mov_b32 m0, s47
	v_lshl_add_u64 v[148:149], v[220:221], 0, s[8:9]
	global_load_lds_dwordx4 v[148:149], off
	s_waitcnt vmcnt(8)
	s_waitcnt lgkmcnt(0)
	s_barrier
	s_setprio 1
	s_waitcnt lgkmcnt(0)
	v_mfma_f32_16x16x32_bf16 v[60:63], v[144:147], v[184:187], v[60:63]
	v_mfma_f32_16x16x32_bf16 v[56:59], v[160:163], v[184:187], v[56:59]
	v_mfma_f32_16x16x32_bf16 v[44:47], v[144:147], v[192:195], v[44:47]
	v_mfma_f32_16x16x32_bf16 v[40:43], v[160:163], v[192:195], v[40:43]
	v_mfma_f32_16x16x32_bf16 v[28:31], v[144:147], v[200:203], v[28:31]
	v_mfma_f32_16x16x32_bf16 v[24:27], v[160:163], v[200:203], v[24:27]
	v_mfma_f32_16x16x32_bf16 v[12:15], v[144:147], v[208:211], v[12:15]
	v_mfma_f32_16x16x32_bf16 v[8:11], v[160:163], v[208:211], v[8:11]
	v_mfma_f32_16x16x32_bf16 v[60:63], v[156:159], v[188:191], v[60:63]
	v_mfma_f32_16x16x32_bf16 v[56:59], v[164:167], v[188:191], v[56:59]
	v_mfma_f32_16x16x32_bf16 v[44:47], v[156:159], v[196:199], v[44:47]
	v_mfma_f32_16x16x32_bf16 v[40:43], v[164:167], v[196:199], v[40:43]
	v_mfma_f32_16x16x32_bf16 v[28:31], v[156:159], v[204:207], v[28:31]
	v_mfma_f32_16x16x32_bf16 v[24:27], v[164:167], v[204:207], v[24:27]
	v_mfma_f32_16x16x32_bf16 v[12:15], v[156:159], v[212:215], v[12:15]
	v_mfma_f32_16x16x32_bf16 v[8:11], v[164:167], v[212:215], v[8:11]
	v_mfma_f32_16x16x32_bf16 v[52:55], v[168:171], v[184:187], v[52:55]
	v_mfma_f32_16x16x32_bf16 v[48:51], v[176:179], v[184:187], v[48:51]
	v_mfma_f32_16x16x32_bf16 v[36:39], v[168:171], v[192:195], v[36:39]
	v_mfma_f32_16x16x32_bf16 v[32:35], v[176:179], v[192:195], v[32:35]
	v_mfma_f32_16x16x32_bf16 v[20:23], v[168:171], v[200:203], v[20:23]
	v_mfma_f32_16x16x32_bf16 v[16:19], v[176:179], v[200:203], v[16:19]
	v_mfma_f32_16x16x32_bf16 v[4:7], v[168:171], v[208:211], v[4:7]
	v_mfma_f32_16x16x32_bf16 v[0:3], v[176:179], v[208:211], v[0:3]
	v_mfma_f32_16x16x32_bf16 v[52:55], v[172:175], v[188:191], v[52:55]
	v_mfma_f32_16x16x32_bf16 v[48:51], v[180:183], v[188:191], v[48:51]
	v_mfma_f32_16x16x32_bf16 v[36:39], v[172:175], v[196:199], v[36:39]
	v_mfma_f32_16x16x32_bf16 v[32:35], v[180:183], v[196:199], v[32:35]
	v_mfma_f32_16x16x32_bf16 v[20:23], v[172:175], v[204:207], v[20:23]
	v_mfma_f32_16x16x32_bf16 v[16:19], v[180:183], v[204:207], v[16:19]
	v_mfma_f32_16x16x32_bf16 v[4:7], v[172:175], v[212:215], v[4:7]
	v_mfma_f32_16x16x32_bf16 v[0:3], v[180:183], v[212:215], v[0:3]
	s_setprio 0
	s_cmp_eq_u32 s56, s98
	s_cbranch_scc1 .Lmy_nobar_23
	s_barrier
